# v_rsq_f32 replaces IEEE sqrt+div expansions (43 sites), passC sum-of-squares via DPP, rope table binary powers, K-loop barrier shift, P2 epilogue prefetch
# speedup vs baseline: 1.0165x; 1.0113x over previous
; __device__ __forceinline__ void phase_prologue(const Params& p, LAS unsigned char* lds, int wave, int lane) {
;     ...
;         double inv = 1.0; for (int k = 0; k < i; ++k) inv *= 0.8659643233600653;
;         double a = (double)pos * inv;
;         const double kq = __builtin_rint(a * 0.6366197723675814);
;         double t = a - kq * 1.5707963267948966; t -= kq * 6.123233995736766e-17;
;         const double t2 = t * t;
;         double sn = t * (1.0 + t2 * (-1.0 / 6 + t2 * (1.0 / 120 + t2 * (-1.0 / 5040 + t2 * (1.0 / 362880 + t2 * (-1.0 / 39916800 + t2 * (1.0 / 6227020800.0)))))));
;         double cn = 1.0 + t2 * (-0.5 + t2 * (1.0 / 24 + t2 * (-1.0 / 720 + t2 * (1.0 / 40320 + t2 * (-1.0 / 3628800 + t2 * (1.0 / 479001600.0 + t2 * (-1.0 / 87178291200.0)))))));
;         const int q = ((int)kq) & 3;
;         double c = (q == 0) ? cn : (q == 1) ? -sn : (q == 2) ? -cn : sn;
;         double s = (q == 0) ? sn : (q == 1) ? cn : (q == 2) ? -sn : -cn;
.LBB0_64:
	v_mov_b64_e32 v[24:25], 1.0
	v_and_b32_e32 v23, 1, v1
	v_mul_f64 v[26:27], v[24:25], s[16:17]
	v_cmp_ne_u32_e64 s[4:5], 0, v23
	s_nop 1
	v_cndmask_b32_e64 v24, v24, v26, s[4:5]
	v_cndmask_b32_e64 v25, v25, v27, s[4:5]
	s_mov_b32 s30, 0x24115d99
	s_mov_b32 s31, 0x3fe7ff22
	v_and_b32_e32 v23, 2, v1
	v_mul_f64 v[26:27], v[24:25], s[30:31]
	v_cmp_ne_u32_e64 s[4:5], 0, v23
	s_nop 1
	v_cndmask_b32_e64 v24, v24, v26, s[4:5]
	v_cndmask_b32_e64 v25, v25, v27, s[4:5]
	s_mov_b32 s30, 0x3c1c381e
	s_mov_b32 s31, 0x3fe1feb3
	v_and_b32_e32 v23, 4, v1
	v_mul_f64 v[26:27], v[24:25], s[30:31]
	v_cmp_ne_u32_e64 s[4:5], 0, v23
	s_nop 1
	v_cndmask_b32_e64 v24, v24, v26, s[4:5]
	v_cndmask_b32_e64 v25, v25, v27, s[4:5]
	s_mov_b32 s30, 0x6248490f
	s_mov_b32 s31, 0x3fd43d13
	v_and_b32_e32 v23, 8, v1
	v_mul_f64 v[26:27], v[24:25], s[30:31]
	v_cmp_ne_u32_e64 s[4:5], 0, v23
	s_nop 1
	v_cndmask_b32_e64 v24, v24, v26, s[4:5]
	v_cndmask_b32_e64 v25, v25, v27, s[4:5]
	s_mov_b32 s30, 0x99999999
	s_mov_b32 s31, 0x3fb99999
	v_and_b32_e32 v23, 16, v1
	v_mul_f64 v[26:27], v[24:25], s[30:31]
	v_cmp_ne_u32_e64 s[4:5], 0, v23
	s_nop 1
	v_cndmask_b32_e64 v24, v24, v26, s[4:5]
	v_cndmask_b32_e64 v25, v25, v27, s[4:5]
	s_mov_b32 s30, 0x47ae147a
	s_mov_b32 s31, 0x3f847ae1
	v_and_b32_e32 v23, 32, v1
	v_mul_f64 v[26:27], v[24:25], s[30:31]
	v_cmp_ne_u32_e64 s[4:5], 0, v23
	s_nop 1
	v_cndmask_b32_e64 v24, v24, v26, s[4:5]
	v_cndmask_b32_e64 v25, v25, v27, s[4:5]
	v_ashrrev_i32_e32 v23, 6, v22
	v_cvt_f64_i32_e32 v[26:27], v23
	v_mul_f64 v[24:25], v[24:25], v[26:27]
	v_mul_f64 v[26:27], v[24:25], s[18:19]
	v_rndne_f64_e32 v[28:29], v[26:27]
	v_fmac_f64_e32 v[24:25], s[22:23], v[28:29]
	v_fmac_f64_e32 v[24:25], s[24:25], v[28:29]
	v_mul_f64 v[26:27], v[24:25], v[24:25]
	v_fma_f64 v[30:31], s[26:27], v[26:27], v[2:3]
	v_fma_f64 v[30:31], v[26:27], v[30:31], v[4:5]
	v_fma_f64 v[30:31], v[26:27], v[30:31], v[6:7]
	v_fma_f64 v[30:31], v[26:27], v[30:31], v[8:9]
	v_fma_f64 v[30:31], v[26:27], v[30:31], v[10:11]
	v_fma_f64 v[30:31], v[26:27], v[30:31], 1.0
	v_mul_f64 v[24:25], v[24:25], v[30:31]
	v_fma_f64 v[30:31], s[28:29], v[26:27], v[12:13]
	v_fma_f64 v[30:31], v[26:27], v[30:31], v[14:15]
	v_fma_f64 v[30:31], v[26:27], v[30:31], v[16:17]
	v_fma_f64 v[30:31], v[26:27], v[30:31], v[18:19]
	v_fma_f64 v[30:31], v[26:27], v[30:31], v[20:21]
	v_fma_f64 v[30:31], v[26:27], v[30:31], -0.5
	v_cvt_i32_f64_e32 v23, v[28:29]
	v_fma_f64 v[26:27], v[26:27], v[30:31], 1.0
	v_and_b32_e32 v23, 3, v23
	v_cmp_eq_u32_e64 s[4:5], 0, v23
	v_cmp_ne_u32_e64 s[6:7], 0, v23
	v_mov_b64_e32 v[28:29], v[26:27]
	s_and_saveexec_b64 s[30:31], s[6:7]
	s_cbranch_execz .LBB0_63
	v_cmp_ne_u32_e64 s[6:7], 1, v23
	v_xor_b32_e32 v29, 0x80000000, v25
	v_mov_b32_e32 v28, v24
	s_and_saveexec_b64 s[34:35], s[6:7]
	s_xor_b64 s[34:35], exec, s[34:35]
	s_cbranch_execz .LBB0_62
	v_xor_b32_e32 v28, 0x80000000, v27
	v_cmp_eq_u32_e64 s[6:7], 2, v23
	s_nop 1
	v_cndmask_b32_e64 v29, v25, v28, s[6:7]
	v_cndmask_b32_e64 v28, v24, v26, s[6:7]
	s_branch .LBB0_62

; __device__ __forceinline__ unsigned cvtpk(float lo, float hi) { f32x2 v = {lo, hi}; bf16x2_t b = __builtin_convertvector(v, bf16x2_t); return __builtin_bit_cast(unsigned, b); }
; __device__ __forceinline__ int hw_lane() { int l; asm volatile("v_mbcnt_lo_u32_b32 %0, -1, 0\n\tv_mbcnt_hi_u32_b32 %0, -1, %0" : "=v"(l)); return l; }
; __device__ __forceinline__ void rms_row_to_bf16(const float* xrow, bf16_t* orow, int lane) {
;     const f32x4* xr = (const f32x4*)xrow + lane;
;     f32x4 v[8]; float s = 0.f;
; #pragma unroll
;     for (int j = 0; j < 8; ++j) { v[j] = xr[64 * j]; s += (v[j].x * v[j].x + v[j].y * v[j].y) + (v[j].z * v[j].z + v[j].w * v[j].w); }
;     const float rstd = 1.0f / sqrtf(wave_sum(s) * (1.0f / DM) + EPS);
;     u32x2* o8 = (u32x2*)orow + lane;
; #pragma unroll
;     for (int j = 0; j < 8; ++j) { u32x2 w; w.x = cvtpk(v[j].x * rstd, v[j].y * rstd); w.y = cvtpk(v[j].z * rstd, v[j].w * rstd); o8[64 * j] = w; }
; }
; __device__ __forceinline__ void norm_pass(const float* src, bf16_t* XN, int gw, int NGW, int lane) {
;     lane = hw_lane();
;     for (int m = gw; m < MTOK; m += NGW) rms_row_to_bf16(src + (size_t)m * DM, XN + (size_t)m * DM, lane);
.LBB0_76:
	global_load_dwordx4 v[4:7], v[24:25], off offset:-4096
	global_load_dwordx4 v[0:3], v[24:25], off offset:-3072
	global_load_dwordx4 v[8:11], v[24:25], off offset:-2048
	global_load_dwordx4 v[12:15], v[24:25], off
	global_load_dwordx4 v[16:19], v[24:25], off offset:-1024
	global_load_dwordx4 v[20:23], v[24:25], off offset:1024
	global_load_dwordx4 v[36:39], v[24:25], off offset:3072
	global_load_dwordx4 v[40:43], v[24:25], off offset:2048
	s_add_i32 s10, s10, s0
	v_lshl_add_u64 v[24:25], v[24:25], 0, s[2:3]
	s_cmpk_gt_i32 s10, 0x3fff
	s_waitcnt vmcnt(7)
	v_mov_b32_e32 v46, v5
	s_waitcnt vmcnt(6)
	v_mov_b32_e32 v47, v1
	v_mov_b32_e32 v50, v7
	v_mov_b32_e32 v51, v3
	v_mov_b32_e32 v44, v4
	v_mov_b32_e32 v45, v0
	v_mov_b32_e32 v48, v6
	v_mov_b32_e32 v49, v2
	s_waitcnt vmcnt(5)
	v_pk_mul_f32 v[52:53], v[10:11], v[10:11]
	v_pk_mul_f32 v[54:55], v[8:9], v[8:9]
	v_pk_mul_f32 v[46:47], v[46:47], v[46:47]
	v_pk_mul_f32 v[50:51], v[50:51], v[50:51]
	v_pk_mov_b32 v[68:69], v[54:55], v[52:53] op_sel:[1,0]
	v_mov_b32_e32 v55, v53
	v_pk_fma_f32 v[44:45], v[44:45], v[44:45], v[46:47]
	v_pk_fma_f32 v[46:47], v[48:49], v[48:49], v[50:51]
	s_waitcnt vmcnt(3)
	v_mul_f32_e32 v56, v17, v17
	v_mul_f32_e32 v58, v19, v19
	v_pk_add_f32 v[48:49], v[68:69], v[54:55]
	v_pk_add_f32 v[44:45], v[44:45], v[46:47]
	v_mul_f32_e32 v67, v12, v12
	v_mul_f32_e32 v70, v13, v13
	v_mul_f32_e32 v71, v14, v14
	v_mul_f32_e32 v72, v15, v15
	v_pk_fma_f32 v[52:53], v[16:17], v[16:17], v[56:57] op_sel_hi:[1,1,0]
	v_pk_fma_f32 v[56:57], v[18:19], v[18:19], v[58:59] op_sel_hi:[1,1,0]
	v_pk_add_f32 v[46:47], v[48:49], v[48:49] op_sel:[0,1] op_sel_hi:[1,0]
	v_pk_add_f32 v[44:45], v[44:45], v[44:45] op_sel:[0,1] op_sel_hi:[1,0]
	s_waitcnt vmcnt(2)
	v_pk_mul_f32 v[60:61], v[22:23], v[22:23]
	v_pk_mul_f32 v[62:63], v[20:21], v[20:21]
	v_mov_b32_e32 v53, v71
	v_mov_b32_e32 v57, v72
	v_mov_b32_e32 v47, v70
	v_mov_b32_e32 v45, v67
	v_pk_mov_b32 v[58:59], v[62:63], v[60:61] op_sel:[1,0]
	v_mov_b32_e32 v63, v61
	v_pk_add_f32 v[48:49], v[52:53], v[56:57]
	v_pk_add_f32 v[44:45], v[44:45], v[46:47]
	s_waitcnt vmcnt(0)
	v_mul_f32_e32 v64, v41, v41
	v_mul_f32_e32 v66, v43, v43
	v_pk_add_f32 v[50:51], v[58:59], v[62:63]
	v_pk_add_f32 v[44:45], v[44:45], v[48:49]
	v_mul_f32_e32 v73, v36, v36
	v_mul_f32_e32 v74, v37, v37
	v_mul_f32_e32 v75, v38, v38
	v_mul_f32_e32 v76, v39, v39
	v_pk_fma_f32 v[60:61], v[40:41], v[40:41], v[64:65] op_sel_hi:[1,1,0]
	v_pk_fma_f32 v[64:65], v[42:43], v[42:43], v[66:67] op_sel_hi:[1,1,0]
	v_pk_add_f32 v[50:51], v[50:51], v[50:51] op_sel:[0,1] op_sel_hi:[1,0]
	v_pk_add_f32 v[44:45], v[44:45], v[44:45] op_sel:[0,1] op_sel_hi:[1,0]
	v_mov_b32_e32 v61, v75
	v_mov_b32_e32 v65, v76
	v_mov_b32_e32 v51, v74
	v_mov_b32_e32 v45, v73
	v_pk_add_f32 v[52:53], v[60:61], v[64:65]
	v_pk_add_f32 v[44:45], v[44:45], v[50:51]
	s_nop 0
	v_pk_add_f32 v[44:45], v[44:45], v[52:53]
	s_nop 0
	v_add_f32_e32 v44, v44, v45
	ds_bpermute_b32 v45, v28, v44
	s_waitcnt lgkmcnt(0)
	v_add_f32_e32 v44, v44, v45
	ds_bpermute_b32 v45, v29, v44
	s_waitcnt lgkmcnt(0)
	v_add_f32_e32 v44, v44, v45
	ds_bpermute_b32 v45, v30, v44
	s_waitcnt lgkmcnt(0)
	v_add_f32_e32 v44, v44, v45
	ds_bpermute_b32 v45, v31, v44
	s_waitcnt lgkmcnt(0)
	v_add_f32_e32 v44, v44, v45
	ds_bpermute_b32 v45, v32, v44
	s_waitcnt lgkmcnt(0)
	v_add_f32_e32 v44, v44, v45
	ds_bpermute_b32 v45, v33, v44
	s_waitcnt lgkmcnt(0)
	v_add_f32_e32 v44, v44, v45
	v_fmamk_f32 v44, v44, 0x3a000000, v34
	s_nop 1
	v_rsq_f32_e32 v44, v44
	s_nop 1
	s_nop 0
	v_mov_b32_e32 v44, v44
	s_nop 0
	v_mov_b32_e32 v44, v44
	v_pk_mul_f32 v[4:5], v[4:5], v[44:45] op_sel_hi:[1,0]
	v_pk_mul_f32 v[6:7], v[6:7], v[44:45] op_sel_hi:[1,0]
	v_pk_mul_f32 v[0:1], v[0:1], v[44:45] op_sel_hi:[1,0]
	v_pk_mul_f32 v[2:3], v[2:3], v[44:45] op_sel_hi:[1,0]
	v_pk_mul_f32 v[8:9], v[8:9], v[44:45] op_sel_hi:[1,0]
	v_pk_mul_f32 v[10:11], v[10:11], v[44:45] op_sel_hi:[1,0]
	v_pk_mul_f32 v[16:17], v[16:17], v[44:45] op_sel_hi:[1,0]
	v_pk_mul_f32 v[18:19], v[18:19], v[44:45] op_sel_hi:[1,0]
	v_pk_mul_f32 v[12:13], v[12:13], v[44:45] op_sel_hi:[1,0]
	v_pk_mul_f32 v[14:15], v[14:15], v[44:45] op_sel_hi:[1,0]
	v_pk_mul_f32 v[20:21], v[20:21], v[44:45] op_sel_hi:[1,0]
	v_pk_mul_f32 v[22:23], v[22:23], v[44:45] op_sel_hi:[1,0]
	v_pk_mul_f32 v[40:41], v[40:41], v[44:45] op_sel_hi:[1,0]
	v_pk_mul_f32 v[42:43], v[42:43], v[44:45] op_sel_hi:[1,0]
	v_pk_mul_f32 v[36:37], v[36:37], v[44:45] op_sel_hi:[1,0]
	v_pk_mul_f32 v[38:39], v[38:39], v[44:45] op_sel_hi:[1,0]
	v_cvt_pk_bf16_f32 v4, v4, v5
	v_cvt_pk_bf16_f32 v5, v6, v7
	v_cvt_pk_bf16_f32 v0, v0, v1
	v_cvt_pk_bf16_f32 v1, v2, v3
	v_cvt_pk_bf16_f32 v2, v8, v9
	v_cvt_pk_bf16_f32 v3, v10, v11
	v_cvt_pk_bf16_f32 v6, v16, v17
	v_cvt_pk_bf16_f32 v7, v18, v19
	v_cvt_pk_bf16_f32 v8, v12, v13
	v_cvt_pk_bf16_f32 v9, v14, v15
	v_cvt_pk_bf16_f32 v10, v20, v21
	v_cvt_pk_bf16_f32 v11, v22, v23
	v_cvt_pk_bf16_f32 v12, v40, v41
	v_cvt_pk_bf16_f32 v13, v42, v43
	v_cvt_pk_bf16_f32 v14, v36, v37
	v_cvt_pk_bf16_f32 v15, v38, v39
	global_store_dwordx2 v[26:27], v[4:5], off
	global_store_dwordx2 v[26:27], v[0:1], off offset:512
	global_store_dwordx2 v[26:27], v[2:3], off offset:1024
	global_store_dwordx2 v[26:27], v[6:7], off offset:1536
	global_store_dwordx2 v[26:27], v[8:9], off offset:2048
	global_store_dwordx2 v[26:27], v[10:11], off offset:2560
	global_store_dwordx2 v[26:27], v[12:13], off offset:3072
	global_store_dwordx2 v[26:27], v[14:15], off offset:3584
	v_lshl_add_u64 v[26:27], v[26:27], 0, s[6:7]
	s_cbranch_scc0 .LBB0_76

; __device__ __forceinline__ unsigned cvt_pk_bf16(float lo, float hi) { unsigned r; asm volatile("v_cvt_pk_bf16_f32 %0, %1, %2" : "=v"(r) : "v"(lo), "v"(hi)); return r; }
;     __device__ __forceinline__ void operator()(const f32x4 (&acc)[2][2][4][2], const Unit& u, int wr, int wc, int fr, int fq) const {
;     ...
;             for (int m = 0; m < 4; ++m) { const int row = row0 + ai * HALF + m * 16;
;                 const float rs = 1.0f / sqrtf(rowss[row] * (1.0f / 2048.0f) + 1e-6f);
; #pragma unroll
;                 for (int bj = 0; bj < 2; ++bj) { const f32x4 v0 = acc[ai][bj][m][0] * rs, v1 = acc[ai][bj][m][1] * rs;
;                     u32x4 w; w.x = cvt_pk_bf16(v0[0], v0[1]); w.y = cvt_pk_bf16(v0[2], v0[3]); w.z = cvt_pk_bf16(v1[0], v1[1]); w.w = cvt_pk_bf16(v1[2], v1[3]);
.LBB0_396:
	s_lshl_b32 s0, s0, 8
	s_add_i32 s5, s0, s54
	v_or_b32_e32 v148, s5, v139
	v_ashrrev_i32_e32 v149, 31, v148
	v_lshl_add_u64 v[150:151], v[148:149], 2, s[16:17]
	global_load_dword v136, v[150:151], off
	s_lshl_b32 s38, s4, 8
	v_lshlrev_b32_e32 v149, 7, v148
	s_add_i32 s0, s38, 0xfffff400
	v_and_b32_e32 v149, 0x7e780, v149
	s_lshr_b32 s0, s0, 10
	s_ashr_i32 s5, s5, 9
	s_lshl_b64 s[40:41], s[0:1], 25
	s_and_b32 s29, s5, -8
	s_cmp_gt_i32 s4, 11
	s_cselect_b64 s[10:11], -1, 0
	s_mov_b64 s[8:9], -1
	s_waitcnt vmcnt(0)
	v_fmamk_f32 v136, v136, 0x3a000000, v162
	s_nop 1
	v_rsq_f32_e32 v136, v136
	v_lshlrev_b32_e32 v152, 1, v149
	s_nop 1
	s_nop 0
	v_mov_b32_e32 v136, v136
	s_and_b64 s[4:5], exec, s[10:11]
	s_nop 0
	v_mov_b32_e32 v156, v136
	v_pk_mul_f32 v[164:165], v[122:123], v[156:157] op_sel_hi:[1,0]
	v_pk_mul_f32 v[122:123], v[120:121], v[156:157] op_sel_hi:[1,0]
	s_mov_b64 vcc, s[4:5]
	v_pk_mul_f32 v[126:127], v[126:127], v[156:157] op_sel_hi:[1,0]
	v_pk_mul_f32 v[124:125], v[124:125], v[156:157] op_sel_hi:[1,0]
	s_nop 0
	v_cvt_pk_bf16_f32 v120, v124, v125
	v_cvt_pk_bf16_f32 v121, v126, v127
	v_cvt_pk_bf16_f32 v122, v122, v123
	v_cvt_pk_bf16_f32 v123, v164, v165
	s_cbranch_vccz .LBB0_398
	s_lshr_b32 s0, s38, 7
	s_and_b32 s0, s0, 6
	s_add_u32 s8, s52, s40
	s_addc_u32 s9, s53, s41
	s_or_b32 s4, s29, s0
	s_ashr_i32 s5, s4, 31
	s_lshl_b64 s[4:5], s[4:5], 20
	s_add_u32 s4, s8, s4
	s_addc_u32 s5, s9, s5
	v_mov_b32_e32 v153, v137
	v_lshl_add_u64 v[154:155], s[4:5], 0, v[152:153]
	s_mov_b64 s[8:9], 0

; __device__ __forceinline__ unsigned cvt_pk_bf16(float lo, float hi) { unsigned r; asm volatile("v_cvt_pk_bf16_f32 %0, %1, %2" : "=v"(r) : "v"(lo), "v"(hi)); return r; }
;     __device__ __forceinline__ void operator()(const f32x4 (&acc)[2][2][4][2], const Unit& u, int wr, int wc, int fr, int fq) const {
;     ...
;             for (int m = 0; m < 4; ++m) { const int row = row0 + ai * HALF + m * 16;
;                 const float rs = 1.0f / sqrtf(rowss[row] * (1.0f / 2048.0f) + 1e-6f);
; #pragma unroll
;                 for (int bj = 0; bj < 2; ++bj) { const f32x4 v0 = acc[ai][bj][m][0] * rs, v1 = acc[ai][bj][m][1] * rs;
;                     u32x4 w; w.x = cvt_pk_bf16(v0[0], v0[1]); w.y = cvt_pk_bf16(v0[2], v0[3]); w.z = cvt_pk_bf16(v1[0], v1[1]); w.w = cvt_pk_bf16(v1[2], v1[3]);
.LBB0_404:
	v_lshl_add_u64 v[116:117], v[116:117], 0, v[136:137]
	global_store_dwordx4 v[116:117], v[112:115], off
	s_mov_b64 s[44:45], -1
	s_nop 0
	v_or_b32_e32 v112, 16, v148
	v_ashrrev_i32_e32 v113, 31, v112
	v_lshl_add_u64 v[114:115], v[112:113], 2, s[16:17]
	global_load_dword v113, v[114:115], off
	v_cndmask_b32_e64 v115, 0, 1, s[10:11]
	v_cmp_ne_u32_e64 s[8:9], 1, v115
	v_lshlrev_b32_e32 v116, 7, v112
	s_waitcnt vmcnt(0)
	v_fmamk_f32 v113, v113, 0x3a000000, v162
	s_nop 1
	v_rsq_f32_e32 v113, v113
	v_and_b32_e32 v118, 0x7ef80, v116
	s_nop 0
	s_nop 1
	s_nop 0
	v_mov_b32_e32 v113, v113
	s_nop 0
	v_mov_b32_e32 v114, v113
	v_pk_mul_f32 v[108:109], v[108:109], v[114:115] op_sel_hi:[1,0]
	s_andn2_b64 vcc, exec, s[10:11]
	v_pk_mul_f32 v[110:111], v[110:111], v[114:115] op_sel_hi:[1,0]
	v_pk_mul_f32 v[116:117], v[106:107], v[114:115] op_sel_hi:[1,0]
	v_pk_mul_f32 v[106:107], v[104:105], v[114:115] op_sel_hi:[1,0]
	v_cvt_pk_bf16_f32 v104, v108, v109
	v_lshlrev_b32_e32 v108, 1, v118
	v_cvt_pk_bf16_f32 v105, v110, v111
	v_cvt_pk_bf16_f32 v106, v106, v107
	v_cvt_pk_bf16_f32 v107, v116, v117
	s_cbranch_vccnz .LBB0_406
	s_lshr_b32 s4, s38, 7
	s_and_b32 s4, s4, 6
	s_add_u32 s10, s52, s40
	s_addc_u32 s11, s53, s41
	s_or_b32 s4, s29, s4
	s_ashr_i32 s5, s4, 31
	s_lshl_b64 s[4:5], s[4:5], 20
	s_add_u32 s4, s10, s4
	s_addc_u32 s5, s11, s5
	v_mov_b32_e32 v109, v137
	v_lshl_add_u64 v[110:111], s[4:5], 0, v[108:109]
	s_mov_b64 s[44:45], 0

; __device__ __forceinline__ unsigned cvt_pk_bf16(float lo, float hi) { unsigned r; asm volatile("v_cvt_pk_bf16_f32 %0, %1, %2" : "=v"(r) : "v"(lo), "v"(hi)); return r; }
;     __device__ __forceinline__ void operator()(const f32x4 (&acc)[2][2][4][2], const Unit& u, int wr, int wc, int fr, int fq) const {
;     ...
;             for (int m = 0; m < 4; ++m) { const int row = row0 + ai * HALF + m * 16;
;                 const float rs = 1.0f / sqrtf(rowss[row] * (1.0f / 2048.0f) + 1e-6f);
; #pragma unroll
;                 for (int bj = 0; bj < 2; ++bj) { const f32x4 v0 = acc[ai][bj][m][0] * rs, v1 = acc[ai][bj][m][1] * rs;
;                     u32x4 w; w.x = cvt_pk_bf16(v0[0], v0[1]); w.y = cvt_pk_bf16(v0[2], v0[3]); w.z = cvt_pk_bf16(v1[0], v1[1]); w.w = cvt_pk_bf16(v1[2], v1[3]);
.LBB0_412:
	v_lshl_add_u64 v[100:101], v[100:101], 0, v[136:137]
	global_store_dwordx4 v[100:101], v[96:99], off
	s_mov_b64 s[42:43], -1
	s_nop 0
	v_or_b32_e32 v96, 32, v148
	v_ashrrev_i32_e32 v97, 31, v96
	v_lshl_add_u64 v[98:99], v[96:97], 2, s[16:17]
	global_load_dword v97, v[98:99], off
	v_lshlrev_b32_e32 v99, 7, v96
	v_and_b32_e32 v99, 0x7f780, v99
	s_waitcnt vmcnt(0)
	v_fmamk_f32 v97, v97, 0x3a000000, v162
	s_nop 1
	v_rsq_f32_e32 v97, v97
	s_nop 1
	s_nop 0
	v_mov_b32_e32 v97, v97
	s_nop 0
	v_mov_b32_e32 v98, v97
	v_pk_mul_f32 v[92:93], v[92:93], v[98:99] op_sel_hi:[1,0]
	s_and_b64 vcc, exec, s[8:9]
	v_pk_mul_f32 v[94:95], v[94:95], v[98:99] op_sel_hi:[1,0]
	v_pk_mul_f32 v[100:101], v[90:91], v[98:99] op_sel_hi:[1,0]
	v_pk_mul_f32 v[90:91], v[88:89], v[98:99] op_sel_hi:[1,0]
	v_cvt_pk_bf16_f32 v88, v92, v93
	v_lshlrev_b32_e32 v92, 1, v99
	v_cvt_pk_bf16_f32 v89, v94, v95
	v_cvt_pk_bf16_f32 v90, v90, v91
	v_cvt_pk_bf16_f32 v91, v100, v101
	s_cbranch_vccnz .LBB0_414
	s_lshr_b32 s4, s38, 7
	s_and_b32 s4, s4, 6
	s_add_u32 s31, s52, s40
	s_addc_u32 s33, s53, s41
	s_or_b32 s4, s29, s4
	s_ashr_i32 s5, s4, 31
	s_lshl_b64 s[4:5], s[4:5], 20
	s_add_u32 s4, s31, s4
	s_addc_u32 s5, s33, s5
	v_mov_b32_e32 v93, v137
	v_lshl_add_u64 v[94:95], s[4:5], 0, v[92:93]
	s_mov_b64 s[42:43], 0

; __device__ __forceinline__ unsigned cvt_pk_bf16(float lo, float hi) { unsigned r; asm volatile("v_cvt_pk_bf16_f32 %0, %1, %2" : "=v"(r) : "v"(lo), "v"(hi)); return r; }
;     __device__ __forceinline__ void operator()(const f32x4 (&acc)[2][2][4][2], const Unit& u, int wr, int wc, int fr, int fq) const {
;     ...
;             for (int m = 0; m < 4; ++m) { const int row = row0 + ai * HALF + m * 16;
;                 const float rs = 1.0f / sqrtf(rowss[row] * (1.0f / 2048.0f) + 1e-6f);
; #pragma unroll
;                 for (int bj = 0; bj < 2; ++bj) { const f32x4 v0 = acc[ai][bj][m][0] * rs, v1 = acc[ai][bj][m][1] * rs;
;                     u32x4 w; w.x = cvt_pk_bf16(v0[0], v0[1]); w.y = cvt_pk_bf16(v0[2], v0[3]); w.z = cvt_pk_bf16(v1[0], v1[1]); w.w = cvt_pk_bf16(v1[2], v1[3]);
.LBB0_420:
	v_lshl_add_u64 v[84:85], v[84:85], 0, v[136:137]
	global_store_dwordx4 v[84:85], v[80:83], off
	s_mov_b64 s[42:43], -1
	s_nop 0
	v_or_b32_e32 v80, 48, v148
	v_ashrrev_i32_e32 v81, 31, v80
	v_lshl_add_u64 v[82:83], v[80:81], 2, s[16:17]
	global_load_dword v81, v[82:83], off
	v_lshlrev_b32_e32 v83, 7, v80
	v_and_b32_e32 v83, 0x7ff80, v83
	s_waitcnt vmcnt(0)
	v_fmamk_f32 v81, v81, 0x3a000000, v162
	s_nop 1
	v_rsq_f32_e32 v81, v81
	s_nop 1
	s_nop 0
	v_mov_b32_e32 v81, v81
	s_nop 0
	v_mov_b32_e32 v82, v81
	v_pk_mul_f32 v[76:77], v[76:77], v[82:83] op_sel_hi:[1,0]
	s_and_b64 vcc, exec, s[8:9]
	v_pk_mul_f32 v[78:79], v[78:79], v[82:83] op_sel_hi:[1,0]
	v_pk_mul_f32 v[84:85], v[74:75], v[82:83] op_sel_hi:[1,0]
	v_pk_mul_f32 v[74:75], v[72:73], v[82:83] op_sel_hi:[1,0]
	v_cvt_pk_bf16_f32 v72, v76, v77
	v_lshlrev_b32_e32 v76, 1, v83
	v_cvt_pk_bf16_f32 v73, v78, v79
	v_cvt_pk_bf16_f32 v74, v74, v75
	v_cvt_pk_bf16_f32 v75, v84, v85
	s_cbranch_vccnz .LBB0_422
	s_lshr_b32 s4, s38, 7
	s_and_b32 s4, s4, 6
	s_add_u32 s31, s52, s40
	s_addc_u32 s33, s53, s41
	s_or_b32 s4, s29, s4
	s_ashr_i32 s5, s4, 31
	s_lshl_b64 s[4:5], s[4:5], 20
	s_add_u32 s4, s31, s4
	s_addc_u32 s5, s33, s5
	v_mov_b32_e32 v77, v137
	v_lshl_add_u64 v[78:79], s[4:5], 0, v[76:77]
	s_mov_b64 s[42:43], 0

; __device__ __forceinline__ unsigned cvt_pk_bf16(float lo, float hi) { unsigned r; asm volatile("v_cvt_pk_bf16_f32 %0, %1, %2" : "=v"(r) : "v"(lo), "v"(hi)); return r; }
;     __device__ __forceinline__ void operator()(const f32x4 (&acc)[2][2][4][2], const Unit& u, int wr, int wc, int fr, int fq) const {
;     ...
;             for (int m = 0; m < 4; ++m) { const int row = row0 + ai * HALF + m * 16;
;                 const float rs = 1.0f / sqrtf(rowss[row] * (1.0f / 2048.0f) + 1e-6f);
; #pragma unroll
;                 for (int bj = 0; bj < 2; ++bj) { const f32x4 v0 = acc[ai][bj][m][0] * rs, v1 = acc[ai][bj][m][1] * rs;
;                     u32x4 w; w.x = cvt_pk_bf16(v0[0], v0[1]); w.y = cvt_pk_bf16(v0[2], v0[3]); w.z = cvt_pk_bf16(v1[0], v1[1]); w.w = cvt_pk_bf16(v1[2], v1[3]);
.LBB0_428:
	v_lshl_add_u64 v[68:69], v[68:69], 0, v[136:137]
	global_store_dwordx4 v[68:69], v[64:67], off
	global_load_dword v64, v[150:151], off offset:512
	s_mov_b64 s[42:43], -1
	v_add_u32_e32 v67, 0x80, v148
	v_lshlrev_b32_e32 v68, 7, v67
	v_ashrrev_i32_e32 v66, 9, v67
	v_and_b32_e32 v66, -8, v66
	s_waitcnt vmcnt(0)
	v_fmamk_f32 v64, v64, 0x3a000000, v162
	s_nop 1
	v_rsq_f32_e32 v64, v64
	v_and_b32_e32 v70, 0x7e780, v68
	s_nop 0
	s_nop 0
	v_mov_b32_e32 v64, v64
	s_nop 0
	v_mov_b32_e32 v64, v64
	v_pk_mul_f32 v[60:61], v[60:61], v[64:65] op_sel_hi:[1,0]
	s_and_b64 vcc, exec, s[8:9]
	v_pk_mul_f32 v[62:63], v[62:63], v[64:65] op_sel_hi:[1,0]
	v_pk_mul_f32 v[68:69], v[58:59], v[64:65] op_sel_hi:[1,0]
	v_pk_mul_f32 v[58:59], v[56:57], v[64:65] op_sel_hi:[1,0]
	v_cvt_pk_bf16_f32 v56, v60, v61
	v_lshlrev_b32_e32 v60, 1, v70
	v_cvt_pk_bf16_f32 v57, v62, v63
	v_cvt_pk_bf16_f32 v58, v58, v59
	v_cvt_pk_bf16_f32 v59, v68, v69
	s_cbranch_vccnz .LBB0_430
	s_lshr_b32 s29, s38, 7
	v_and_or_b32 v62, s29, 6, v66
	s_add_u32 s4, s52, s40
	v_ashrrev_i32_e32 v63, 31, v62
	s_addc_u32 s5, s53, s41
	v_lshlrev_b64 v[62:63], 20, v[62:63]
	v_lshl_add_u64 v[62:63], s[4:5], 0, v[62:63]
	v_mov_b32_e32 v61, v137
	v_lshl_add_u64 v[62:63], v[62:63], 0, v[60:61]
	s_mov_b64 s[42:43], 0

; __device__ __forceinline__ unsigned cvt_pk_bf16(float lo, float hi) { unsigned r; asm volatile("v_cvt_pk_bf16_f32 %0, %1, %2" : "=v"(r) : "v"(lo), "v"(hi)); return r; }
;     __device__ __forceinline__ void operator()(const f32x4 (&acc)[2][2][4][2], const Unit& u, int wr, int wc, int fr, int fq) const {
;     ...
;             for (int m = 0; m < 4; ++m) { const int row = row0 + ai * HALF + m * 16;
;                 const float rs = 1.0f / sqrtf(rowss[row] * (1.0f / 2048.0f) + 1e-6f);
; #pragma unroll
;                 for (int bj = 0; bj < 2; ++bj) { const f32x4 v0 = acc[ai][bj][m][0] * rs, v1 = acc[ai][bj][m][1] * rs;
;                     u32x4 w; w.x = cvt_pk_bf16(v0[0], v0[1]); w.y = cvt_pk_bf16(v0[2], v0[3]); w.z = cvt_pk_bf16(v1[0], v1[1]); w.w = cvt_pk_bf16(v1[2], v1[3]);
.LBB0_436:
	v_lshl_add_u64 v[52:53], v[52:53], 0, v[136:137]
	global_store_dwordx4 v[52:53], v[48:51], off
	global_load_dword v48, v[150:151], off offset:576
	s_mov_b64 s[42:43], -1
	v_add_u32_e32 v50, 0x90, v148
	v_lshlrev_b32_e32 v51, 7, v50
	v_and_b32_e32 v51, 0x7ef80, v51
	s_waitcnt vmcnt(0)
	v_fmamk_f32 v48, v48, 0x3a000000, v162
	s_nop 1
	v_rsq_f32_e32 v48, v48
	s_nop 1
	s_nop 0
	v_mov_b32_e32 v48, v48
	s_nop 0
	v_mov_b32_e32 v48, v48
	v_pk_mul_f32 v[44:45], v[44:45], v[48:49] op_sel_hi:[1,0]
	s_and_b64 vcc, exec, s[8:9]
	v_pk_mul_f32 v[46:47], v[46:47], v[48:49] op_sel_hi:[1,0]
	v_pk_mul_f32 v[52:53], v[42:43], v[48:49] op_sel_hi:[1,0]
	v_pk_mul_f32 v[42:43], v[40:41], v[48:49] op_sel_hi:[1,0]
	v_cvt_pk_bf16_f32 v40, v44, v45
	v_lshlrev_b32_e32 v44, 1, v51
	v_cvt_pk_bf16_f32 v41, v46, v47
	v_cvt_pk_bf16_f32 v42, v42, v43
	v_cvt_pk_bf16_f32 v43, v52, v53
	s_cbranch_vccnz .LBB0_438
	s_lshr_b32 s29, s38, 7
	v_and_or_b32 v46, s29, 6, v66
	s_add_u32 s4, s52, s40
	v_ashrrev_i32_e32 v47, 31, v46
	s_addc_u32 s5, s53, s41
	v_lshlrev_b64 v[46:47], 20, v[46:47]
	v_lshl_add_u64 v[46:47], s[4:5], 0, v[46:47]
	v_mov_b32_e32 v45, v137
	v_lshl_add_u64 v[46:47], v[46:47], 0, v[44:45]
	s_mov_b64 s[42:43], 0

; __device__ __forceinline__ unsigned cvt_pk_bf16(float lo, float hi) { unsigned r; asm volatile("v_cvt_pk_bf16_f32 %0, %1, %2" : "=v"(r) : "v"(lo), "v"(hi)); return r; }
;     __device__ __forceinline__ void operator()(const f32x4 (&acc)[2][2][4][2], const Unit& u, int wr, int wc, int fr, int fq) const {
;     ...
;             for (int m = 0; m < 4; ++m) { const int row = row0 + ai * HALF + m * 16;
;                 const float rs = 1.0f / sqrtf(rowss[row] * (1.0f / 2048.0f) + 1e-6f);
; #pragma unroll
;                 for (int bj = 0; bj < 2; ++bj) { const f32x4 v0 = acc[ai][bj][m][0] * rs, v1 = acc[ai][bj][m][1] * rs;
;                     u32x4 w; w.x = cvt_pk_bf16(v0[0], v0[1]); w.y = cvt_pk_bf16(v0[2], v0[3]); w.z = cvt_pk_bf16(v1[0], v1[1]); w.w = cvt_pk_bf16(v1[2], v1[3]);
.LBB0_444:
	v_lshl_add_u64 v[36:37], v[36:37], 0, v[136:137]
	global_store_dwordx4 v[36:37], v[32:35], off
	global_load_dword v32, v[150:151], off offset:640
	s_mov_b64 s[42:43], -1
	v_add_u32_e32 v34, 0xa0, v148
	v_lshlrev_b32_e32 v35, 7, v34
	v_and_b32_e32 v35, 0x7f780, v35
	s_waitcnt vmcnt(0)
	v_fmamk_f32 v32, v32, 0x3a000000, v162
	s_nop 1
	v_rsq_f32_e32 v32, v32
	s_nop 1
	s_nop 0
	v_mov_b32_e32 v32, v32
	s_nop 0
	v_mov_b32_e32 v32, v32
	v_pk_mul_f32 v[28:29], v[28:29], v[32:33] op_sel_hi:[1,0]
	s_and_b64 vcc, exec, s[8:9]
	v_pk_mul_f32 v[30:31], v[30:31], v[32:33] op_sel_hi:[1,0]
	v_pk_mul_f32 v[36:37], v[26:27], v[32:33] op_sel_hi:[1,0]
	v_pk_mul_f32 v[26:27], v[24:25], v[32:33] op_sel_hi:[1,0]
	v_cvt_pk_bf16_f32 v24, v28, v29
	v_lshlrev_b32_e32 v28, 1, v35
	v_cvt_pk_bf16_f32 v25, v30, v31
	v_cvt_pk_bf16_f32 v26, v26, v27
	v_cvt_pk_bf16_f32 v27, v36, v37
	s_cbranch_vccnz .LBB0_446
	s_lshr_b32 s29, s38, 7
	v_and_or_b32 v30, s29, 6, v66
	s_add_u32 s4, s52, s40
	v_ashrrev_i32_e32 v31, 31, v30
	s_addc_u32 s5, s53, s41
	v_lshlrev_b64 v[30:31], 20, v[30:31]
	v_lshl_add_u64 v[30:31], s[4:5], 0, v[30:31]
	v_mov_b32_e32 v29, v137
	v_lshl_add_u64 v[30:31], v[30:31], 0, v[28:29]
	s_mov_b64 s[42:43], 0

; __device__ __forceinline__ unsigned cvt_pk_bf16(float lo, float hi) { unsigned r; asm volatile("v_cvt_pk_bf16_f32 %0, %1, %2" : "=v"(r) : "v"(lo), "v"(hi)); return r; }
;     __device__ __forceinline__ void operator()(const f32x4 (&acc)[2][2][4][2], const Unit& u, int wr, int wc, int fr, int fq) const {
;     ...
;             for (int m = 0; m < 4; ++m) { const int row = row0 + ai * HALF + m * 16;
;                 const float rs = 1.0f / sqrtf(rowss[row] * (1.0f / 2048.0f) + 1e-6f);
; #pragma unroll
;                 for (int bj = 0; bj < 2; ++bj) { const f32x4 v0 = acc[ai][bj][m][0] * rs, v1 = acc[ai][bj][m][1] * rs;
;                     u32x4 w; w.x = cvt_pk_bf16(v0[0], v0[1]); w.y = cvt_pk_bf16(v0[2], v0[3]); w.z = cvt_pk_bf16(v1[0], v1[1]); w.w = cvt_pk_bf16(v1[2], v1[3]);
.LBB0_452:
	v_lshl_add_u64 v[20:21], v[20:21], 0, v[136:137]
	global_store_dwordx4 v[20:21], v[16:19], off
	global_load_dword v16, v[150:151], off offset:704
	s_mov_b64 s[42:43], -1
	v_add_u32_e32 v18, 0xb0, v148
	v_lshlrev_b32_e32 v19, 7, v18
	v_and_b32_e32 v19, 0x7ff80, v19
	s_waitcnt vmcnt(0)
	v_fmamk_f32 v16, v16, 0x3a000000, v162
	s_nop 1
	v_rsq_f32_e32 v16, v16
	s_nop 1
	s_nop 0
	v_mov_b32_e32 v16, v16
	s_nop 0
	v_mov_b32_e32 v16, v16
	v_pk_mul_f32 v[12:13], v[12:13], v[16:17] op_sel_hi:[1,0]
	s_and_b64 vcc, exec, s[8:9]
	v_pk_mul_f32 v[14:15], v[14:15], v[16:17] op_sel_hi:[1,0]
	v_pk_mul_f32 v[20:21], v[10:11], v[16:17] op_sel_hi:[1,0]
	v_pk_mul_f32 v[10:11], v[8:9], v[16:17] op_sel_hi:[1,0]
	v_cvt_pk_bf16_f32 v8, v12, v13
	v_lshlrev_b32_e32 v12, 1, v19
	v_cvt_pk_bf16_f32 v9, v14, v15
	v_cvt_pk_bf16_f32 v10, v10, v11
	v_cvt_pk_bf16_f32 v11, v20, v21
	s_cbranch_vccnz .LBB0_454
	s_lshr_b32 s8, s38, 7
	v_and_or_b32 v14, s8, 6, v66
	s_add_u32 s4, s52, s40
	v_ashrrev_i32_e32 v15, 31, v14
	s_addc_u32 s5, s53, s41
	v_lshlrev_b64 v[14:15], 20, v[14:15]
	v_lshl_add_u64 v[14:15], s[4:5], 0, v[14:15]
	v_mov_b32_e32 v13, v137
	v_lshl_add_u64 v[14:15], v[14:15], 0, v[12:13]
	s_mov_b64 s[42:43], 0

; __device__ __forceinline__ f32x4 mfma16(bf16x8 a, bf16x8 b, f32x4 c) { return __builtin_amdgcn_mfma_f32_16x16x32_bf16(a, b, c, 0, 0, 0); }
; __device__ __forceinline__ void phase_qkrope_gla_prep(const Params& p, LAS unsigned char* lds, int wave, int lane) {
;     ...
;             const int m0 = bc * 64;
;             __syncthreads();
;             f32x4 accg[4];
; #pragma unroll
;             for (int ti = 0; ti < 4; ++ti) accg[ti] = (f32x4){0.f, 0.f, 0.f, 0.f};
; #pragma unroll
;             for (int k8 = 0; k8 < 8; ++k8) { const int kk = 256 * wave + 32 * k8 + 8 * g;
;                 const bf16x8 bfr = *(const bf16x8*)(wgl + (size_t)fr * DM + kk);
; #pragma unroll
;                 for (int ti = 0; ti < 4; ++ti) { const bf16x8 afr = *(const bf16x8*)(X1B + (size_t)(m0 + 16 * ti + fr) * DM + kk);
;                     accg[ti] = mfma16(afr, bfr, accg[ti]); } }
; #pragma unroll
;             for (int ti = 0; ti < 4; ++ti)
; #pragma unroll
;                 for (int jj = 0; jj < 4; ++jj) part[(wave * 64 + 16 * ti + 4 * g + jj) * 16 + fr] = accg[ti][jj];
.LBB0_518:
	v_add_u32_e32 v78, s0, v52
	v_subrev_u32_e32 v0, 63, v78
	v_ashrrev_i32_e32 v1, 31, v0
	v_lshlrev_b64 v[0:1], 12, v[0:1]
	v_lshl_add_u64 v[0:1], v[12:13], 0, v[0:1]
	s_barrier
	global_load_dwordx4 v[46:49], v[0:1], off
	global_load_dwordx4 v[62:65], v[10:11], off
	v_subrev_u32_e32 v2, 47, v78
	v_ashrrev_i32_e32 v3, 31, v2
	v_lshlrev_b64 v[2:3], 12, v[2:3]
	v_lshl_add_u64 v[2:3], v[12:13], 0, v[2:3]
	s_sub_i32 s19, s0, 63
	s_waitcnt vmcnt(0)
	v_mfma_f32_16x16x32_bf16 v[66:69], v[46:49], v[62:65], 0
	global_load_dwordx4 v[46:49], v[2:3], off
	s_waitcnt vmcnt(0)
	v_mfma_f32_16x16x32_bf16 v[70:73], v[46:49], v[62:65], 0
	v_subrev_u32_e32 v46, 31, v78
	v_add_u32_e32 v48, -15, v78
	v_ashrrev_i32_e32 v47, 31, v46
	v_ashrrev_i32_e32 v49, 31, v48
	v_lshlrev_b64 v[46:47], 12, v[46:47]
	v_lshlrev_b64 v[48:49], 12, v[48:49]
	v_lshl_add_u64 v[46:47], v[12:13], 0, v[46:47]
	v_lshl_add_u64 v[48:49], v[12:13], 0, v[48:49]
	global_load_dwordx4 v[74:77], v[46:47], off
	global_load_dwordx4 v[78:81], v[48:49], off
	s_waitcnt vmcnt(1)
	v_mfma_f32_16x16x32_bf16 v[74:77], v[74:77], v[62:65], 0
	s_waitcnt vmcnt(0)
	v_mfma_f32_16x16x32_bf16 v[62:65], v[78:81], v[62:65], 0
	global_load_dwordx4 v[78:81], v[10:11], off offset:64
	global_load_dwordx4 v[82:85], v[0:1], off offset:64
	s_waitcnt vmcnt(0)
	v_mfma_f32_16x16x32_bf16 v[66:69], v[82:85], v[78:81], v[66:69]
	global_load_dwordx4 v[82:85], v[2:3], off offset:64
	s_waitcnt vmcnt(0)
	v_mfma_f32_16x16x32_bf16 v[70:73], v[82:85], v[78:81], v[70:73]
	global_load_dwordx4 v[82:85], v[46:47], off offset:64
	s_waitcnt vmcnt(0)
	v_mfma_f32_16x16x32_bf16 v[74:77], v[82:85], v[78:81], v[74:77]
	global_load_dwordx4 v[82:85], v[48:49], off offset:64
	s_waitcnt vmcnt(0)
	v_mfma_f32_16x16x32_bf16 v[62:65], v[82:85], v[78:81], v[62:65]
	global_load_dwordx4 v[78:81], v[10:11], off offset:128
	global_load_dwordx4 v[82:85], v[0:1], off offset:128
	s_waitcnt vmcnt(0)
	v_mfma_f32_16x16x32_bf16 v[66:69], v[82:85], v[78:81], v[66:69]
	global_load_dwordx4 v[82:85], v[2:3], off offset:128
	s_waitcnt vmcnt(0)
	v_mfma_f32_16x16x32_bf16 v[70:73], v[82:85], v[78:81], v[70:73]
	global_load_dwordx4 v[82:85], v[46:47], off offset:128
	s_waitcnt vmcnt(0)
	v_mfma_f32_16x16x32_bf16 v[74:77], v[82:85], v[78:81], v[74:77]
	global_load_dwordx4 v[82:85], v[48:49], off offset:128
	s_waitcnt vmcnt(0)
	v_mfma_f32_16x16x32_bf16 v[62:65], v[82:85], v[78:81], v[62:65]
	global_load_dwordx4 v[78:81], v[10:11], off offset:192
	global_load_dwordx4 v[82:85], v[0:1], off offset:192
	s_waitcnt vmcnt(0)
	v_mfma_f32_16x16x32_bf16 v[66:69], v[82:85], v[78:81], v[66:69]
	global_load_dwordx4 v[82:85], v[2:3], off offset:192
	s_waitcnt vmcnt(0)
	v_mfma_f32_16x16x32_bf16 v[70:73], v[82:85], v[78:81], v[70:73]
	global_load_dwordx4 v[82:85], v[46:47], off offset:192
	s_waitcnt vmcnt(0)
	v_mfma_f32_16x16x32_bf16 v[74:77], v[82:85], v[78:81], v[74:77]
	global_load_dwordx4 v[82:85], v[48:49], off offset:192
	s_waitcnt vmcnt(0)
	v_mfma_f32_16x16x32_bf16 v[62:65], v[82:85], v[78:81], v[62:65]
	global_load_dwordx4 v[78:81], v[10:11], off offset:256
	global_load_dwordx4 v[82:85], v[0:1], off offset:256
	s_waitcnt vmcnt(0)
	v_mfma_f32_16x16x32_bf16 v[66:69], v[82:85], v[78:81], v[66:69]
	global_load_dwordx4 v[82:85], v[2:3], off offset:256
	s_waitcnt vmcnt(0)
	v_mfma_f32_16x16x32_bf16 v[70:73], v[82:85], v[78:81], v[70:73]
	global_load_dwordx4 v[82:85], v[46:47], off offset:256
	s_waitcnt vmcnt(0)
	v_mfma_f32_16x16x32_bf16 v[74:77], v[82:85], v[78:81], v[74:77]
	global_load_dwordx4 v[82:85], v[48:49], off offset:256
	s_waitcnt vmcnt(0)
	v_mfma_f32_16x16x32_bf16 v[62:65], v[82:85], v[78:81], v[62:65]
	global_load_dwordx4 v[78:81], v[10:11], off offset:320
	global_load_dwordx4 v[82:85], v[0:1], off offset:320
	s_waitcnt vmcnt(0)
	v_mfma_f32_16x16x32_bf16 v[66:69], v[82:85], v[78:81], v[66:69]
	global_load_dwordx4 v[82:85], v[2:3], off offset:320
	s_waitcnt vmcnt(0)
	v_mfma_f32_16x16x32_bf16 v[70:73], v[82:85], v[78:81], v[70:73]
	global_load_dwordx4 v[82:85], v[46:47], off offset:320
	s_waitcnt vmcnt(0)
	v_mfma_f32_16x16x32_bf16 v[74:77], v[82:85], v[78:81], v[74:77]
	global_load_dwordx4 v[82:85], v[48:49], off offset:320
	s_waitcnt vmcnt(0)
	v_mfma_f32_16x16x32_bf16 v[62:65], v[82:85], v[78:81], v[62:65]
	global_load_dwordx4 v[78:81], v[10:11], off offset:384
	global_load_dwordx4 v[82:85], v[0:1], off offset:384
	s_waitcnt vmcnt(0)
	v_mfma_f32_16x16x32_bf16 v[66:69], v[82:85], v[78:81], v[66:69]
	global_load_dwordx4 v[82:85], v[2:3], off offset:384
	s_waitcnt vmcnt(0)
	v_mfma_f32_16x16x32_bf16 v[70:73], v[82:85], v[78:81], v[70:73]
	global_load_dwordx4 v[82:85], v[46:47], off offset:384
	s_waitcnt vmcnt(0)
	v_mfma_f32_16x16x32_bf16 v[74:77], v[82:85], v[78:81], v[74:77]
	global_load_dwordx4 v[82:85], v[48:49], off offset:384
	s_waitcnt vmcnt(0)
	v_mfma_f32_16x16x32_bf16 v[62:65], v[82:85], v[78:81], v[62:65]
	global_load_dwordx4 v[78:81], v[10:11], off offset:448
	global_load_dwordx4 v[82:85], v[0:1], off offset:448
	s_nop 0
	global_load_dwordx4 v[0:3], v[2:3], off offset:448
	s_waitcnt vmcnt(1)
	v_mfma_f32_16x16x32_bf16 v[66:69], v[82:85], v[78:81], v[66:69]
	s_waitcnt vmcnt(0)
	v_mfma_f32_16x16x32_bf16 v[0:3], v[0:3], v[78:81], v[70:73]
	s_nop 2
	global_load_dwordx4 v[70:73], v[46:47], off offset:448
	s_nop 0
	global_load_dwordx4 v[46:49], v[48:49], off offset:448
	s_waitcnt vmcnt(1)
	v_mfma_f32_16x16x32_bf16 v[70:73], v[70:73], v[78:81], v[74:77]
	s_waitcnt vmcnt(0)
	v_mfma_f32_16x16x32_bf16 v[46:49], v[46:49], v[78:81], v[62:65]
	ds_write2_b32 v55, v66, v67 offset1:16
	ds_write2_b32 v55, v68, v69 offset0:32 offset1:48
	ds_write2_b32 v58, v0, v1 offset1:16
	ds_write2_b32 v58, v2, v3 offset0:32 offset1:48
	s_nop 1
	ds_write2_b32 v59, v70, v71 offset1:16
	ds_write2_b32 v59, v72, v73 offset0:32 offset1:48
	ds_write2_b32 v60, v46, v47 offset1:16
	ds_write2_b32 v60, v48, v49 offset0:32 offset1:48
	s_waitcnt lgkmcnt(0)
	s_barrier
; __device__ __forceinline__ float fexp(float x) { return __builtin_amdgcn_exp2f(x * 1.44269504089f); }
; __device__ __forceinline__ void phase_qkrope_gla_prep(const Params& p, LAS unsigned char* lds, int wave, int lane) {
;     ...
;             for (int i = 0; i < 2; ++i) { const int idx = tid + 512 * i, tok = idx >> 4; float sum = 0.f;
; #pragma unroll
;                 for (int w = 0; w < 8; ++w) sum += part[w * 1024 + idx];
;                 gl[idx] = sum / sqrtf(rss1[m0 + tok] * (1.0f / DM) + EPS); }
;             float gu[16];
; #pragma unroll
;             for (int r = 0; r < 16; ++r) gu[r] = p.gup[r * 512 + d];
;             const float bias = p.gbias[d];
;             __syncthreads();
;             float bl[64]; float run = 0.f;
; #pragma unroll
;             for (int t = 0; t < 64; ++t) { float lg = bias;
; #pragma unroll
;                 for (int r = 0; r < 16; ++r) lg += gl[t * 16 + r] * gu[r];
;                 const float ls = fminf(lg, 0.f) - 0.69314718056f * __builtin_amdgcn_logf(1.0f + fexp(-fabsf(lg)));
;                 run += ls * (1.0f / 16.0f); bl[t] = run; }
	ds_read2st64_b32 v[0:1], v6 offset1:8
	ds_read2st64_b32 v[2:3], v6 offset0:16 offset1:24
	v_add_u32_e32 v70, s19, v53
	v_ashrrev_i32_e32 v71, 31, v70
	v_lshl_add_u64 v[70:71], v[70:71], 2, s[16:17]
	s_waitcnt lgkmcnt(1)
	v_add_f32_e32 v0, 0, v0
	s_waitcnt lgkmcnt(0)
	v_add_f32_e32 v0, v0, v2
	global_load_dword v2, v[70:71], off
	ds_read2st64_b32 v[46:47], v6 offset0:32 offset1:40
	ds_read2st64_b32 v[48:49], v6 offset0:48 offset1:56
	ds_read2st64_b32 v[62:63], v6 offset0:64 offset1:72
	ds_read2st64_b32 v[64:65], v6 offset0:80 offset1:88
	ds_read2st64_b32 v[66:67], v6 offset0:96 offset1:104
	s_waitcnt lgkmcnt(4)
	v_add_f32_e32 v0, v0, v46
	s_waitcnt lgkmcnt(3)
	v_add_f32_e32 v0, v0, v48
	s_waitcnt lgkmcnt(2)
	v_add_f32_e32 v0, v0, v62
	ds_read2st64_b32 v[68:69], v6 offset0:112 offset1:120
	s_waitcnt lgkmcnt(2)
	v_add_f32_e32 v0, v0, v64
	s_waitcnt lgkmcnt(1)
	v_add_f32_e32 v0, v0, v66
	s_waitcnt lgkmcnt(0)
	v_add_f32_e32 v0, v0, v68
	s_waitcnt vmcnt(0)
	v_fmamk_f32 v2, v2, 0x3a000000, v56
	s_nop 0
	v_rsq_f32_e32 v2, v2
	s_nop 1
	s_nop 0
	v_mov_b32_e32 v2, v2
	s_nop 0
	v_mul_f32_e32 v2, v0, v2
	v_add_f32_e32 v0, 0, v1
	v_add_f32_e32 v0, v0, v3
	v_add_f32_e32 v0, v0, v47
	v_add_f32_e32 v0, v0, v49
	v_add_f32_e32 v0, v0, v63
	v_add_f32_e32 v0, v0, v65
	v_add_f32_e32 v0, v0, v67
	v_add_f32_e32 v3, v0, v69
	v_add_u32_e32 v0, s19, v54
	v_ashrrev_i32_e32 v1, 31, v0
	v_lshl_add_u64 v[0:1], v[0:1], 2, s[16:17]
	global_load_dword v0, v[0:1], off
	s_waitcnt vmcnt(0)
	v_fmamk_f32 v0, v0, 0x3a000000, v56
	s_nop 0
	v_rsq_f32_e32 v0, v0
	s_nop 1
	s_nop 0
	v_mov_b32_e32 v0, v0
	s_nop 0
	v_mul_f32_e32 v0, v3, v0
	ds_write2st64_b32 v6, v2, v0 offset0:128 offset1:136
	global_load_dword v0, v[14:15], off
	global_load_dword v1, v[14:15], off offset:2048
	global_load_dword v2, v[16:17], off
	global_load_dword v3, v[18:19], off
	global_load_dword v133, v[20:21], off
	global_load_dword v130, v[22:23], off
	global_load_dword v131, v[24:25], off
	global_load_dword v132, v[26:27], off
	global_load_dword v126, v[28:29], off
	global_load_dword v127, v[30:31], off
	global_load_dword v128, v[32:33], off
	global_load_dword v129, v[34:35], off
	global_load_dword v47, v[36:37], off
	global_load_dword v76, v[38:39], off
	global_load_dword v124, v[40:41], off
	global_load_dword v125, v[42:43], off
	global_load_dword v46, v[44:45], off
	s_waitcnt lgkmcnt(0)
	s_barrier
	ds_read_b128 v[62:65], v7 offset:32768
	ds_read_b128 v[66:69], v7 offset:32784
	ds_read_b128 v[70:73], v7 offset:32800
	ds_read_b128 v[78:81], v7 offset:32816
	ds_read_b128 v[134:137], v7 offset:36096
	s_waitcnt vmcnt(0) lgkmcnt(4)
	v_fma_f32 v48, v0, v62, v46
	v_fmac_f32_e32 v48, v1, v63
	v_fmac_f32_e32 v48, v2, v64
	v_fmac_f32_e32 v48, v3, v65
	s_waitcnt lgkmcnt(3)
	v_fmac_f32_e32 v48, v133, v66
	v_fmac_f32_e32 v48, v130, v67
	v_fmac_f32_e32 v48, v131, v68
	v_fmac_f32_e32 v48, v132, v69
	s_waitcnt lgkmcnt(2)
	v_fmac_f32_e32 v48, v126, v70
	v_fmac_f32_e32 v48, v127, v71
	v_fmac_f32_e32 v48, v128, v72
	v_fmac_f32_e32 v48, v129, v73
	s_waitcnt lgkmcnt(1)
	v_fmac_f32_e32 v48, v47, v78
	v_fmac_f32_e32 v48, v76, v79
	v_fmac_f32_e32 v48, v124, v80
	v_fmac_f32_e32 v48, v125, v81
	v_min_f32_e32 v49, 0, v48
	v_mul_f32_e64 v48, |v48|, s3
	v_exp_f32_e32 v48, v48
	ds_read_b128 v[62:65], v7 offset:32832
	v_add_f32_e32 v48, 1.0, v48
	v_log_f32_e32 v48, v48
	s_nop 0
	v_fmac_f32_e32 v49, 0xbf317218, v48
	s_waitcnt lgkmcnt(0)
	v_fma_f32 v48, v0, v62, v46
	v_fmac_f32_e32 v48, v1, v63
	v_fmac_f32_e32 v48, v2, v64
	v_fmac_f32_e32 v48, v3, v65
	ds_read_b128 v[62:65], v7 offset:32848
	v_fma_f32 v100, v49, s21, 0
	s_waitcnt lgkmcnt(0)
	v_fmac_f32_e32 v48, v133, v62
	v_fmac_f32_e32 v48, v130, v63
	v_fmac_f32_e32 v48, v131, v64
	v_fmac_f32_e32 v48, v132, v65
	ds_read_b128 v[62:65], v7 offset:32864
	s_waitcnt lgkmcnt(0)
	v_fmac_f32_e32 v48, v126, v62
	v_fmac_f32_e32 v48, v127, v63
	v_fmac_f32_e32 v48, v128, v64
	v_fmac_f32_e32 v48, v129, v65
	ds_read_b128 v[62:65], v7 offset:32880
	s_waitcnt lgkmcnt(0)
	v_fmac_f32_e32 v48, v47, v62
	v_fmac_f32_e32 v48, v76, v63
	v_fmac_f32_e32 v48, v124, v64
	v_fmac_f32_e32 v48, v125, v65
	v_min_f32_e32 v49, 0, v48
	v_mul_f32_e64 v48, |v48|, s3
	v_exp_f32_e32 v48, v48
	ds_read_b128 v[62:65], v7 offset:32896
	v_add_f32_e32 v48, 1.0, v48
	v_log_f32_e32 v48, v48
	s_nop 0
	v_fmac_f32_e32 v49, 0xbf317218, v48
	s_waitcnt lgkmcnt(0)
	v_fma_f32 v48, v0, v62, v46
	v_fmac_f32_e32 v48, v1, v63
	v_fmac_f32_e32 v48, v2, v64
	v_fmac_f32_e32 v48, v3, v65
	ds_read_b128 v[62:65], v7 offset:32912
	v_fmamk_f32 v102, v49, 0x3d800000, v100
	s_waitcnt lgkmcnt(0)
	v_fmac_f32_e32 v48, v133, v62
	v_fmac_f32_e32 v48, v130, v63
	v_fmac_f32_e32 v48, v131, v64
	v_fmac_f32_e32 v48, v132, v65
	ds_read_b128 v[62:65], v7 offset:32928
	s_waitcnt lgkmcnt(0)
	v_fmac_f32_e32 v48, v126, v62
	v_fmac_f32_e32 v48, v127, v63
	v_fmac_f32_e32 v48, v128, v64
	v_fmac_f32_e32 v48, v129, v65
	ds_read_b128 v[62:65], v7 offset:32944
	s_waitcnt lgkmcnt(0)
	v_fmac_f32_e32 v48, v47, v62
	v_fmac_f32_e32 v48, v76, v63
	v_fmac_f32_e32 v48, v124, v64
	v_fmac_f32_e32 v48, v125, v65
	v_min_f32_e32 v49, 0, v48
	v_mul_f32_e64 v48, |v48|, s3
	v_exp_f32_e32 v48, v48
	ds_read_b128 v[62:65], v7 offset:32960
	v_add_f32_e32 v48, 1.0, v48
	v_log_f32_e32 v48, v48
	s_nop 0
	v_fmac_f32_e32 v49, 0xbf317218, v48
	s_waitcnt lgkmcnt(0)
	v_fma_f32 v48, v0, v62, v46
	v_fmac_f32_e32 v48, v1, v63
	v_fmac_f32_e32 v48, v2, v64
	v_fmac_f32_e32 v48, v3, v65
	ds_read_b128 v[62:65], v7 offset:32976
	v_fmamk_f32 v104, v49, 0x3d800000, v102
	s_waitcnt lgkmcnt(0)
	v_fmac_f32_e32 v48, v133, v62
	v_fmac_f32_e32 v48, v130, v63
	v_fmac_f32_e32 v48, v131, v64
	v_fmac_f32_e32 v48, v132, v65
	ds_read_b128 v[62:65], v7 offset:32992
	s_waitcnt lgkmcnt(0)
; __device__ __forceinline__ float fexp(float x) { return __builtin_amdgcn_exp2f(x * 1.44269504089f); }
; __device__ __forceinline__ void phase_qkrope_gla_prep(const Params& p, LAS unsigned char* lds, int wave, int lane) {
;     ...
;             for (int t = 0; t < 64; ++t) { float lg = bias;
; #pragma unroll
;                 for (int r = 0; r < 16; ++r) lg += gl[t * 16 + r] * gu[r];
;                 const float ls = fminf(lg, 0.f) - 0.69314718056f * __builtin_amdgcn_logf(1.0f + fexp(-fabsf(lg)));
;                 run += ls * (1.0f / 16.0f); bl[t] = run; }
	v_fmac_f32_e32 v48, v126, v62
	v_fmac_f32_e32 v48, v127, v63
	v_fmac_f32_e32 v48, v128, v64
	v_fmac_f32_e32 v48, v129, v65
	ds_read_b128 v[62:65], v7 offset:33008
	s_waitcnt lgkmcnt(0)
	v_fmac_f32_e32 v48, v47, v62
	v_fmac_f32_e32 v48, v76, v63
	v_fmac_f32_e32 v48, v124, v64
	v_fmac_f32_e32 v48, v125, v65
	v_min_f32_e32 v49, 0, v48
	v_mul_f32_e64 v48, |v48|, s3
	v_exp_f32_e32 v48, v48
	ds_read_b128 v[62:65], v7 offset:33024
	v_add_f32_e32 v48, 1.0, v48
	v_log_f32_e32 v48, v48
	s_nop 0
	v_fmac_f32_e32 v49, 0xbf317218, v48
	s_waitcnt lgkmcnt(0)
	v_fma_f32 v48, v0, v62, v46
	v_fmac_f32_e32 v48, v1, v63
	v_fmac_f32_e32 v48, v2, v64
	v_fmac_f32_e32 v48, v3, v65
	ds_read_b128 v[62:65], v7 offset:33040
	v_fmamk_f32 v107, v49, 0x3d800000, v104
	s_waitcnt lgkmcnt(0)
	v_fmac_f32_e32 v48, v133, v62
	v_fmac_f32_e32 v48, v130, v63
	v_fmac_f32_e32 v48, v131, v64
	v_fmac_f32_e32 v48, v132, v65
	ds_read_b128 v[62:65], v7 offset:33056
	s_waitcnt lgkmcnt(0)
	v_fmac_f32_e32 v48, v126, v62
	v_fmac_f32_e32 v48, v127, v63
	v_fmac_f32_e32 v48, v128, v64
	v_fmac_f32_e32 v48, v129, v65
	ds_read_b128 v[62:65], v7 offset:33072
	s_waitcnt lgkmcnt(0)
	v_fmac_f32_e32 v48, v47, v62
	v_fmac_f32_e32 v48, v76, v63
	v_fmac_f32_e32 v48, v124, v64
	v_fmac_f32_e32 v48, v125, v65
	v_min_f32_e32 v49, 0, v48
	v_mul_f32_e64 v48, |v48|, s3
	v_exp_f32_e32 v48, v48
	ds_read_b128 v[62:65], v7 offset:33088
	v_add_f32_e32 v48, 1.0, v48
	v_log_f32_e32 v48, v48
	s_nop 0
	v_fmac_f32_e32 v49, 0xbf317218, v48
	s_waitcnt lgkmcnt(0)
	v_fma_f32 v48, v0, v62, v46
	v_fmac_f32_e32 v48, v1, v63
	v_fmac_f32_e32 v48, v2, v64
	v_fmac_f32_e32 v48, v3, v65
	ds_read_b128 v[62:65], v7 offset:33104
	v_fmamk_f32 v109, v49, 0x3d800000, v107
	s_waitcnt lgkmcnt(0)
	v_fmac_f32_e32 v48, v133, v62
	v_fmac_f32_e32 v48, v130, v63
	v_fmac_f32_e32 v48, v131, v64
	v_fmac_f32_e32 v48, v132, v65
	ds_read_b128 v[62:65], v7 offset:33120
	s_waitcnt lgkmcnt(0)
	v_fmac_f32_e32 v48, v126, v62
	v_fmac_f32_e32 v48, v127, v63
	v_fmac_f32_e32 v48, v128, v64
	v_fmac_f32_e32 v48, v129, v65
	ds_read_b128 v[62:65], v7 offset:33136
	s_waitcnt lgkmcnt(0)
	v_fmac_f32_e32 v48, v47, v62
	v_fmac_f32_e32 v48, v76, v63
	v_fmac_f32_e32 v48, v124, v64
	v_fmac_f32_e32 v48, v125, v65
	v_min_f32_e32 v49, 0, v48
	v_mul_f32_e64 v48, |v48|, s3
	v_exp_f32_e32 v48, v48
	ds_read_b128 v[62:65], v7 offset:33152
	v_add_f32_e32 v48, 1.0, v48
	v_log_f32_e32 v48, v48
	s_nop 0
	v_fmac_f32_e32 v49, 0xbf317218, v48
	s_waitcnt lgkmcnt(0)
	v_fma_f32 v48, v0, v62, v46
	v_fmac_f32_e32 v48, v1, v63
	v_fmac_f32_e32 v48, v2, v64
	v_fmac_f32_e32 v48, v3, v65
	ds_read_b128 v[62:65], v7 offset:33168
	v_fmamk_f32 v111, v49, 0x3d800000, v109
	s_waitcnt lgkmcnt(0)
	v_fmac_f32_e32 v48, v133, v62
	v_fmac_f32_e32 v48, v130, v63
	v_fmac_f32_e32 v48, v131, v64
	v_fmac_f32_e32 v48, v132, v65
	ds_read_b128 v[62:65], v7 offset:33184
	s_waitcnt lgkmcnt(0)
	v_fmac_f32_e32 v48, v126, v62
	v_fmac_f32_e32 v48, v127, v63
	v_fmac_f32_e32 v48, v128, v64
	v_fmac_f32_e32 v48, v129, v65
	ds_read_b128 v[62:65], v7 offset:33200
	s_waitcnt lgkmcnt(0)
	v_fmac_f32_e32 v48, v47, v62
	v_fmac_f32_e32 v48, v76, v63
	v_fmac_f32_e32 v48, v124, v64
	v_fmac_f32_e32 v48, v125, v65
	v_min_f32_e32 v49, 0, v48
	v_mul_f32_e64 v48, |v48|, s3
	v_exp_f32_e32 v48, v48
	ds_read_b128 v[62:65], v7 offset:33216
	v_add_f32_e32 v48, 1.0, v48
	v_log_f32_e32 v48, v48
	s_nop 0
	v_fmac_f32_e32 v49, 0xbf317218, v48
	s_waitcnt lgkmcnt(0)
	v_fma_f32 v48, v0, v62, v46
	v_fmac_f32_e32 v48, v1, v63
	v_fmac_f32_e32 v48, v2, v64
	v_fmac_f32_e32 v48, v3, v65
	ds_read_b128 v[62:65], v7 offset:33232
	v_fmamk_f32 v112, v49, 0x3d800000, v111
	s_waitcnt lgkmcnt(0)
	v_fmac_f32_e32 v48, v133, v62
	v_fmac_f32_e32 v48, v130, v63
	v_fmac_f32_e32 v48, v131, v64
	v_fmac_f32_e32 v48, v132, v65
	ds_read_b128 v[62:65], v7 offset:33248
	s_waitcnt lgkmcnt(0)
	v_fmac_f32_e32 v48, v126, v62
	v_fmac_f32_e32 v48, v127, v63
	v_fmac_f32_e32 v48, v128, v64
	v_fmac_f32_e32 v48, v129, v65
	ds_read_b128 v[62:65], v7 offset:33264
	s_waitcnt lgkmcnt(0)
	v_fmac_f32_e32 v48, v47, v62
	v_fmac_f32_e32 v48, v76, v63
	v_fmac_f32_e32 v48, v124, v64
	v_fmac_f32_e32 v48, v125, v65
	v_min_f32_e32 v49, 0, v48
	v_mul_f32_e64 v48, |v48|, s3
	v_exp_f32_e32 v48, v48
	ds_read_b128 v[62:65], v7 offset:33280
	v_add_f32_e32 v48, 1.0, v48
	v_log_f32_e32 v48, v48
	s_nop 0
	v_fmac_f32_e32 v49, 0xbf317218, v48
	s_waitcnt lgkmcnt(0)
	v_fma_f32 v48, v0, v62, v46
	v_fmac_f32_e32 v48, v1, v63
	v_fmac_f32_e32 v48, v2, v64
	v_fmac_f32_e32 v48, v3, v65
	ds_read_b128 v[62:65], v7 offset:33296
	v_fmamk_f32 v114, v49, 0x3d800000, v112
	s_waitcnt lgkmcnt(0)
	v_fmac_f32_e32 v48, v133, v62
	v_fmac_f32_e32 v48, v130, v63
	v_fmac_f32_e32 v48, v131, v64
	v_fmac_f32_e32 v48, v132, v65
	ds_read_b128 v[62:65], v7 offset:33312
	s_waitcnt lgkmcnt(0)
	v_fmac_f32_e32 v48, v126, v62
	v_fmac_f32_e32 v48, v127, v63
	v_fmac_f32_e32 v48, v128, v64
	v_fmac_f32_e32 v48, v129, v65
	ds_read_b128 v[62:65], v7 offset:33328
	s_waitcnt lgkmcnt(0)
	v_fmac_f32_e32 v48, v47, v62
	v_fmac_f32_e32 v48, v76, v63
	v_fmac_f32_e32 v48, v124, v64
	v_fmac_f32_e32 v48, v125, v65
	v_min_f32_e32 v49, 0, v48
	v_mul_f32_e64 v48, |v48|, s3
	v_exp_f32_e32 v48, v48
	ds_read_b128 v[62:65], v7 offset:33344
	v_add_f32_e32 v48, 1.0, v48
	v_log_f32_e32 v48, v48
	s_nop 0
	v_fmac_f32_e32 v49, 0xbf317218, v48
	s_waitcnt lgkmcnt(0)
	v_fma_f32 v48, v0, v62, v46
	v_fmac_f32_e32 v48, v1, v63
	v_fmac_f32_e32 v48, v2, v64
	v_fmac_f32_e32 v48, v3, v65
	ds_read_b128 v[62:65], v7 offset:33360
	v_fmamk_f32 v116, v49, 0x3d800000, v114
	s_waitcnt lgkmcnt(0)
	v_fmac_f32_e32 v48, v133, v62
	v_fmac_f32_e32 v48, v130, v63
	v_fmac_f32_e32 v48, v131, v64
	v_fmac_f32_e32 v48, v132, v65
	ds_read_b128 v[62:65], v7 offset:33376
	s_waitcnt lgkmcnt(0)
; __device__ __forceinline__ float fexp(float x) { return __builtin_amdgcn_exp2f(x * 1.44269504089f); }
; __device__ __forceinline__ void phase_qkrope_gla_prep(const Params& p, LAS unsigned char* lds, int wave, int lane) {
;     ...
;             for (int t = 0; t < 64; ++t) { float lg = bias;
; #pragma unroll
;                 for (int r = 0; r < 16; ++r) lg += gl[t * 16 + r] * gu[r];
;                 const float ls = fminf(lg, 0.f) - 0.69314718056f * __builtin_amdgcn_logf(1.0f + fexp(-fabsf(lg)));
;                 run += ls * (1.0f / 16.0f); bl[t] = run; }
	v_fmac_f32_e32 v48, v126, v62
	v_fmac_f32_e32 v48, v127, v63
	v_fmac_f32_e32 v48, v128, v64
	v_fmac_f32_e32 v48, v129, v65
	ds_read_b128 v[62:65], v7 offset:33392
	s_waitcnt lgkmcnt(0)
	v_fmac_f32_e32 v48, v47, v62
	v_fmac_f32_e32 v48, v76, v63
	v_fmac_f32_e32 v48, v124, v64
	v_fmac_f32_e32 v48, v125, v65
	v_min_f32_e32 v49, 0, v48
	v_mul_f32_e64 v48, |v48|, s3
	v_exp_f32_e32 v48, v48
	ds_read_b128 v[62:65], v7 offset:33408
	v_add_f32_e32 v48, 1.0, v48
	v_log_f32_e32 v48, v48
	s_nop 0
	v_fmac_f32_e32 v49, 0xbf317218, v48
	s_waitcnt lgkmcnt(0)
	v_fma_f32 v48, v0, v62, v46
	v_fmac_f32_e32 v48, v1, v63
	v_fmac_f32_e32 v48, v2, v64
	v_fmac_f32_e32 v48, v3, v65
	ds_read_b128 v[62:65], v7 offset:33424
	v_fmamk_f32 v117, v49, 0x3d800000, v116
	s_waitcnt lgkmcnt(0)
	v_fmac_f32_e32 v48, v133, v62
	v_fmac_f32_e32 v48, v130, v63
	v_fmac_f32_e32 v48, v131, v64
	v_fmac_f32_e32 v48, v132, v65
	ds_read_b128 v[62:65], v7 offset:33440
	s_waitcnt lgkmcnt(0)
	v_fmac_f32_e32 v48, v126, v62
	v_fmac_f32_e32 v48, v127, v63
	v_fmac_f32_e32 v48, v128, v64
	v_fmac_f32_e32 v48, v129, v65
	ds_read_b128 v[62:65], v7 offset:33456
	s_waitcnt lgkmcnt(0)
	v_fmac_f32_e32 v48, v47, v62
	v_fmac_f32_e32 v48, v76, v63
	v_fmac_f32_e32 v48, v124, v64
	v_fmac_f32_e32 v48, v125, v65
	v_min_f32_e32 v49, 0, v48
	v_mul_f32_e64 v48, |v48|, s3
	v_exp_f32_e32 v48, v48
	ds_read_b128 v[62:65], v7 offset:33472
	v_add_f32_e32 v48, 1.0, v48
	v_log_f32_e32 v48, v48
	s_nop 0
	v_fmac_f32_e32 v49, 0xbf317218, v48
	s_waitcnt lgkmcnt(0)
	v_fma_f32 v48, v0, v62, v46
	v_fmac_f32_e32 v48, v1, v63
	v_fmac_f32_e32 v48, v2, v64
	v_fmac_f32_e32 v48, v3, v65
	ds_read_b128 v[62:65], v7 offset:33488
	v_fmamk_f32 v118, v49, 0x3d800000, v117
	s_waitcnt lgkmcnt(0)
	v_fmac_f32_e32 v48, v133, v62
	v_fmac_f32_e32 v48, v130, v63
	v_fmac_f32_e32 v48, v131, v64
	v_fmac_f32_e32 v48, v132, v65
	ds_read_b128 v[62:65], v7 offset:33504
	s_waitcnt lgkmcnt(0)
	v_fmac_f32_e32 v48, v126, v62
	v_fmac_f32_e32 v48, v127, v63
	v_fmac_f32_e32 v48, v128, v64
	v_fmac_f32_e32 v48, v129, v65
	ds_read_b128 v[62:65], v7 offset:33520
	s_waitcnt lgkmcnt(0)
	v_fmac_f32_e32 v48, v47, v62
	v_fmac_f32_e32 v48, v76, v63
	v_fmac_f32_e32 v48, v124, v64
	v_fmac_f32_e32 v48, v125, v65
	v_min_f32_e32 v49, 0, v48
	v_mul_f32_e64 v48, |v48|, s3
	v_exp_f32_e32 v48, v48
	ds_read_b128 v[62:65], v7 offset:33536
	v_add_f32_e32 v48, 1.0, v48
	v_log_f32_e32 v48, v48
	s_nop 0
	v_fmac_f32_e32 v49, 0xbf317218, v48
	s_waitcnt lgkmcnt(0)
	v_fma_f32 v48, v0, v62, v46
	v_fmac_f32_e32 v48, v1, v63
	v_fmac_f32_e32 v48, v2, v64
	v_fmac_f32_e32 v48, v3, v65
	ds_read_b128 v[62:65], v7 offset:33552
	v_fmamk_f32 v119, v49, 0x3d800000, v118
	s_waitcnt lgkmcnt(0)
	v_fmac_f32_e32 v48, v133, v62
	v_fmac_f32_e32 v48, v130, v63
	v_fmac_f32_e32 v48, v131, v64
	v_fmac_f32_e32 v48, v132, v65
	ds_read_b128 v[62:65], v7 offset:33568
	s_waitcnt lgkmcnt(0)
	v_fmac_f32_e32 v48, v126, v62
	v_fmac_f32_e32 v48, v127, v63
	v_fmac_f32_e32 v48, v128, v64
	v_fmac_f32_e32 v48, v129, v65
	ds_read_b128 v[62:65], v7 offset:33584
	s_waitcnt lgkmcnt(0)
	v_fmac_f32_e32 v48, v47, v62
	v_fmac_f32_e32 v48, v76, v63
	v_fmac_f32_e32 v48, v124, v64
	v_fmac_f32_e32 v48, v125, v65
	v_min_f32_e32 v49, 0, v48
	v_mul_f32_e64 v48, |v48|, s3
	v_exp_f32_e32 v48, v48
	ds_read_b128 v[62:65], v7 offset:33600
	v_add_f32_e32 v48, 1.0, v48
	v_log_f32_e32 v48, v48
	s_nop 0
	v_fmac_f32_e32 v49, 0xbf317218, v48
	s_waitcnt lgkmcnt(0)
	v_fma_f32 v48, v0, v62, v46
	v_fmac_f32_e32 v48, v1, v63
	v_fmac_f32_e32 v48, v2, v64
	v_fmac_f32_e32 v48, v3, v65
	ds_read_b128 v[62:65], v7 offset:33616
	v_fmamk_f32 v120, v49, 0x3d800000, v119
	s_waitcnt lgkmcnt(0)
	v_fmac_f32_e32 v48, v133, v62
	v_fmac_f32_e32 v48, v130, v63
	v_fmac_f32_e32 v48, v131, v64
	v_fmac_f32_e32 v48, v132, v65
	ds_read_b128 v[62:65], v7 offset:33632
	s_waitcnt lgkmcnt(0)
	v_fmac_f32_e32 v48, v126, v62
	v_fmac_f32_e32 v48, v127, v63
	v_fmac_f32_e32 v48, v128, v64
	v_fmac_f32_e32 v48, v129, v65
	ds_read_b128 v[62:65], v7 offset:33648
	s_waitcnt lgkmcnt(0)
	v_fmac_f32_e32 v48, v47, v62
	v_fmac_f32_e32 v48, v76, v63
	v_fmac_f32_e32 v48, v124, v64
	v_fmac_f32_e32 v48, v125, v65
	v_min_f32_e32 v49, 0, v48
	v_mul_f32_e64 v48, |v48|, s3
	v_exp_f32_e32 v48, v48
	ds_read_b128 v[62:65], v7 offset:33664
	v_add_f32_e32 v48, 1.0, v48
	v_log_f32_e32 v48, v48
	s_nop 0
	v_fmac_f32_e32 v49, 0xbf317218, v48
	s_waitcnt lgkmcnt(0)
	v_fma_f32 v48, v0, v62, v46
	v_fmac_f32_e32 v48, v1, v63
	v_fmac_f32_e32 v48, v2, v64
	v_fmac_f32_e32 v48, v3, v65
	ds_read_b128 v[62:65], v7 offset:33680
	v_fmamk_f32 v121, v49, 0x3d800000, v120
	s_waitcnt lgkmcnt(0)
	v_fmac_f32_e32 v48, v133, v62
	v_fmac_f32_e32 v48, v130, v63
	v_fmac_f32_e32 v48, v131, v64
	v_fmac_f32_e32 v48, v132, v65
	ds_read_b128 v[62:65], v7 offset:33696
	s_waitcnt lgkmcnt(0)
	v_fmac_f32_e32 v48, v126, v62
	v_fmac_f32_e32 v48, v127, v63
	v_fmac_f32_e32 v48, v128, v64
	v_fmac_f32_e32 v48, v129, v65
	ds_read_b128 v[62:65], v7 offset:33712
	s_waitcnt lgkmcnt(0)
	v_fmac_f32_e32 v48, v47, v62
	v_fmac_f32_e32 v48, v76, v63
	v_fmac_f32_e32 v48, v124, v64
	v_fmac_f32_e32 v48, v125, v65
	v_min_f32_e32 v49, 0, v48
	v_mul_f32_e64 v48, |v48|, s3
	v_exp_f32_e32 v48, v48
	ds_read_b128 v[62:65], v7 offset:33728
	v_add_f32_e32 v48, 1.0, v48
	v_log_f32_e32 v48, v48
	s_nop 0
	v_fmac_f32_e32 v49, 0xbf317218, v48
	s_waitcnt lgkmcnt(0)
	v_fma_f32 v48, v0, v62, v46
	v_fmac_f32_e32 v48, v1, v63
	v_fmac_f32_e32 v48, v2, v64
	v_fmac_f32_e32 v48, v3, v65
	ds_read_b128 v[62:65], v7 offset:33744
	v_fmamk_f32 v122, v49, 0x3d800000, v121
	s_waitcnt lgkmcnt(0)
	v_fmac_f32_e32 v48, v133, v62
	v_fmac_f32_e32 v48, v130, v63
	v_fmac_f32_e32 v48, v131, v64
	v_fmac_f32_e32 v48, v132, v65
	ds_read_b128 v[62:65], v7 offset:33760
	s_waitcnt lgkmcnt(0)
; __device__ __forceinline__ float fexp(float x) { return __builtin_amdgcn_exp2f(x * 1.44269504089f); }
; __device__ __forceinline__ void phase_qkrope_gla_prep(const Params& p, LAS unsigned char* lds, int wave, int lane) {
;     ...
;             for (int t = 0; t < 64; ++t) { float lg = bias;
; #pragma unroll
;                 for (int r = 0; r < 16; ++r) lg += gl[t * 16 + r] * gu[r];
;                 const float ls = fminf(lg, 0.f) - 0.69314718056f * __builtin_amdgcn_logf(1.0f + fexp(-fabsf(lg)));
;                 run += ls * (1.0f / 16.0f); bl[t] = run; }
	v_fmac_f32_e32 v48, v126, v62
	v_fmac_f32_e32 v48, v127, v63
	v_fmac_f32_e32 v48, v128, v64
	v_fmac_f32_e32 v48, v129, v65
	ds_read_b128 v[62:65], v7 offset:33776
	s_waitcnt lgkmcnt(0)
	v_fmac_f32_e32 v48, v47, v62
	v_fmac_f32_e32 v48, v76, v63
	v_fmac_f32_e32 v48, v124, v64
	v_fmac_f32_e32 v48, v125, v65
	v_min_f32_e32 v49, 0, v48
	v_mul_f32_e64 v48, |v48|, s3
	v_exp_f32_e32 v48, v48
	ds_read_b128 v[62:65], v7 offset:33792
	v_add_f32_e32 v48, 1.0, v48
	v_log_f32_e32 v48, v48
	s_nop 0
	v_fmac_f32_e32 v49, 0xbf317218, v48
	s_waitcnt lgkmcnt(0)
	v_fma_f32 v48, v0, v62, v46
	v_fmac_f32_e32 v48, v1, v63
	v_fmac_f32_e32 v48, v2, v64
	v_fmac_f32_e32 v48, v3, v65
	ds_read_b128 v[62:65], v7 offset:33808
	v_fmamk_f32 v123, v49, 0x3d800000, v122
	s_waitcnt lgkmcnt(0)
	v_fmac_f32_e32 v48, v133, v62
	v_fmac_f32_e32 v48, v130, v63
	v_fmac_f32_e32 v48, v131, v64
	v_fmac_f32_e32 v48, v132, v65
	ds_read_b128 v[62:65], v7 offset:33824
	s_waitcnt lgkmcnt(0)
	v_fmac_f32_e32 v48, v126, v62
	v_fmac_f32_e32 v48, v127, v63
	v_fmac_f32_e32 v48, v128, v64
	v_fmac_f32_e32 v48, v129, v65
	ds_read_b128 v[62:65], v7 offset:33840
	s_waitcnt lgkmcnt(0)
	v_fmac_f32_e32 v48, v47, v62
	v_fmac_f32_e32 v48, v76, v63
	v_fmac_f32_e32 v48, v124, v64
	v_fmac_f32_e32 v48, v125, v65
	v_min_f32_e32 v49, 0, v48
	v_mul_f32_e64 v48, |v48|, s3
	v_exp_f32_e32 v48, v48
	ds_read_b128 v[62:65], v7 offset:33856
	v_add_f32_e32 v48, 1.0, v48
	v_log_f32_e32 v48, v48
	s_nop 0
	v_fmac_f32_e32 v49, 0xbf317218, v48
	s_waitcnt lgkmcnt(0)
	v_fma_f32 v48, v0, v62, v46
	v_fmac_f32_e32 v48, v1, v63
	v_fmac_f32_e32 v48, v2, v64
	v_fmac_f32_e32 v48, v3, v65
	ds_read_b128 v[62:65], v7 offset:33872
	v_fmamk_f32 v81, v49, 0x3d800000, v123
	s_waitcnt lgkmcnt(0)
	v_fmac_f32_e32 v48, v133, v62
	v_fmac_f32_e32 v48, v130, v63
	v_fmac_f32_e32 v48, v131, v64
	v_fmac_f32_e32 v48, v132, v65
	ds_read_b128 v[62:65], v7 offset:33888
	s_waitcnt lgkmcnt(0)
	v_fmac_f32_e32 v48, v126, v62
	v_fmac_f32_e32 v48, v127, v63
	v_fmac_f32_e32 v48, v128, v64
	v_fmac_f32_e32 v48, v129, v65
	ds_read_b128 v[62:65], v7 offset:33904
	s_waitcnt lgkmcnt(0)
	v_fmac_f32_e32 v48, v47, v62
	v_fmac_f32_e32 v48, v76, v63
	v_fmac_f32_e32 v48, v124, v64
	v_fmac_f32_e32 v48, v125, v65
	v_min_f32_e32 v49, 0, v48
	v_mul_f32_e64 v48, |v48|, s3
	v_exp_f32_e32 v48, v48
	ds_read_b128 v[62:65], v7 offset:33920
	v_add_f32_e32 v48, 1.0, v48
	v_log_f32_e32 v48, v48
	s_nop 0
	v_fmac_f32_e32 v49, 0xbf317218, v48
	s_waitcnt lgkmcnt(0)
	v_fma_f32 v48, v0, v62, v46
	v_fmac_f32_e32 v48, v1, v63
	v_fmac_f32_e32 v48, v2, v64
	v_fmac_f32_e32 v48, v3, v65
	ds_read_b128 v[62:65], v7 offset:33936
	v_fmamk_f32 v82, v49, 0x3d800000, v81
	s_waitcnt lgkmcnt(0)
	v_fmac_f32_e32 v48, v133, v62
	v_fmac_f32_e32 v48, v130, v63
	v_fmac_f32_e32 v48, v131, v64
	v_fmac_f32_e32 v48, v132, v65
	ds_read_b128 v[62:65], v7 offset:33952
	s_waitcnt lgkmcnt(0)
	v_fmac_f32_e32 v48, v126, v62
	v_fmac_f32_e32 v48, v127, v63
	v_fmac_f32_e32 v48, v128, v64
	v_fmac_f32_e32 v48, v129, v65
	ds_read_b128 v[62:65], v7 offset:33968
	s_waitcnt lgkmcnt(0)
	v_fmac_f32_e32 v48, v47, v62
	v_fmac_f32_e32 v48, v76, v63
	v_fmac_f32_e32 v48, v124, v64
	v_fmac_f32_e32 v48, v125, v65
	v_min_f32_e32 v49, 0, v48
	v_mul_f32_e64 v48, |v48|, s3
	v_exp_f32_e32 v48, v48
	ds_read_b128 v[62:65], v7 offset:33984
	v_add_f32_e32 v48, 1.0, v48
	v_log_f32_e32 v48, v48
	s_nop 0
	v_fmac_f32_e32 v49, 0xbf317218, v48
	s_waitcnt lgkmcnt(0)
	v_fma_f32 v48, v0, v62, v46
	v_fmac_f32_e32 v48, v1, v63
	v_fmac_f32_e32 v48, v2, v64
	v_fmac_f32_e32 v48, v3, v65
	ds_read_b128 v[62:65], v7 offset:34000
	v_fmamk_f32 v85, v49, 0x3d800000, v82
	s_waitcnt lgkmcnt(0)
	v_fmac_f32_e32 v48, v133, v62
	v_fmac_f32_e32 v48, v130, v63
	v_fmac_f32_e32 v48, v131, v64
	v_fmac_f32_e32 v48, v132, v65
	ds_read_b128 v[62:65], v7 offset:34016
	s_waitcnt lgkmcnt(0)
	v_fmac_f32_e32 v48, v126, v62
	v_fmac_f32_e32 v48, v127, v63
	v_fmac_f32_e32 v48, v128, v64
	v_fmac_f32_e32 v48, v129, v65
	ds_read_b128 v[62:65], v7 offset:34032
	s_waitcnt lgkmcnt(0)
	v_fmac_f32_e32 v48, v47, v62
	v_fmac_f32_e32 v48, v76, v63
	v_fmac_f32_e32 v48, v124, v64
	v_fmac_f32_e32 v48, v125, v65
	v_min_f32_e32 v49, 0, v48
	v_mul_f32_e64 v48, |v48|, s3
	v_exp_f32_e32 v48, v48
	ds_read_b128 v[62:65], v7 offset:34048
	v_add_f32_e32 v48, 1.0, v48
	v_log_f32_e32 v48, v48
	s_nop 0
	v_fmac_f32_e32 v49, 0xbf317218, v48
	s_waitcnt lgkmcnt(0)
	v_fma_f32 v48, v0, v62, v46
	v_fmac_f32_e32 v48, v1, v63
	v_fmac_f32_e32 v48, v2, v64
	v_fmac_f32_e32 v48, v3, v65
	ds_read_b128 v[62:65], v7 offset:34064
	v_fmamk_f32 v88, v49, 0x3d800000, v85
	s_waitcnt lgkmcnt(0)
	v_fmac_f32_e32 v48, v133, v62
	v_fmac_f32_e32 v48, v130, v63
	v_fmac_f32_e32 v48, v131, v64
	v_fmac_f32_e32 v48, v132, v65
	ds_read_b128 v[62:65], v7 offset:34080
	s_waitcnt lgkmcnt(0)
	v_fmac_f32_e32 v48, v126, v62
	v_fmac_f32_e32 v48, v127, v63
	v_fmac_f32_e32 v48, v128, v64
	v_fmac_f32_e32 v48, v129, v65
	ds_read_b128 v[62:65], v7 offset:34096
	s_waitcnt lgkmcnt(0)
	v_fmac_f32_e32 v48, v47, v62
	v_fmac_f32_e32 v48, v76, v63
	v_fmac_f32_e32 v48, v124, v64
	v_fmac_f32_e32 v48, v125, v65
	v_min_f32_e32 v49, 0, v48
	v_mul_f32_e64 v48, |v48|, s3
	v_exp_f32_e32 v48, v48
	ds_read_b128 v[62:65], v7 offset:34112
	v_add_f32_e32 v48, 1.0, v48
	v_log_f32_e32 v48, v48
	s_nop 0
	v_fmac_f32_e32 v49, 0xbf317218, v48
	s_waitcnt lgkmcnt(0)
	v_fma_f32 v48, v0, v62, v46
	v_fmac_f32_e32 v48, v1, v63
	v_fmac_f32_e32 v48, v2, v64
	v_fmac_f32_e32 v48, v3, v65
	ds_read_b128 v[62:65], v7 offset:34128
	v_fmamk_f32 v90, v49, 0x3d800000, v88
	s_waitcnt lgkmcnt(0)
	v_fmac_f32_e32 v48, v133, v62
	v_fmac_f32_e32 v48, v130, v63
	v_fmac_f32_e32 v48, v131, v64
	v_fmac_f32_e32 v48, v132, v65
	ds_read_b128 v[62:65], v7 offset:34144
	s_waitcnt lgkmcnt(0)
; __device__ __forceinline__ float fexp(float x) { return __builtin_amdgcn_exp2f(x * 1.44269504089f); }
; __device__ __forceinline__ void phase_qkrope_gla_prep(const Params& p, LAS unsigned char* lds, int wave, int lane) {
;     ...
;             for (int t = 0; t < 64; ++t) { float lg = bias;
; #pragma unroll
;                 for (int r = 0; r < 16; ++r) lg += gl[t * 16 + r] * gu[r];
;                 const float ls = fminf(lg, 0.f) - 0.69314718056f * __builtin_amdgcn_logf(1.0f + fexp(-fabsf(lg)));
;                 run += ls * (1.0f / 16.0f); bl[t] = run; }
	v_fmac_f32_e32 v48, v126, v62
	v_fmac_f32_e32 v48, v127, v63
	v_fmac_f32_e32 v48, v128, v64
	v_fmac_f32_e32 v48, v129, v65
	ds_read_b128 v[62:65], v7 offset:34160
	s_waitcnt lgkmcnt(0)
	v_fmac_f32_e32 v48, v47, v62
	v_fmac_f32_e32 v48, v76, v63
	v_fmac_f32_e32 v48, v124, v64
	v_fmac_f32_e32 v48, v125, v65
	v_min_f32_e32 v49, 0, v48
	v_mul_f32_e64 v48, |v48|, s3
	v_exp_f32_e32 v48, v48
	ds_read_b128 v[62:65], v7 offset:34176
	v_add_f32_e32 v48, 1.0, v48
	v_log_f32_e32 v48, v48
	s_nop 0
	v_fmac_f32_e32 v49, 0xbf317218, v48
	s_waitcnt lgkmcnt(0)
	v_fma_f32 v48, v0, v62, v46
	v_fmac_f32_e32 v48, v1, v63
	v_fmac_f32_e32 v48, v2, v64
	v_fmac_f32_e32 v48, v3, v65
	ds_read_b128 v[62:65], v7 offset:34192
	v_fmamk_f32 v92, v49, 0x3d800000, v90
	s_waitcnt lgkmcnt(0)
	v_fmac_f32_e32 v48, v133, v62
	v_fmac_f32_e32 v48, v130, v63
	v_fmac_f32_e32 v48, v131, v64
	v_fmac_f32_e32 v48, v132, v65
	ds_read_b128 v[62:65], v7 offset:34208
	s_waitcnt lgkmcnt(0)
	v_fmac_f32_e32 v48, v126, v62
	v_fmac_f32_e32 v48, v127, v63
	v_fmac_f32_e32 v48, v128, v64
	v_fmac_f32_e32 v48, v129, v65
	ds_read_b128 v[62:65], v7 offset:34224
	s_waitcnt lgkmcnt(0)
	v_fmac_f32_e32 v48, v47, v62
	v_fmac_f32_e32 v48, v76, v63
	v_fmac_f32_e32 v48, v124, v64
	v_fmac_f32_e32 v48, v125, v65
	v_min_f32_e32 v49, 0, v48
	v_mul_f32_e64 v48, |v48|, s3
	v_exp_f32_e32 v48, v48
	ds_read_b128 v[62:65], v7 offset:34240
	v_add_f32_e32 v48, 1.0, v48
	v_log_f32_e32 v48, v48
	s_nop 0
	v_fmac_f32_e32 v49, 0xbf317218, v48
	s_waitcnt lgkmcnt(0)
	v_fma_f32 v48, v0, v62, v46
	v_fmac_f32_e32 v48, v1, v63
	v_fmac_f32_e32 v48, v2, v64
	v_fmac_f32_e32 v48, v3, v65
	ds_read_b128 v[62:65], v7 offset:34256
	v_fmamk_f32 v94, v49, 0x3d800000, v92
	s_waitcnt lgkmcnt(0)
	v_fmac_f32_e32 v48, v133, v62
	v_fmac_f32_e32 v48, v130, v63
	v_fmac_f32_e32 v48, v131, v64
	v_fmac_f32_e32 v48, v132, v65
	ds_read_b128 v[62:65], v7 offset:34272
	s_waitcnt lgkmcnt(0)
	v_fmac_f32_e32 v48, v126, v62
	v_fmac_f32_e32 v48, v127, v63
	v_fmac_f32_e32 v48, v128, v64
	v_fmac_f32_e32 v48, v129, v65
	ds_read_b128 v[62:65], v7 offset:34288
	s_waitcnt lgkmcnt(0)
	v_fmac_f32_e32 v48, v47, v62
	v_fmac_f32_e32 v48, v76, v63
	v_fmac_f32_e32 v48, v124, v64
	v_fmac_f32_e32 v48, v125, v65
	v_min_f32_e32 v49, 0, v48
	v_mul_f32_e64 v48, |v48|, s3
	v_exp_f32_e32 v48, v48
	ds_read_b128 v[62:65], v7 offset:34304
	v_add_f32_e32 v48, 1.0, v48
	v_log_f32_e32 v48, v48
	s_nop 0
	v_fmac_f32_e32 v49, 0xbf317218, v48
	s_waitcnt lgkmcnt(0)
	v_fma_f32 v48, v0, v62, v46
	v_fmac_f32_e32 v48, v1, v63
	v_fmac_f32_e32 v48, v2, v64
	v_fmac_f32_e32 v48, v3, v65
	ds_read_b128 v[62:65], v7 offset:34320
	v_fmamk_f32 v96, v49, 0x3d800000, v94
	s_waitcnt lgkmcnt(0)
	v_fmac_f32_e32 v48, v133, v62
	v_fmac_f32_e32 v48, v130, v63
	v_fmac_f32_e32 v48, v131, v64
	v_fmac_f32_e32 v48, v132, v65
	ds_read_b128 v[62:65], v7 offset:34336
	s_waitcnt lgkmcnt(0)
	v_fmac_f32_e32 v48, v126, v62
	v_fmac_f32_e32 v48, v127, v63
	v_fmac_f32_e32 v48, v128, v64
	v_fmac_f32_e32 v48, v129, v65
	ds_read_b128 v[62:65], v7 offset:34352
	s_waitcnt lgkmcnt(0)
	v_fmac_f32_e32 v48, v47, v62
	v_fmac_f32_e32 v48, v76, v63
	v_fmac_f32_e32 v48, v124, v64
	v_fmac_f32_e32 v48, v125, v65
	v_min_f32_e32 v49, 0, v48
	v_mul_f32_e64 v48, |v48|, s3
	v_exp_f32_e32 v48, v48
	ds_read_b128 v[62:65], v7 offset:34368
	v_add_f32_e32 v48, 1.0, v48
	v_log_f32_e32 v48, v48
	s_nop 0
	v_fmac_f32_e32 v49, 0xbf317218, v48
	s_waitcnt lgkmcnt(0)
	v_fma_f32 v48, v0, v62, v46
	v_fmac_f32_e32 v48, v1, v63
	v_fmac_f32_e32 v48, v2, v64
	v_fmac_f32_e32 v48, v3, v65
	ds_read_b128 v[62:65], v7 offset:34384
	v_fmamk_f32 v98, v49, 0x3d800000, v96
	s_waitcnt lgkmcnt(0)
	v_fmac_f32_e32 v48, v133, v62
	v_fmac_f32_e32 v48, v130, v63
	v_fmac_f32_e32 v48, v131, v64
	v_fmac_f32_e32 v48, v132, v65
	ds_read_b128 v[62:65], v7 offset:34400
	s_waitcnt lgkmcnt(0)
	v_fmac_f32_e32 v48, v126, v62
	v_fmac_f32_e32 v48, v127, v63
	v_fmac_f32_e32 v48, v128, v64
	v_fmac_f32_e32 v48, v129, v65
	ds_read_b128 v[62:65], v7 offset:34416
	s_waitcnt lgkmcnt(0)
	v_fmac_f32_e32 v48, v47, v62
	v_fmac_f32_e32 v48, v76, v63
	v_fmac_f32_e32 v48, v124, v64
	v_fmac_f32_e32 v48, v125, v65
	v_min_f32_e32 v49, 0, v48
	v_mul_f32_e64 v48, |v48|, s3
	v_exp_f32_e32 v48, v48
	ds_read_b128 v[62:65], v7 offset:34432
	v_add_f32_e32 v48, 1.0, v48
	v_log_f32_e32 v48, v48
	s_nop 0
	v_fmac_f32_e32 v49, 0xbf317218, v48
	s_waitcnt lgkmcnt(0)
	v_fma_f32 v48, v0, v62, v46
	v_fmac_f32_e32 v48, v1, v63
	v_fmac_f32_e32 v48, v2, v64
	v_fmac_f32_e32 v48, v3, v65
	ds_read_b128 v[62:65], v7 offset:34448
	v_fmamk_f32 v101, v49, 0x3d800000, v98
	s_waitcnt lgkmcnt(0)
	v_fmac_f32_e32 v48, v133, v62
	v_fmac_f32_e32 v48, v130, v63
	v_fmac_f32_e32 v48, v131, v64
	v_fmac_f32_e32 v48, v132, v65
	ds_read_b128 v[62:65], v7 offset:34464
	s_waitcnt lgkmcnt(0)
	v_fmac_f32_e32 v48, v126, v62
	v_fmac_f32_e32 v48, v127, v63
	v_fmac_f32_e32 v48, v128, v64
	v_fmac_f32_e32 v48, v129, v65
	ds_read_b128 v[62:65], v7 offset:34480
	s_waitcnt lgkmcnt(0)
	v_fmac_f32_e32 v48, v47, v62
	v_fmac_f32_e32 v48, v76, v63
	v_fmac_f32_e32 v48, v124, v64
	v_fmac_f32_e32 v48, v125, v65
	v_min_f32_e32 v49, 0, v48
	v_mul_f32_e64 v48, |v48|, s3
	v_exp_f32_e32 v48, v48
	ds_read_b128 v[62:65], v7 offset:34496
	v_add_f32_e32 v48, 1.0, v48
	v_log_f32_e32 v48, v48
	s_nop 0
	v_fmac_f32_e32 v49, 0xbf317218, v48
	s_waitcnt lgkmcnt(0)
	v_fma_f32 v48, v0, v62, v46
	v_fmac_f32_e32 v48, v1, v63
	v_fmac_f32_e32 v48, v2, v64
	v_fmac_f32_e32 v48, v3, v65
	ds_read_b128 v[62:65], v7 offset:34512
	v_fmamk_f32 v105, v49, 0x3d800000, v101
	s_waitcnt lgkmcnt(0)
	v_fmac_f32_e32 v48, v133, v62
	v_fmac_f32_e32 v48, v130, v63
	v_fmac_f32_e32 v48, v131, v64
	v_fmac_f32_e32 v48, v132, v65
	ds_read_b128 v[62:65], v7 offset:34528
	s_waitcnt lgkmcnt(0)
; __device__ __forceinline__ float fexp(float x) { return __builtin_amdgcn_exp2f(x * 1.44269504089f); }
; __device__ __forceinline__ void phase_qkrope_gla_prep(const Params& p, LAS unsigned char* lds, int wave, int lane) {
;     ...
;             for (int t = 0; t < 64; ++t) { float lg = bias;
; #pragma unroll
;                 for (int r = 0; r < 16; ++r) lg += gl[t * 16 + r] * gu[r];
;                 const float ls = fminf(lg, 0.f) - 0.69314718056f * __builtin_amdgcn_logf(1.0f + fexp(-fabsf(lg)));
;                 run += ls * (1.0f / 16.0f); bl[t] = run; }
;             const float bref = bl[31], blast = bl[63];
; #pragma unroll
;             for (int tb = 0; tb < 4; ++tb) {
;                 unsigned short qv[16], kv[16];
; #pragma unroll
;                 for (int t = 0; t < 16; ++t) { const size_t ro = (size_t)(m0 + 16 * tb + t) * ZP + d; qv[t] = Z[ro + C_QG]; kv[t] = Z[ro + C_KG]; }
; #pragma unroll
;                 for (int t = 0; t < 16; ++t) { const size_t ro = (size_t)(m0 + 16 * tb + t) * ZP + d; const float bb = bl[16 * tb + t];
;                     const float qs = bf2f(qv[t]) * 0.08838834764831845f * fexp(bb - bref), ks = bf2f(kv[t]) * fexp(bref - bb);
	v_fmac_f32_e32 v48, v126, v62
	v_fmac_f32_e32 v48, v127, v63
	v_fmac_f32_e32 v48, v128, v64
	v_fmac_f32_e32 v48, v129, v65
	ds_read_b128 v[62:65], v7 offset:34544
	s_waitcnt lgkmcnt(0)
	v_fmac_f32_e32 v48, v47, v62
	v_fmac_f32_e32 v48, v76, v63
	v_fmac_f32_e32 v48, v124, v64
	v_fmac_f32_e32 v48, v125, v65
	v_min_f32_e32 v49, 0, v48
	v_mul_f32_e64 v48, |v48|, s3
	v_exp_f32_e32 v48, v48
	ds_read_b128 v[62:65], v7 offset:34560
	v_add_f32_e32 v48, 1.0, v48
	v_log_f32_e32 v48, v48
	s_nop 0
	v_fmac_f32_e32 v49, 0xbf317218, v48
	s_waitcnt lgkmcnt(0)
	v_fma_f32 v48, v0, v62, v46
	v_fmac_f32_e32 v48, v1, v63
	v_fmac_f32_e32 v48, v2, v64
	v_fmac_f32_e32 v48, v3, v65
	ds_read_b128 v[62:65], v7 offset:34576
	v_fmamk_f32 v108, v49, 0x3d800000, v105
	s_waitcnt lgkmcnt(0)
	v_fmac_f32_e32 v48, v133, v62
	v_fmac_f32_e32 v48, v130, v63
	v_fmac_f32_e32 v48, v131, v64
	v_fmac_f32_e32 v48, v132, v65
	ds_read_b128 v[62:65], v7 offset:34592
	s_waitcnt lgkmcnt(0)
	v_fmac_f32_e32 v48, v126, v62
	v_fmac_f32_e32 v48, v127, v63
	v_fmac_f32_e32 v48, v128, v64
	v_fmac_f32_e32 v48, v129, v65
	ds_read_b128 v[62:65], v7 offset:34608
	s_waitcnt lgkmcnt(0)
	v_fmac_f32_e32 v48, v47, v62
	v_fmac_f32_e32 v48, v76, v63
	v_fmac_f32_e32 v48, v124, v64
	v_fmac_f32_e32 v48, v125, v65
	v_min_f32_e32 v49, 0, v48
	v_mul_f32_e64 v48, |v48|, s3
	v_exp_f32_e32 v48, v48
	ds_read_b128 v[62:65], v7 offset:34624
	v_add_f32_e32 v48, 1.0, v48
	v_log_f32_e32 v48, v48
	s_nop 0
	v_fmac_f32_e32 v49, 0xbf317218, v48
	s_waitcnt lgkmcnt(0)
	v_fma_f32 v48, v0, v62, v46
	v_fmac_f32_e32 v48, v1, v63
	v_fmac_f32_e32 v48, v2, v64
	v_fmac_f32_e32 v48, v3, v65
	ds_read_b128 v[62:65], v7 offset:34640
	v_fmamk_f32 v110, v49, 0x3d800000, v108
	s_waitcnt lgkmcnt(0)
	v_fmac_f32_e32 v48, v133, v62
	v_fmac_f32_e32 v48, v130, v63
	v_fmac_f32_e32 v48, v131, v64
	v_fmac_f32_e32 v48, v132, v65
	ds_read_b128 v[62:65], v7 offset:34656
	s_waitcnt lgkmcnt(0)
	v_fmac_f32_e32 v48, v126, v62
	v_fmac_f32_e32 v48, v127, v63
	v_fmac_f32_e32 v48, v128, v64
	v_fmac_f32_e32 v48, v129, v65
	ds_read_b128 v[62:65], v7 offset:34672
	s_waitcnt lgkmcnt(0)
	v_fmac_f32_e32 v48, v47, v62
	v_fmac_f32_e32 v48, v76, v63
	v_fmac_f32_e32 v48, v124, v64
	v_fmac_f32_e32 v48, v125, v65
	v_min_f32_e32 v49, 0, v48
	v_mul_f32_e64 v48, |v48|, s3
	v_exp_f32_e32 v48, v48
	ds_read_b128 v[62:65], v7 offset:34688
	v_add_f32_e32 v48, 1.0, v48
	v_log_f32_e32 v48, v48
	s_nop 0
	v_fmac_f32_e32 v49, 0xbf317218, v48
	s_waitcnt lgkmcnt(0)
	v_fma_f32 v48, v0, v62, v46
	v_fmac_f32_e32 v48, v1, v63
	v_fmac_f32_e32 v48, v2, v64
	v_fmac_f32_e32 v48, v3, v65
	ds_read_b128 v[62:65], v7 offset:34704
	v_fmamk_f32 v113, v49, 0x3d800000, v110
	s_waitcnt lgkmcnt(0)
	v_fmac_f32_e32 v48, v133, v62
	v_fmac_f32_e32 v48, v130, v63
	v_fmac_f32_e32 v48, v131, v64
	v_fmac_f32_e32 v48, v132, v65
	ds_read_b128 v[62:65], v7 offset:34720
	s_waitcnt lgkmcnt(0)
	v_fmac_f32_e32 v48, v126, v62
	v_fmac_f32_e32 v48, v127, v63
	v_fmac_f32_e32 v48, v128, v64
	v_fmac_f32_e32 v48, v129, v65
	ds_read_b128 v[62:65], v7 offset:34736
	s_waitcnt lgkmcnt(0)
	v_fmac_f32_e32 v48, v47, v62
	v_fmac_f32_e32 v48, v76, v63
	v_fmac_f32_e32 v48, v124, v64
	v_fmac_f32_e32 v48, v125, v65
	v_min_f32_e32 v49, 0, v48
	v_mul_f32_e64 v48, |v48|, s3
	v_exp_f32_e32 v48, v48
	ds_read_b128 v[62:65], v7 offset:34752
	v_add_f32_e32 v48, 1.0, v48
	v_log_f32_e32 v48, v48
	s_nop 0
	v_fmac_f32_e32 v49, 0xbf317218, v48
	s_waitcnt lgkmcnt(0)
	v_fma_f32 v48, v0, v62, v46
	v_fmac_f32_e32 v48, v1, v63
	v_fmac_f32_e32 v48, v2, v64
	v_fmac_f32_e32 v48, v3, v65
	ds_read_b128 v[62:65], v7 offset:34768
	v_fmamk_f32 v115, v49, 0x3d800000, v113
	s_waitcnt lgkmcnt(0)
	v_fmac_f32_e32 v48, v133, v62
	v_fmac_f32_e32 v48, v130, v63
	v_fmac_f32_e32 v48, v131, v64
	v_fmac_f32_e32 v48, v132, v65
	ds_read_b128 v[62:65], v7 offset:34784
	s_waitcnt lgkmcnt(0)
	v_fmac_f32_e32 v48, v126, v62
	v_fmac_f32_e32 v48, v127, v63
	v_fmac_f32_e32 v48, v128, v64
	v_fmac_f32_e32 v48, v129, v65
	ds_read_b128 v[62:65], v7 offset:34800
	s_waitcnt lgkmcnt(0)
	v_fmac_f32_e32 v48, v47, v62
	v_fmac_f32_e32 v48, v76, v63
	v_fmac_f32_e32 v48, v124, v64
	v_fmac_f32_e32 v48, v125, v65
	v_min_f32_e32 v49, 0, v48
	v_mul_f32_e64 v48, |v48|, s3
	v_exp_f32_e32 v48, v48
	ds_read_b128 v[62:65], v7 offset:34816
	v_add_f32_e32 v48, 1.0, v48
	v_log_f32_e32 v48, v48
	s_nop 0
	v_fmac_f32_e32 v49, 0xbf317218, v48
	v_fmamk_f32 v48, v49, 0x3d800000, v115
	s_waitcnt lgkmcnt(0)
	v_fma_f32 v49, v0, v62, v46
	v_fmac_f32_e32 v49, v1, v63
	v_fmac_f32_e32 v49, v2, v64
	v_fmac_f32_e32 v49, v3, v65
	ds_read_b128 v[62:65], v7 offset:34832
	v_sub_f32_e32 v151, v100, v48
	v_mul_f32_e32 v151, 0x3fb8aa3b, v151
	v_exp_f32_e32 v151, v151
	v_sub_f32_e32 v100, v48, v100
	s_waitcnt lgkmcnt(0)
	v_fmac_f32_e32 v49, v133, v62
	v_fmac_f32_e32 v49, v130, v63
	v_fmac_f32_e32 v49, v131, v64
	v_fmac_f32_e32 v49, v132, v65
	ds_read_b128 v[62:65], v7 offset:34848
	v_mul_f32_e32 v100, 0x3fb8aa3b, v100
	v_exp_f32_e32 v100, v100
	s_waitcnt lgkmcnt(0)
	v_fmac_f32_e32 v49, v126, v62
	v_fmac_f32_e32 v49, v127, v63
	v_fmac_f32_e32 v49, v128, v64
	v_fmac_f32_e32 v49, v129, v65
	ds_read_b128 v[62:65], v7 offset:34864
	s_waitcnt lgkmcnt(0)
	v_fmac_f32_e32 v49, v47, v62
	v_fmac_f32_e32 v49, v76, v63
	v_fmac_f32_e32 v49, v124, v64
	v_fmac_f32_e32 v49, v125, v65
	v_min_f32_e32 v62, 0, v49
	v_mul_f32_e64 v49, |v49|, s3
	v_exp_f32_e32 v49, v49
	s_nop 0
	v_add_f32_e32 v49, 1.0, v49
	v_log_f32_e32 v49, v49
	s_nop 0
	v_fmac_f32_e32 v62, 0xbf317218, v49
	v_fmamk_f32 v68, v62, 0x3d800000, v48
	ds_read_b128 v[62:65], v7 offset:34880
	s_waitcnt lgkmcnt(0)
; __device__ __forceinline__ float fexp(float x) { return __builtin_amdgcn_exp2f(x * 1.44269504089f); }
; __device__ __forceinline__ void phase_qkrope_gla_prep(const Params& p, LAS unsigned char* lds, int wave, int lane) {
;     ...
;             for (int t = 0; t < 64; ++t) { float lg = bias;
; #pragma unroll
;                 for (int r = 0; r < 16; ++r) lg += gl[t * 16 + r] * gu[r];
;                 const float ls = fminf(lg, 0.f) - 0.69314718056f * __builtin_amdgcn_logf(1.0f + fexp(-fabsf(lg)));
;                 run += ls * (1.0f / 16.0f); bl[t] = run; }
	v_fma_f32 v49, v0, v62, v46
	v_fmac_f32_e32 v49, v1, v63
	v_fmac_f32_e32 v49, v2, v64
	v_fmac_f32_e32 v49, v3, v65
	ds_read_b128 v[62:65], v7 offset:34896
	s_waitcnt lgkmcnt(0)
	v_fmac_f32_e32 v49, v133, v62
	v_fmac_f32_e32 v49, v130, v63
	v_fmac_f32_e32 v49, v131, v64
	v_fmac_f32_e32 v49, v132, v65
	ds_read_b128 v[62:65], v7 offset:34912
	s_waitcnt lgkmcnt(0)
	v_fmac_f32_e32 v49, v126, v62
	v_fmac_f32_e32 v49, v127, v63
	v_fmac_f32_e32 v49, v128, v64
	v_fmac_f32_e32 v49, v129, v65
	ds_read_b128 v[62:65], v7 offset:34928
	s_waitcnt lgkmcnt(0)
	v_fmac_f32_e32 v49, v47, v62
	v_fmac_f32_e32 v49, v76, v63
	v_fmac_f32_e32 v49, v124, v64
	v_fmac_f32_e32 v49, v125, v65
	v_min_f32_e32 v62, 0, v49
	v_mul_f32_e64 v49, |v49|, s3
	v_exp_f32_e32 v49, v49
	s_nop 0
	v_add_f32_e32 v49, 1.0, v49
	v_log_f32_e32 v49, v49
	s_nop 0
	v_fmac_f32_e32 v62, 0xbf317218, v49
	v_fmamk_f32 v70, v62, 0x3d800000, v68
	ds_read_b128 v[62:65], v7 offset:34944
	s_waitcnt lgkmcnt(0)
	v_fma_f32 v49, v0, v62, v46
	v_fmac_f32_e32 v49, v1, v63
	v_fmac_f32_e32 v49, v2, v64
	v_fmac_f32_e32 v49, v3, v65
	ds_read_b128 v[62:65], v7 offset:34960
	s_waitcnt lgkmcnt(0)
	v_fmac_f32_e32 v49, v133, v62
	v_fmac_f32_e32 v49, v130, v63
	v_fmac_f32_e32 v49, v131, v64
	v_fmac_f32_e32 v49, v132, v65
	ds_read_b128 v[62:65], v7 offset:34976
	s_waitcnt lgkmcnt(0)
	v_fmac_f32_e32 v49, v126, v62
	v_fmac_f32_e32 v49, v127, v63
	v_fmac_f32_e32 v49, v128, v64
	v_fmac_f32_e32 v49, v129, v65
	ds_read_b128 v[62:65], v7 offset:34992
	s_waitcnt lgkmcnt(0)
	v_fmac_f32_e32 v49, v47, v62
	v_fmac_f32_e32 v49, v76, v63
	v_fmac_f32_e32 v49, v124, v64
	v_fmac_f32_e32 v49, v125, v65
	v_min_f32_e32 v62, 0, v49
	v_mul_f32_e64 v49, |v49|, s3
	v_exp_f32_e32 v49, v49
	s_nop 0
	v_add_f32_e32 v49, 1.0, v49
	v_log_f32_e32 v49, v49
	s_nop 0
	v_fmac_f32_e32 v62, 0xbf317218, v49
	v_fmamk_f32 v72, v62, 0x3d800000, v70
	ds_read_b128 v[62:65], v7 offset:35008
	s_waitcnt lgkmcnt(0)
	v_fma_f32 v49, v0, v62, v46
	v_fmac_f32_e32 v49, v1, v63
	v_fmac_f32_e32 v49, v2, v64
	v_fmac_f32_e32 v49, v3, v65
	ds_read_b128 v[62:65], v7 offset:35024
	s_waitcnt lgkmcnt(0)
	v_fmac_f32_e32 v49, v133, v62
	v_fmac_f32_e32 v49, v130, v63
	v_fmac_f32_e32 v49, v131, v64
	v_fmac_f32_e32 v49, v132, v65
	ds_read_b128 v[62:65], v7 offset:35040
	s_waitcnt lgkmcnt(0)
	v_fmac_f32_e32 v49, v126, v62
	v_fmac_f32_e32 v49, v127, v63
	v_fmac_f32_e32 v49, v128, v64
	v_fmac_f32_e32 v49, v129, v65
	ds_read_b128 v[62:65], v7 offset:35056
	s_waitcnt lgkmcnt(0)
	v_fmac_f32_e32 v49, v47, v62
	v_fmac_f32_e32 v49, v76, v63
	v_fmac_f32_e32 v49, v124, v64
	v_fmac_f32_e32 v49, v125, v65
	v_min_f32_e32 v62, 0, v49
	v_mul_f32_e64 v49, |v49|, s3
	v_exp_f32_e32 v49, v49
	s_nop 0
	v_add_f32_e32 v49, 1.0, v49
	v_log_f32_e32 v49, v49
	s_nop 0
	v_fmac_f32_e32 v62, 0xbf317218, v49
	v_fmamk_f32 v74, v62, 0x3d800000, v72
	ds_read_b128 v[62:65], v7 offset:35072
	s_waitcnt lgkmcnt(0)
	v_fma_f32 v49, v0, v62, v46
	v_fmac_f32_e32 v49, v1, v63
	v_fmac_f32_e32 v49, v2, v64
	v_fmac_f32_e32 v49, v3, v65
	ds_read_b128 v[62:65], v7 offset:35088
	s_waitcnt lgkmcnt(0)
	v_fmac_f32_e32 v49, v133, v62
	v_fmac_f32_e32 v49, v130, v63
	v_fmac_f32_e32 v49, v131, v64
	v_fmac_f32_e32 v49, v132, v65
	ds_read_b128 v[62:65], v7 offset:35104
	s_waitcnt lgkmcnt(0)
	v_fmac_f32_e32 v49, v126, v62
	v_fmac_f32_e32 v49, v127, v63
	v_fmac_f32_e32 v49, v128, v64
	v_fmac_f32_e32 v49, v129, v65
	ds_read_b128 v[62:65], v7 offset:35120
	s_waitcnt lgkmcnt(0)
	v_fmac_f32_e32 v49, v47, v62
	v_fmac_f32_e32 v49, v76, v63
	v_fmac_f32_e32 v49, v124, v64
	v_fmac_f32_e32 v49, v125, v65
	v_min_f32_e32 v62, 0, v49
	v_mul_f32_e64 v49, |v49|, s3
	v_exp_f32_e32 v49, v49
	s_nop 0
	v_add_f32_e32 v49, 1.0, v49
	v_log_f32_e32 v49, v49
	s_nop 0
	v_fmac_f32_e32 v62, 0xbf317218, v49
	v_fmamk_f32 v77, v62, 0x3d800000, v74
	ds_read_b128 v[62:65], v7 offset:35136
	s_waitcnt lgkmcnt(0)
	v_fma_f32 v49, v0, v62, v46
	v_fmac_f32_e32 v49, v1, v63
	v_fmac_f32_e32 v49, v2, v64
	v_fmac_f32_e32 v49, v3, v65
	ds_read_b128 v[62:65], v7 offset:35152
	s_waitcnt lgkmcnt(0)
	v_fmac_f32_e32 v49, v133, v62
	v_fmac_f32_e32 v49, v130, v63
	v_fmac_f32_e32 v49, v131, v64
	v_fmac_f32_e32 v49, v132, v65
	ds_read_b128 v[62:65], v7 offset:35168
	s_waitcnt lgkmcnt(0)
	v_fmac_f32_e32 v49, v126, v62
	v_fmac_f32_e32 v49, v127, v63
	v_fmac_f32_e32 v49, v128, v64
	v_fmac_f32_e32 v49, v129, v65
	ds_read_b128 v[62:65], v7 offset:35184
	s_waitcnt lgkmcnt(0)
	v_fmac_f32_e32 v49, v47, v62
	v_fmac_f32_e32 v49, v76, v63
	v_fmac_f32_e32 v49, v124, v64
	v_fmac_f32_e32 v49, v125, v65
	v_min_f32_e32 v62, 0, v49
	v_mul_f32_e64 v49, |v49|, s3
	v_exp_f32_e32 v49, v49
	s_nop 0
	v_add_f32_e32 v49, 1.0, v49
	v_log_f32_e32 v49, v49
	s_nop 0
	v_fmac_f32_e32 v62, 0xbf317218, v49
	v_fmamk_f32 v79, v62, 0x3d800000, v77
	ds_read_b128 v[62:65], v7 offset:35200
	s_waitcnt lgkmcnt(0)
	v_fma_f32 v49, v0, v62, v46
	v_fmac_f32_e32 v49, v1, v63
	v_fmac_f32_e32 v49, v2, v64
	v_fmac_f32_e32 v49, v3, v65
	ds_read_b128 v[62:65], v7 offset:35216
	s_waitcnt lgkmcnt(0)
	v_fmac_f32_e32 v49, v133, v62
	v_fmac_f32_e32 v49, v130, v63
	v_fmac_f32_e32 v49, v131, v64
	v_fmac_f32_e32 v49, v132, v65
	ds_read_b128 v[62:65], v7 offset:35232
	s_waitcnt lgkmcnt(0)
	v_fmac_f32_e32 v49, v126, v62
	v_fmac_f32_e32 v49, v127, v63
	v_fmac_f32_e32 v49, v128, v64
	v_fmac_f32_e32 v49, v129, v65
	ds_read_b128 v[62:65], v7 offset:35248
	s_waitcnt lgkmcnt(0)
	v_fmac_f32_e32 v49, v47, v62
	v_fmac_f32_e32 v49, v76, v63
	v_fmac_f32_e32 v49, v124, v64
	v_fmac_f32_e32 v49, v125, v65
	v_min_f32_e32 v62, 0, v49
	v_mul_f32_e64 v49, |v49|, s3
	v_exp_f32_e32 v49, v49
	s_nop 0
	v_add_f32_e32 v49, 1.0, v49
	v_log_f32_e32 v49, v49
	s_nop 0
	v_fmac_f32_e32 v62, 0xbf317218, v49
	v_fmamk_f32 v83, v62, 0x3d800000, v79
	ds_read_b128 v[62:65], v7 offset:35264
	s_waitcnt lgkmcnt(0)
; __device__ __forceinline__ float fexp(float x) { return __builtin_amdgcn_exp2f(x * 1.44269504089f); }
; __device__ __forceinline__ void phase_qkrope_gla_prep(const Params& p, LAS unsigned char* lds, int wave, int lane) {
;     ...
;             for (int t = 0; t < 64; ++t) { float lg = bias;
; #pragma unroll
;                 for (int r = 0; r < 16; ++r) lg += gl[t * 16 + r] * gu[r];
;                 const float ls = fminf(lg, 0.f) - 0.69314718056f * __builtin_amdgcn_logf(1.0f + fexp(-fabsf(lg)));
;                 run += ls * (1.0f / 16.0f); bl[t] = run; }
	v_fma_f32 v49, v0, v62, v46
	v_fmac_f32_e32 v49, v1, v63
	v_fmac_f32_e32 v49, v2, v64
	v_fmac_f32_e32 v49, v3, v65
	ds_read_b128 v[62:65], v7 offset:35280
	s_waitcnt lgkmcnt(0)
	v_fmac_f32_e32 v49, v133, v62
	v_fmac_f32_e32 v49, v130, v63
	v_fmac_f32_e32 v49, v131, v64
	v_fmac_f32_e32 v49, v132, v65
	ds_read_b128 v[62:65], v7 offset:35296
	s_waitcnt lgkmcnt(0)
	v_fmac_f32_e32 v49, v126, v62
	v_fmac_f32_e32 v49, v127, v63
	v_fmac_f32_e32 v49, v128, v64
	v_fmac_f32_e32 v49, v129, v65
	ds_read_b128 v[62:65], v7 offset:35312
	s_waitcnt lgkmcnt(0)
	v_fmac_f32_e32 v49, v47, v62
	v_fmac_f32_e32 v49, v76, v63
	v_fmac_f32_e32 v49, v124, v64
	v_fmac_f32_e32 v49, v125, v65
	v_min_f32_e32 v62, 0, v49
	v_mul_f32_e64 v49, |v49|, s3
	v_exp_f32_e32 v49, v49
	s_nop 0
	v_add_f32_e32 v49, 1.0, v49
	v_log_f32_e32 v49, v49
	s_nop 0
	v_fmac_f32_e32 v62, 0xbf317218, v49
	v_fmamk_f32 v86, v62, 0x3d800000, v83
	ds_read_b128 v[62:65], v7 offset:35328
	s_waitcnt lgkmcnt(0)
	v_fma_f32 v49, v0, v62, v46
	v_fmac_f32_e32 v49, v1, v63
	v_fmac_f32_e32 v49, v2, v64
	v_fmac_f32_e32 v49, v3, v65
	ds_read_b128 v[62:65], v7 offset:35344
	s_waitcnt lgkmcnt(0)
	v_fmac_f32_e32 v49, v133, v62
	v_fmac_f32_e32 v49, v130, v63
	v_fmac_f32_e32 v49, v131, v64
	v_fmac_f32_e32 v49, v132, v65
	ds_read_b128 v[62:65], v7 offset:35360
	s_waitcnt lgkmcnt(0)
	v_fmac_f32_e32 v49, v126, v62
	v_fmac_f32_e32 v49, v127, v63
	v_fmac_f32_e32 v49, v128, v64
	v_fmac_f32_e32 v49, v129, v65
	ds_read_b128 v[62:65], v7 offset:35376
	s_waitcnt lgkmcnt(0)
	v_fmac_f32_e32 v49, v47, v62
	v_fmac_f32_e32 v49, v76, v63
	v_fmac_f32_e32 v49, v124, v64
	v_fmac_f32_e32 v49, v125, v65
	v_min_f32_e32 v62, 0, v49
	v_mul_f32_e64 v49, |v49|, s3
	v_exp_f32_e32 v49, v49
	s_nop 0
	v_add_f32_e32 v49, 1.0, v49
	v_log_f32_e32 v49, v49
	s_nop 0
	v_fmac_f32_e32 v62, 0xbf317218, v49
	v_fmamk_f32 v89, v62, 0x3d800000, v86
	ds_read_b128 v[62:65], v7 offset:35392
	s_waitcnt lgkmcnt(0)
	v_fma_f32 v49, v0, v62, v46
	v_fmac_f32_e32 v49, v1, v63
	v_fmac_f32_e32 v49, v2, v64
	v_fmac_f32_e32 v49, v3, v65
	ds_read_b128 v[62:65], v7 offset:35408
	s_waitcnt lgkmcnt(0)
	v_fmac_f32_e32 v49, v133, v62
	v_fmac_f32_e32 v49, v130, v63
	v_fmac_f32_e32 v49, v131, v64
	v_fmac_f32_e32 v49, v132, v65
	ds_read_b128 v[62:65], v7 offset:35424
	s_waitcnt lgkmcnt(0)
	v_fmac_f32_e32 v49, v126, v62
	v_fmac_f32_e32 v49, v127, v63
	v_fmac_f32_e32 v49, v128, v64
	v_fmac_f32_e32 v49, v129, v65
	ds_read_b128 v[62:65], v7 offset:35440
	s_waitcnt lgkmcnt(0)
	v_fmac_f32_e32 v49, v47, v62
	v_fmac_f32_e32 v49, v76, v63
	v_fmac_f32_e32 v49, v124, v64
	v_fmac_f32_e32 v49, v125, v65
	v_min_f32_e32 v62, 0, v49
	v_mul_f32_e64 v49, |v49|, s3
	v_exp_f32_e32 v49, v49
	s_nop 0
	v_add_f32_e32 v49, 1.0, v49
	v_log_f32_e32 v49, v49
	s_nop 0
	v_fmac_f32_e32 v62, 0xbf317218, v49
	v_fmamk_f32 v91, v62, 0x3d800000, v89
	ds_read_b128 v[62:65], v7 offset:35456
	s_waitcnt lgkmcnt(0)
	v_fma_f32 v49, v0, v62, v46
	v_fmac_f32_e32 v49, v1, v63
	v_fmac_f32_e32 v49, v2, v64
	v_fmac_f32_e32 v49, v3, v65
	ds_read_b128 v[62:65], v7 offset:35472
	s_waitcnt lgkmcnt(0)
	v_fmac_f32_e32 v49, v133, v62
	v_fmac_f32_e32 v49, v130, v63
	v_fmac_f32_e32 v49, v131, v64
	v_fmac_f32_e32 v49, v132, v65
	ds_read_b128 v[62:65], v7 offset:35488
	s_waitcnt lgkmcnt(0)
	v_fmac_f32_e32 v49, v126, v62
	v_fmac_f32_e32 v49, v127, v63
	v_fmac_f32_e32 v49, v128, v64
	v_fmac_f32_e32 v49, v129, v65
	ds_read_b128 v[62:65], v7 offset:35504
	s_waitcnt lgkmcnt(0)
	v_fmac_f32_e32 v49, v47, v62
	v_fmac_f32_e32 v49, v76, v63
	v_fmac_f32_e32 v49, v124, v64
	v_fmac_f32_e32 v49, v125, v65
	v_min_f32_e32 v62, 0, v49
	v_mul_f32_e64 v49, |v49|, s3
	v_exp_f32_e32 v49, v49
	s_nop 0
	v_add_f32_e32 v49, 1.0, v49
	v_log_f32_e32 v49, v49
	s_nop 0
	v_fmac_f32_e32 v62, 0xbf317218, v49
	v_fmamk_f32 v93, v62, 0x3d800000, v91
	ds_read_b128 v[62:65], v7 offset:35520
	s_waitcnt lgkmcnt(0)
	v_fma_f32 v49, v0, v62, v46
	v_fmac_f32_e32 v49, v1, v63
	v_fmac_f32_e32 v49, v2, v64
	v_fmac_f32_e32 v49, v3, v65
	ds_read_b128 v[62:65], v7 offset:35536
	s_waitcnt lgkmcnt(0)
	v_fmac_f32_e32 v49, v133, v62
	v_fmac_f32_e32 v49, v130, v63
	v_fmac_f32_e32 v49, v131, v64
	v_fmac_f32_e32 v49, v132, v65
	ds_read_b128 v[62:65], v7 offset:35552
	s_waitcnt lgkmcnt(0)
	v_fmac_f32_e32 v49, v126, v62
	v_fmac_f32_e32 v49, v127, v63
	v_fmac_f32_e32 v49, v128, v64
	v_fmac_f32_e32 v49, v129, v65
	ds_read_b128 v[62:65], v7 offset:35568
	s_waitcnt lgkmcnt(0)
	v_fmac_f32_e32 v49, v47, v62
	v_fmac_f32_e32 v49, v76, v63
	v_fmac_f32_e32 v49, v124, v64
	v_fmac_f32_e32 v49, v125, v65
	v_min_f32_e32 v62, 0, v49
	v_mul_f32_e64 v49, |v49|, s3
	v_exp_f32_e32 v49, v49
	s_nop 0
	v_add_f32_e32 v49, 1.0, v49
	v_log_f32_e32 v49, v49
	s_nop 0
	v_fmac_f32_e32 v62, 0xbf317218, v49
	v_fmamk_f32 v95, v62, 0x3d800000, v93
	ds_read_b128 v[62:65], v7 offset:35584
	s_waitcnt lgkmcnt(0)
	v_fma_f32 v49, v0, v62, v46
	v_fmac_f32_e32 v49, v1, v63
	v_fmac_f32_e32 v49, v2, v64
	v_fmac_f32_e32 v49, v3, v65
	ds_read_b128 v[62:65], v7 offset:35600
	s_waitcnt lgkmcnt(0)
	v_fmac_f32_e32 v49, v133, v62
	v_fmac_f32_e32 v49, v130, v63
	v_fmac_f32_e32 v49, v131, v64
	v_fmac_f32_e32 v49, v132, v65
	ds_read_b128 v[62:65], v7 offset:35616
	s_waitcnt lgkmcnt(0)
	v_fmac_f32_e32 v49, v126, v62
	v_fmac_f32_e32 v49, v127, v63
	v_fmac_f32_e32 v49, v128, v64
	v_fmac_f32_e32 v49, v129, v65
	ds_read_b128 v[62:65], v7 offset:35632
	s_waitcnt lgkmcnt(0)
	v_fmac_f32_e32 v49, v47, v62
	v_fmac_f32_e32 v49, v76, v63
	v_fmac_f32_e32 v49, v124, v64
	v_fmac_f32_e32 v49, v125, v65
	v_min_f32_e32 v62, 0, v49
	v_mul_f32_e64 v49, |v49|, s3
	v_exp_f32_e32 v49, v49
	s_nop 0
	v_add_f32_e32 v49, 1.0, v49
	v_log_f32_e32 v49, v49
	s_nop 0
	v_fmac_f32_e32 v62, 0xbf317218, v49
	v_fmamk_f32 v97, v62, 0x3d800000, v95
	ds_read_b128 v[62:65], v7 offset:35648
	s_waitcnt lgkmcnt(0)
; __device__ __forceinline__ float fexp(float x) { return __builtin_amdgcn_exp2f(x * 1.44269504089f); }
; __device__ __forceinline__ void phase_qkrope_gla_prep(const Params& p, LAS unsigned char* lds, int wave, int lane) {
;     ...
;             for (int t = 0; t < 64; ++t) { float lg = bias;
; #pragma unroll
;                 for (int r = 0; r < 16; ++r) lg += gl[t * 16 + r] * gu[r];
;                 const float ls = fminf(lg, 0.f) - 0.69314718056f * __builtin_amdgcn_logf(1.0f + fexp(-fabsf(lg)));
;                 run += ls * (1.0f / 16.0f); bl[t] = run; }
	v_fma_f32 v49, v0, v62, v46
	v_fmac_f32_e32 v49, v1, v63
	v_fmac_f32_e32 v49, v2, v64
	v_fmac_f32_e32 v49, v3, v65
	ds_read_b128 v[62:65], v7 offset:35664
	s_waitcnt lgkmcnt(0)
	v_fmac_f32_e32 v49, v133, v62
	v_fmac_f32_e32 v49, v130, v63
	v_fmac_f32_e32 v49, v131, v64
	v_fmac_f32_e32 v49, v132, v65
	ds_read_b128 v[62:65], v7 offset:35680
	s_waitcnt lgkmcnt(0)
	v_fmac_f32_e32 v49, v126, v62
	v_fmac_f32_e32 v49, v127, v63
	v_fmac_f32_e32 v49, v128, v64
	v_fmac_f32_e32 v49, v129, v65
	ds_read_b128 v[62:65], v7 offset:35696
	s_waitcnt lgkmcnt(0)
	v_fmac_f32_e32 v49, v47, v62
	v_fmac_f32_e32 v49, v76, v63
	v_fmac_f32_e32 v49, v124, v64
	v_fmac_f32_e32 v49, v125, v65
	v_min_f32_e32 v62, 0, v49
	v_mul_f32_e64 v49, |v49|, s3
	v_exp_f32_e32 v49, v49
	s_nop 0
	v_add_f32_e32 v49, 1.0, v49
	v_log_f32_e32 v49, v49
	s_nop 0
	v_fmac_f32_e32 v62, 0xbf317218, v49
	v_fmamk_f32 v99, v62, 0x3d800000, v97
	ds_read_b128 v[62:65], v7 offset:35712
	s_waitcnt lgkmcnt(0)
	v_fma_f32 v49, v0, v62, v46
	v_fmac_f32_e32 v49, v1, v63
	v_fmac_f32_e32 v49, v2, v64
	v_fmac_f32_e32 v49, v3, v65
	ds_read_b128 v[62:65], v7 offset:35728
	s_waitcnt lgkmcnt(0)
	v_fmac_f32_e32 v49, v133, v62
	v_fmac_f32_e32 v49, v130, v63
	v_fmac_f32_e32 v49, v131, v64
	v_fmac_f32_e32 v49, v132, v65
	ds_read_b128 v[62:65], v7 offset:35744
	s_waitcnt lgkmcnt(0)
	v_fmac_f32_e32 v49, v126, v62
	v_fmac_f32_e32 v49, v127, v63
	v_fmac_f32_e32 v49, v128, v64
	v_fmac_f32_e32 v49, v129, v65
	ds_read_b128 v[62:65], v7 offset:35760
	s_waitcnt lgkmcnt(0)
	v_fmac_f32_e32 v49, v47, v62
	v_fmac_f32_e32 v49, v76, v63
	v_fmac_f32_e32 v49, v124, v64
	v_fmac_f32_e32 v49, v125, v65
	v_min_f32_e32 v62, 0, v49
	v_mul_f32_e64 v49, |v49|, s3
	v_exp_f32_e32 v49, v49
	s_nop 0
	v_add_f32_e32 v49, 1.0, v49
	v_log_f32_e32 v49, v49
	s_nop 0
	v_fmac_f32_e32 v62, 0xbf317218, v49
	v_fmamk_f32 v103, v62, 0x3d800000, v99
	ds_read_b128 v[62:65], v7 offset:35776
	s_waitcnt lgkmcnt(0)
	v_fma_f32 v49, v0, v62, v46
	v_fmac_f32_e32 v49, v1, v63
	v_fmac_f32_e32 v49, v2, v64
	v_fmac_f32_e32 v49, v3, v65
	ds_read_b128 v[62:65], v7 offset:35792
	s_waitcnt lgkmcnt(0)
	v_fmac_f32_e32 v49, v133, v62
	v_fmac_f32_e32 v49, v130, v63
	v_fmac_f32_e32 v49, v131, v64
	v_fmac_f32_e32 v49, v132, v65
	ds_read_b128 v[62:65], v7 offset:35808
	s_waitcnt lgkmcnt(0)
	v_fmac_f32_e32 v49, v126, v62
	v_fmac_f32_e32 v49, v127, v63
	v_fmac_f32_e32 v49, v128, v64
	v_fmac_f32_e32 v49, v129, v65
	ds_read_b128 v[62:65], v7 offset:35824
	s_waitcnt lgkmcnt(0)
	v_fmac_f32_e32 v49, v47, v62
	v_fmac_f32_e32 v49, v76, v63
	v_fmac_f32_e32 v49, v124, v64
	v_fmac_f32_e32 v49, v125, v65
	v_min_f32_e32 v62, 0, v49
	v_mul_f32_e64 v49, |v49|, s3
	v_exp_f32_e32 v49, v49
	s_nop 0
	v_add_f32_e32 v49, 1.0, v49
	v_log_f32_e32 v49, v49
	s_nop 0
	v_fmac_f32_e32 v62, 0xbf317218, v49
	v_fmamk_f32 v106, v62, 0x3d800000, v103
	ds_read_b128 v[62:65], v7 offset:35840
	s_waitcnt lgkmcnt(0)
	v_fma_f32 v49, v0, v62, v46
	v_fmac_f32_e32 v49, v1, v63
	v_fmac_f32_e32 v49, v2, v64
	v_fmac_f32_e32 v49, v3, v65
	ds_read_b128 v[62:65], v7 offset:35856
	s_waitcnt lgkmcnt(0)
	v_fmac_f32_e32 v49, v133, v62
	v_fmac_f32_e32 v49, v130, v63
	v_fmac_f32_e32 v49, v131, v64
	v_fmac_f32_e32 v49, v132, v65
	ds_read_b128 v[62:65], v7 offset:35872
	s_waitcnt lgkmcnt(0)
	v_fmac_f32_e32 v49, v126, v62
	v_fmac_f32_e32 v49, v127, v63
	v_fmac_f32_e32 v49, v128, v64
	v_fmac_f32_e32 v49, v129, v65
	ds_read_b128 v[62:65], v7 offset:35888
	s_waitcnt lgkmcnt(0)
	v_fmac_f32_e32 v49, v47, v62
	v_fmac_f32_e32 v49, v76, v63
	v_fmac_f32_e32 v49, v124, v64
	v_fmac_f32_e32 v49, v125, v65
	v_min_f32_e32 v62, 0, v49
	v_mul_f32_e64 v49, |v49|, s3
	v_exp_f32_e32 v49, v49
	s_nop 0
	v_add_f32_e32 v49, 1.0, v49
	v_log_f32_e32 v49, v49
	s_nop 0
	v_fmac_f32_e32 v62, 0xbf317218, v49
	v_fmamk_f32 v49, v62, 0x3d800000, v106
	ds_read_b128 v[62:65], v7 offset:35904
	s_waitcnt lgkmcnt(0)
	v_fma_f32 v66, v0, v62, v46
	v_fmac_f32_e32 v66, v1, v63
	v_fmac_f32_e32 v66, v2, v64
	v_fmac_f32_e32 v66, v3, v65
	ds_read_b128 v[62:65], v7 offset:35920
	s_waitcnt lgkmcnt(0)
	v_fmac_f32_e32 v66, v133, v62
	v_fmac_f32_e32 v66, v130, v63
	v_fmac_f32_e32 v66, v131, v64
	v_fmac_f32_e32 v66, v132, v65
	ds_read_b128 v[62:65], v7 offset:35936
	s_waitcnt lgkmcnt(0)
	v_fmac_f32_e32 v66, v126, v62
	v_fmac_f32_e32 v66, v127, v63
	v_fmac_f32_e32 v66, v128, v64
	v_fmac_f32_e32 v66, v129, v65
	ds_read_b128 v[62:65], v7 offset:35952
	s_waitcnt lgkmcnt(0)
	v_fmac_f32_e32 v66, v47, v62
	v_fmac_f32_e32 v66, v76, v63
	v_fmac_f32_e32 v66, v124, v64
	v_fmac_f32_e32 v66, v125, v65
	v_mul_f32_e64 v63, |v66|, s3
	v_exp_f32_e32 v63, v63
	v_min_f32_e32 v62, 0, v66
	ds_read_b128 v[64:67], v7 offset:35968
	v_add_f32_e32 v63, 1.0, v63
	v_log_f32_e32 v63, v63
	s_nop 0
	v_fmac_f32_e32 v62, 0xbf317218, v63
	s_waitcnt lgkmcnt(0)
	v_fma_f32 v63, v0, v64, v46
	v_fmac_f32_e32 v63, v1, v65
	v_fmac_f32_e32 v63, v2, v66
	v_fmac_f32_e32 v63, v3, v67
	ds_read_b128 v[64:67], v7 offset:35984
	v_fmamk_f32 v62, v62, 0x3d800000, v49
	s_waitcnt lgkmcnt(0)
	v_fmac_f32_e32 v63, v133, v64
	v_fmac_f32_e32 v63, v130, v65
	v_fmac_f32_e32 v63, v131, v66
	v_fmac_f32_e32 v63, v132, v67
	ds_read_b128 v[64:67], v7 offset:36000
	s_waitcnt lgkmcnt(0)
	v_fmac_f32_e32 v63, v126, v64
	v_fmac_f32_e32 v63, v127, v65
	v_fmac_f32_e32 v63, v128, v66
	v_fmac_f32_e32 v63, v129, v67
	ds_read_b128 v[64:67], v7 offset:36016
	s_waitcnt lgkmcnt(0)
	v_fmac_f32_e32 v63, v47, v64
	v_fmac_f32_e32 v63, v76, v65
	v_fmac_f32_e32 v63, v124, v66
	v_fmac_f32_e32 v63, v125, v67
	v_min_f32_e32 v64, 0, v63
	v_mul_f32_e64 v63, |v63|, s3
	v_exp_f32_e32 v63, v63
	s_nop 0
	v_add_f32_e32 v63, 1.0, v63
	v_log_f32_e32 v63, v63
	s_nop 0
	v_fmac_f32_e32 v64, 0xbf317218, v63
	v_fmamk_f32 v63, v64, 0x3d800000, v62
	ds_read_b128 v[64:67], v7 offset:36032
	s_waitcnt lgkmcnt(0)
; __device__ __forceinline__ float fexp(float x) { return __builtin_amdgcn_exp2f(x * 1.44269504089f); }
; __device__ __forceinline__ void phase_qkrope_gla_prep(const Params& p, LAS unsigned char* lds, int wave, int lane) {
;     ...
;             for (int t = 0; t < 64; ++t) { float lg = bias;
; #pragma unroll
;                 for (int r = 0; r < 16; ++r) lg += gl[t * 16 + r] * gu[r];
;                 const float ls = fminf(lg, 0.f) - 0.69314718056f * __builtin_amdgcn_logf(1.0f + fexp(-fabsf(lg)));
;                 run += ls * (1.0f / 16.0f); bl[t] = run; }
	v_fma_f32 v69, v0, v64, v46
	v_fmac_f32_e32 v69, v1, v65
	v_fmac_f32_e32 v69, v2, v66
	v_fmac_f32_e32 v69, v3, v67
	ds_read_b128 v[64:67], v7 offset:36048
	s_waitcnt lgkmcnt(0)
	v_fmac_f32_e32 v69, v133, v64
	v_fmac_f32_e32 v69, v130, v65
	v_fmac_f32_e32 v69, v131, v66
	v_fmac_f32_e32 v69, v132, v67
	ds_read_b128 v[64:67], v7 offset:36064
	s_waitcnt lgkmcnt(0)
	v_fmac_f32_e32 v69, v126, v64
	v_fmac_f32_e32 v69, v127, v65
	v_fmac_f32_e32 v69, v128, v66
	v_fmac_f32_e32 v69, v129, v67
	ds_read_b128 v[64:67], v7 offset:36080
	s_waitcnt lgkmcnt(0)
	v_fmac_f32_e32 v69, v47, v64
	v_fmac_f32_e32 v69, v76, v65
	v_fmac_f32_e32 v69, v124, v66
	v_fmac_f32_e32 v69, v125, v67
	v_mul_f32_e64 v65, |v69|, s3
	v_exp_f32_e32 v65, v65
	v_min_f32_e32 v64, 0, v69
	v_add_f32_e32 v65, 1.0, v65
	v_log_f32_e32 v65, v65
	s_nop 0
	v_fmac_f32_e32 v64, 0xbf317218, v65
	v_fma_f32 v65, v0, v134, v46
	v_fmac_f32_e32 v65, v1, v135
	v_fmac_f32_e32 v65, v2, v136
	v_fmac_f32_e32 v65, v3, v137
	ds_read_b128 v[134:137], v7 offset:36112
	v_fmamk_f32 v64, v64, 0x3d800000, v63
	s_waitcnt lgkmcnt(0)
	v_fmac_f32_e32 v65, v133, v134
	v_fmac_f32_e32 v65, v130, v135
	v_fmac_f32_e32 v65, v131, v136
	v_fmac_f32_e32 v65, v132, v137
	ds_read_b128 v[134:137], v7 offset:36128
	s_waitcnt lgkmcnt(0)
	v_fmac_f32_e32 v65, v126, v134
	v_fmac_f32_e32 v65, v127, v135
	v_fmac_f32_e32 v65, v128, v136
	v_fmac_f32_e32 v65, v129, v137
	ds_read_b128 v[134:137], v7 offset:36144
	s_waitcnt lgkmcnt(0)
	v_fmac_f32_e32 v65, v47, v134
	v_fmac_f32_e32 v65, v76, v135
	v_fmac_f32_e32 v65, v124, v136
	v_fmac_f32_e32 v65, v125, v137
	v_min_f32_e32 v66, 0, v65
	v_mul_f32_e64 v65, |v65|, s3
	v_exp_f32_e32 v65, v65
	ds_read_b128 v[134:137], v7 offset:36160
	v_add_f32_e32 v65, 1.0, v65
	v_log_f32_e32 v65, v65
	s_nop 0
	v_fmac_f32_e32 v66, 0xbf317218, v65
	v_fmamk_f32 v65, v66, 0x3d800000, v64
	s_waitcnt lgkmcnt(0)
	v_fma_f32 v66, v0, v134, v46
	v_fmac_f32_e32 v66, v1, v135
	v_fmac_f32_e32 v66, v2, v136
	v_fmac_f32_e32 v66, v3, v137
	ds_read_b128 v[134:137], v7 offset:36176
	s_waitcnt lgkmcnt(0)
	v_fmac_f32_e32 v66, v133, v134
	v_fmac_f32_e32 v66, v130, v135
	v_fmac_f32_e32 v66, v131, v136
	v_fmac_f32_e32 v66, v132, v137
	ds_read_b128 v[134:137], v7 offset:36192
	s_waitcnt lgkmcnt(0)
	v_fmac_f32_e32 v66, v126, v134
	v_fmac_f32_e32 v66, v127, v135
	v_fmac_f32_e32 v66, v128, v136
	v_fmac_f32_e32 v66, v129, v137
	ds_read_b128 v[134:137], v7 offset:36208
	s_waitcnt lgkmcnt(0)
	v_fmac_f32_e32 v66, v47, v134
	v_fmac_f32_e32 v66, v76, v135
	v_fmac_f32_e32 v66, v124, v136
	v_fmac_f32_e32 v66, v125, v137
	v_min_f32_e32 v67, 0, v66
	v_mul_f32_e64 v66, |v66|, s3
	v_exp_f32_e32 v66, v66
	ds_read_b128 v[134:137], v7 offset:36224
	v_add_f32_e32 v66, 1.0, v66
	v_log_f32_e32 v66, v66
	s_nop 0
	v_fmac_f32_e32 v67, 0xbf317218, v66
	v_fmamk_f32 v66, v67, 0x3d800000, v65
	s_waitcnt lgkmcnt(0)
	v_fma_f32 v67, v0, v134, v46
	v_fmac_f32_e32 v67, v1, v135
	v_fmac_f32_e32 v67, v2, v136
	v_fmac_f32_e32 v67, v3, v137
	ds_read_b128 v[134:137], v7 offset:36240
	s_waitcnt lgkmcnt(0)
	v_fmac_f32_e32 v67, v133, v134
	v_fmac_f32_e32 v67, v130, v135
	v_fmac_f32_e32 v67, v131, v136
	v_fmac_f32_e32 v67, v132, v137
	ds_read_b128 v[134:137], v7 offset:36256
	s_waitcnt lgkmcnt(0)
	v_fmac_f32_e32 v67, v126, v134
	v_fmac_f32_e32 v67, v127, v135
	v_fmac_f32_e32 v67, v128, v136
	v_fmac_f32_e32 v67, v129, v137
	ds_read_b128 v[134:137], v7 offset:36272
	s_waitcnt lgkmcnt(0)
	v_fmac_f32_e32 v67, v47, v134
	v_fmac_f32_e32 v67, v76, v135
	v_fmac_f32_e32 v67, v124, v136
	v_fmac_f32_e32 v67, v125, v137
	v_min_f32_e32 v69, 0, v67
	v_mul_f32_e64 v67, |v67|, s3
	v_exp_f32_e32 v67, v67
	ds_read_b128 v[134:137], v7 offset:36288
	v_add_f32_e32 v67, 1.0, v67
	v_log_f32_e32 v67, v67
	s_nop 0
	v_fmac_f32_e32 v69, 0xbf317218, v67
	v_fmamk_f32 v67, v69, 0x3d800000, v66
	s_waitcnt lgkmcnt(0)
	v_fma_f32 v69, v0, v134, v46
	v_fmac_f32_e32 v69, v1, v135
	v_fmac_f32_e32 v69, v2, v136
	v_fmac_f32_e32 v69, v3, v137
	ds_read_b128 v[134:137], v7 offset:36304
	s_waitcnt lgkmcnt(0)
	v_fmac_f32_e32 v69, v133, v134
	v_fmac_f32_e32 v69, v130, v135
	v_fmac_f32_e32 v69, v131, v136
	v_fmac_f32_e32 v69, v132, v137
	ds_read_b128 v[134:137], v7 offset:36320
	s_waitcnt lgkmcnt(0)
	v_fmac_f32_e32 v69, v126, v134
	v_fmac_f32_e32 v69, v127, v135
	v_fmac_f32_e32 v69, v128, v136
	v_fmac_f32_e32 v69, v129, v137
	ds_read_b128 v[134:137], v7 offset:36336
	s_waitcnt lgkmcnt(0)
	v_fmac_f32_e32 v69, v47, v134
	v_fmac_f32_e32 v69, v76, v135
	v_fmac_f32_e32 v69, v124, v136
	v_fmac_f32_e32 v69, v125, v137
	v_min_f32_e32 v71, 0, v69
	v_mul_f32_e64 v69, |v69|, s3
	v_exp_f32_e32 v69, v69
	ds_read_b128 v[134:137], v7 offset:36352
	v_add_f32_e32 v69, 1.0, v69
	v_log_f32_e32 v69, v69
	s_nop 0
	v_fmac_f32_e32 v71, 0xbf317218, v69
	v_fmamk_f32 v69, v71, 0x3d800000, v67
	s_waitcnt lgkmcnt(0)
	v_fma_f32 v71, v0, v134, v46
	v_fmac_f32_e32 v71, v1, v135
	v_fmac_f32_e32 v71, v2, v136
	v_fmac_f32_e32 v71, v3, v137
	ds_read_b128 v[134:137], v7 offset:36368
	s_waitcnt lgkmcnt(0)
	v_fmac_f32_e32 v71, v133, v134
	v_fmac_f32_e32 v71, v130, v135
	v_fmac_f32_e32 v71, v131, v136
	v_fmac_f32_e32 v71, v132, v137
	ds_read_b128 v[134:137], v7 offset:36384
	s_waitcnt lgkmcnt(0)
	v_fmac_f32_e32 v71, v126, v134
	v_fmac_f32_e32 v71, v127, v135
	v_fmac_f32_e32 v71, v128, v136
	v_fmac_f32_e32 v71, v129, v137
	ds_read_b128 v[134:137], v7 offset:36400
	s_waitcnt lgkmcnt(0)
	v_fmac_f32_e32 v71, v47, v134
	v_fmac_f32_e32 v71, v76, v135
	v_fmac_f32_e32 v71, v124, v136
	v_fmac_f32_e32 v71, v125, v137
	v_min_f32_e32 v73, 0, v71
	v_mul_f32_e64 v71, |v71|, s3
	v_exp_f32_e32 v71, v71
	ds_read_b128 v[134:137], v7 offset:36416
	v_add_f32_e32 v71, 1.0, v71
	v_log_f32_e32 v71, v71
	s_nop 0
	v_fmac_f32_e32 v73, 0xbf317218, v71
	v_fmamk_f32 v71, v73, 0x3d800000, v69
	s_waitcnt lgkmcnt(0)
; __device__ __forceinline__ float fexp(float x) { return __builtin_amdgcn_exp2f(x * 1.44269504089f); }
; __device__ __forceinline__ void phase_qkrope_gla_prep(const Params& p, LAS unsigned char* lds, int wave, int lane) {
;     ...
;             for (int t = 0; t < 64; ++t) { float lg = bias;
; #pragma unroll
;                 for (int r = 0; r < 16; ++r) lg += gl[t * 16 + r] * gu[r];
;                 const float ls = fminf(lg, 0.f) - 0.69314718056f * __builtin_amdgcn_logf(1.0f + fexp(-fabsf(lg)));
;                 run += ls * (1.0f / 16.0f); bl[t] = run; }
	v_fma_f32 v73, v0, v134, v46
	v_fmac_f32_e32 v73, v1, v135
	v_fmac_f32_e32 v73, v2, v136
	v_fmac_f32_e32 v73, v3, v137
	ds_read_b128 v[134:137], v7 offset:36432
	s_waitcnt lgkmcnt(0)
	v_fmac_f32_e32 v73, v133, v134
	v_fmac_f32_e32 v73, v130, v135
	v_fmac_f32_e32 v73, v131, v136
	v_fmac_f32_e32 v73, v132, v137
	ds_read_b128 v[134:137], v7 offset:36448
	s_waitcnt lgkmcnt(0)
	v_fmac_f32_e32 v73, v126, v134
	v_fmac_f32_e32 v73, v127, v135
	v_fmac_f32_e32 v73, v128, v136
	v_fmac_f32_e32 v73, v129, v137
	ds_read_b128 v[134:137], v7 offset:36464
	s_waitcnt lgkmcnt(0)
	v_fmac_f32_e32 v73, v47, v134
	v_fmac_f32_e32 v73, v76, v135
	v_fmac_f32_e32 v73, v124, v136
	v_fmac_f32_e32 v73, v125, v137
	v_min_f32_e32 v75, 0, v73
	v_mul_f32_e64 v73, |v73|, s3
	v_exp_f32_e32 v73, v73
	ds_read_b128 v[134:137], v7 offset:36480
	v_add_f32_e32 v73, 1.0, v73
	v_log_f32_e32 v73, v73
	s_nop 0
	v_fmac_f32_e32 v75, 0xbf317218, v73
	v_fmamk_f32 v73, v75, 0x3d800000, v71
	s_waitcnt lgkmcnt(0)
	v_fma_f32 v75, v0, v134, v46
	v_fmac_f32_e32 v75, v1, v135
	v_fmac_f32_e32 v75, v2, v136
	v_fmac_f32_e32 v75, v3, v137
	ds_read_b128 v[134:137], v7 offset:36496
	s_waitcnt lgkmcnt(0)
	v_fmac_f32_e32 v75, v133, v134
	v_fmac_f32_e32 v75, v130, v135
	v_fmac_f32_e32 v75, v131, v136
	v_fmac_f32_e32 v75, v132, v137
	ds_read_b128 v[134:137], v7 offset:36512
	s_waitcnt lgkmcnt(0)
	v_fmac_f32_e32 v75, v126, v134
	v_fmac_f32_e32 v75, v127, v135
	v_fmac_f32_e32 v75, v128, v136
	v_fmac_f32_e32 v75, v129, v137
	ds_read_b128 v[134:137], v7 offset:36528
	s_waitcnt lgkmcnt(0)
	v_fmac_f32_e32 v75, v47, v134
	v_fmac_f32_e32 v75, v76, v135
	v_fmac_f32_e32 v75, v124, v136
	v_fmac_f32_e32 v75, v125, v137
	v_min_f32_e32 v78, 0, v75
	v_mul_f32_e64 v75, |v75|, s3
	v_exp_f32_e32 v75, v75
	ds_read_b128 v[134:137], v7 offset:36544
	v_add_f32_e32 v75, 1.0, v75
	v_log_f32_e32 v75, v75
	s_nop 0
	v_fmac_f32_e32 v78, 0xbf317218, v75
	v_fmamk_f32 v75, v78, 0x3d800000, v73
	s_waitcnt lgkmcnt(0)
	v_fma_f32 v78, v0, v134, v46
	v_fmac_f32_e32 v78, v1, v135
	v_fmac_f32_e32 v78, v2, v136
	v_fmac_f32_e32 v78, v3, v137
	ds_read_b128 v[134:137], v7 offset:36560
	s_waitcnt lgkmcnt(0)
	v_fmac_f32_e32 v78, v133, v134
	v_fmac_f32_e32 v78, v130, v135
	v_fmac_f32_e32 v78, v131, v136
	v_fmac_f32_e32 v78, v132, v137
	ds_read_b128 v[134:137], v7 offset:36576
	s_waitcnt lgkmcnt(0)
	v_fmac_f32_e32 v78, v126, v134
	v_fmac_f32_e32 v78, v127, v135
	v_fmac_f32_e32 v78, v128, v136
	v_fmac_f32_e32 v78, v129, v137
	ds_read_b128 v[134:137], v7 offset:36592
	s_waitcnt lgkmcnt(0)
	v_fmac_f32_e32 v78, v47, v134
	v_fmac_f32_e32 v78, v76, v135
	v_fmac_f32_e32 v78, v124, v136
	v_fmac_f32_e32 v78, v125, v137
	v_min_f32_e32 v80, 0, v78
	v_mul_f32_e64 v78, |v78|, s3
	v_exp_f32_e32 v78, v78
	ds_read_b128 v[134:137], v7 offset:36608
	v_add_f32_e32 v78, 1.0, v78
	v_log_f32_e32 v78, v78
	s_nop 0
	v_fmac_f32_e32 v80, 0xbf317218, v78
	v_fmamk_f32 v78, v80, 0x3d800000, v75
	s_waitcnt lgkmcnt(0)
	v_fma_f32 v80, v0, v134, v46
	v_fmac_f32_e32 v80, v1, v135
	v_fmac_f32_e32 v80, v2, v136
	v_fmac_f32_e32 v80, v3, v137
	ds_read_b128 v[134:137], v7 offset:36624
	s_waitcnt lgkmcnt(0)
	v_fmac_f32_e32 v80, v133, v134
	v_fmac_f32_e32 v80, v130, v135
	v_fmac_f32_e32 v80, v131, v136
	v_fmac_f32_e32 v80, v132, v137
	ds_read_b128 v[134:137], v7 offset:36640
	s_waitcnt lgkmcnt(0)
	v_fmac_f32_e32 v80, v126, v134
	v_fmac_f32_e32 v80, v127, v135
	v_fmac_f32_e32 v80, v128, v136
	v_fmac_f32_e32 v80, v129, v137
	ds_read_b128 v[134:137], v7 offset:36656
	s_waitcnt lgkmcnt(0)
	v_fmac_f32_e32 v80, v47, v134
	v_fmac_f32_e32 v80, v76, v135
	v_fmac_f32_e32 v80, v124, v136
	v_fmac_f32_e32 v80, v125, v137
	v_min_f32_e32 v84, 0, v80
	v_mul_f32_e64 v80, |v80|, s3
	v_exp_f32_e32 v80, v80
	ds_read_b128 v[134:137], v7 offset:36672
	v_add_f32_e32 v80, 1.0, v80
	v_log_f32_e32 v80, v80
	s_nop 0
	v_fmac_f32_e32 v84, 0xbf317218, v80
	v_fmamk_f32 v80, v84, 0x3d800000, v78
	s_waitcnt lgkmcnt(0)
	v_fma_f32 v84, v0, v134, v46
	v_fmac_f32_e32 v84, v1, v135
	v_fmac_f32_e32 v84, v2, v136
	v_fmac_f32_e32 v84, v3, v137
	ds_read_b128 v[134:137], v7 offset:36688
	s_waitcnt lgkmcnt(0)
	v_fmac_f32_e32 v84, v133, v134
	v_fmac_f32_e32 v84, v130, v135
	v_fmac_f32_e32 v84, v131, v136
	v_fmac_f32_e32 v84, v132, v137
	ds_read_b128 v[134:137], v7 offset:36704
	s_waitcnt lgkmcnt(0)
	v_fmac_f32_e32 v84, v126, v134
	v_fmac_f32_e32 v84, v127, v135
	v_fmac_f32_e32 v84, v128, v136
	v_fmac_f32_e32 v84, v129, v137
	ds_read_b128 v[134:137], v7 offset:36720
	s_waitcnt lgkmcnt(0)
	v_fmac_f32_e32 v84, v47, v134
	v_fmac_f32_e32 v84, v76, v135
	v_fmac_f32_e32 v84, v124, v136
	v_fmac_f32_e32 v84, v125, v137
	v_min_f32_e32 v87, 0, v84
	v_mul_f32_e64 v84, |v84|, s3
	v_exp_f32_e32 v84, v84
	ds_read_b128 v[134:137], v7 offset:36736
	v_add_f32_e32 v84, 1.0, v84
	v_log_f32_e32 v84, v84
	s_nop 0
	v_fmac_f32_e32 v87, 0xbf317218, v84
	v_fmamk_f32 v84, v87, 0x3d800000, v80
	s_waitcnt lgkmcnt(0)
	v_fma_f32 v87, v0, v134, v46
	v_fmac_f32_e32 v87, v1, v135
	v_fmac_f32_e32 v87, v2, v136
	v_fmac_f32_e32 v87, v3, v137
	ds_read_b128 v[134:137], v7 offset:36752
	s_waitcnt lgkmcnt(0)
	v_fmac_f32_e32 v87, v133, v134
	v_fmac_f32_e32 v87, v130, v135
	v_fmac_f32_e32 v87, v131, v136
	v_fmac_f32_e32 v87, v132, v137
	ds_read_b128 v[134:137], v7 offset:36768
	s_waitcnt lgkmcnt(0)
	v_fmac_f32_e32 v87, v126, v134
	v_fmac_f32_e32 v87, v127, v135
	v_fmac_f32_e32 v87, v128, v136
	v_fmac_f32_e32 v87, v129, v137
	ds_read_b128 v[134:137], v7 offset:36784
	s_waitcnt lgkmcnt(0)
; __device__ __forceinline__ unsigned cvtpk(float lo, float hi) { f32x2 v = {lo, hi}; bf16x2_t b = __builtin_convertvector(v, bf16x2_t); return __builtin_bit_cast(unsigned, b); }
; __device__ __forceinline__ float fexp(float x) { return __builtin_amdgcn_exp2f(x * 1.44269504089f); }
; __device__ __forceinline__ void phase_qkrope_gla_prep(const Params& p, LAS unsigned char* lds, int wave, int lane) {
;     ...
;             for (int t = 0; t < 64; ++t) { float lg = bias;
; #pragma unroll
;                 for (int r = 0; r < 16; ++r) lg += gl[t * 16 + r] * gu[r];
;                 const float ls = fminf(lg, 0.f) - 0.69314718056f * __builtin_amdgcn_logf(1.0f + fexp(-fabsf(lg)));
;                 run += ls * (1.0f / 16.0f); bl[t] = run; }
;             const float bref = bl[31], blast = bl[63];
; #pragma unroll
;             for (int tb = 0; tb < 4; ++tb) {
;                 unsigned short qv[16], kv[16];
; #pragma unroll
;                 for (int t = 0; t < 16; ++t) { const size_t ro = (size_t)(m0 + 16 * tb + t) * ZP + d; qv[t] = Z[ro + C_QG]; kv[t] = Z[ro + C_KG]; }
; #pragma unroll
;                 for (int t = 0; t < 16; ++t) { const size_t ro = (size_t)(m0 + 16 * tb + t) * ZP + d; const float bb = bl[16 * tb + t];
;                     const float qs = bf2f(qv[t]) * 0.08838834764831845f * fexp(bb - bref), ks = bf2f(kv[t]) * fexp(bref - bb);
;                     Z[ro + C_QG] = (bf16_t)(cvtpk(qs, 0.f) & 0xffffu); Z[ro + C_KG] = (bf16_t)(cvtpk(ks, 0.f) & 0xffffu); }
	v_fmac_f32_e32 v87, v47, v134
	v_fmac_f32_e32 v87, v76, v135
	v_fmac_f32_e32 v87, v124, v136
	v_fmac_f32_e32 v87, v125, v137
	v_min_f32_e32 v134, 0, v87
	v_mul_f32_e64 v87, |v87|, s3
	v_exp_f32_e32 v87, v87
	s_nop 0
	v_add_f32_e32 v87, 1.0, v87
	v_log_f32_e32 v87, v87
	s_nop 0
	v_fmac_f32_e32 v134, 0xbf317218, v87
	v_fmamk_f32 v87, v134, 0x3d800000, v84
	ds_read_b128 v[134:137], v7 offset:36800
	s_waitcnt lgkmcnt(0)
	v_fmac_f32_e32 v46, v0, v134
	v_fmac_f32_e32 v46, v1, v135
	v_fmac_f32_e32 v46, v2, v136
	v_fmac_f32_e32 v46, v3, v137
	ds_read_b128 v[0:3], v7 offset:36816
	s_waitcnt lgkmcnt(0)
	v_fmac_f32_e32 v46, v133, v0
	v_fmac_f32_e32 v46, v130, v1
	v_fmac_f32_e32 v46, v131, v2
	v_fmac_f32_e32 v46, v132, v3
	ds_read_b128 v[0:3], v7 offset:36832
	s_waitcnt lgkmcnt(0)
	v_fmac_f32_e32 v46, v126, v0
	v_fmac_f32_e32 v46, v127, v1
	v_fmac_f32_e32 v46, v128, v2
	v_fmac_f32_e32 v46, v129, v3
	ds_read_b128 v[0:3], v7 offset:36848
	s_waitcnt lgkmcnt(0)
	v_fmac_f32_e32 v46, v47, v0
	v_fmac_f32_e32 v46, v76, v1
	v_fmac_f32_e32 v46, v124, v2
	v_fmac_f32_e32 v46, v125, v3
	v_mul_f32_e64 v1, |v46|, s3
	v_exp_f32_e32 v1, v1
	v_min_f32_e32 v0, 0, v46
	v_add_f32_e32 v1, 1.0, v1
	v_log_f32_e32 v1, v1
	s_nop 0
	v_fmac_f32_e32 v0, 0xbf317218, v1
	v_fmamk_f32 v76, v0, 0x3d800000, v87
	v_mad_i64_i32 v[0:1], s[4:5], s19, v61, v[8:9]
	global_load_ushort v150, v[0:1], off
	s_sub_i32 s4, s0, 62
	v_mad_i64_i32 v[124:125], s[4:5], s4, v61, v[8:9]
	s_sub_i32 s4, s0, 61
	s_nop 0
	v_mad_i64_i32 v[126:127], s[4:5], s4, v61, v[8:9]
	s_sub_i32 s4, s0, 60
	s_nop 0
	v_mad_i64_i32 v[128:129], s[4:5], s4, v61, v[8:9]
	s_sub_i32 s4, s0, 59
	s_nop 0
	v_mad_i64_i32 v[130:131], s[4:5], s4, v61, v[8:9]
	s_sub_i32 s4, s0, 58
	s_nop 0
	v_mad_i64_i32 v[132:133], s[4:5], s4, v61, v[8:9]
	s_sub_i32 s4, s0, 57
	s_nop 0
	v_mad_i64_i32 v[134:135], s[4:5], s4, v61, v[8:9]
	s_sub_i32 s4, s0, 56
	s_nop 0
	v_mad_i64_i32 v[136:137], s[4:5], s4, v61, v[8:9]
	s_sub_i32 s4, s0, 55
	s_nop 0
	v_mad_i64_i32 v[138:139], s[4:5], s4, v61, v[8:9]
	s_sub_i32 s4, s0, 54
	s_nop 0
	v_mad_i64_i32 v[140:141], s[4:5], s4, v61, v[8:9]
	s_sub_i32 s4, s0, 53
	s_nop 0
	v_mad_i64_i32 v[142:143], s[4:5], s4, v61, v[8:9]
	s_sub_i32 s4, s0, 52
	s_nop 0
	v_mad_i64_i32 v[144:145], s[4:5], s4, v61, v[8:9]
	s_sub_i32 s4, s0, 51
	s_nop 0
	v_mad_i64_i32 v[146:147], s[4:5], s4, v61, v[8:9]
	s_sub_i32 s4, s0, 50
	s_nop 0
	v_mad_i64_i32 v[148:149], s[4:5], s4, v61, v[8:9]
	s_sub_i32 s4, s0, 49
	s_nop 0
	v_mad_i64_i32 v[46:47], s[4:5], s4, v61, v[8:9]
	s_sub_i32 s4, s0, 48
	s_nop 0
	v_mad_i64_i32 v[2:3], s[4:5], s4, v61, v[8:9]
	s_sub_i32 s4, s0, 47
	s_ashr_i32 s19, s18, 31
	s_waitcnt vmcnt(0)
	v_lshlrev_b32_e32 v150, 16, v150
	v_mul_f32_e32 v150, 0x3db504f3, v150
	v_mul_f32_e32 v150, v151, v150
	global_load_ushort v151, v[0:1], off offset:1024
	v_cvt_pk_bf16_f32 v150, v150, s0
	s_waitcnt vmcnt(0)
	v_lshlrev_b32_e32 v151, 16, v151
	v_mul_f32_e32 v100, v100, v151
	global_load_ushort v151, v[124:125], off
	global_load_ushort v152, v[124:125], off offset:1024
	global_load_ushort v153, v[126:127], off
	global_load_ushort v154, v[126:127], off offset:1024
	global_load_ushort v155, v[128:129], off
	global_load_ushort v156, v[128:129], off offset:1024
	global_load_ushort v157, v[130:131], off
	global_load_ushort v158, v[130:131], off offset:1024
	global_load_ushort v159, v[132:133], off
	global_load_ushort v160, v[132:133], off offset:1024
	global_load_ushort v161, v[134:135], off
	global_load_ushort v162, v[134:135], off offset:1024
	global_load_ushort v163, v[136:137], off
	global_load_ushort v164, v[136:137], off offset:1024
	global_load_ushort v165, v[138:139], off
	global_load_ushort v166, v[138:139], off offset:1024
	global_load_ushort v167, v[140:141], off
	global_load_ushort v168, v[140:141], off offset:1024
	global_load_ushort v169, v[142:143], off
	global_load_ushort v170, v[142:143], off offset:1024
	global_load_ushort v171, v[144:145], off
	global_load_ushort v172, v[144:145], off offset:1024
	global_load_ushort v173, v[146:147], off
	global_load_ushort v174, v[146:147], off offset:1024
	global_load_ushort v175, v[148:149], off
	global_load_ushort v176, v[148:149], off offset:1024
	global_load_ushort v177, v[46:47], off
	global_load_ushort v178, v[46:47], off offset:1024
	global_load_ushort v179, v[2:3], off
	global_load_ushort v180, v[2:3], off offset:1024
	v_cvt_pk_bf16_f32 v100, v100, s0
	global_store_short v[0:1], v150, off
	global_store_short v[0:1], v100, off offset:1024
	v_sub_f32_e32 v1, v102, v48
	v_mul_f32_e32 v1, 0x3fb8aa3b, v1
	v_sub_f32_e32 v100, v48, v102
	v_exp_f32_e32 v1, v1
	v_mul_f32_e32 v100, 0x3fb8aa3b, v100
	v_exp_f32_e32 v100, v100
	v_sub_f32_e32 v102, v81, v48
	v_mul_f32_e32 v102, 0x3fb8aa3b, v102
	v_exp_f32_e32 v102, v102
	v_sub_f32_e32 v81, v48, v81
	v_mul_f32_e32 v81, 0x3fb8aa3b, v81
	v_exp_f32_e32 v81, v81
	s_waitcnt vmcnt(31)
	v_lshlrev_b32_e32 v0, 16, v151
	v_mul_f32_e32 v0, 0x3db504f3, v0
	v_mul_f32_e32 v0, v1, v0
	s_waitcnt vmcnt(30)
	v_lshlrev_b32_e32 v1, 16, v152
	v_mul_f32_e32 v1, v100, v1
	v_cvt_pk_bf16_f32 v0, v0, s0
	global_store_short v[124:125], v0, off
	v_cvt_pk_bf16_f32 v0, v1, s0
	v_sub_f32_e32 v1, v104, v48
	v_mul_f32_e32 v1, 0x3fb8aa3b, v1
	v_sub_f32_e32 v100, v48, v104
	v_exp_f32_e32 v1, v1
	v_mul_f32_e32 v100, 0x3fb8aa3b, v100
	v_exp_f32_e32 v100, v100
	global_store_short v[124:125], v0, off offset:1024
	s_waitcnt vmcnt(31)
	v_lshlrev_b32_e32 v0, 16, v153
	v_mul_f32_e32 v0, 0x3db504f3, v0
	v_mul_f32_e32 v0, v1, v0
	s_waitcnt vmcnt(30)
; __device__ __forceinline__ unsigned cvtpk(float lo, float hi) { f32x2 v = {lo, hi}; bf16x2_t b = __builtin_convertvector(v, bf16x2_t); return __builtin_bit_cast(unsigned, b); }
; __device__ __forceinline__ float fexp(float x) { return __builtin_amdgcn_exp2f(x * 1.44269504089f); }
; __device__ __forceinline__ void phase_qkrope_gla_prep(const Params& p, LAS unsigned char* lds, int wave, int lane) {
;     ...
;             for (int tb = 0; tb < 4; ++tb) {
;                 unsigned short qv[16], kv[16];
; #pragma unroll
;                 for (int t = 0; t < 16; ++t) { const size_t ro = (size_t)(m0 + 16 * tb + t) * ZP + d; qv[t] = Z[ro + C_QG]; kv[t] = Z[ro + C_KG]; }
; #pragma unroll
;                 for (int t = 0; t < 16; ++t) { const size_t ro = (size_t)(m0 + 16 * tb + t) * ZP + d; const float bb = bl[16 * tb + t];
;                     const float qs = bf2f(qv[t]) * 0.08838834764831845f * fexp(bb - bref), ks = bf2f(kv[t]) * fexp(bref - bb);
;                     Z[ro + C_QG] = (bf16_t)(cvtpk(qs, 0.f) & 0xffffu); Z[ro + C_KG] = (bf16_t)(cvtpk(ks, 0.f) & 0xffffu); }
	v_lshlrev_b32_e32 v1, 16, v154
	v_mul_f32_e32 v1, v100, v1
	v_cvt_pk_bf16_f32 v0, v0, s0
	global_store_short v[126:127], v0, off
	v_cvt_pk_bf16_f32 v0, v1, s0
	v_sub_f32_e32 v1, v107, v48
	v_mul_f32_e32 v1, 0x3fb8aa3b, v1
	v_sub_f32_e32 v100, v48, v107
	v_exp_f32_e32 v1, v1
	v_mul_f32_e32 v100, 0x3fb8aa3b, v100
	v_exp_f32_e32 v100, v100
	global_store_short v[126:127], v0, off offset:1024
	s_waitcnt vmcnt(31)
	v_lshlrev_b32_e32 v0, 16, v155
	v_mul_f32_e32 v0, 0x3db504f3, v0
	v_mul_f32_e32 v0, v1, v0
	s_waitcnt vmcnt(30)
	v_lshlrev_b32_e32 v1, 16, v156
	v_mul_f32_e32 v1, v100, v1
	v_cvt_pk_bf16_f32 v0, v0, s0
	global_store_short v[128:129], v0, off
	v_cvt_pk_bf16_f32 v0, v1, s0
	v_sub_f32_e32 v1, v109, v48
	v_mul_f32_e32 v1, 0x3fb8aa3b, v1
	v_sub_f32_e32 v100, v48, v109
	v_exp_f32_e32 v1, v1
	v_mul_f32_e32 v100, 0x3fb8aa3b, v100
	v_exp_f32_e32 v100, v100
	global_store_short v[128:129], v0, off offset:1024
	s_waitcnt vmcnt(31)
	v_lshlrev_b32_e32 v0, 16, v157
	v_mul_f32_e32 v0, 0x3db504f3, v0
	v_mul_f32_e32 v0, v1, v0
	s_waitcnt vmcnt(30)
	v_lshlrev_b32_e32 v1, 16, v158
	v_mul_f32_e32 v1, v100, v1
	v_cvt_pk_bf16_f32 v0, v0, s0
	global_store_short v[130:131], v0, off
	v_cvt_pk_bf16_f32 v0, v1, s0
	v_sub_f32_e32 v1, v111, v48
	v_mul_f32_e32 v1, 0x3fb8aa3b, v1
	v_sub_f32_e32 v100, v48, v111
	v_exp_f32_e32 v1, v1
	v_mul_f32_e32 v100, 0x3fb8aa3b, v100
	v_exp_f32_e32 v100, v100
	global_store_short v[130:131], v0, off offset:1024
	s_waitcnt vmcnt(31)
	v_lshlrev_b32_e32 v0, 16, v159
	v_mul_f32_e32 v0, 0x3db504f3, v0
	v_mul_f32_e32 v0, v1, v0
	s_waitcnt vmcnt(30)
	v_lshlrev_b32_e32 v1, 16, v160
	v_mul_f32_e32 v1, v100, v1
	v_cvt_pk_bf16_f32 v0, v0, s0
	global_store_short v[132:133], v0, off
	v_cvt_pk_bf16_f32 v0, v1, s0
	v_sub_f32_e32 v1, v112, v48
	v_mul_f32_e32 v1, 0x3fb8aa3b, v1
	v_sub_f32_e32 v100, v48, v112
	v_exp_f32_e32 v1, v1
	v_mul_f32_e32 v100, 0x3fb8aa3b, v100
	v_exp_f32_e32 v100, v100
	global_store_short v[132:133], v0, off offset:1024
	s_waitcnt vmcnt(31)
	v_lshlrev_b32_e32 v0, 16, v161
	v_mul_f32_e32 v0, 0x3db504f3, v0
	v_mul_f32_e32 v0, v1, v0
	s_waitcnt vmcnt(30)
	v_lshlrev_b32_e32 v1, 16, v162
	v_mul_f32_e32 v1, v100, v1
	v_cvt_pk_bf16_f32 v0, v0, s0
	global_store_short v[134:135], v0, off
	v_cvt_pk_bf16_f32 v0, v1, s0
	v_sub_f32_e32 v1, v114, v48
	v_mul_f32_e32 v1, 0x3fb8aa3b, v1
	v_sub_f32_e32 v100, v48, v114
	v_exp_f32_e32 v1, v1
	v_mul_f32_e32 v100, 0x3fb8aa3b, v100
	v_exp_f32_e32 v100, v100
	global_store_short v[134:135], v0, off offset:1024
	s_waitcnt vmcnt(31)
	v_lshlrev_b32_e32 v0, 16, v163
	v_mul_f32_e32 v0, 0x3db504f3, v0
	v_mul_f32_e32 v0, v1, v0
	s_waitcnt vmcnt(30)
	v_lshlrev_b32_e32 v1, 16, v164
	v_mul_f32_e32 v1, v100, v1
	v_cvt_pk_bf16_f32 v0, v0, s0
	global_store_short v[136:137], v0, off
	v_cvt_pk_bf16_f32 v0, v1, s0
	v_sub_f32_e32 v1, v116, v48
	v_mul_f32_e32 v1, 0x3fb8aa3b, v1
	v_sub_f32_e32 v100, v48, v116
	v_exp_f32_e32 v1, v1
	v_mul_f32_e32 v100, 0x3fb8aa3b, v100
	v_exp_f32_e32 v100, v100
	global_store_short v[136:137], v0, off offset:1024
	s_waitcnt vmcnt(31)
	v_lshlrev_b32_e32 v0, 16, v165
	v_mul_f32_e32 v0, 0x3db504f3, v0
	v_mul_f32_e32 v0, v1, v0
	s_waitcnt vmcnt(30)
	v_lshlrev_b32_e32 v1, 16, v166
	v_mul_f32_e32 v1, v100, v1
	v_cvt_pk_bf16_f32 v0, v0, s0
	global_store_short v[138:139], v0, off
	v_cvt_pk_bf16_f32 v0, v1, s0
	v_sub_f32_e32 v1, v117, v48
	v_mul_f32_e32 v1, 0x3fb8aa3b, v1
	v_sub_f32_e32 v100, v48, v117
	v_exp_f32_e32 v1, v1
	v_mul_f32_e32 v100, 0x3fb8aa3b, v100
	v_exp_f32_e32 v100, v100
	global_store_short v[138:139], v0, off offset:1024
	s_waitcnt vmcnt(31)
	v_lshlrev_b32_e32 v0, 16, v167
	v_mul_f32_e32 v0, 0x3db504f3, v0
	v_mul_f32_e32 v0, v1, v0
	s_waitcnt vmcnt(30)
	v_lshlrev_b32_e32 v1, 16, v168
	v_mul_f32_e32 v1, v100, v1
	v_cvt_pk_bf16_f32 v0, v0, s0
	global_store_short v[140:141], v0, off
	v_cvt_pk_bf16_f32 v0, v1, s0
	v_sub_f32_e32 v1, v118, v48
	v_mul_f32_e32 v1, 0x3fb8aa3b, v1
	v_sub_f32_e32 v100, v48, v118
	v_exp_f32_e32 v1, v1
	v_mul_f32_e32 v100, 0x3fb8aa3b, v100
	v_exp_f32_e32 v100, v100
	global_store_short v[140:141], v0, off offset:1024
	s_waitcnt vmcnt(31)
	v_lshlrev_b32_e32 v0, 16, v169
	v_mul_f32_e32 v0, 0x3db504f3, v0
	v_mul_f32_e32 v0, v1, v0
	s_waitcnt vmcnt(30)
	v_lshlrev_b32_e32 v1, 16, v170
	v_mul_f32_e32 v1, v100, v1
	v_cvt_pk_bf16_f32 v0, v0, s0
	global_store_short v[142:143], v0, off
	v_cvt_pk_bf16_f32 v0, v1, s0
	v_sub_f32_e32 v1, v119, v48
	v_mul_f32_e32 v1, 0x3fb8aa3b, v1
	v_sub_f32_e32 v100, v48, v119
	v_exp_f32_e32 v1, v1
	v_mul_f32_e32 v100, 0x3fb8aa3b, v100
	v_exp_f32_e32 v100, v100
	global_store_short v[142:143], v0, off offset:1024
	s_waitcnt vmcnt(31)
	v_lshlrev_b32_e32 v0, 16, v171
	v_mul_f32_e32 v0, 0x3db504f3, v0
	v_mul_f32_e32 v0, v1, v0
	s_waitcnt vmcnt(30)
	v_lshlrev_b32_e32 v1, 16, v172
	v_mul_f32_e32 v1, v100, v1
	v_cvt_pk_bf16_f32 v0, v0, s0
	global_store_short v[144:145], v0, off
	v_cvt_pk_bf16_f32 v0, v1, s0
	v_sub_f32_e32 v1, v120, v48
	v_mul_f32_e32 v1, 0x3fb8aa3b, v1
	v_sub_f32_e32 v100, v48, v120
	v_exp_f32_e32 v1, v1
	v_mul_f32_e32 v100, 0x3fb8aa3b, v100
	v_exp_f32_e32 v100, v100
	global_store_short v[144:145], v0, off offset:1024
	s_waitcnt vmcnt(31)
	v_lshlrev_b32_e32 v0, 16, v173
	v_mul_f32_e32 v0, 0x3db504f3, v0
	v_mul_f32_e32 v0, v1, v0
	s_waitcnt vmcnt(30)
	v_lshlrev_b32_e32 v1, 16, v174
	v_mul_f32_e32 v1, v100, v1
	v_cvt_pk_bf16_f32 v0, v0, s0
	global_store_short v[146:147], v0, off
	v_cvt_pk_bf16_f32 v0, v1, s0
	v_sub_f32_e32 v1, v121, v48
	v_mul_f32_e32 v1, 0x3fb8aa3b, v1
	v_sub_f32_e32 v100, v48, v121
	v_exp_f32_e32 v1, v1
	v_mul_f32_e32 v100, 0x3fb8aa3b, v100
	v_exp_f32_e32 v100, v100
	global_store_short v[146:147], v0, off offset:1024
	s_waitcnt vmcnt(31)
; __device__ __forceinline__ unsigned cvtpk(float lo, float hi) { f32x2 v = {lo, hi}; bf16x2_t b = __builtin_convertvector(v, bf16x2_t); return __builtin_bit_cast(unsigned, b); }
; __device__ __forceinline__ float fexp(float x) { return __builtin_amdgcn_exp2f(x * 1.44269504089f); }
; __device__ __forceinline__ void phase_qkrope_gla_prep(const Params& p, LAS unsigned char* lds, int wave, int lane) {
;     ...
;             for (int tb = 0; tb < 4; ++tb) {
;                 unsigned short qv[16], kv[16];
; #pragma unroll
;                 for (int t = 0; t < 16; ++t) { const size_t ro = (size_t)(m0 + 16 * tb + t) * ZP + d; qv[t] = Z[ro + C_QG]; kv[t] = Z[ro + C_KG]; }
; #pragma unroll
;                 for (int t = 0; t < 16; ++t) { const size_t ro = (size_t)(m0 + 16 * tb + t) * ZP + d; const float bb = bl[16 * tb + t];
;                     const float qs = bf2f(qv[t]) * 0.08838834764831845f * fexp(bb - bref), ks = bf2f(kv[t]) * fexp(bref - bb);
;                     Z[ro + C_QG] = (bf16_t)(cvtpk(qs, 0.f) & 0xffffu); Z[ro + C_KG] = (bf16_t)(cvtpk(ks, 0.f) & 0xffffu); }
	v_lshlrev_b32_e32 v0, 16, v175
	v_mul_f32_e32 v0, 0x3db504f3, v0
	v_mul_f32_e32 v0, v1, v0
	s_waitcnt vmcnt(30)
	v_lshlrev_b32_e32 v1, 16, v176
	v_mul_f32_e32 v1, v100, v1
	v_cvt_pk_bf16_f32 v0, v0, s0
	global_store_short v[148:149], v0, off
	v_cvt_pk_bf16_f32 v0, v1, s0
	v_sub_f32_e32 v1, v122, v48
	v_mul_f32_e32 v1, 0x3fb8aa3b, v1
	v_sub_f32_e32 v100, v48, v122
	v_exp_f32_e32 v1, v1
	v_mul_f32_e32 v100, 0x3fb8aa3b, v100
	v_exp_f32_e32 v100, v100
	global_store_short v[148:149], v0, off offset:1024
	s_waitcnt vmcnt(31)
	v_lshlrev_b32_e32 v0, 16, v177
	v_mul_f32_e32 v0, 0x3db504f3, v0
	v_mul_f32_e32 v0, v1, v0
	s_waitcnt vmcnt(30)
	v_lshlrev_b32_e32 v1, 16, v178
	v_mul_f32_e32 v1, v100, v1
	v_cvt_pk_bf16_f32 v0, v0, s0
	global_store_short v[46:47], v0, off
	v_cvt_pk_bf16_f32 v0, v1, s0
	v_sub_f32_e32 v1, v123, v48
	global_store_short v[46:47], v0, off offset:1024
	v_mul_f32_e32 v1, 0x3fb8aa3b, v1
	v_sub_f32_e32 v46, v48, v123
	v_exp_f32_e32 v1, v1
	v_mul_f32_e32 v46, 0x3fb8aa3b, v46
	v_exp_f32_e32 v46, v46
	s_waitcnt vmcnt(31)
	v_lshlrev_b32_e32 v0, 16, v179
	v_mul_f32_e32 v0, 0x3db504f3, v0
	v_mul_f32_e32 v0, v1, v0
	s_waitcnt vmcnt(30)
	v_lshlrev_b32_e32 v1, 16, v180
	v_mul_f32_e32 v1, v46, v1
	v_mad_i64_i32 v[46:47], s[4:5], s4, v61, v[8:9]
	global_load_ushort v100, v[46:47], off
	s_sub_i32 s4, s0, 46
	v_mad_i64_i32 v[116:117], s[4:5], s4, v61, v[8:9]
	s_sub_i32 s4, s0, 45
	s_nop 0
	v_mad_i64_i32 v[118:119], s[4:5], s4, v61, v[8:9]
	s_sub_i32 s4, s0, 44
	s_nop 0
	v_mad_i64_i32 v[120:121], s[4:5], s4, v61, v[8:9]
	s_sub_i32 s4, s0, 43
	s_nop 0
	v_mad_i64_i32 v[122:123], s[4:5], s4, v61, v[8:9]
	s_sub_i32 s4, s0, 42
	s_nop 0
	v_mad_i64_i32 v[124:125], s[4:5], s4, v61, v[8:9]
	s_sub_i32 s4, s0, 41
	s_nop 0
	v_mad_i64_i32 v[126:127], s[4:5], s4, v61, v[8:9]
	s_sub_i32 s4, s0, 40
	s_nop 0
	v_mad_i64_i32 v[128:129], s[4:5], s4, v61, v[8:9]
	s_sub_i32 s4, s0, 39
	s_nop 0
	v_mad_i64_i32 v[130:131], s[4:5], s4, v61, v[8:9]
	s_sub_i32 s4, s0, 38
	s_nop 0
	v_mad_i64_i32 v[132:133], s[4:5], s4, v61, v[8:9]
	s_sub_i32 s4, s0, 37
	s_nop 0
	v_mad_i64_i32 v[134:135], s[4:5], s4, v61, v[8:9]
	s_sub_i32 s4, s0, 36
	s_nop 0
	v_mad_i64_i32 v[136:137], s[4:5], s4, v61, v[8:9]
	s_sub_i32 s4, s0, 35
	s_nop 0
	v_mad_i64_i32 v[138:139], s[4:5], s4, v61, v[8:9]
	s_sub_i32 s4, s0, 34
	v_cvt_pk_bf16_f32 v0, v0, s0
	v_mad_i64_i32 v[140:141], s[4:5], s4, v61, v[8:9]
	global_store_short v[2:3], v0, off
	v_cvt_pk_bf16_f32 v0, v1, s0
	s_sub_i32 s4, s0, 33
	global_store_short v[2:3], v0, off offset:1024
	v_mad_i64_i32 v[2:3], s[4:5], s4, v61, v[8:9]
	s_sub_i32 s4, s0, 32
	s_nop 0
	v_mad_i64_i32 v[0:1], s[4:5], s4, v61, v[8:9]
	s_sub_i32 s4, s0, 31
	s_waitcnt vmcnt(2)
	v_lshlrev_b32_e32 v100, 16, v100
	v_mul_f32_e32 v100, 0x3db504f3, v100
	v_mul_f32_e32 v100, v102, v100
	global_load_ushort v102, v[46:47], off offset:1024
	v_cvt_pk_bf16_f32 v100, v100, s0
	s_waitcnt vmcnt(0)
	v_lshlrev_b32_e32 v102, 16, v102
	v_mul_f32_e32 v81, v81, v102
	global_load_ushort v102, v[116:117], off
	global_load_ushort v104, v[116:117], off offset:1024
	global_load_ushort v107, v[118:119], off
	global_load_ushort v109, v[118:119], off offset:1024
	global_load_ushort v111, v[120:121], off
	global_load_ushort v112, v[120:121], off offset:1024
	global_load_ushort v114, v[122:123], off
	global_load_ushort v142, v[122:123], off offset:1024
	global_load_ushort v143, v[124:125], off
	global_load_ushort v144, v[124:125], off offset:1024
	global_load_ushort v145, v[126:127], off
	global_load_ushort v146, v[126:127], off offset:1024
	global_load_ushort v147, v[128:129], off
	global_load_ushort v148, v[128:129], off offset:1024
	global_load_ushort v149, v[130:131], off
	global_load_ushort v150, v[130:131], off offset:1024
	global_load_ushort v151, v[132:133], off
	global_load_ushort v152, v[132:133], off offset:1024
	global_load_ushort v153, v[134:135], off
	global_load_ushort v154, v[134:135], off offset:1024
	global_load_ushort v155, v[136:137], off
	global_load_ushort v156, v[136:137], off offset:1024
	global_load_ushort v157, v[138:139], off
	global_load_ushort v158, v[138:139], off offset:1024
	global_load_ushort v159, v[140:141], off
	global_load_ushort v160, v[140:141], off offset:1024
	global_load_ushort v161, v[2:3], off
	global_load_ushort v162, v[2:3], off offset:1024
	global_load_ushort v163, v[0:1], off
	global_load_ushort v164, v[0:1], off offset:1024
	v_cvt_pk_bf16_f32 v81, v81, s0
	global_store_short v[46:47], v100, off
	global_store_short v[46:47], v81, off offset:1024
	v_sub_f32_e32 v47, v82, v48
	v_mul_f32_e32 v47, 0x3fb8aa3b, v47
	v_sub_f32_e32 v81, v48, v82
	v_exp_f32_e32 v47, v47
	v_mul_f32_e32 v81, 0x3fb8aa3b, v81
	v_exp_f32_e32 v81, v81
	v_sub_f32_e32 v82, v68, v48
	v_mul_f32_e32 v82, 0x3fb8aa3b, v82
	v_exp_f32_e32 v82, v82
	v_sub_f32_e32 v68, v48, v68
	v_mul_f32_e32 v68, 0x3fb8aa3b, v68
	v_exp_f32_e32 v68, v68
	s_waitcnt vmcnt(31)
	v_lshlrev_b32_e32 v46, 16, v102
	v_mul_f32_e32 v46, 0x3db504f3, v46
	v_mul_f32_e32 v46, v47, v46
	s_waitcnt vmcnt(30)
	v_lshlrev_b32_e32 v47, 16, v104
	v_mul_f32_e32 v47, v81, v47
	v_cvt_pk_bf16_f32 v46, v46, s0
	global_store_short v[116:117], v46, off
	v_cvt_pk_bf16_f32 v46, v47, s0
	v_sub_f32_e32 v47, v85, v48
	v_mul_f32_e32 v47, 0x3fb8aa3b, v47
	v_sub_f32_e32 v81, v48, v85
	v_exp_f32_e32 v47, v47
	v_mul_f32_e32 v81, 0x3fb8aa3b, v81
	v_exp_f32_e32 v81, v81
	global_store_short v[116:117], v46, off offset:1024
	s_waitcnt vmcnt(31)
	v_lshlrev_b32_e32 v46, 16, v107
	v_mul_f32_e32 v46, 0x3db504f3, v46
	v_mul_f32_e32 v46, v47, v46
	s_waitcnt vmcnt(30)
; __device__ __forceinline__ unsigned cvtpk(float lo, float hi) { f32x2 v = {lo, hi}; bf16x2_t b = __builtin_convertvector(v, bf16x2_t); return __builtin_bit_cast(unsigned, b); }
; __device__ __forceinline__ float fexp(float x) { return __builtin_amdgcn_exp2f(x * 1.44269504089f); }
; __device__ __forceinline__ void phase_qkrope_gla_prep(const Params& p, LAS unsigned char* lds, int wave, int lane) {
;     ...
;             for (int tb = 0; tb < 4; ++tb) {
;                 unsigned short qv[16], kv[16];
; #pragma unroll
;                 for (int t = 0; t < 16; ++t) { const size_t ro = (size_t)(m0 + 16 * tb + t) * ZP + d; qv[t] = Z[ro + C_QG]; kv[t] = Z[ro + C_KG]; }
; #pragma unroll
;                 for (int t = 0; t < 16; ++t) { const size_t ro = (size_t)(m0 + 16 * tb + t) * ZP + d; const float bb = bl[16 * tb + t];
;                     const float qs = bf2f(qv[t]) * 0.08838834764831845f * fexp(bb - bref), ks = bf2f(kv[t]) * fexp(bref - bb);
;                     Z[ro + C_QG] = (bf16_t)(cvtpk(qs, 0.f) & 0xffffu); Z[ro + C_KG] = (bf16_t)(cvtpk(ks, 0.f) & 0xffffu); }
	v_lshlrev_b32_e32 v47, 16, v109
	v_mul_f32_e32 v47, v81, v47
	v_cvt_pk_bf16_f32 v46, v46, s0
	global_store_short v[118:119], v46, off
	v_cvt_pk_bf16_f32 v46, v47, s0
	v_sub_f32_e32 v47, v88, v48
	v_mul_f32_e32 v47, 0x3fb8aa3b, v47
	v_sub_f32_e32 v81, v48, v88
	v_exp_f32_e32 v47, v47
	v_mul_f32_e32 v81, 0x3fb8aa3b, v81
	v_exp_f32_e32 v81, v81
	global_store_short v[118:119], v46, off offset:1024
	s_waitcnt vmcnt(31)
	v_lshlrev_b32_e32 v46, 16, v111
	v_mul_f32_e32 v46, 0x3db504f3, v46
	v_mul_f32_e32 v46, v47, v46
	s_waitcnt vmcnt(30)
	v_lshlrev_b32_e32 v47, 16, v112
	v_mul_f32_e32 v47, v81, v47
	v_cvt_pk_bf16_f32 v46, v46, s0
	global_store_short v[120:121], v46, off
	v_cvt_pk_bf16_f32 v46, v47, s0
	v_sub_f32_e32 v47, v90, v48
	v_mul_f32_e32 v47, 0x3fb8aa3b, v47
	v_sub_f32_e32 v81, v48, v90
	v_exp_f32_e32 v47, v47
	v_mul_f32_e32 v81, 0x3fb8aa3b, v81
	v_exp_f32_e32 v81, v81
	global_store_short v[120:121], v46, off offset:1024
	s_waitcnt vmcnt(31)
	v_lshlrev_b32_e32 v46, 16, v114
	v_mul_f32_e32 v46, 0x3db504f3, v46
	v_mul_f32_e32 v46, v47, v46
	s_waitcnt vmcnt(30)
	v_lshlrev_b32_e32 v47, 16, v142
	v_mul_f32_e32 v47, v81, v47
	v_cvt_pk_bf16_f32 v46, v46, s0
	global_store_short v[122:123], v46, off
	v_cvt_pk_bf16_f32 v46, v47, s0
	v_sub_f32_e32 v47, v92, v48
	v_mul_f32_e32 v47, 0x3fb8aa3b, v47
	v_sub_f32_e32 v81, v48, v92
	v_exp_f32_e32 v47, v47
	v_mul_f32_e32 v81, 0x3fb8aa3b, v81
	v_exp_f32_e32 v81, v81
	global_store_short v[122:123], v46, off offset:1024
	s_waitcnt vmcnt(31)
	v_lshlrev_b32_e32 v46, 16, v143
	v_mul_f32_e32 v46, 0x3db504f3, v46
	v_mul_f32_e32 v46, v47, v46
	s_waitcnt vmcnt(30)
	v_lshlrev_b32_e32 v47, 16, v144
	v_mul_f32_e32 v47, v81, v47
	v_cvt_pk_bf16_f32 v46, v46, s0
	global_store_short v[124:125], v46, off
	v_cvt_pk_bf16_f32 v46, v47, s0
	v_sub_f32_e32 v47, v94, v48
	v_mul_f32_e32 v47, 0x3fb8aa3b, v47
	v_sub_f32_e32 v81, v48, v94
	v_exp_f32_e32 v47, v47
	v_mul_f32_e32 v81, 0x3fb8aa3b, v81
	v_exp_f32_e32 v81, v81
	global_store_short v[124:125], v46, off offset:1024
	s_waitcnt vmcnt(31)
	v_lshlrev_b32_e32 v46, 16, v145
	v_mul_f32_e32 v46, 0x3db504f3, v46
	v_mul_f32_e32 v46, v47, v46
	s_waitcnt vmcnt(30)
	v_lshlrev_b32_e32 v47, 16, v146
	v_mul_f32_e32 v47, v81, v47
	v_cvt_pk_bf16_f32 v46, v46, s0
	global_store_short v[126:127], v46, off
	v_cvt_pk_bf16_f32 v46, v47, s0
	v_sub_f32_e32 v47, v96, v48
	v_mul_f32_e32 v47, 0x3fb8aa3b, v47
	v_sub_f32_e32 v81, v48, v96
	v_exp_f32_e32 v47, v47
	v_mul_f32_e32 v81, 0x3fb8aa3b, v81
	v_exp_f32_e32 v81, v81
	global_store_short v[126:127], v46, off offset:1024
	s_waitcnt vmcnt(31)
	v_lshlrev_b32_e32 v46, 16, v147
	v_mul_f32_e32 v46, 0x3db504f3, v46
	v_mul_f32_e32 v46, v47, v46
	s_waitcnt vmcnt(30)
	v_lshlrev_b32_e32 v47, 16, v148
	v_mul_f32_e32 v47, v81, v47
	v_cvt_pk_bf16_f32 v46, v46, s0
	global_store_short v[128:129], v46, off
	v_cvt_pk_bf16_f32 v46, v47, s0
	v_sub_f32_e32 v47, v98, v48
	v_mul_f32_e32 v47, 0x3fb8aa3b, v47
	v_sub_f32_e32 v81, v48, v98
	v_exp_f32_e32 v47, v47
	v_mul_f32_e32 v81, 0x3fb8aa3b, v81
	v_exp_f32_e32 v81, v81
	global_store_short v[128:129], v46, off offset:1024
	s_waitcnt vmcnt(31)
	v_lshlrev_b32_e32 v46, 16, v149
	v_mul_f32_e32 v46, 0x3db504f3, v46
	v_mul_f32_e32 v46, v47, v46
	s_waitcnt vmcnt(30)
	v_lshlrev_b32_e32 v47, 16, v150
	v_mul_f32_e32 v47, v81, v47
	v_cvt_pk_bf16_f32 v46, v46, s0
	global_store_short v[130:131], v46, off
	v_cvt_pk_bf16_f32 v46, v47, s0
	v_sub_f32_e32 v47, v101, v48
	v_mul_f32_e32 v47, 0x3fb8aa3b, v47
	v_sub_f32_e32 v81, v48, v101
	v_exp_f32_e32 v47, v47
	v_mul_f32_e32 v81, 0x3fb8aa3b, v81
	v_exp_f32_e32 v81, v81
	global_store_short v[130:131], v46, off offset:1024
	s_waitcnt vmcnt(31)
	v_lshlrev_b32_e32 v46, 16, v151
	v_mul_f32_e32 v46, 0x3db504f3, v46
	v_mul_f32_e32 v46, v47, v46
	s_waitcnt vmcnt(30)
	v_lshlrev_b32_e32 v47, 16, v152
	v_mul_f32_e32 v47, v81, v47
	v_cvt_pk_bf16_f32 v46, v46, s0
	global_store_short v[132:133], v46, off
	v_cvt_pk_bf16_f32 v46, v47, s0
	v_sub_f32_e32 v47, v105, v48
	v_mul_f32_e32 v47, 0x3fb8aa3b, v47
	v_sub_f32_e32 v81, v48, v105
	v_exp_f32_e32 v47, v47
	v_mul_f32_e32 v81, 0x3fb8aa3b, v81
	v_exp_f32_e32 v81, v81
	global_store_short v[132:133], v46, off offset:1024
	s_waitcnt vmcnt(31)
	v_lshlrev_b32_e32 v46, 16, v153
	v_mul_f32_e32 v46, 0x3db504f3, v46
	v_mul_f32_e32 v46, v47, v46
	s_waitcnt vmcnt(30)
	v_lshlrev_b32_e32 v47, 16, v154
	v_mul_f32_e32 v47, v81, v47
	v_cvt_pk_bf16_f32 v46, v46, s0
	global_store_short v[134:135], v46, off
	v_cvt_pk_bf16_f32 v46, v47, s0
	v_sub_f32_e32 v47, v108, v48
	v_mul_f32_e32 v47, 0x3fb8aa3b, v47
	v_sub_f32_e32 v81, v48, v108
	v_exp_f32_e32 v47, v47
	v_mul_f32_e32 v81, 0x3fb8aa3b, v81
	v_exp_f32_e32 v81, v81
	global_store_short v[134:135], v46, off offset:1024
	s_waitcnt vmcnt(31)
	v_lshlrev_b32_e32 v46, 16, v155
	v_mul_f32_e32 v46, 0x3db504f3, v46
	v_mul_f32_e32 v46, v47, v46
	s_waitcnt vmcnt(30)
	v_lshlrev_b32_e32 v47, 16, v156
	v_mul_f32_e32 v47, v81, v47
	v_cvt_pk_bf16_f32 v46, v46, s0
	global_store_short v[136:137], v46, off
	v_cvt_pk_bf16_f32 v46, v47, s0
	v_sub_f32_e32 v47, v110, v48
	v_mul_f32_e32 v47, 0x3fb8aa3b, v47
	v_sub_f32_e32 v81, v48, v110
	v_exp_f32_e32 v47, v47
	v_mul_f32_e32 v81, 0x3fb8aa3b, v81
	v_exp_f32_e32 v81, v81
	global_store_short v[136:137], v46, off offset:1024
	s_waitcnt vmcnt(31)
	v_lshlrev_b32_e32 v46, 16, v157
	v_mul_f32_e32 v46, 0x3db504f3, v46
	v_mul_f32_e32 v46, v47, v46
	s_waitcnt vmcnt(30)
	v_lshlrev_b32_e32 v47, 16, v158
	v_mul_f32_e32 v47, v81, v47
	v_cvt_pk_bf16_f32 v46, v46, s0
	global_store_short v[138:139], v46, off
	v_cvt_pk_bf16_f32 v46, v47, s0
	v_sub_f32_e32 v47, v113, v48
	v_mul_f32_e32 v47, 0x3fb8aa3b, v47
	v_sub_f32_e32 v81, v48, v113
	v_exp_f32_e32 v47, v47
	v_mul_f32_e32 v81, 0x3fb8aa3b, v81
	v_exp_f32_e32 v81, v81
	global_store_short v[138:139], v46, off offset:1024
	s_waitcnt vmcnt(31)
; __device__ __forceinline__ unsigned cvtpk(float lo, float hi) { f32x2 v = {lo, hi}; bf16x2_t b = __builtin_convertvector(v, bf16x2_t); return __builtin_bit_cast(unsigned, b); }
; __device__ __forceinline__ float fexp(float x) { return __builtin_amdgcn_exp2f(x * 1.44269504089f); }
; __device__ __forceinline__ void phase_qkrope_gla_prep(const Params& p, LAS unsigned char* lds, int wave, int lane) {
;     ...
;             for (int tb = 0; tb < 4; ++tb) {
;                 unsigned short qv[16], kv[16];
; #pragma unroll
;                 for (int t = 0; t < 16; ++t) { const size_t ro = (size_t)(m0 + 16 * tb + t) * ZP + d; qv[t] = Z[ro + C_QG]; kv[t] = Z[ro + C_KG]; }
; #pragma unroll
;                 for (int t = 0; t < 16; ++t) { const size_t ro = (size_t)(m0 + 16 * tb + t) * ZP + d; const float bb = bl[16 * tb + t];
;                     const float qs = bf2f(qv[t]) * 0.08838834764831845f * fexp(bb - bref), ks = bf2f(kv[t]) * fexp(bref - bb);
;                     Z[ro + C_QG] = (bf16_t)(cvtpk(qs, 0.f) & 0xffffu); Z[ro + C_KG] = (bf16_t)(cvtpk(ks, 0.f) & 0xffffu); }
	v_lshlrev_b32_e32 v46, 16, v159
	v_mul_f32_e32 v46, 0x3db504f3, v46
	v_mul_f32_e32 v46, v47, v46
	s_waitcnt vmcnt(30)
	v_lshlrev_b32_e32 v47, 16, v160
	v_mul_f32_e32 v47, v81, v47
	v_cvt_pk_bf16_f32 v46, v46, s0
	global_store_short v[140:141], v46, off
	v_cvt_pk_bf16_f32 v46, v47, s0
	v_sub_f32_e32 v47, v115, v48
	v_mul_f32_e32 v47, 0x3fb8aa3b, v47
	v_sub_f32_e32 v81, v48, v115
	v_exp_f32_e32 v47, v47
	v_mul_f32_e32 v81, 0x3fb8aa3b, v81
	v_exp_f32_e32 v81, v81
	global_store_short v[140:141], v46, off offset:1024
	s_waitcnt vmcnt(31)
	v_lshlrev_b32_e32 v46, 16, v161
	v_mul_f32_e32 v46, 0x3db504f3, v46
	v_mul_f32_e32 v46, v47, v46
	s_waitcnt vmcnt(30)
	v_lshlrev_b32_e32 v47, 16, v162
	v_mul_f32_e32 v47, v81, v47
	v_cvt_pk_bf16_f32 v46, v46, s0
	global_store_short v[2:3], v46, off
	v_cvt_pk_bf16_f32 v46, v47, s0
	global_store_short v[2:3], v46, off offset:1024
	v_sub_f32_e32 v3, v48, v48
	v_mul_f32_e32 v3, 0x3fb8aa3b, v3
	v_exp_f32_e32 v3, v3
	s_waitcnt vmcnt(31)
	v_lshlrev_b32_e32 v2, 16, v163
	v_mul_f32_e32 v2, 0x3db504f3, v2
	s_waitcnt vmcnt(30)
	v_lshlrev_b32_e32 v46, 16, v164
	v_mul_f32_e32 v2, v3, v2
	v_mul_f32_e32 v3, v3, v46
	v_mad_i64_i32 v[46:47], s[4:5], s4, v61, v[8:9]
	global_load_ushort v81, v[46:47], off
	s_sub_i32 s4, s0, 30
	v_mad_i64_i32 v[100:101], s[4:5], s4, v61, v[8:9]
	s_sub_i32 s4, s0, 29
	s_nop 0
	v_mad_i64_i32 v[104:105], s[4:5], s4, v61, v[8:9]
	s_sub_i32 s4, s0, 28
	s_nop 0
	v_mad_i64_i32 v[108:109], s[4:5], s4, v61, v[8:9]
	s_sub_i32 s4, s0, 27
	s_nop 0
	v_mad_i64_i32 v[110:111], s[4:5], s4, v61, v[8:9]
	s_sub_i32 s4, s0, 26
	s_nop 0
	v_mad_i64_i32 v[112:113], s[4:5], s4, v61, v[8:9]
	s_sub_i32 s4, s0, 25
	s_nop 0
	v_mad_i64_i32 v[114:115], s[4:5], s4, v61, v[8:9]
	s_sub_i32 s4, s0, 24
	s_nop 0
	v_mad_i64_i32 v[116:117], s[4:5], s4, v61, v[8:9]
	s_sub_i32 s4, s0, 23
	s_nop 0
	v_mad_i64_i32 v[118:119], s[4:5], s4, v61, v[8:9]
	s_sub_i32 s4, s0, 22
	s_nop 0
	v_mad_i64_i32 v[120:121], s[4:5], s4, v61, v[8:9]
	s_sub_i32 s4, s0, 21
	s_nop 0
	v_mad_i64_i32 v[122:123], s[4:5], s4, v61, v[8:9]
	s_sub_i32 s4, s0, 20
	s_nop 0
	v_mad_i64_i32 v[124:125], s[4:5], s4, v61, v[8:9]
	s_sub_i32 s4, s0, 19
	s_nop 0
	v_mad_i64_i32 v[126:127], s[4:5], s4, v61, v[8:9]
	s_sub_i32 s4, s0, 18
	v_cvt_pk_bf16_f32 v2, v2, s0
	v_mad_i64_i32 v[128:129], s[4:5], s4, v61, v[8:9]
	global_store_short v[0:1], v2, off
	v_cvt_pk_bf16_f32 v2, v3, s0
	s_sub_i32 s4, s0, 17
	global_store_short v[0:1], v2, off offset:1024
	v_mad_i64_i32 v[2:3], s[4:5], s4, v61, v[8:9]
	s_add_i32 s4, s0, -16
	s_nop 0
	v_mad_i64_i32 v[0:1], s[4:5], s4, v61, v[8:9]
	s_add_i32 s4, s0, -15
	s_waitcnt vmcnt(2)
	v_lshlrev_b32_e32 v81, 16, v81
	v_mul_f32_e32 v81, 0x3db504f3, v81
	v_mul_f32_e32 v81, v82, v81
	global_load_ushort v82, v[46:47], off offset:1024
	v_cvt_pk_bf16_f32 v81, v81, s0
	s_waitcnt vmcnt(0)
	v_lshlrev_b32_e32 v82, 16, v82
	v_mul_f32_e32 v68, v68, v82
	global_load_ushort v82, v[100:101], off
	global_load_ushort v85, v[100:101], off offset:1024
	global_load_ushort v88, v[104:105], off
	global_load_ushort v90, v[104:105], off offset:1024
	global_load_ushort v92, v[108:109], off
	global_load_ushort v94, v[108:109], off offset:1024
	global_load_ushort v96, v[110:111], off
	global_load_ushort v98, v[110:111], off offset:1024
	global_load_ushort v102, v[112:113], off
	global_load_ushort v107, v[112:113], off offset:1024
	global_load_ushort v130, v[114:115], off
	global_load_ushort v131, v[114:115], off offset:1024
	global_load_ushort v132, v[116:117], off
	global_load_ushort v133, v[116:117], off offset:1024
	global_load_ushort v134, v[118:119], off
	global_load_ushort v135, v[118:119], off offset:1024
	global_load_ushort v136, v[120:121], off
	global_load_ushort v137, v[120:121], off offset:1024
	global_load_ushort v138, v[122:123], off
	global_load_ushort v139, v[122:123], off offset:1024
	global_load_ushort v140, v[124:125], off
	global_load_ushort v141, v[124:125], off offset:1024
	global_load_ushort v142, v[126:127], off
	global_load_ushort v143, v[126:127], off offset:1024
	global_load_ushort v144, v[128:129], off
	global_load_ushort v145, v[128:129], off offset:1024
	global_load_ushort v146, v[2:3], off
	global_load_ushort v147, v[2:3], off offset:1024
	global_load_ushort v148, v[0:1], off
	global_load_ushort v149, v[0:1], off offset:1024
	v_cvt_pk_bf16_f32 v68, v68, s0
	global_store_short v[46:47], v81, off
	global_store_short v[46:47], v68, off offset:1024
	v_sub_f32_e32 v47, v70, v48
	v_mul_f32_e32 v47, 0x3fb8aa3b, v47
	v_sub_f32_e32 v68, v48, v70
	v_exp_f32_e32 v47, v47
	v_mul_f32_e32 v68, 0x3fb8aa3b, v68
	v_exp_f32_e32 v68, v68
	v_sub_f32_e32 v70, v49, v48
	v_mul_f32_e32 v70, 0x3fb8aa3b, v70
	v_exp_f32_e32 v70, v70
	v_sub_f32_e32 v49, v48, v49
	v_mul_f32_e32 v49, 0x3fb8aa3b, v49
	v_exp_f32_e32 v49, v49
	s_waitcnt vmcnt(31)
	v_lshlrev_b32_e32 v46, 16, v82
	v_mul_f32_e32 v46, 0x3db504f3, v46
	v_mul_f32_e32 v46, v47, v46
	s_waitcnt vmcnt(30)
	v_lshlrev_b32_e32 v47, 16, v85
	v_mul_f32_e32 v47, v68, v47
	v_cvt_pk_bf16_f32 v46, v46, s0
	global_store_short v[100:101], v46, off
	v_cvt_pk_bf16_f32 v46, v47, s0
	v_sub_f32_e32 v47, v72, v48
	v_mul_f32_e32 v47, 0x3fb8aa3b, v47
	v_sub_f32_e32 v68, v48, v72
	v_exp_f32_e32 v47, v47
	v_mul_f32_e32 v68, 0x3fb8aa3b, v68
	v_exp_f32_e32 v68, v68
	global_store_short v[100:101], v46, off offset:1024
	s_waitcnt vmcnt(31)
	v_lshlrev_b32_e32 v46, 16, v88
	v_mul_f32_e32 v46, 0x3db504f3, v46
	v_mul_f32_e32 v46, v47, v46
	s_waitcnt vmcnt(30)
; __device__ __forceinline__ unsigned cvtpk(float lo, float hi) { f32x2 v = {lo, hi}; bf16x2_t b = __builtin_convertvector(v, bf16x2_t); return __builtin_bit_cast(unsigned, b); }
; __device__ __forceinline__ float fexp(float x) { return __builtin_amdgcn_exp2f(x * 1.44269504089f); }
; __device__ __forceinline__ void phase_qkrope_gla_prep(const Params& p, LAS unsigned char* lds, int wave, int lane) {
;     ...
;             for (int tb = 0; tb < 4; ++tb) {
;                 unsigned short qv[16], kv[16];
; #pragma unroll
;                 for (int t = 0; t < 16; ++t) { const size_t ro = (size_t)(m0 + 16 * tb + t) * ZP + d; qv[t] = Z[ro + C_QG]; kv[t] = Z[ro + C_KG]; }
; #pragma unroll
;                 for (int t = 0; t < 16; ++t) { const size_t ro = (size_t)(m0 + 16 * tb + t) * ZP + d; const float bb = bl[16 * tb + t];
;                     const float qs = bf2f(qv[t]) * 0.08838834764831845f * fexp(bb - bref), ks = bf2f(kv[t]) * fexp(bref - bb);
;                     Z[ro + C_QG] = (bf16_t)(cvtpk(qs, 0.f) & 0xffffu); Z[ro + C_KG] = (bf16_t)(cvtpk(ks, 0.f) & 0xffffu); }
	v_lshlrev_b32_e32 v47, 16, v90
	v_mul_f32_e32 v47, v68, v47
	v_cvt_pk_bf16_f32 v46, v46, s0
	global_store_short v[104:105], v46, off
	v_cvt_pk_bf16_f32 v46, v47, s0
	v_sub_f32_e32 v47, v74, v48
	v_mul_f32_e32 v47, 0x3fb8aa3b, v47
	v_sub_f32_e32 v68, v48, v74
	v_exp_f32_e32 v47, v47
	v_mul_f32_e32 v68, 0x3fb8aa3b, v68
	v_exp_f32_e32 v68, v68
	global_store_short v[104:105], v46, off offset:1024
	s_waitcnt vmcnt(31)
	v_lshlrev_b32_e32 v46, 16, v92
	v_mul_f32_e32 v46, 0x3db504f3, v46
	v_mul_f32_e32 v46, v47, v46
	s_waitcnt vmcnt(30)
	v_lshlrev_b32_e32 v47, 16, v94
	v_mul_f32_e32 v47, v68, v47
	v_cvt_pk_bf16_f32 v46, v46, s0
	global_store_short v[108:109], v46, off
	v_cvt_pk_bf16_f32 v46, v47, s0
	v_sub_f32_e32 v47, v77, v48
	v_mul_f32_e32 v47, 0x3fb8aa3b, v47
	v_sub_f32_e32 v68, v48, v77
	v_exp_f32_e32 v47, v47
	v_mul_f32_e32 v68, 0x3fb8aa3b, v68
	v_exp_f32_e32 v68, v68
	global_store_short v[108:109], v46, off offset:1024
	s_waitcnt vmcnt(31)
	v_lshlrev_b32_e32 v46, 16, v96
	v_mul_f32_e32 v46, 0x3db504f3, v46
	v_mul_f32_e32 v46, v47, v46
	s_waitcnt vmcnt(30)
	v_lshlrev_b32_e32 v47, 16, v98
	v_mul_f32_e32 v47, v68, v47
	v_cvt_pk_bf16_f32 v46, v46, s0
	global_store_short v[110:111], v46, off
	v_cvt_pk_bf16_f32 v46, v47, s0
	v_sub_f32_e32 v47, v79, v48
	v_mul_f32_e32 v47, 0x3fb8aa3b, v47
	v_sub_f32_e32 v68, v48, v79
	v_exp_f32_e32 v47, v47
	v_mul_f32_e32 v68, 0x3fb8aa3b, v68
	v_exp_f32_e32 v68, v68
	global_store_short v[110:111], v46, off offset:1024
	s_waitcnt vmcnt(31)
	v_lshlrev_b32_e32 v46, 16, v102
	v_mul_f32_e32 v46, 0x3db504f3, v46
	v_mul_f32_e32 v46, v47, v46
	s_waitcnt vmcnt(30)
	v_lshlrev_b32_e32 v47, 16, v107
	v_mul_f32_e32 v47, v68, v47
	v_cvt_pk_bf16_f32 v46, v46, s0
	global_store_short v[112:113], v46, off
	v_cvt_pk_bf16_f32 v46, v47, s0
	v_sub_f32_e32 v47, v83, v48
	v_mul_f32_e32 v47, 0x3fb8aa3b, v47
	v_sub_f32_e32 v68, v48, v83
	v_exp_f32_e32 v47, v47
	v_mul_f32_e32 v68, 0x3fb8aa3b, v68
	v_exp_f32_e32 v68, v68
	global_store_short v[112:113], v46, off offset:1024
	s_waitcnt vmcnt(31)
	v_lshlrev_b32_e32 v46, 16, v130
	v_mul_f32_e32 v46, 0x3db504f3, v46
	v_mul_f32_e32 v46, v47, v46
	s_waitcnt vmcnt(30)
	v_lshlrev_b32_e32 v47, 16, v131
	v_mul_f32_e32 v47, v68, v47
	v_cvt_pk_bf16_f32 v46, v46, s0
	global_store_short v[114:115], v46, off
	v_cvt_pk_bf16_f32 v46, v47, s0
	v_sub_f32_e32 v47, v86, v48
	v_mul_f32_e32 v47, 0x3fb8aa3b, v47
	v_sub_f32_e32 v68, v48, v86
	v_exp_f32_e32 v47, v47
	v_mul_f32_e32 v68, 0x3fb8aa3b, v68
	v_exp_f32_e32 v68, v68
	global_store_short v[114:115], v46, off offset:1024
	s_waitcnt vmcnt(31)
	v_lshlrev_b32_e32 v46, 16, v132
	v_mul_f32_e32 v46, 0x3db504f3, v46
	v_mul_f32_e32 v46, v47, v46
	s_waitcnt vmcnt(30)
	v_lshlrev_b32_e32 v47, 16, v133
	v_mul_f32_e32 v47, v68, v47
	v_cvt_pk_bf16_f32 v46, v46, s0
	global_store_short v[116:117], v46, off
	v_cvt_pk_bf16_f32 v46, v47, s0
	v_sub_f32_e32 v47, v89, v48
	v_mul_f32_e32 v47, 0x3fb8aa3b, v47
	v_sub_f32_e32 v68, v48, v89
	v_exp_f32_e32 v47, v47
	v_mul_f32_e32 v68, 0x3fb8aa3b, v68
	v_exp_f32_e32 v68, v68
	global_store_short v[116:117], v46, off offset:1024
	s_waitcnt vmcnt(31)
	v_lshlrev_b32_e32 v46, 16, v134
	v_mul_f32_e32 v46, 0x3db504f3, v46
	v_mul_f32_e32 v46, v47, v46
	s_waitcnt vmcnt(30)
	v_lshlrev_b32_e32 v47, 16, v135
	v_mul_f32_e32 v47, v68, v47
	v_cvt_pk_bf16_f32 v46, v46, s0
	global_store_short v[118:119], v46, off
	v_cvt_pk_bf16_f32 v46, v47, s0
	v_sub_f32_e32 v47, v91, v48
	v_mul_f32_e32 v47, 0x3fb8aa3b, v47
	v_sub_f32_e32 v68, v48, v91
	v_exp_f32_e32 v47, v47
	v_mul_f32_e32 v68, 0x3fb8aa3b, v68
	v_exp_f32_e32 v68, v68
	global_store_short v[118:119], v46, off offset:1024
	s_waitcnt vmcnt(31)
	v_lshlrev_b32_e32 v46, 16, v136
	v_mul_f32_e32 v46, 0x3db504f3, v46
	v_mul_f32_e32 v46, v47, v46
	s_waitcnt vmcnt(30)
	v_lshlrev_b32_e32 v47, 16, v137
	v_mul_f32_e32 v47, v68, v47
	v_cvt_pk_bf16_f32 v46, v46, s0
	global_store_short v[120:121], v46, off
	v_cvt_pk_bf16_f32 v46, v47, s0
	v_sub_f32_e32 v47, v93, v48
	v_mul_f32_e32 v47, 0x3fb8aa3b, v47
	v_sub_f32_e32 v68, v48, v93
	v_exp_f32_e32 v47, v47
	v_mul_f32_e32 v68, 0x3fb8aa3b, v68
	v_exp_f32_e32 v68, v68
	global_store_short v[120:121], v46, off offset:1024
	s_waitcnt vmcnt(31)
	v_lshlrev_b32_e32 v46, 16, v138
	v_mul_f32_e32 v46, 0x3db504f3, v46
	v_mul_f32_e32 v46, v47, v46
	s_waitcnt vmcnt(30)
	v_lshlrev_b32_e32 v47, 16, v139
	v_mul_f32_e32 v47, v68, v47
	v_cvt_pk_bf16_f32 v46, v46, s0
	global_store_short v[122:123], v46, off
	v_cvt_pk_bf16_f32 v46, v47, s0
	v_sub_f32_e32 v47, v95, v48
	v_mul_f32_e32 v47, 0x3fb8aa3b, v47
	v_sub_f32_e32 v68, v48, v95
	v_exp_f32_e32 v47, v47
	v_mul_f32_e32 v68, 0x3fb8aa3b, v68
	v_exp_f32_e32 v68, v68
	global_store_short v[122:123], v46, off offset:1024
	s_waitcnt vmcnt(31)
	v_lshlrev_b32_e32 v46, 16, v140
	v_mul_f32_e32 v46, 0x3db504f3, v46
	v_mul_f32_e32 v46, v47, v46
	s_waitcnt vmcnt(30)
	v_lshlrev_b32_e32 v47, 16, v141
	v_mul_f32_e32 v47, v68, v47
	v_cvt_pk_bf16_f32 v46, v46, s0
	global_store_short v[124:125], v46, off
	v_cvt_pk_bf16_f32 v46, v47, s0
	v_sub_f32_e32 v47, v97, v48
	v_mul_f32_e32 v47, 0x3fb8aa3b, v47
	v_sub_f32_e32 v68, v48, v97
	v_exp_f32_e32 v47, v47
	v_mul_f32_e32 v68, 0x3fb8aa3b, v68
	v_exp_f32_e32 v68, v68
	global_store_short v[124:125], v46, off offset:1024
	s_waitcnt vmcnt(31)
	v_lshlrev_b32_e32 v46, 16, v142
	v_mul_f32_e32 v46, 0x3db504f3, v46
	v_mul_f32_e32 v46, v47, v46
	s_waitcnt vmcnt(30)
	v_lshlrev_b32_e32 v47, 16, v143
	v_mul_f32_e32 v47, v68, v47
	v_cvt_pk_bf16_f32 v46, v46, s0
	global_store_short v[126:127], v46, off
	v_cvt_pk_bf16_f32 v46, v47, s0
	v_sub_f32_e32 v47, v99, v48
	v_mul_f32_e32 v47, 0x3fb8aa3b, v47
	v_sub_f32_e32 v68, v48, v99
	v_exp_f32_e32 v47, v47
	v_mul_f32_e32 v68, 0x3fb8aa3b, v68
	v_exp_f32_e32 v68, v68
	global_store_short v[126:127], v46, off offset:1024
	s_waitcnt vmcnt(31)
; __device__ __forceinline__ unsigned cvtpk(float lo, float hi) { f32x2 v = {lo, hi}; bf16x2_t b = __builtin_convertvector(v, bf16x2_t); return __builtin_bit_cast(unsigned, b); }
; __device__ __forceinline__ float fexp(float x) { return __builtin_amdgcn_exp2f(x * 1.44269504089f); }
; __device__ __forceinline__ void phase_qkrope_gla_prep(const Params& p, LAS unsigned char* lds, int wave, int lane) {
;     ...
;             for (int tb = 0; tb < 4; ++tb) {
;                 unsigned short qv[16], kv[16];
; #pragma unroll
;                 for (int t = 0; t < 16; ++t) { const size_t ro = (size_t)(m0 + 16 * tb + t) * ZP + d; qv[t] = Z[ro + C_QG]; kv[t] = Z[ro + C_KG]; }
; #pragma unroll
;                 for (int t = 0; t < 16; ++t) { const size_t ro = (size_t)(m0 + 16 * tb + t) * ZP + d; const float bb = bl[16 * tb + t];
;                     const float qs = bf2f(qv[t]) * 0.08838834764831845f * fexp(bb - bref), ks = bf2f(kv[t]) * fexp(bref - bb);
;                     Z[ro + C_QG] = (bf16_t)(cvtpk(qs, 0.f) & 0xffffu); Z[ro + C_KG] = (bf16_t)(cvtpk(ks, 0.f) & 0xffffu); }
	v_lshlrev_b32_e32 v46, 16, v144
	v_mul_f32_e32 v46, 0x3db504f3, v46
	v_mul_f32_e32 v46, v47, v46
	s_waitcnt vmcnt(30)
	v_lshlrev_b32_e32 v47, 16, v145
	v_mul_f32_e32 v47, v68, v47
	v_cvt_pk_bf16_f32 v46, v46, s0
	global_store_short v[128:129], v46, off
	v_cvt_pk_bf16_f32 v46, v47, s0
	v_sub_f32_e32 v47, v103, v48
	v_mul_f32_e32 v47, 0x3fb8aa3b, v47
	v_sub_f32_e32 v68, v48, v103
	v_exp_f32_e32 v47, v47
	v_mul_f32_e32 v68, 0x3fb8aa3b, v68
	v_exp_f32_e32 v68, v68
	global_store_short v[128:129], v46, off offset:1024
	s_waitcnt vmcnt(31)
	v_lshlrev_b32_e32 v46, 16, v146
	v_mul_f32_e32 v46, 0x3db504f3, v46
	v_mul_f32_e32 v46, v47, v46
	s_waitcnt vmcnt(30)
	v_lshlrev_b32_e32 v47, 16, v147
	v_mul_f32_e32 v47, v68, v47
	v_cvt_pk_bf16_f32 v46, v46, s0
	global_store_short v[2:3], v46, off
	v_cvt_pk_bf16_f32 v46, v47, s0
	global_store_short v[2:3], v46, off offset:1024
	v_sub_f32_e32 v3, v106, v48
	v_mul_f32_e32 v3, 0x3fb8aa3b, v3
	v_sub_f32_e32 v46, v48, v106
	v_exp_f32_e32 v3, v3
	v_mul_f32_e32 v46, 0x3fb8aa3b, v46
	v_exp_f32_e32 v46, v46
	s_waitcnt vmcnt(31)
	v_lshlrev_b32_e32 v2, 16, v148
	v_mul_f32_e32 v2, 0x3db504f3, v2
	v_mul_f32_e32 v2, v3, v2
	s_waitcnt vmcnt(30)
	v_lshlrev_b32_e32 v3, 16, v149
	v_mul_f32_e32 v3, v46, v3
	v_mad_i64_i32 v[46:47], s[4:5], s4, v61, v[8:9]
	global_load_ushort v68, v[46:47], off
	s_add_i32 s4, s0, -14
	v_mad_i64_i32 v[82:83], s[4:5], s4, v61, v[8:9]
	s_add_i32 s4, s0, -13
	s_nop 0
	v_mad_i64_i32 v[88:89], s[4:5], s4, v61, v[8:9]
	s_add_i32 s4, s0, -12
	s_nop 0
	v_mad_i64_i32 v[90:91], s[4:5], s4, v61, v[8:9]
	s_add_i32 s4, s0, -11
	s_nop 0
	v_mad_i64_i32 v[92:93], s[4:5], s4, v61, v[8:9]
	s_add_i32 s4, s0, -10
	s_nop 0
	v_mad_i64_i32 v[94:95], s[4:5], s4, v61, v[8:9]
	s_add_i32 s4, s0, -9
	s_nop 0
	v_mad_i64_i32 v[96:97], s[4:5], s4, v61, v[8:9]
	s_add_i32 s4, s0, -8
	s_nop 0
	v_mad_i64_i32 v[98:99], s[4:5], s4, v61, v[8:9]
	s_add_i32 s4, s0, -7
	s_nop 0
	v_mad_i64_i32 v[100:101], s[4:5], s4, v61, v[8:9]
	s_add_i32 s4, s0, -6
	s_nop 0
	v_mad_i64_i32 v[102:103], s[4:5], s4, v61, v[8:9]
	s_add_i32 s4, s0, -5
	s_nop 0
	v_mad_i64_i32 v[104:105], s[4:5], s4, v61, v[8:9]
	s_add_i32 s4, s0, -4
	s_nop 0
	v_mad_i64_i32 v[106:107], s[4:5], s4, v61, v[8:9]
	s_add_i32 s4, s0, -3
	s_nop 0
	v_mad_i64_i32 v[108:109], s[4:5], s4, v61, v[8:9]
	v_cvt_pk_bf16_f32 v2, v2, s0
	s_add_i32 s4, s0, -2
	global_store_short v[0:1], v2, off
	v_cvt_pk_bf16_f32 v2, v3, s0
	v_mad_i64_i32 v[110:111], s[4:5], s4, v61, v[8:9]
	global_store_short v[0:1], v2, off offset:1024
	s_add_i32 s4, s0, -1
	v_mad_i64_i32 v[2:3], s[4:5], s4, v61, v[8:9]
	v_mad_i64_i32 v[0:1], s[4:5], s0, v61, v[8:9]
	s_lshl_b64 s[4:5], s[18:19], 9
	s_add_i32 s18, s18, s70
	s_waitcnt vmcnt(2)
	v_lshlrev_b32_e32 v68, 16, v68
	v_mul_f32_e32 v68, 0x3db504f3, v68
	v_mul_f32_e32 v68, v70, v68
	global_load_ushort v70, v[46:47], off offset:1024
	v_cvt_pk_bf16_f32 v68, v68, s0
	s_waitcnt vmcnt(0)
	v_lshlrev_b32_e32 v70, 16, v70
	v_mul_f32_e32 v49, v49, v70
	global_load_ushort v70, v[82:83], off
	global_load_ushort v72, v[82:83], off offset:1024
	global_load_ushort v74, v[88:89], off
	global_load_ushort v77, v[88:89], off offset:1024
	global_load_ushort v79, v[90:91], off
	global_load_ushort v81, v[90:91], off offset:1024
	global_load_ushort v85, v[92:93], off
	global_load_ushort v86, v[92:93], off offset:1024
	global_load_ushort v112, v[94:95], off
	global_load_ushort v113, v[94:95], off offset:1024
	global_load_ushort v114, v[96:97], off
	global_load_ushort v115, v[96:97], off offset:1024
	global_load_ushort v116, v[98:99], off
	global_load_ushort v117, v[98:99], off offset:1024
	global_load_ushort v118, v[100:101], off
	global_load_ushort v119, v[100:101], off offset:1024
	global_load_ushort v120, v[102:103], off
	global_load_ushort v121, v[102:103], off offset:1024
	global_load_ushort v122, v[104:105], off
	global_load_ushort v123, v[104:105], off offset:1024
	global_load_ushort v124, v[106:107], off
	global_load_ushort v125, v[106:107], off offset:1024
	global_load_ushort v126, v[108:109], off
	global_load_ushort v127, v[108:109], off offset:1024
	global_load_ushort v128, v[110:111], off
	global_load_ushort v129, v[110:111], off offset:1024
	global_load_ushort v130, v[2:3], off
	global_load_ushort v131, v[2:3], off offset:1024
	global_load_ushort v132, v[0:1], off
	global_load_ushort v133, v[0:1], off offset:1024
	v_cvt_pk_bf16_f32 v49, v49, s0
	global_store_short v[46:47], v68, off
	global_store_short v[46:47], v49, off offset:1024
	v_sub_f32_e32 v47, v62, v48
	v_mul_f32_e32 v47, 0x3fb8aa3b, v47
	v_sub_f32_e32 v49, v48, v62
	v_exp_f32_e32 v47, v47
	v_mul_f32_e32 v49, 0x3fb8aa3b, v49
	v_exp_f32_e32 v49, v49
	s_waitcnt vmcnt(31)
	v_lshlrev_b32_e32 v46, 16, v70
	v_mul_f32_e32 v46, 0x3db504f3, v46
	v_mul_f32_e32 v46, v47, v46
	s_waitcnt vmcnt(30)
	v_lshlrev_b32_e32 v47, 16, v72
	v_mul_f32_e32 v47, v49, v47
	v_cvt_pk_bf16_f32 v46, v46, s0
	global_store_short v[82:83], v46, off
	v_cvt_pk_bf16_f32 v46, v47, s0
	v_sub_f32_e32 v47, v63, v48
	v_mul_f32_e32 v47, 0x3fb8aa3b, v47
	v_sub_f32_e32 v49, v48, v63
	v_exp_f32_e32 v47, v47
	v_mul_f32_e32 v49, 0x3fb8aa3b, v49
	v_exp_f32_e32 v49, v49
	global_store_short v[82:83], v46, off offset:1024
	s_waitcnt vmcnt(31)
	v_lshlrev_b32_e32 v46, 16, v74
	v_mul_f32_e32 v46, 0x3db504f3, v46
	v_mul_f32_e32 v46, v47, v46
	s_waitcnt vmcnt(30)
	v_lshlrev_b32_e32 v47, 16, v77
	v_mul_f32_e32 v47, v49, v47
	v_cvt_pk_bf16_f32 v46, v46, s0
	global_store_short v[88:89], v46, off
	v_cvt_pk_bf16_f32 v46, v47, s0
	v_sub_f32_e32 v47, v64, v48
	v_mul_f32_e32 v47, 0x3fb8aa3b, v47
	v_sub_f32_e32 v49, v48, v64
	v_exp_f32_e32 v47, v47
	v_mul_f32_e32 v49, 0x3fb8aa3b, v49
	v_exp_f32_e32 v49, v49
	global_store_short v[88:89], v46, off offset:1024
	s_waitcnt vmcnt(31)
; __device__ __forceinline__ unsigned cvtpk(float lo, float hi) { f32x2 v = {lo, hi}; bf16x2_t b = __builtin_convertvector(v, bf16x2_t); return __builtin_bit_cast(unsigned, b); }
; __device__ __forceinline__ float fexp(float x) { return __builtin_amdgcn_exp2f(x * 1.44269504089f); }
; __device__ __forceinline__ void phase_qkrope_gla_prep(const Params& p, LAS unsigned char* lds, int wave, int lane) {
;     ...
;             for (int tb = 0; tb < 4; ++tb) {
;                 unsigned short qv[16], kv[16];
; #pragma unroll
;                 for (int t = 0; t < 16; ++t) { const size_t ro = (size_t)(m0 + 16 * tb + t) * ZP + d; qv[t] = Z[ro + C_QG]; kv[t] = Z[ro + C_KG]; }
; #pragma unroll
;                 for (int t = 0; t < 16; ++t) { const size_t ro = (size_t)(m0 + 16 * tb + t) * ZP + d; const float bb = bl[16 * tb + t];
;                     const float qs = bf2f(qv[t]) * 0.08838834764831845f * fexp(bb - bref), ks = bf2f(kv[t]) * fexp(bref - bb);
;                     Z[ro + C_QG] = (bf16_t)(cvtpk(qs, 0.f) & 0xffffu); Z[ro + C_KG] = (bf16_t)(cvtpk(ks, 0.f) & 0xffffu); }
	v_lshlrev_b32_e32 v46, 16, v79
	v_mul_f32_e32 v46, 0x3db504f3, v46
	v_mul_f32_e32 v46, v47, v46
	s_waitcnt vmcnt(30)
	v_lshlrev_b32_e32 v47, 16, v81
	v_mul_f32_e32 v47, v49, v47
	v_cvt_pk_bf16_f32 v46, v46, s0
	global_store_short v[90:91], v46, off
	v_cvt_pk_bf16_f32 v46, v47, s0
	v_sub_f32_e32 v47, v65, v48
	v_mul_f32_e32 v47, 0x3fb8aa3b, v47
	v_sub_f32_e32 v49, v48, v65
	v_exp_f32_e32 v47, v47
	v_mul_f32_e32 v49, 0x3fb8aa3b, v49
	v_exp_f32_e32 v49, v49
	global_store_short v[90:91], v46, off offset:1024
	s_waitcnt vmcnt(31)
	v_lshlrev_b32_e32 v46, 16, v85
	v_mul_f32_e32 v46, 0x3db504f3, v46
	v_mul_f32_e32 v46, v47, v46
	s_waitcnt vmcnt(30)
	v_lshlrev_b32_e32 v47, 16, v86
	v_mul_f32_e32 v47, v49, v47
	v_cvt_pk_bf16_f32 v46, v46, s0
	global_store_short v[92:93], v46, off
	v_cvt_pk_bf16_f32 v46, v47, s0
	v_sub_f32_e32 v47, v66, v48
	v_mul_f32_e32 v47, 0x3fb8aa3b, v47
	v_sub_f32_e32 v49, v48, v66
	v_exp_f32_e32 v47, v47
	v_mul_f32_e32 v49, 0x3fb8aa3b, v49
	v_exp_f32_e32 v49, v49
	global_store_short v[92:93], v46, off offset:1024
	s_waitcnt vmcnt(31)
	v_lshlrev_b32_e32 v46, 16, v112
	v_mul_f32_e32 v46, 0x3db504f3, v46
	v_mul_f32_e32 v46, v47, v46
	s_waitcnt vmcnt(30)
	v_lshlrev_b32_e32 v47, 16, v113
	v_mul_f32_e32 v47, v49, v47
	v_cvt_pk_bf16_f32 v46, v46, s0
	global_store_short v[94:95], v46, off
	v_cvt_pk_bf16_f32 v46, v47, s0
	v_sub_f32_e32 v47, v67, v48
	v_mul_f32_e32 v47, 0x3fb8aa3b, v47
	v_sub_f32_e32 v49, v48, v67
	v_exp_f32_e32 v47, v47
	v_mul_f32_e32 v49, 0x3fb8aa3b, v49
	v_exp_f32_e32 v49, v49
	global_store_short v[94:95], v46, off offset:1024
	s_waitcnt vmcnt(31)
	v_lshlrev_b32_e32 v46, 16, v114
	v_mul_f32_e32 v46, 0x3db504f3, v46
	v_mul_f32_e32 v46, v47, v46
	s_waitcnt vmcnt(30)
	v_lshlrev_b32_e32 v47, 16, v115
	v_mul_f32_e32 v47, v49, v47
	v_cvt_pk_bf16_f32 v46, v46, s0
	global_store_short v[96:97], v46, off
	v_cvt_pk_bf16_f32 v46, v47, s0
	v_sub_f32_e32 v47, v69, v48
	v_mul_f32_e32 v47, 0x3fb8aa3b, v47
	v_sub_f32_e32 v49, v48, v69
	v_exp_f32_e32 v47, v47
	v_mul_f32_e32 v49, 0x3fb8aa3b, v49
	v_exp_f32_e32 v49, v49
	global_store_short v[96:97], v46, off offset:1024
	s_waitcnt vmcnt(31)
	v_lshlrev_b32_e32 v46, 16, v116
	v_mul_f32_e32 v46, 0x3db504f3, v46
	v_mul_f32_e32 v46, v47, v46
	s_waitcnt vmcnt(30)
	v_lshlrev_b32_e32 v47, 16, v117
	v_mul_f32_e32 v47, v49, v47
	v_cvt_pk_bf16_f32 v46, v46, s0
	global_store_short v[98:99], v46, off
	v_cvt_pk_bf16_f32 v46, v47, s0
	v_sub_f32_e32 v47, v71, v48
	v_mul_f32_e32 v47, 0x3fb8aa3b, v47
	v_sub_f32_e32 v49, v48, v71
	v_exp_f32_e32 v47, v47
	v_mul_f32_e32 v49, 0x3fb8aa3b, v49
	v_exp_f32_e32 v49, v49
	global_store_short v[98:99], v46, off offset:1024
	s_waitcnt vmcnt(31)
	v_lshlrev_b32_e32 v46, 16, v118
	v_mul_f32_e32 v46, 0x3db504f3, v46
	v_mul_f32_e32 v46, v47, v46
	s_waitcnt vmcnt(30)
	v_lshlrev_b32_e32 v47, 16, v119
	v_mul_f32_e32 v47, v49, v47
	v_cvt_pk_bf16_f32 v46, v46, s0
	global_store_short v[100:101], v46, off
	v_cvt_pk_bf16_f32 v46, v47, s0
	v_sub_f32_e32 v47, v73, v48
	v_mul_f32_e32 v47, 0x3fb8aa3b, v47
	v_sub_f32_e32 v49, v48, v73
	v_exp_f32_e32 v47, v47
	v_mul_f32_e32 v49, 0x3fb8aa3b, v49
	v_exp_f32_e32 v49, v49
	global_store_short v[100:101], v46, off offset:1024
	s_waitcnt vmcnt(31)
	v_lshlrev_b32_e32 v46, 16, v120
	v_mul_f32_e32 v46, 0x3db504f3, v46
	v_mul_f32_e32 v46, v47, v46
	s_waitcnt vmcnt(30)
	v_lshlrev_b32_e32 v47, 16, v121
	v_mul_f32_e32 v47, v49, v47
	v_cvt_pk_bf16_f32 v46, v46, s0
	global_store_short v[102:103], v46, off
	v_cvt_pk_bf16_f32 v46, v47, s0
	v_sub_f32_e32 v47, v75, v48
	v_mul_f32_e32 v47, 0x3fb8aa3b, v47
	v_sub_f32_e32 v49, v48, v75
	v_exp_f32_e32 v47, v47
	v_mul_f32_e32 v49, 0x3fb8aa3b, v49
	v_exp_f32_e32 v49, v49
	global_store_short v[102:103], v46, off offset:1024
	s_waitcnt vmcnt(31)
; __device__ __forceinline__ unsigned cvtpk(float lo, float hi) { f32x2 v = {lo, hi}; bf16x2_t b = __builtin_convertvector(v, bf16x2_t); return __builtin_bit_cast(unsigned, b); }
; __device__ __forceinline__ float fexp(float x) { return __builtin_amdgcn_exp2f(x * 1.44269504089f); }
; __device__ __forceinline__ void phase_qkrope_gla_prep(const Params& p, LAS unsigned char* lds, int wave, int lane) {
;     ...
;             for (int tb = 0; tb < 4; ++tb) {
;                 unsigned short qv[16], kv[16];
; #pragma unroll
;                 for (int t = 0; t < 16; ++t) { const size_t ro = (size_t)(m0 + 16 * tb + t) * ZP + d; qv[t] = Z[ro + C_QG]; kv[t] = Z[ro + C_KG]; }
; #pragma unroll
;                 for (int t = 0; t < 16; ++t) { const size_t ro = (size_t)(m0 + 16 * tb + t) * ZP + d; const float bb = bl[16 * tb + t];
;                     const float qs = bf2f(qv[t]) * 0.08838834764831845f * fexp(bb - bref), ks = bf2f(kv[t]) * fexp(bref - bb);
;                     Z[ro + C_QG] = (bf16_t)(cvtpk(qs, 0.f) & 0xffffu); Z[ro + C_KG] = (bf16_t)(cvtpk(ks, 0.f) & 0xffffu); }
;             }
;             { const size_t eo = (size_t)bc * 512 + d; E1[eo] = fexp(bref); E2[eo] = fexp(blast - bref); E3[eo] = fexp(blast); }
	v_lshlrev_b32_e32 v46, 16, v122
	v_mul_f32_e32 v46, 0x3db504f3, v46
	v_mul_f32_e32 v46, v47, v46
	s_waitcnt vmcnt(30)
	v_lshlrev_b32_e32 v47, 16, v123
	v_mul_f32_e32 v47, v49, v47
	v_cvt_pk_bf16_f32 v46, v46, s0
	global_store_short v[104:105], v46, off
	v_cvt_pk_bf16_f32 v46, v47, s0
	v_sub_f32_e32 v47, v78, v48
	v_mul_f32_e32 v47, 0x3fb8aa3b, v47
	v_sub_f32_e32 v49, v48, v78
	v_exp_f32_e32 v47, v47
	v_mul_f32_e32 v49, 0x3fb8aa3b, v49
	v_exp_f32_e32 v49, v49
	global_store_short v[104:105], v46, off offset:1024
	s_waitcnt vmcnt(31)
	v_lshlrev_b32_e32 v46, 16, v124
	v_mul_f32_e32 v46, 0x3db504f3, v46
	v_mul_f32_e32 v46, v47, v46
	s_waitcnt vmcnt(30)
	v_lshlrev_b32_e32 v47, 16, v125
	v_mul_f32_e32 v47, v49, v47
	v_cvt_pk_bf16_f32 v46, v46, s0
	global_store_short v[106:107], v46, off
	v_cvt_pk_bf16_f32 v46, v47, s0
	v_sub_f32_e32 v47, v80, v48
	v_mul_f32_e32 v47, 0x3fb8aa3b, v47
	v_sub_f32_e32 v49, v48, v80
	v_exp_f32_e32 v47, v47
	v_mul_f32_e32 v49, 0x3fb8aa3b, v49
	v_exp_f32_e32 v49, v49
	global_store_short v[106:107], v46, off offset:1024
	s_waitcnt vmcnt(31)
	v_lshlrev_b32_e32 v46, 16, v126
	v_mul_f32_e32 v46, 0x3db504f3, v46
	v_mul_f32_e32 v46, v47, v46
	s_waitcnt vmcnt(30)
	v_lshlrev_b32_e32 v47, 16, v127
	v_mul_f32_e32 v47, v49, v47
	v_cvt_pk_bf16_f32 v46, v46, s0
	global_store_short v[108:109], v46, off
	v_cvt_pk_bf16_f32 v46, v47, s0
	v_sub_f32_e32 v47, v84, v48
	v_mul_f32_e32 v47, 0x3fb8aa3b, v47
	v_sub_f32_e32 v49, v48, v84
	v_exp_f32_e32 v47, v47
	v_mul_f32_e32 v49, 0x3fb8aa3b, v49
	v_exp_f32_e32 v49, v49
	global_store_short v[108:109], v46, off offset:1024
	s_waitcnt vmcnt(31)
	v_lshlrev_b32_e32 v46, 16, v128
	v_mul_f32_e32 v46, 0x3db504f3, v46
	v_mul_f32_e32 v46, v47, v46
	s_waitcnt vmcnt(30)
	v_lshlrev_b32_e32 v47, 16, v129
	v_mul_f32_e32 v47, v49, v47
	v_cvt_pk_bf16_f32 v46, v46, s0
	global_store_short v[110:111], v46, off
	v_cvt_pk_bf16_f32 v46, v47, s0
	v_sub_f32_e32 v47, v87, v48
	v_mul_f32_e32 v47, 0x3fb8aa3b, v47
	v_sub_f32_e32 v49, v48, v87
	v_exp_f32_e32 v47, v47
	v_mul_f32_e32 v49, 0x3fb8aa3b, v49
	v_exp_f32_e32 v49, v49
	global_store_short v[110:111], v46, off offset:1024
	s_waitcnt vmcnt(31)
	v_lshlrev_b32_e32 v46, 16, v130
	v_mul_f32_e32 v46, 0x3db504f3, v46
	v_mul_f32_e32 v46, v47, v46
	s_waitcnt vmcnt(30)
	v_lshlrev_b32_e32 v47, 16, v131
	v_mul_f32_e32 v47, v49, v47
	v_cvt_pk_bf16_f32 v46, v46, s0
	global_store_short v[2:3], v46, off
	v_cvt_pk_bf16_f32 v46, v47, s0
	global_store_short v[2:3], v46, off offset:1024
	s_waitcnt vmcnt(31)
	v_lshlrev_b32_e32 v2, 16, v132
	v_mul_f32_e32 v3, 0x3db504f3, v2
	v_sub_f32_e32 v2, v76, v48
	v_mul_f32_e32 v2, 0x3fb8aa3b, v2
	v_sub_f32_e32 v47, v48, v76
	v_exp_f32_e32 v2, v2
	v_mul_f32_e32 v47, 0x3fb8aa3b, v47
	v_exp_f32_e32 v47, v47
	s_waitcnt vmcnt(30)
	v_lshlrev_b32_e32 v46, 16, v133
	v_mul_f32_e32 v3, v2, v3
	v_cvt_pk_bf16_f32 v3, v3, s0
	v_mul_f32_e32 v46, v47, v46
	global_store_short v[0:1], v3, off
	v_cvt_pk_bf16_f32 v3, v46, s0
	global_store_short v[0:1], v3, off offset:1024
	v_mul_f32_e32 v3, 0x3fb8aa3b, v48
	v_exp_f32_e32 v3, v3
	v_lshl_add_u64 v[0:1], s[4:5], 0, v[4:5]
	v_lshlrev_b64 v[0:1], 2, v[0:1]
	v_lshl_add_u64 v[46:47], s[6:7], 0, v[0:1]
	global_store_dword v[46:47], v3, off
	v_lshl_add_u64 v[46:47], s[8:9], 0, v[0:1]
	global_store_dword v[46:47], v2, off
	v_mul_f32_e32 v2, 0x3fb8aa3b, v76
	v_exp_f32_e32 v2, v2
	s_add_i32 s0, s0, s1
	v_lshl_add_u64 v[0:1], s[10:11], 0, v[0:1]
	s_cmpk_gt_i32 s18, 0xff
	global_store_dword v[0:1], v2, off
	s_cbranch_scc0 .LBB0_518

; __device__ __forceinline__ void phase_qkrope_gla_prep(const Params& p, LAS unsigned char* lds, int wave, int lane) {
;     ...
;         for (int m = gw; m < MTOK; m += NGW) {
;             const int pos = m & (SEQ - 1);
;             bf16_t* row0 = (bf16_t*)(p.ws + WS_QKVC) + (isk ? QKV_ELEMS : 0) + ((size_t)(m >> 12) * 8 * SEQ + pos) * 128;
;             unsigned w1[8], w2[8];
; #pragma unroll
;             for (int h = 0; h < 8; ++h) { w1[h] = *(const unsigned*)(row0 + (size_t)h * SEQ * 128 + 2 * i); w2[h] = *(const unsigned*)(row0 + (size_t)h * SEQ * 128 + 64 + 2 * i); }
;             const f32x4 c4 = *(const f32x4*)(cs + pos * 64 + 2 * i);
;             unsigned o1[8], o2[8];
; #pragma unroll
;             for (int h = 0; h < 8; ++h) {
;                 const float x1a = bflo(w1[h]), x1b = bfhi(w1[h]), x2a = bflo(w2[h]), x2b = bfhi(w2[h]);
;                 float ss = (x1a * x1a + x1b * x1b) + (x2a * x2a + x2b * x2b);
; #pragma unroll
;                 for (int o = 1; o < 32; o <<= 1) ss += __shfl_xor(ss, o);
;                 const float rstd = osc / sqrtf(ss * (1.0f / 128.0f) + EPS);
.LBB0_521:
	s_ashr_i32 s2, s20, 12
	s_ashr_i32 s3, s2, 31
	s_and_b32 s4, s20, 0xfff
	s_lshl_b64 s[2:3], s[2:3], 23
	s_lshl_b32 s0, s4, 8
	v_lshl_add_u64 v[0:1], v[10:11], 0, s[2:3]
	v_lshl_add_u64 v[0:1], v[0:1], 0, s[0:1]
	v_lshl_add_u64 v[34:35], v[0:1], 0, v[4:5]
	v_add_co_u32_e32 v26, vcc, 0x100000, v34
	s_lshl_b32 s0, s4, 9
	s_nop 0
	v_addc_co_u32_e32 v27, vcc, 0, v35, vcc
	v_add_co_u32_e32 v24, vcc, 0x200000, v34
	v_lshl_add_u64 v[14:15], v[8:9], 0, s[0:1]
	s_nop 0
	v_addc_co_u32_e32 v25, vcc, 0, v35, vcc
	v_add_co_u32_e32 v18, vcc, 0x300000, v34
	global_load_dword v28, v[34:35], off offset:128
	global_load_dword v29, v[34:35], off
	global_load_dwordx4 v[0:3], v[14:15], off
	v_addc_co_u32_e32 v19, vcc, 0, v35, vcc
	v_add_co_u32_e32 v14, vcc, 0x400000, v34
	global_load_dword v36, v[26:27], off
	global_load_dword v37, v[26:27], off offset:128
	v_addc_co_u32_e32 v15, vcc, 0, v35, vcc
	v_add_co_u32_e32 v16, vcc, 0x500000, v34
	global_load_dword v38, v[24:25], off offset:128
	global_load_dword v39, v[24:25], off
	v_addc_co_u32_e32 v17, vcc, 0, v35, vcc
	global_load_dword v40, v[18:19], off offset:128
	global_load_dword v41, v[18:19], off
	v_add_co_u32_e32 v20, vcc, 0x600000, v34
	global_load_dword v42, v[14:15], off offset:128
	global_load_dword v43, v[14:15], off
	v_addc_co_u32_e32 v21, vcc, 0, v35, vcc
	global_load_dword v45, v[16:17], off offset:128
	global_load_dword v44, v[16:17], off
	v_add_co_u32_e32 v22, vcc, 0x700000, v34
	global_load_dword v74, v[20:21], off offset:128
	global_load_dword v75, v[20:21], off
	v_addc_co_u32_e32 v23, vcc, 0, v35, vcc
	global_load_dword v78, v[22:23], off offset:128
	global_load_dword v79, v[22:23], off
	s_add_i32 s20, s20, s24
	s_cmpk_lt_i32 s20, 0x4000
	s_waitcnt vmcnt(16)
	v_lshlrev_b32_e32 v62, 16, v28
	s_waitcnt vmcnt(15)
	v_and_b32_e32 v63, 0xffff0000, v29
	v_lshlrev_b32_e32 v64, 16, v29
	v_and_b32_e32 v65, 0xffff0000, v28
	s_waitcnt vmcnt(14)
	v_mov_b32_e32 v29, v2
	v_mov_b32_e32 v30, v1
	v_mov_b32_e32 v31, v3
	v_mov_b32_e32 v32, v1
	v_mov_b32_e32 v33, v2
	v_mov_b32_e32 v1, v3
	v_pk_mul_f32 v[2:3], v[62:63], v[62:63]
	s_waitcnt vmcnt(12)
	v_lshlrev_b32_e32 v58, 16, v37
	v_pk_fma_f32 v[2:3], v[64:65], v[64:65], v[2:3] op_sel:[0,0,1] op_sel_hi:[1,1,0]
	v_and_b32_e32 v59, 0xffff0000, v36
	v_add_f32_e32 v80, v2, v3
	v_lshlrev_b32_e32 v60, 16, v36
	v_and_b32_e32 v61, 0xffff0000, v37
	v_pk_mul_f32 v[2:3], v[58:59], v[58:59]
	s_waitcnt vmcnt(11)
	v_lshlrev_b32_e32 v54, 16, v38
	s_waitcnt vmcnt(10)
	v_and_b32_e32 v55, 0xffff0000, v39
	ds_bpermute_b32 v81, v68, v80
	v_lshlrev_b32_e32 v56, 16, v39
	v_and_b32_e32 v57, 0xffff0000, v38
	v_pk_fma_f32 v[2:3], v[60:61], v[60:61], v[2:3] op_sel:[0,0,1] op_sel_hi:[1,1,0]
	v_pk_mul_f32 v[36:37], v[54:55], v[54:55]
	s_waitcnt vmcnt(9)
	v_lshlrev_b32_e32 v50, 16, v40
	s_waitcnt vmcnt(8)
	v_and_b32_e32 v51, 0xffff0000, v41
	v_lshlrev_b32_e32 v52, 16, v41
	v_and_b32_e32 v53, 0xffff0000, v40
	v_add_f32_e32 v82, v2, v3
	v_pk_fma_f32 v[2:3], v[56:57], v[56:57], v[36:37] op_sel:[0,0,1] op_sel_hi:[1,1,0]
	v_pk_mul_f32 v[36:37], v[50:51], v[50:51]
	s_waitcnt vmcnt(7)
	v_lshlrev_b32_e32 v46, 16, v42
	s_waitcnt vmcnt(6)
	v_and_b32_e32 v47, 0xffff0000, v43
	v_lshlrev_b32_e32 v48, 16, v43
	v_and_b32_e32 v49, 0xffff0000, v42
	ds_bpermute_b32 v83, v68, v82
	v_add_f32_e32 v84, v2, v3
	v_pk_fma_f32 v[2:3], v[52:53], v[52:53], v[36:37] op_sel:[0,0,1] op_sel_hi:[1,1,0]
	v_pk_mul_f32 v[36:37], v[46:47], v[46:47]
	s_waitcnt vmcnt(5)
	v_lshlrev_b32_e32 v42, 16, v45
	s_waitcnt vmcnt(4)
	v_and_b32_e32 v43, 0xffff0000, v44
	v_lshlrev_b32_e32 v44, 16, v44
	v_and_b32_e32 v45, 0xffff0000, v45
	ds_bpermute_b32 v85, v68, v84
	v_add_f32_e32 v86, v2, v3
	v_pk_fma_f32 v[2:3], v[48:49], v[48:49], v[36:37] op_sel:[0,0,1] op_sel_hi:[1,1,0]
	v_pk_mul_f32 v[36:37], v[42:43], v[42:43]
	s_waitcnt vmcnt(3)
	v_lshlrev_b32_e32 v38, 16, v74
	s_waitcnt vmcnt(2)
	v_and_b32_e32 v39, 0xffff0000, v75
	v_lshlrev_b32_e32 v40, 16, v75
	v_and_b32_e32 v41, 0xffff0000, v74
	v_add_f32_e32 v88, v2, v3
	v_pk_fma_f32 v[74:75], v[44:45], v[44:45], v[36:37] op_sel:[0,0,1] op_sel_hi:[1,1,0]
	v_pk_mul_f32 v[76:77], v[38:39], v[38:39]
	s_waitcnt vmcnt(1)
	v_lshlrev_b32_e32 v2, 16, v78
	s_waitcnt vmcnt(0)
	v_and_b32_e32 v3, 0xffff0000, v79
	v_and_b32_e32 v37, 0xffff0000, v78
	s_waitcnt lgkmcnt(2)
	v_add_f32_e32 v78, v80, v81
	v_lshlrev_b32_e32 v36, 16, v79
	v_add_f32_e32 v80, v74, v75
	v_pk_fma_f32 v[74:75], v[40:41], v[40:41], v[76:77] op_sel:[0,0,1] op_sel_hi:[1,1,0]
	v_pk_mul_f32 v[76:77], v[2:3], v[2:3]
	ds_bpermute_b32 v81, v69, v78
	ds_bpermute_b32 v87, v68, v86
	ds_bpermute_b32 v79, v68, v88
	v_add_f32_e32 v90, v74, v75
	v_pk_fma_f32 v[74:75], v[36:37], v[36:37], v[76:77] op_sel:[0,0,1] op_sel_hi:[1,1,0]
	s_waitcnt lgkmcnt(4)
	v_add_f32_e32 v76, v82, v83
	ds_bpermute_b32 v77, v68, v90
	v_add_f32_e32 v74, v74, v75
	ds_bpermute_b32 v89, v68, v80
	ds_bpermute_b32 v75, v69, v76
	s_waitcnt lgkmcnt(6)
	v_add_f32_e32 v82, v84, v85
	ds_bpermute_b32 v83, v68, v74
	ds_bpermute_b32 v84, v69, v82
	s_waitcnt lgkmcnt(7)
	v_add_f32_e32 v78, v78, v81
	s_waitcnt lgkmcnt(6)
	v_add_f32_e32 v85, v86, v87
	s_waitcnt lgkmcnt(5)
	v_add_f32_e32 v79, v88, v79
	ds_bpermute_b32 v87, v70, v78
	ds_bpermute_b32 v86, v69, v85
	ds_bpermute_b32 v81, v69, v79
	s_waitcnt lgkmcnt(7)
	v_add_f32_e32 v77, v90, v77
	s_waitcnt lgkmcnt(6)
	v_add_f32_e32 v80, v80, v89
	s_waitcnt lgkmcnt(5)
	v_add_f32_e32 v75, v76, v75
	ds_bpermute_b32 v76, v69, v77
	s_waitcnt lgkmcnt(5)
	v_add_f32_e32 v74, v74, v83
	ds_bpermute_b32 v88, v69, v80
	ds_bpermute_b32 v83, v70, v75
	s_waitcnt lgkmcnt(6)
	v_add_f32_e32 v82, v82, v84
	ds_bpermute_b32 v84, v69, v74
	ds_bpermute_b32 v89, v70, v82
	s_waitcnt lgkmcnt(7)
; __device__ __forceinline__ void phase_qkrope_gla_prep(const Params& p, LAS unsigned char* lds, int wave, int lane) {
;     ...
;                 const float x1a = bflo(w1[h]), x1b = bfhi(w1[h]), x2a = bflo(w2[h]), x2b = bfhi(w2[h]);
;                 float ss = (x1a * x1a + x1b * x1b) + (x2a * x2a + x2b * x2b);
; #pragma unroll
;                 for (int o = 1; o < 32; o <<= 1) ss += __shfl_xor(ss, o);
;                 const float rstd = osc / sqrtf(ss * (1.0f / 128.0f) + EPS);
	v_add_f32_e32 v78, v78, v87
	s_waitcnt lgkmcnt(6)
	v_add_f32_e32 v85, v85, v86
	s_waitcnt lgkmcnt(5)
	v_add_f32_e32 v79, v79, v81
	ds_bpermute_b32 v87, v71, v78
	ds_bpermute_b32 v86, v70, v85
	ds_bpermute_b32 v81, v70, v79
	s_waitcnt lgkmcnt(7)
	v_add_f32_e32 v76, v77, v76
	s_waitcnt lgkmcnt(6)
	v_add_f32_e32 v80, v80, v88
	s_waitcnt lgkmcnt(5)
	v_add_f32_e32 v75, v75, v83
	ds_bpermute_b32 v77, v70, v76
	s_waitcnt lgkmcnt(5)
	v_add_f32_e32 v74, v74, v84
	ds_bpermute_b32 v88, v70, v80
	ds_bpermute_b32 v83, v71, v75
	s_waitcnt lgkmcnt(6)
	v_add_f32_e32 v82, v82, v89
	ds_bpermute_b32 v84, v70, v74
	ds_bpermute_b32 v89, v71, v82
	s_waitcnt lgkmcnt(7)
	v_add_f32_e32 v78, v78, v87
	s_waitcnt lgkmcnt(6)
	v_add_f32_e32 v85, v85, v86
	s_waitcnt lgkmcnt(5)
	v_add_f32_e32 v79, v79, v81
	ds_bpermute_b32 v87, v72, v78
	ds_bpermute_b32 v86, v71, v85
	ds_bpermute_b32 v81, v71, v79
	s_waitcnt lgkmcnt(7)
	v_add_f32_e32 v76, v76, v77
	s_waitcnt lgkmcnt(6)
	v_add_f32_e32 v80, v80, v88
	s_waitcnt lgkmcnt(5)
	v_add_f32_e32 v75, v75, v83
	ds_bpermute_b32 v77, v71, v76
	s_waitcnt lgkmcnt(5)
	v_add_f32_e32 v74, v74, v84
	ds_bpermute_b32 v88, v71, v80
	ds_bpermute_b32 v83, v72, v75
	s_waitcnt lgkmcnt(6)
	v_add_f32_e32 v82, v82, v89
	ds_bpermute_b32 v84, v71, v74
	ds_bpermute_b32 v89, v72, v82
	s_waitcnt lgkmcnt(7)
	v_add_f32_e32 v78, v78, v87
	s_waitcnt lgkmcnt(6)
	v_add_f32_e32 v85, v85, v86
	s_waitcnt lgkmcnt(5)
	v_add_f32_e32 v79, v79, v81
	v_fmamk_f32 v78, v78, 0x3c000000, v67
	ds_bpermute_b32 v86, v72, v85
	ds_bpermute_b32 v81, v72, v79
	s_waitcnt lgkmcnt(6)
	v_add_f32_e32 v76, v76, v77
	s_waitcnt lgkmcnt(5)
	v_add_f32_e32 v80, v80, v88
	s_waitcnt lgkmcnt(4)
	v_add_f32_e32 v75, v75, v83
	ds_bpermute_b32 v83, v72, v76
	s_waitcnt lgkmcnt(4)
	v_add_f32_e32 v74, v74, v84
	v_rsq_f32_e32 v77, v78
	ds_bpermute_b32 v87, v72, v80
	v_fmamk_f32 v75, v75, 0x3c000000, v67
	s_waitcnt lgkmcnt(4)
	v_add_f32_e32 v78, v82, v89
	ds_bpermute_b32 v82, v72, v74
	v_fmamk_f32 v78, v78, 0x3c000000, v67
	s_waitcnt lgkmcnt(4)
	v_add_f32_e32 v85, v85, v86
	v_rsq_f32_e32 v75, v75
	s_waitcnt lgkmcnt(3)
	v_add_f32_e32 v79, v79, v81
	v_fmamk_f32 v85, v85, 0x3c000000, v67
	v_rsq_f32_e32 v78, v78
	s_waitcnt lgkmcnt(2)
	v_add_f32_e32 v76, v76, v83
	v_fmamk_f32 v79, v79, 0x3c000000, v67
	s_waitcnt lgkmcnt(1)
	v_add_f32_e32 v80, v80, v87
	s_waitcnt lgkmcnt(0)
; __device__ __forceinline__ unsigned cvtpk(float lo, float hi) { f32x2 v = {lo, hi}; bf16x2_t b = __builtin_convertvector(v, bf16x2_t); return __builtin_bit_cast(unsigned, b); }
; __device__ __forceinline__ void phase_qkrope_gla_prep(const Params& p, LAS unsigned char* lds, int wave, int lane) {
;     ...
;         for (int m = gw; m < MTOK; m += NGW) {
;             const int pos = m & (SEQ - 1);
;             bf16_t* row0 = (bf16_t*)(p.ws + WS_QKVC) + (isk ? QKV_ELEMS : 0) + ((size_t)(m >> 12) * 8 * SEQ + pos) * 128;
;             unsigned w1[8], w2[8];
; #pragma unroll
;             for (int h = 0; h < 8; ++h) { w1[h] = *(const unsigned*)(row0 + (size_t)h * SEQ * 128 + 2 * i); w2[h] = *(const unsigned*)(row0 + (size_t)h * SEQ * 128 + 64 + 2 * i); }
;             const f32x4 c4 = *(const f32x4*)(cs + pos * 64 + 2 * i);
;             unsigned o1[8], o2[8];
; #pragma unroll
;             for (int h = 0; h < 8; ++h) {
;                 const float x1a = bflo(w1[h]), x1b = bfhi(w1[h]), x2a = bflo(w2[h]), x2b = bfhi(w2[h]);
;                 float ss = (x1a * x1a + x1b * x1b) + (x2a * x2a + x2b * x2b);
; #pragma unroll
;                 for (int o = 1; o < 32; o <<= 1) ss += __shfl_xor(ss, o);
;                 const float rstd = osc / sqrtf(ss * (1.0f / 128.0f) + EPS);
;                 const float y1a = x1a * rstd * g1a, y1b = x1b * rstd * g1b, y2a = x2a * rstd * g2a, y2b = x2b * rstd * g2b;
;                 const float o1a = y1a * c4.x - y2a * c4.y, o2a = y2a * c4.x + y1a * c4.y;
;                 const float o1b = y1b * c4.z - y2b * c4.w, o2b = y2b * c4.z + y1b * c4.w;
;                 o1[h] = cvtpk(o1a, o1b); o2[h] = cvtpk(o2a, o2b); }
; #pragma unroll
;             for (int h = 0; h < 8; ++h) { *(unsigned*)(row0 + (size_t)h * SEQ * 128 + 2 * i) = o1[h]; *(unsigned*)(row0 + (size_t)h * SEQ * 128 + 64 + 2 * i) = o2[h]; }
;         }
	v_add_f32_e32 v74, v74, v82
	v_rsq_f32_e32 v85, v85
	v_fmamk_f32 v80, v80, 0x3c000000, v67
	v_rsq_f32_e32 v79, v79
	v_fmamk_f32 v76, v76, 0x3c000000, v67
	v_rsq_f32_e32 v80, v80
	v_fmamk_f32 v74, v74, 0x3c000000, v67
	v_rsq_f32_e32 v76, v76
	v_rsq_f32_e32 v74, v74
	s_nop 0
	v_mov_b32_e32 v77, v77
	s_nop 0
	v_mov_b32_e32 v75, v75
	s_nop 0
	v_mov_b32_e32 v81, v78
	s_nop 0
	v_mov_b32_e32 v85, v85
	s_nop 0
	v_mov_b32_e32 v96, v79
	s_nop 0
	v_mov_b32_e32 v80, v80
	s_nop 0
	v_mov_b32_e32 v102, v76
	s_nop 0
	v_mov_b32_e32 v105, v74
	s_nop 0
	v_mul_f32_e32 v74, v66, v77
	v_pk_mul_f32 v[62:63], v[74:75], v[62:63] op_sel_hi:[0,1]
	v_pk_mul_f32 v[64:65], v[74:75], v[64:65] op_sel_hi:[0,1]
	v_pk_mul_f32 v[62:63], v[6:7], v[62:63]
	v_pk_mul_f32 v[64:65], v[12:13], v[64:65]
	s_nop 0
	v_mul_f32_e32 v74, v66, v75
	v_mov_b32_e32 v77, v63
	v_mov_b32_e32 v78, v62
	v_mov_b32_e32 v79, v65
	v_pk_mul_f32 v[62:63], v[0:1], v[62:63]
	v_pk_mul_f32 v[58:59], v[74:75], v[58:59] op_sel_hi:[0,1]
	v_pk_mul_f32 v[60:61], v[74:75], v[60:61] op_sel_hi:[0,1]
	s_nop 0
	v_mul_f32_e32 v74, v66, v81
	v_mov_b32_e32 v28, v0
	v_mov_b32_e32 v76, v64
	v_pk_mul_f32 v[78:79], v[30:31], v[78:79]
	v_pk_fma_f32 v[62:63], v[32:33], v[64:65], v[62:63]
	v_pk_mul_f32 v[58:59], v[6:7], v[58:59]
	v_pk_mul_f32 v[60:61], v[12:13], v[60:61]
	v_pk_mul_f32 v[54:55], v[74:75], v[54:55] op_sel_hi:[0,1]
	v_pk_mul_f32 v[56:57], v[74:75], v[56:57] op_sel_hi:[0,1]
	s_nop 0
	v_mul_f32_e32 v64, v66, v85
	v_pk_fma_f32 v[74:75], v[28:29], v[76:77], v[78:79] neg_lo:[0,0,1] neg_hi:[0,0,1]
	v_cvt_pk_bf16_f32 v78, v62, v63
	v_mov_b32_e32 v63, v59
	v_mov_b32_e32 v76, v58
	v_mov_b32_e32 v77, v61
	v_pk_mul_f32 v[58:59], v[0:1], v[58:59]
	v_pk_mul_f32 v[54:55], v[6:7], v[54:55]
	v_pk_mul_f32 v[56:57], v[12:13], v[56:57]
	v_pk_mul_f32 v[50:51], v[64:65], v[50:51] op_sel_hi:[0,1]
	v_pk_mul_f32 v[52:53], v[64:65], v[52:53] op_sel_hi:[0,1]
	s_nop 0
	v_mul_f32_e32 v64, v66, v96
	v_mov_b32_e32 v62, v60
	v_cvt_pk_bf16_f32 v81, v74, v75
	v_pk_mul_f32 v[74:75], v[30:31], v[76:77]
	v_pk_fma_f32 v[58:59], v[32:33], v[60:61], v[58:59]
	v_mov_b32_e32 v61, v55
	v_mov_b32_e32 v76, v54
	v_mov_b32_e32 v77, v57
	v_pk_mul_f32 v[54:55], v[0:1], v[54:55]
	v_pk_mul_f32 v[50:51], v[6:7], v[50:51]
	v_pk_mul_f32 v[52:53], v[12:13], v[52:53]
	v_pk_mul_f32 v[46:47], v[64:65], v[46:47] op_sel_hi:[0,1]
	v_pk_mul_f32 v[48:49], v[64:65], v[48:49] op_sel_hi:[0,1]
	s_nop 0
	v_mul_f32_e32 v64, v66, v80
	v_mov_b32_e32 v60, v56
	global_store_dword v[34:35], v78, off offset:128
	v_pk_fma_f32 v[62:63], v[28:29], v[62:63], v[74:75] neg_lo:[0,0,1] neg_hi:[0,0,1]
	v_cvt_pk_bf16_f32 v78, v58, v59
	v_pk_mul_f32 v[58:59], v[30:31], v[76:77]
	v_pk_fma_f32 v[54:55], v[32:33], v[56:57], v[54:55]
	v_mov_b32_e32 v57, v51
	v_mov_b32_e32 v74, v50
	v_mov_b32_e32 v75, v53
	v_pk_mul_f32 v[50:51], v[0:1], v[50:51]
	v_pk_mul_f32 v[46:47], v[6:7], v[46:47]
	v_pk_mul_f32 v[48:49], v[12:13], v[48:49]
	v_pk_mul_f32 v[42:43], v[64:65], v[42:43] op_sel_hi:[0,1]
	v_pk_mul_f32 v[44:45], v[64:65], v[44:45] op_sel_hi:[0,1]
	s_nop 0
	v_mul_f32_e32 v64, v66, v102
	v_mov_b32_e32 v56, v52
	global_store_dword v[34:35], v81, off
	v_pk_fma_f32 v[34:35], v[28:29], v[60:61], v[58:59] neg_lo:[0,0,1] neg_hi:[0,0,1]
	v_cvt_pk_bf16_f32 v61, v54, v55
	v_pk_mul_f32 v[54:55], v[30:31], v[74:75]
	v_pk_fma_f32 v[50:51], v[32:33], v[52:53], v[50:51]
	v_mov_b32_e32 v53, v47
	v_mov_b32_e32 v58, v46
	v_mov_b32_e32 v59, v49
	v_pk_mul_f32 v[46:47], v[0:1], v[46:47]
	v_pk_mul_f32 v[42:43], v[6:7], v[42:43]
	v_pk_mul_f32 v[44:45], v[12:13], v[44:45]
	v_pk_mul_f32 v[38:39], v[64:65], v[38:39] op_sel_hi:[0,1]
	v_pk_mul_f32 v[40:41], v[64:65], v[40:41] op_sel_hi:[0,1]
	s_nop 0
	v_mul_f32_e32 v60, v66, v105
	v_cvt_pk_bf16_f32 v62, v62, v63
	v_mov_b32_e32 v52, v48
	v_cvt_pk_bf16_f32 v63, v34, v35
	v_pk_fma_f32 v[34:35], v[28:29], v[56:57], v[54:55] neg_lo:[0,0,1] neg_hi:[0,0,1]
	v_cvt_pk_bf16_f32 v56, v50, v51
	v_pk_mul_f32 v[50:51], v[30:31], v[58:59]
	v_pk_fma_f32 v[46:47], v[32:33], v[48:49], v[46:47]
	v_mov_b32_e32 v49, v43
	v_mov_b32_e32 v54, v42
	v_mov_b32_e32 v55, v45
	v_pk_mul_f32 v[42:43], v[0:1], v[42:43]
	v_pk_mul_f32 v[38:39], v[6:7], v[38:39]
	v_pk_mul_f32 v[40:41], v[12:13], v[40:41]
	v_pk_mul_f32 v[2:3], v[60:61], v[2:3] op_sel_hi:[0,1]
	v_pk_mul_f32 v[36:37], v[60:61], v[36:37] op_sel_hi:[0,1]
	global_store_dword v[26:27], v78, off offset:128
	v_mov_b32_e32 v48, v44
	global_store_dword v[26:27], v62, off
	global_store_dword v[24:25], v61, off offset:128
	v_cvt_pk_bf16_f32 v57, v34, v35
	v_pk_fma_f32 v[26:27], v[28:29], v[52:53], v[50:51] neg_lo:[0,0,1] neg_hi:[0,0,1]
	v_cvt_pk_bf16_f32 v50, v46, v47
	v_pk_mul_f32 v[34:35], v[30:31], v[54:55]
	v_pk_fma_f32 v[42:43], v[32:33], v[44:45], v[42:43]
	v_mov_b32_e32 v45, v39
	v_mov_b32_e32 v46, v38
	v_mov_b32_e32 v47, v41
	v_pk_mul_f32 v[38:39], v[0:1], v[38:39]
	v_pk_mul_f32 v[2:3], v[6:7], v[2:3]
	v_pk_mul_f32 v[36:37], v[12:13], v[36:37]
	v_mov_b32_e32 v44, v40
	global_store_dword v[24:25], v63, off
	global_store_dword v[18:19], v56, off offset:128
	v_cvt_pk_bf16_f32 v51, v26, v27
	v_pk_fma_f32 v[24:25], v[28:29], v[48:49], v[34:35] neg_lo:[0,0,1] neg_hi:[0,0,1]
	v_pk_mul_f32 v[26:27], v[30:31], v[46:47]
	v_pk_fma_f32 v[34:35], v[32:33], v[40:41], v[38:39]
	v_mov_b32_e32 v40, v2
	v_mov_b32_e32 v41, v37
	v_mov_b32_e32 v38, v36
	v_mov_b32_e32 v39, v3
	v_pk_mul_f32 v[0:1], v[0:1], v[2:3]
	global_store_dword v[18:19], v57, off
	global_store_dword v[14:15], v50, off offset:128
	v_pk_fma_f32 v[2:3], v[28:29], v[44:45], v[26:27] neg_lo:[0,0,1] neg_hi:[0,0,1]
	v_pk_mul_f32 v[18:19], v[30:31], v[40:41]
	v_cvt_pk_bf16_f32 v42, v42, v43
	v_cvt_pk_bf16_f32 v24, v24, v25
	v_pk_fma_f32 v[0:1], v[32:33], v[36:37], v[0:1]
	global_store_dword v[14:15], v51, off
	global_store_dword v[16:17], v42, off offset:128
	v_cvt_pk_bf16_f32 v14, v2, v3
	v_pk_fma_f32 v[2:3], v[28:29], v[38:39], v[18:19] neg_lo:[0,0,1] neg_hi:[0,0,1]
	v_cvt_pk_bf16_f32 v25, v34, v35
	v_cvt_pk_bf16_f32 v0, v0, v1
	global_store_dword v[16:17], v24, off
	global_store_dword v[20:21], v25, off offset:128
	v_cvt_pk_bf16_f32 v1, v2, v3
	global_store_dword v[20:21], v14, off
	global_store_dword v[22:23], v0, off offset:128
	global_store_dword v[22:23], v1, off
	s_cbranch_scc1 .LBB0_521

; #define LAS __attribute__((address_space(3)))
; __device__ __forceinline__ unsigned cvtpk(float lo, float hi) { f32x2 v = {lo, hi}; bf16x2_t b = __builtin_convertvector(v, bf16x2_t); return __builtin_bit_cast(unsigned, b); }
; __device__ __forceinline__ void gla_passC(const Params& p, LAS unsigned char* lds, int item, int wave, int lane) {
;     ...
;         __syncthreads();
; #pragma unroll
;         for (int ti = 0; ti < 4; ++ti)
; #pragma unroll
;             for (int jj = 0; jj < 4; ++jj) { const int tok = 16 * ti + 4 * g + jj;
;                 const f32x4 sa = *(const LAS f32x4*)(L + G_SS + tok * 32), sb = *(const LAS f32x4*)(L + G_SS + tok * 32 + 16);
;                 const float tot = ((sa.x + sa.y) + (sa.z + sa.w)) + ((sb.x + sb.y) + (sb.z + sb.w));
;                 const float rstd = 1.0f / sqrtf(tot * (1.0f / 256.0f) + EPS);
;                 *(LAS unsigned short*)(L + G_OL + tok * 528 + (32 * wave + fr) * 2) = (unsigned short)(cvtpk(oacc[ti][0][jj] * rstd * gn0, 0.f) & 0xffffu);
;                 *(LAS unsigned short*)(L + G_OL + tok * 528 + (32 * wave + 16 + fr) * 2) = (unsigned short)(cvtpk(oacc[ti][1][jj] * rstd * gn1, 0.f) & 0xffffu); }
.LBB0_720:
	s_or_b64 exec, exec, s[4:5]
	s_add_i32 s6, 0, 0x13600
	v_lshl_add_u32 v48, v79, 7, s6
	s_waitcnt lgkmcnt(0)
	s_barrier
	ds_read_b128 v[82:85], v48
	ds_read_b128 v[86:89], v48 offset:16
	v_mov_b32_e32 v90, s47
	v_mad_u32_u24 v79, v79, s48, v90
	s_lshl_b32 s2, s2, 1
	s_waitcnt lgkmcnt(1)
	v_add_f32_e32 v48, v82, v83
	v_add_f32_e32 v50, v84, v85
	v_add_f32_e32 v48, v48, v50
	s_waitcnt lgkmcnt(0)
	v_add_f32_e32 v50, v86, v87
	v_add_f32_e32 v82, v88, v89
	v_add_f32_e32 v50, v50, v82
	v_add_f32_e32 v48, v48, v50
	v_fmamk_f32 v48, v48, 0x3b800000, v64
	s_nop 1
	v_rsq_f32_e32 v48, v48
	s_nop 1
	s_nop 0
	v_mov_b32_e32 v82, v48
	v_lshlrev_b32_e32 v50, 1, v52
	v_or_b32_e32 v48, 32, v50
	s_nop 0
	v_mov_b32_e32 v52, v82
	v_mul_f32_e32 v44, v44, v52
	v_mul_f32_e32 v44, v73, v44
	v_mul_f32_e32 v40, v40, v52
	v_cvt_pk_bf16_f32 v44, v44, s0
	v_add_u32_e32 v82, v79, v50
	v_mul_f32_e32 v40, v72, v40
	ds_write_b16 v82, v44
	v_cvt_pk_bf16_f32 v40, v40, s0
	v_add_u32_e32 v44, v79, v48
	ds_write_b16 v44, v40
	v_lshl_add_u32 v40, v77, 5, s6
	ds_read_b128 v[82:85], v40
	ds_read_b128 v[86:89], v40 offset:16
	s_waitcnt lgkmcnt(1)
	v_add_f32_e32 v40, v82, v83
	v_add_f32_e32 v44, v84, v85
	v_add_f32_e32 v40, v40, v44
	s_waitcnt lgkmcnt(0)
	v_add_f32_e32 v44, v86, v87
	v_add_f32_e32 v52, v88, v89
	v_add_f32_e32 v44, v44, v52
	v_add_f32_e32 v40, v40, v44
	v_fmamk_f32 v40, v40, 0x3b800000, v64
	s_nop 1
	v_rsq_f32_e32 v40, v40
	s_nop 1
	s_nop 0
	v_mov_b32_e32 v40, v40
	s_nop 0
	v_mov_b32_e32 v44, v40
	v_mul_f32_e32 v40, v45, v44
	v_mul_f32_e32 v40, v73, v40
	v_mul_f32_e32 v41, v41, v44
	v_cvt_pk_bf16_f32 v45, v40, s0
	v_mad_u32_u24 v40, v77, s42, v90
	v_mul_f32_e32 v41, v72, v41
	v_add_u32_e32 v52, v40, v50
	v_cvt_pk_bf16_f32 v41, v41, s0
	v_add_u32_e32 v44, v40, v48
	ds_write_b16 v52, v45
	ds_write_b16 v44, v41
	v_lshl_add_u32 v41, v78, 5, s6
	ds_read_b128 v[82:85], v41
	ds_read_b128 v[86:89], v41 offset:16
	s_waitcnt lgkmcnt(1)
	v_add_f32_e32 v41, v82, v83
	v_add_f32_e32 v44, v84, v85
	v_add_f32_e32 v41, v41, v44
	s_waitcnt lgkmcnt(0)
	v_add_f32_e32 v44, v86, v87
	v_add_f32_e32 v45, v88, v89
	v_add_f32_e32 v44, v44, v45
	v_add_f32_e32 v41, v41, v44
	v_fmamk_f32 v41, v41, 0x3b800000, v64
	s_nop 1
	v_rsq_f32_e32 v41, v41
	s_nop 1
	s_nop 0
	v_mov_b32_e32 v41, v41
	s_nop 0
	v_mov_b32_e32 v41, v41
	v_mul_f32_e32 v44, v46, v41
	v_mul_f32_e32 v41, v42, v41
	v_mul_f32_e32 v44, v73, v44
	v_add_u32_e32 v45, 0x210, v40
	v_mul_f32_e32 v41, v72, v41
	v_cvt_pk_bf16_f32 v44, v44, s0
	v_add_u32_e32 v46, v45, v50
	v_cvt_pk_bf16_f32 v41, v41, s0
	v_add_u32_e32 v42, v45, v48
	ds_write_b16 v46, v44
	ds_write_b16 v42, v41
	v_lshl_add_u32 v41, v76, 5, s6
	ds_read_b128 v[76:79], v41
	ds_read_b128 v[82:85], v41 offset:16
	s_waitcnt lgkmcnt(1)
	v_add_f32_e32 v41, v76, v77
	v_add_f32_e32 v42, v78, v79
	v_add_f32_e32 v41, v41, v42
	s_waitcnt lgkmcnt(0)
	v_add_f32_e32 v42, v82, v83
	v_add_f32_e32 v44, v84, v85
	v_add_f32_e32 v42, v42, v44
	v_add_f32_e32 v41, v41, v42
	v_fmamk_f32 v41, v41, 0x3b800000, v64
	s_nop 1
	v_rsq_f32_e32 v41, v41
	s_nop 1
	s_nop 0
	v_mov_b32_e32 v41, v41
	s_nop 0
	v_mov_b32_e32 v41, v41
	v_mul_f32_e32 v42, v47, v41
	v_mul_f32_e32 v42, v73, v42
	v_add_u32_e32 v44, 0x420, v40
	v_mul_f32_e32 v41, v43, v41
	v_cvt_pk_bf16_f32 v42, v42, s0
	v_add_u32_e32 v45, v44, v50
	v_mul_f32_e32 v41, v72, v41
	ds_write_b16 v45, v42
	v_cvt_pk_bf16_f32 v41, v41, s0
	v_add_u32_e32 v42, v44, v48
	ds_write_b16 v42, v41
	v_lshl_add_u32 v41, v81, 5, s6
	ds_read_b128 v[42:45], v41
	ds_read_b128 v[76:79], v41 offset:16
	s_waitcnt lgkmcnt(1)
	v_add_f32_e32 v41, v42, v43
	v_add_f32_e32 v42, v44, v45
	v_add_f32_e32 v41, v41, v42
	s_waitcnt lgkmcnt(0)
	v_add_f32_e32 v42, v76, v77
	v_add_f32_e32 v43, v78, v79
	v_add_f32_e32 v42, v42, v43
	v_add_f32_e32 v41, v41, v42
	v_fmamk_f32 v41, v41, 0x3b800000, v64
	s_nop 1
	v_rsq_f32_e32 v41, v41
	s_nop 1
	s_nop 0
	v_mov_b32_e32 v41, v41
	s_nop 0
	v_mov_b32_e32 v41, v41
	v_mul_f32_e32 v36, v36, v41
	v_mul_f32_e32 v36, v73, v36
	v_add_u32_e32 v42, 0x1ef0, v40
	v_mul_f32_e32 v32, v32, v41
	v_cvt_pk_bf16_f32 v36, v36, s0
	v_add_u32_e32 v43, v42, v50
	v_mul_f32_e32 v32, v72, v32
	ds_write_b16 v43, v36
	v_cvt_pk_bf16_f32 v32, v32, s0
	v_add_u32_e32 v36, v42, v48
	ds_write_b16 v36, v32
	v_lshl_add_u32 v41, v75, 5, s6
	ds_read_b128 v[42:45], v41 offset:544
	ds_read_b128 v[76:79], v41 offset:560
	s_waitcnt lgkmcnt(1)
	v_add_f32_e32 v32, v42, v43
	v_add_f32_e32 v36, v44, v45
	v_add_f32_e32 v32, v32, v36
	s_waitcnt lgkmcnt(0)
	v_add_f32_e32 v36, v76, v77
	v_add_f32_e32 v42, v78, v79
	v_add_f32_e32 v36, v36, v42
	v_add_f32_e32 v32, v32, v36
	v_fmamk_f32 v32, v32, 0x3b800000, v64
	s_nop 1
	v_rsq_f32_e32 v32, v32
	s_nop 1
	s_nop 0
	v_mov_b32_e32 v32, v32
	s_nop 0
	v_mov_b32_e32 v32, v32
	v_mul_f32_e32 v36, v37, v32
	v_mul_f32_e32 v32, v33, v32
	v_mul_f32_e32 v36, v73, v36
	v_add_u32_e32 v37, 0x2100, v40
	v_mul_f32_e32 v32, v72, v32
	v_cvt_pk_bf16_f32 v36, v36, s0
	v_add_u32_e32 v42, v37, v50
	v_cvt_pk_bf16_f32 v32, v32, s0
	v_add_u32_e32 v33, v37, v48
	ds_write_b16 v42, v36
	ds_write_b16 v33, v32
	ds_read_b128 v[42:45], v41 offset:576
	ds_read_b128 v[76:79], v41 offset:592
	s_waitcnt lgkmcnt(1)
	v_add_f32_e32 v32, v42, v43
	v_add_f32_e32 v33, v44, v45
	v_add_f32_e32 v32, v32, v33
	s_waitcnt lgkmcnt(0)
	v_add_f32_e32 v33, v76, v77
	v_add_f32_e32 v36, v78, v79
	v_add_f32_e32 v33, v33, v36
	v_add_f32_e32 v32, v32, v33
	v_fmamk_f32 v32, v32, 0x3b800000, v64
	s_nop 1
	v_rsq_f32_e32 v32, v32
	s_nop 1
	s_nop 0
	v_mov_b32_e32 v32, v32
	s_nop 0
	v_mov_b32_e32 v32, v32
	v_mul_f32_e32 v33, v38, v32
	v_mul_f32_e32 v33, v73, v33
	v_add_u32_e32 v36, 0x2310, v40
	v_mul_f32_e32 v32, v34, v32
	v_cvt_pk_bf16_f32 v33, v33, s0
	v_add_u32_e32 v37, v36, v50
	v_mul_f32_e32 v32, v72, v32
	ds_write_b16 v37, v33
	v_cvt_pk_bf16_f32 v32, v32, s0
	v_add_u32_e32 v33, v36, v48
	ds_write_b16 v33, v32
	ds_read_b128 v[42:45], v41 offset:608
	ds_read_b128 v[76:79], v41 offset:624
	s_waitcnt lgkmcnt(1)
; #define LAS __attribute__((address_space(3)))
; __device__ __forceinline__ unsigned cvtpk(float lo, float hi) { f32x2 v = {lo, hi}; bf16x2_t b = __builtin_convertvector(v, bf16x2_t); return __builtin_bit_cast(unsigned, b); }
; __device__ __forceinline__ void gla_passC(const Params& p, LAS unsigned char* lds, int item, int wave, int lane) {
;     ...
;         __syncthreads();
; #pragma unroll
;         for (int ti = 0; ti < 4; ++ti)
; #pragma unroll
;             for (int jj = 0; jj < 4; ++jj) { const int tok = 16 * ti + 4 * g + jj;
;                 const f32x4 sa = *(const LAS f32x4*)(L + G_SS + tok * 32), sb = *(const LAS f32x4*)(L + G_SS + tok * 32 + 16);
;                 const float tot = ((sa.x + sa.y) + (sa.z + sa.w)) + ((sb.x + sb.y) + (sb.z + sb.w));
;                 const float rstd = 1.0f / sqrtf(tot * (1.0f / 256.0f) + EPS);
;                 *(LAS unsigned short*)(L + G_OL + tok * 528 + (32 * wave + fr) * 2) = (unsigned short)(cvtpk(oacc[ti][0][jj] * rstd * gn0, 0.f) & 0xffffu);
;                 *(LAS unsigned short*)(L + G_OL + tok * 528 + (32 * wave + 16 + fr) * 2) = (unsigned short)(cvtpk(oacc[ti][1][jj] * rstd * gn1, 0.f) & 0xffffu); }
	v_add_f32_e32 v32, v42, v43
	v_add_f32_e32 v33, v44, v45
	v_add_f32_e32 v32, v32, v33
	s_waitcnt lgkmcnt(0)
	v_add_f32_e32 v33, v76, v77
	v_add_f32_e32 v34, v78, v79
	v_add_f32_e32 v33, v33, v34
	v_add_f32_e32 v32, v32, v33
	v_fmamk_f32 v32, v32, 0x3b800000, v64
	s_nop 1
	v_rsq_f32_e32 v32, v32
	s_nop 1
	s_nop 0
	v_mov_b32_e32 v32, v32
	s_nop 0
	v_mov_b32_e32 v32, v32
	v_mul_f32_e32 v33, v39, v32
	v_mul_f32_e32 v33, v73, v33
	v_add_u32_e32 v34, 0x2520, v40
	v_mul_f32_e32 v32, v35, v32
	v_cvt_pk_bf16_f32 v33, v33, s0
	v_add_u32_e32 v36, v34, v50
	v_mul_f32_e32 v32, v72, v32
	ds_write_b16 v36, v33
	v_cvt_pk_bf16_f32 v32, v32, s0
	v_add_u32_e32 v33, v34, v48
	ds_write_b16 v33, v32
	v_lshl_add_u32 v36, v80, 5, s6
	ds_read_b128 v[32:35], v36
	ds_read_b128 v[36:39], v36 offset:16
	s_waitcnt lgkmcnt(1)
	v_add_f32_e32 v32, v32, v33
	v_add_f32_e32 v33, v34, v35
	v_add_f32_e32 v32, v32, v33
	s_waitcnt lgkmcnt(0)
	v_add_f32_e32 v33, v36, v37
	v_add_f32_e32 v34, v38, v39
	v_add_f32_e32 v33, v33, v34
	v_add_f32_e32 v32, v32, v33
	v_fmamk_f32 v32, v32, 0x3b800000, v64
	s_nop 1
	v_rsq_f32_e32 v32, v32
	s_nop 1
	s_nop 0
	v_mov_b32_e32 v32, v32
	s_nop 0
	v_mov_b32_e32 v32, v32
	v_mul_f32_e32 v28, v28, v32
	v_mul_f32_e32 v28, v73, v28
	v_add_u32_e32 v33, 0x3ff0, v40
	v_mul_f32_e32 v24, v24, v32
	v_cvt_pk_bf16_f32 v28, v28, s0
	v_add_u32_e32 v34, v33, v50
	v_mul_f32_e32 v24, v72, v24
	ds_write_b16 v34, v28
	v_cvt_pk_bf16_f32 v24, v24, s0
	v_add_u32_e32 v28, v33, v48
	ds_write_b16 v28, v24
	ds_read_b128 v[32:35], v41 offset:1056
	ds_read_b128 v[36:39], v41 offset:1072
	s_waitcnt lgkmcnt(1)
	v_add_f32_e32 v24, v32, v33
	v_add_f32_e32 v28, v34, v35
	v_add_f32_e32 v24, v24, v28
	s_waitcnt lgkmcnt(0)
	v_add_f32_e32 v28, v36, v37
	v_add_f32_e32 v32, v38, v39
	v_add_f32_e32 v28, v28, v32
	v_add_f32_e32 v24, v24, v28
	v_fmamk_f32 v24, v24, 0x3b800000, v64
	s_nop 1
	v_rsq_f32_e32 v24, v24
	s_nop 1
	s_nop 0
	v_mov_b32_e32 v24, v24
	s_nop 0
	v_mov_b32_e32 v24, v24
	v_mul_f32_e32 v28, v29, v24
	v_mul_f32_e32 v24, v25, v24
	v_mul_f32_e32 v28, v73, v28
	v_add_u32_e32 v29, 0x4200, v40
	v_mul_f32_e32 v24, v72, v24
	v_cvt_pk_bf16_f32 v28, v28, s0
	v_add_u32_e32 v32, v29, v50
	v_cvt_pk_bf16_f32 v24, v24, s0
	v_add_u32_e32 v25, v29, v48
	ds_write_b16 v32, v28
	ds_write_b16 v25, v24
	ds_read_b128 v[32:35], v41 offset:1088
	ds_read_b128 v[36:39], v41 offset:1104
	s_waitcnt lgkmcnt(1)
	v_add_f32_e32 v24, v32, v33
	v_add_f32_e32 v25, v34, v35
	v_add_f32_e32 v24, v24, v25
	s_waitcnt lgkmcnt(0)
	v_add_f32_e32 v25, v36, v37
	v_add_f32_e32 v28, v38, v39
	v_add_f32_e32 v25, v25, v28
	v_add_f32_e32 v24, v24, v25
	v_fmamk_f32 v24, v24, 0x3b800000, v64
	s_nop 1
	v_rsq_f32_e32 v24, v24
	s_nop 1
	s_nop 0
	v_mov_b32_e32 v24, v24
	s_nop 0
	v_mov_b32_e32 v24, v24
	v_mul_f32_e32 v25, v30, v24
	v_mul_f32_e32 v25, v73, v25
	v_add_u32_e32 v28, 0x4410, v40
	v_mul_f32_e32 v24, v26, v24
	v_cvt_pk_bf16_f32 v25, v25, s0
	v_add_u32_e32 v29, v28, v50
	v_mul_f32_e32 v24, v72, v24
	ds_write_b16 v29, v25
	v_cvt_pk_bf16_f32 v24, v24, s0
	v_add_u32_e32 v25, v28, v48
	ds_write_b16 v25, v24
	ds_read_b128 v[32:35], v41 offset:1120
	ds_read_b128 v[36:39], v41 offset:1136
	s_waitcnt lgkmcnt(1)
	v_add_f32_e32 v24, v32, v33
	v_add_f32_e32 v25, v34, v35
	v_add_f32_e32 v24, v24, v25
	s_waitcnt lgkmcnt(0)
	v_add_f32_e32 v25, v36, v37
	v_add_f32_e32 v26, v38, v39
	v_add_f32_e32 v25, v25, v26
	v_add_f32_e32 v24, v24, v25
	v_fmamk_f32 v24, v24, 0x3b800000, v64
	s_nop 1
	v_rsq_f32_e32 v24, v24
	s_nop 1
	s_nop 0
	v_mov_b32_e32 v24, v24
	s_nop 0
	v_mov_b32_e32 v24, v24
	v_mul_f32_e32 v25, v31, v24
	v_mul_f32_e32 v25, v73, v25
	v_add_u32_e32 v26, 0x4620, v40
	v_mul_f32_e32 v24, v27, v24
	v_cvt_pk_bf16_f32 v25, v25, s0
	v_add_u32_e32 v28, v26, v50
	v_mul_f32_e32 v24, v72, v24
	ds_write_b16 v28, v25
	v_cvt_pk_bf16_f32 v24, v24, s0
	v_add_u32_e32 v25, v26, v48
	ds_write_b16 v25, v24
	v_lshl_add_u32 v28, v51, 5, s6
	ds_read_b128 v[24:27], v28
	ds_read_b128 v[28:31], v28 offset:16
	s_waitcnt lgkmcnt(1)
	v_add_f32_e32 v24, v24, v25
	v_add_f32_e32 v25, v26, v27
	v_add_f32_e32 v24, v24, v25
	s_waitcnt lgkmcnt(0)
	v_add_f32_e32 v25, v28, v29
	v_add_f32_e32 v26, v30, v31
	v_add_f32_e32 v25, v25, v26
	v_add_f32_e32 v24, v24, v25
	v_fmamk_f32 v24, v24, 0x3b800000, v64
	s_nop 1
	v_rsq_f32_e32 v24, v24
	s_nop 1
	s_nop 0
	v_mov_b32_e32 v24, v24
	s_nop 0
	v_mov_b32_e32 v24, v24
	v_mul_f32_e32 v20, v20, v24
	v_mul_f32_e32 v20, v73, v20
	v_add_u32_e32 v25, 0x60f0, v40
	v_mul_f32_e32 v16, v16, v24
	v_cvt_pk_bf16_f32 v20, v20, s0
	v_add_u32_e32 v26, v25, v50
	v_mul_f32_e32 v16, v72, v16
	ds_write_b16 v26, v20
	v_cvt_pk_bf16_f32 v16, v16, s0
	v_add_u32_e32 v20, v25, v48
	ds_write_b16 v20, v16
	ds_read_b128 v[24:27], v41 offset:1568
	ds_read_b128 v[28:31], v41 offset:1584
	s_waitcnt lgkmcnt(1)
	v_add_f32_e32 v16, v24, v25
	v_add_f32_e32 v20, v26, v27
	v_add_f32_e32 v16, v16, v20
	s_waitcnt lgkmcnt(0)
	v_add_f32_e32 v20, v28, v29
	v_add_f32_e32 v24, v30, v31
	v_add_f32_e32 v20, v20, v24
	v_add_f32_e32 v16, v16, v20
	v_fmamk_f32 v16, v16, 0x3b800000, v64
	s_nop 1
	v_rsq_f32_e32 v16, v16
	s_nop 1
	s_nop 0
	v_mov_b32_e32 v16, v16
	s_nop 0
	v_mov_b32_e32 v16, v16
	v_mul_f32_e32 v20, v21, v16
	v_mul_f32_e32 v16, v17, v16
	v_mul_f32_e32 v20, v73, v20
	v_add_u32_e32 v21, 0x6300, v40
	v_mul_f32_e32 v16, v72, v16
	v_cvt_pk_bf16_f32 v20, v20, s0
	v_add_u32_e32 v24, v21, v50
	v_cvt_pk_bf16_f32 v16, v16, s0
	v_add_u32_e32 v17, v21, v48
	ds_write_b16 v24, v20
	ds_write_b16 v17, v16
	ds_read_b128 v[24:27], v41 offset:1600
	ds_read_b128 v[28:31], v41 offset:1616
	s_waitcnt lgkmcnt(1)
	v_add_f32_e32 v16, v24, v25
	v_add_f32_e32 v17, v26, v27
	v_add_f32_e32 v16, v16, v17
	s_waitcnt lgkmcnt(0)
; #define LAS __attribute__((address_space(3)))
; __device__ __forceinline__ unsigned cvtpk(float lo, float hi) { f32x2 v = {lo, hi}; bf16x2_t b = __builtin_convertvector(v, bf16x2_t); return __builtin_bit_cast(unsigned, b); }
; __device__ __forceinline__ float fexp(float x) { return __builtin_amdgcn_exp2f(x * 1.44269504089f); }
; __device__ __forceinline__ void gla_passC(const Params& p, LAS unsigned char* lds, int item, int wave, int lane) {
;     ...
;         __syncthreads();
; #pragma unroll
;         for (int ti = 0; ti < 4; ++ti)
; #pragma unroll
;             for (int jj = 0; jj < 4; ++jj) { const int tok = 16 * ti + 4 * g + jj;
;                 const f32x4 sa = *(const LAS f32x4*)(L + G_SS + tok * 32), sb = *(const LAS f32x4*)(L + G_SS + tok * 32 + 16);
;                 const float tot = ((sa.x + sa.y) + (sa.z + sa.w)) + ((sb.x + sb.y) + (sb.z + sb.w));
;                 const float rstd = 1.0f / sqrtf(tot * (1.0f / 256.0f) + EPS);
;                 *(LAS unsigned short*)(L + G_OL + tok * 528 + (32 * wave + fr) * 2) = (unsigned short)(cvtpk(oacc[ti][0][jj] * rstd * gn0, 0.f) & 0xffffu);
;                 *(LAS unsigned short*)(L + G_OL + tok * 528 + (32 * wave + 16 + fr) * 2) = (unsigned short)(cvtpk(oacc[ti][1][jj] * rstd * gn1, 0.f) & 0xffffu); }
;         __syncthreads();
; #pragma unroll
;         for (int i = 0; i < 4; ++i) { const int ci = tid + 512 * i, row = ci >> 5, cc = ci & 31;
;             const u32x4 ov = *(const LAS u32x4*)(L + G_OL + row * 528 + cc * 16); const u32x4 rv = prg[i]; u32x4 w;
; #pragma unroll
;             for (int e = 0; e < 4; ++e) { const float r0 = bflo(rv[e]), r1 = bfhi(rv[e]);
;                 const float s0 = r0 * __builtin_amdgcn_rcpf(1.0f + fexp(-r0)), s1 = r1 * __builtin_amdgcn_rcpf(1.0f + fexp(-r1));
;                 w[e] = cvtpk(bflo(ov[e]) * s0, bfhi(ov[e]) * s1); }
;             *(u32x4*)(OA + (m0 + row) * DM + h * 256 + 8 * cc) = w; }
	v_add_f32_e32 v17, v28, v29
	v_add_f32_e32 v20, v30, v31
	v_add_f32_e32 v17, v17, v20
	v_add_f32_e32 v16, v16, v17
	v_fmamk_f32 v16, v16, 0x3b800000, v64
	s_nop 1
	v_rsq_f32_e32 v16, v16
	s_nop 1
	s_nop 0
	v_mov_b32_e32 v16, v16
	s_nop 0
	v_mov_b32_e32 v16, v16
	v_mul_f32_e32 v17, v22, v16
	v_mul_f32_e32 v17, v73, v17
	v_add_u32_e32 v20, 0x6510, v40
	v_mul_f32_e32 v16, v18, v16
	v_cvt_pk_bf16_f32 v17, v17, s0
	v_add_u32_e32 v21, v20, v50
	v_mul_f32_e32 v16, v72, v16
	ds_write_b16 v21, v17
	v_cvt_pk_bf16_f32 v16, v16, s0
	v_add_u32_e32 v17, v20, v48
	ds_write_b16 v17, v16
	v_add_u32_e32 v16, s6, v49
	ds_read_b128 v[24:27], v16
	ds_read_b128 v[28:31], v16 offset:16
	s_waitcnt lgkmcnt(1)
	v_add_f32_e32 v16, v24, v25
	v_add_f32_e32 v17, v26, v27
	v_add_f32_e32 v16, v16, v17
	s_waitcnt lgkmcnt(0)
	v_add_f32_e32 v17, v28, v29
	v_add_f32_e32 v18, v30, v31
	v_add_f32_e32 v17, v17, v18
	v_add_f32_e32 v16, v16, v17
	v_fmamk_f32 v16, v16, 0x3b800000, v64
	s_waitcnt vmcnt(3)
	v_lshlrev_b32_e32 v28, 16, v13
	v_and_b32_e32 v29, 0xffff0000, v13
	v_rsq_f32_e32 v16, v16
	s_nop 1
	s_nop 0
	v_mov_b32_e32 v16, v16
	s_add_u32 s4, s36, s2
	s_addc_u32 s5, s37, 0
	s_add_i32 s49, s49, s70
	s_nop 0
	v_mov_b32_e32 v16, v16
	v_mul_f32_e32 v17, v23, v16
	v_mul_f32_e32 v17, v73, v17
	v_add_u32_e32 v18, 0x6720, v40
	v_mul_f32_e32 v16, v19, v16
	v_cvt_pk_bf16_f32 v17, v17, s0
	v_add_u32_e32 v20, v18, v50
	v_mul_f32_e32 v16, v72, v16
	ds_write_b16 v20, v17
	v_cvt_pk_bf16_f32 v16, v16, s0
	v_add_u32_e32 v17, v18, v48
	v_lshlrev_b32_e32 v22, 16, v12
	ds_write_b16 v17, v16
	v_lshlrev_b32_e32 v16, 4, v70
	v_and_b32_e32 v23, 0xffff0000, v12
	v_mul_f32_e32 v12, 0xbfb8aa3b, v22
	v_and_b32_e32 v52, 0x1f0, v16
	v_exp_f32_e32 v12, v12
	v_mul_f32_e32 v16, 0xbfb8aa3b, v23
	v_exp_f32_e32 v16, v16
	v_add_u32_e32 v32, s47, v52
	v_add_f32_e32 v12, 1.0, v12
	v_rcp_f32_e32 v24, v12
	v_add_f32_e32 v12, 1.0, v16
	v_rcp_f32_e32 v25, v12
	v_add_u32_e32 v12, v32, v74
	s_waitcnt lgkmcnt(0)
	s_barrier
	ds_read_b128 v[18:21], v12
	v_mul_f32_e32 v12, 0xbfb8aa3b, v28
	v_exp_f32_e32 v13, v12
	v_mul_f32_e32 v12, 0xbfb8aa3b, v29
	v_exp_f32_e32 v31, v12
	v_add_u32_e32 v12, v32, v71
	v_add_f32_e32 v13, 1.0, v13
	v_rcp_f32_e32 v30, v13
	v_add_f32_e32 v13, 1.0, v31
	v_rcp_f32_e32 v31, v13
	v_pk_mul_f32 v[26:27], v[24:25], v[22:23]
	ds_read_b128 v[22:25], v12
	s_waitcnt lgkmcnt(1)
	v_lshlrev_b32_e32 v12, 16, v18
	v_and_b32_e32 v13, 0xffff0000, v18
	v_pk_mul_f32 v[12:13], v[26:27], v[12:13]
	v_pk_mul_f32 v[26:27], v[30:31], v[28:29]
	v_lshlrev_b32_e32 v28, 16, v14
	v_cvt_pk_bf16_f32 v12, v12, v13
	v_and_b32_e32 v29, 0xffff0000, v14
	v_mul_f32_e32 v13, 0xbfb8aa3b, v28
	v_exp_f32_e32 v13, v13
	v_mul_f32_e32 v14, 0xbfb8aa3b, v29
	v_exp_f32_e32 v14, v14
	v_lshlrev_b32_e32 v18, 16, v19
	v_add_f32_e32 v13, 1.0, v13
	v_rcp_f32_e32 v30, v13
	v_add_f32_e32 v13, 1.0, v14
	v_rcp_f32_e32 v31, v13
	v_and_b32_e32 v19, 0xffff0000, v19
	v_pk_mul_f32 v[18:19], v[26:27], v[18:19]
	v_lshlrev_b32_e32 v26, 16, v15
	v_and_b32_e32 v27, 0xffff0000, v15
	v_mul_f32_e32 v14, 0xbfb8aa3b, v26
	v_exp_f32_e32 v15, v14
	v_mul_f32_e32 v14, 0xbfb8aa3b, v27
	v_cvt_pk_bf16_f32 v13, v18, v19
	v_pk_mul_f32 v[18:19], v[30:31], v[28:29]
	v_exp_f32_e32 v29, v14
	v_add_f32_e32 v15, 1.0, v15
	v_rcp_f32_e32 v28, v15
	v_lshlrev_b32_e32 v14, 16, v20
	v_add_f32_e32 v15, 1.0, v29
	v_rcp_f32_e32 v29, v15
	v_and_b32_e32 v15, 0xffff0000, v20
	v_pk_mul_f32 v[14:15], v[18:19], v[14:15]
	v_lshlrev_b32_e32 v20, 16, v21
	v_pk_mul_f32 v[18:19], v[28:29], v[26:27]
	v_and_b32_e32 v21, 0xffff0000, v21
	v_pk_mul_f32 v[18:19], v[18:19], v[20:21]
	s_waitcnt vmcnt(2)
	v_lshlrev_b32_e32 v20, 16, v8
	v_and_b32_e32 v21, 0xffff0000, v8
	v_mul_f32_e32 v8, 0xbfb8aa3b, v20
	v_cvt_pk_bf16_f32 v14, v14, v15
	v_exp_f32_e32 v8, v8
	v_mul_f32_e32 v15, 0xbfb8aa3b, v21
	v_exp_f32_e32 v26, v15
	v_lshl_add_u64 v[16:17], s[4:5], 0, v[52:53]
	v_add_f32_e32 v8, 1.0, v8
	v_cvt_pk_bf16_f32 v15, v18, v19
	v_rcp_f32_e32 v18, v8
	v_add_f32_e32 v8, 1.0, v26
	v_lshlrev_b64 v[26:27], 12, v[62:63]
	v_rcp_f32_e32 v19, v8
	v_lshl_add_u64 v[26:27], v[16:17], 0, v[26:27]
	global_store_dwordx4 v[26:27], v[12:15], off
	s_add_i32 s38, s38, s39
	s_add_u32 s24, s24, s26
	v_lshlrev_b32_e32 v14, 16, v9
	v_and_b32_e32 v15, 0xffff0000, v9
	v_mul_f32_e32 v8, 0xbfb8aa3b, v14
	v_exp_f32_e32 v9, v8
	v_mul_f32_e32 v8, 0xbfb8aa3b, v15
	v_pk_mul_f32 v[12:13], v[18:19], v[20:21]
	v_exp_f32_e32 v19, v8
	v_add_f32_e32 v9, 1.0, v9
	v_rcp_f32_e32 v18, v9
	s_waitcnt lgkmcnt(0)
; #define LAS __attribute__((address_space(3)))
; __device__ __forceinline__ unsigned cvtpk(float lo, float hi) { f32x2 v = {lo, hi}; bf16x2_t b = __builtin_convertvector(v, bf16x2_t); return __builtin_bit_cast(unsigned, b); }
; __device__ __forceinline__ float fexp(float x) { return __builtin_amdgcn_exp2f(x * 1.44269504089f); }
; __device__ __forceinline__ void gla_passC(const Params& p, LAS unsigned char* lds, int item, int wave, int lane) {
;     ...
; #pragma unroll
;         for (int i = 0; i < 4; ++i) { const int ci = tid + 512 * i, row = ci >> 5, cc = ci & 31;
;             const u32x4 ov = *(const LAS u32x4*)(L + G_OL + row * 528 + cc * 16); const u32x4 rv = prg[i]; u32x4 w;
; #pragma unroll
;             for (int e = 0; e < 4; ++e) { const float r0 = bflo(rv[e]), r1 = bfhi(rv[e]);
;                 const float s0 = r0 * __builtin_amdgcn_rcpf(1.0f + fexp(-r0)), s1 = r1 * __builtin_amdgcn_rcpf(1.0f + fexp(-r1));
;                 w[e] = cvtpk(bflo(ov[e]) * s0, bfhi(ov[e]) * s1); }
;             *(u32x4*)(OA + (m0 + row) * DM + h * 256 + 8 * cc) = w; }
	v_lshlrev_b32_e32 v8, 16, v22
	v_add_f32_e32 v9, 1.0, v19
	v_rcp_f32_e32 v19, v9
	v_and_b32_e32 v9, 0xffff0000, v22
	v_pk_mul_f32 v[8:9], v[12:13], v[8:9]
	s_addc_u32 s25, s25, s27
	v_pk_mul_f32 v[12:13], v[18:19], v[14:15]
	v_lshlrev_b32_e32 v14, 16, v10
	v_cvt_pk_bf16_f32 v8, v8, v9
	v_and_b32_e32 v15, 0xffff0000, v10
	v_mul_f32_e32 v9, 0xbfb8aa3b, v14
	v_exp_f32_e32 v9, v9
	v_mul_f32_e32 v10, 0xbfb8aa3b, v15
	v_exp_f32_e32 v10, v10
	v_lshlrev_b32_e32 v18, 16, v23
	v_add_f32_e32 v9, 1.0, v9
	v_rcp_f32_e32 v20, v9
	v_add_f32_e32 v9, 1.0, v10
	v_rcp_f32_e32 v21, v9
	v_and_b32_e32 v19, 0xffff0000, v23
	v_pk_mul_f32 v[12:13], v[12:13], v[18:19]
	s_cmpk_gt_i32 s49, 0x3ff
	v_cvt_pk_bf16_f32 v9, v12, v13
	v_pk_mul_f32 v[12:13], v[20:21], v[14:15]
	v_lshlrev_b32_e32 v14, 16, v11
	v_and_b32_e32 v15, 0xffff0000, v11
	v_mul_f32_e32 v10, 0xbfb8aa3b, v14
	v_exp_f32_e32 v11, v10
	v_mul_f32_e32 v10, 0xbfb8aa3b, v15
	v_exp_f32_e32 v19, v10
	v_lshlrev_b32_e32 v10, 16, v24
	v_add_f32_e32 v11, 1.0, v11
	v_rcp_f32_e32 v18, v11
	v_add_f32_e32 v11, 1.0, v19
	v_rcp_f32_e32 v19, v11
	v_and_b32_e32 v11, 0xffff0000, v24
	v_pk_mul_f32 v[10:11], v[12:13], v[10:11]
	s_waitcnt vmcnt(2)
	v_lshlrev_b32_e32 v20, 16, v5
	v_pk_mul_f32 v[12:13], v[18:19], v[14:15]
	v_lshlrev_b32_e32 v14, 16, v25
	v_and_b32_e32 v15, 0xffff0000, v25
	v_pk_mul_f32 v[12:13], v[12:13], v[14:15]
	v_lshlrev_b32_e32 v14, 16, v4
	v_and_b32_e32 v15, 0xffff0000, v4
	v_mul_f32_e32 v4, 0xbfb8aa3b, v14
	v_exp_f32_e32 v4, v4
	v_mul_f32_e32 v18, 0xbfb8aa3b, v15
	v_exp_f32_e32 v19, v18
	v_cvt_pk_bf16_f32 v10, v10, v11
	v_add_f32_e32 v4, 1.0, v4
	v_cvt_pk_bf16_f32 v11, v12, v13
	v_lshlrev_b64 v[12:13], 12, v[60:61]
	v_rcp_f32_e32 v18, v4
	v_add_f32_e32 v4, 1.0, v19
	v_lshl_add_u64 v[12:13], v[16:17], 0, v[12:13]
	v_rcp_f32_e32 v19, v4
	v_add_u32_e32 v4, v32, v69
	global_store_dwordx4 v[12:13], v[8:11], off
	ds_read_b128 v[8:11], v4
	v_and_b32_e32 v21, 0xffff0000, v5
	v_mul_f32_e32 v4, 0xbfb8aa3b, v20
	v_exp_f32_e32 v5, v4
	v_mul_f32_e32 v4, 0xbfb8aa3b, v21
	v_exp_f32_e32 v23, v4
	v_add_u32_e32 v4, v32, v68
	v_add_f32_e32 v5, 1.0, v5
	v_rcp_f32_e32 v22, v5
	v_add_f32_e32 v5, 1.0, v23
	v_rcp_f32_e32 v23, v5
	v_pk_mul_f32 v[18:19], v[18:19], v[14:15]
	ds_read_b128 v[12:15], v4
	s_waitcnt lgkmcnt(1)
	v_lshlrev_b32_e32 v4, 16, v8
	v_and_b32_e32 v5, 0xffff0000, v8
	v_pk_mul_f32 v[4:5], v[18:19], v[4:5]
	v_pk_mul_f32 v[18:19], v[22:23], v[20:21]
	v_lshlrev_b32_e32 v20, 16, v6
	v_cvt_pk_bf16_f32 v4, v4, v5
	v_and_b32_e32 v21, 0xffff0000, v6
	v_mul_f32_e32 v5, 0xbfb8aa3b, v20
	v_exp_f32_e32 v5, v5
	v_mul_f32_e32 v6, 0xbfb8aa3b, v21
	v_exp_f32_e32 v6, v6
	v_lshlrev_b32_e32 v8, 16, v9
	v_add_f32_e32 v5, 1.0, v5
	v_rcp_f32_e32 v22, v5
	v_add_f32_e32 v5, 1.0, v6
	v_rcp_f32_e32 v23, v5
	v_and_b32_e32 v9, 0xffff0000, v9
	v_pk_mul_f32 v[8:9], v[18:19], v[8:9]
	v_lshlrev_b32_e32 v18, 16, v7
	v_and_b32_e32 v19, 0xffff0000, v7
	v_mul_f32_e32 v6, 0xbfb8aa3b, v18
	v_exp_f32_e32 v7, v6
	v_mul_f32_e32 v6, 0xbfb8aa3b, v19
	v_cvt_pk_bf16_f32 v5, v8, v9
	v_pk_mul_f32 v[8:9], v[22:23], v[20:21]
	v_exp_f32_e32 v21, v6
	v_add_f32_e32 v7, 1.0, v7
	v_rcp_f32_e32 v20, v7
	v_lshlrev_b32_e32 v6, 16, v10
	v_add_f32_e32 v7, 1.0, v21
	v_rcp_f32_e32 v21, v7
	v_and_b32_e32 v7, 0xffff0000, v10
	v_pk_mul_f32 v[6:7], v[8:9], v[6:7]
	v_lshlrev_b32_e32 v10, 16, v11
	v_pk_mul_f32 v[8:9], v[20:21], v[18:19]
	v_and_b32_e32 v11, 0xffff0000, v11
	v_pk_mul_f32 v[8:9], v[8:9], v[10:11]
	s_waitcnt vmcnt(2)
	v_lshlrev_b32_e32 v10, 16, v0
	v_and_b32_e32 v11, 0xffff0000, v0
	v_mul_f32_e32 v0, 0xbfb8aa3b, v10
	v_cvt_pk_bf16_f32 v6, v6, v7
	v_exp_f32_e32 v0, v0
	v_mul_f32_e32 v7, 0xbfb8aa3b, v11
	v_exp_f32_e32 v18, v7
	v_cvt_pk_bf16_f32 v7, v8, v9
	v_add_f32_e32 v0, 1.0, v0
	v_rcp_f32_e32 v8, v0
	v_add_f32_e32 v0, 1.0, v18
	v_lshlrev_b64 v[18:19], 12, v[58:59]
	v_rcp_f32_e32 v9, v0
	v_lshl_add_u64 v[18:19], v[16:17], 0, v[18:19]
	global_store_dwordx4 v[18:19], v[4:7], off
	s_nop 1
	v_lshlrev_b32_e32 v6, 16, v1
	v_and_b32_e32 v7, 0xffff0000, v1
	v_mul_f32_e32 v0, 0xbfb8aa3b, v6
	v_exp_f32_e32 v1, v0
	v_mul_f32_e32 v0, 0xbfb8aa3b, v7
	v_pk_mul_f32 v[4:5], v[8:9], v[10:11]
	v_exp_f32_e32 v9, v0
	v_add_f32_e32 v1, 1.0, v1
	v_rcp_f32_e32 v8, v1
	s_waitcnt lgkmcnt(0)
	v_lshlrev_b32_e32 v0, 16, v12
	v_add_f32_e32 v1, 1.0, v9
	v_rcp_f32_e32 v9, v1
	v_and_b32_e32 v1, 0xffff0000, v12
	v_pk_mul_f32 v[0:1], v[4:5], v[0:1]
	v_pk_mul_f32 v[4:5], v[8:9], v[6:7]
	v_lshlrev_b32_e32 v6, 16, v2
	v_cvt_pk_bf16_f32 v0, v0, v1
	v_and_b32_e32 v7, 0xffff0000, v2
	v_mul_f32_e32 v1, 0xbfb8aa3b, v6
	v_exp_f32_e32 v1, v1
	v_mul_f32_e32 v2, 0xbfb8aa3b, v7
	v_exp_f32_e32 v2, v2
	v_lshlrev_b32_e32 v8, 16, v13
	v_add_f32_e32 v1, 1.0, v1
	v_rcp_f32_e32 v10, v1
	v_add_f32_e32 v1, 1.0, v2
	v_rcp_f32_e32 v11, v1
	v_and_b32_e32 v9, 0xffff0000, v13
	v_pk_mul_f32 v[4:5], v[4:5], v[8:9]
	s_nop 0
	v_cvt_pk_bf16_f32 v1, v4, v5
	v_pk_mul_f32 v[4:5], v[10:11], v[6:7]
	v_lshlrev_b32_e32 v6, 16, v3
	v_and_b32_e32 v7, 0xffff0000, v3
	v_mul_f32_e32 v2, 0xbfb8aa3b, v6
	v_exp_f32_e32 v3, v2
	v_mul_f32_e32 v2, 0xbfb8aa3b, v7
	v_exp_f32_e32 v9, v2
	v_lshlrev_b32_e32 v2, 16, v14
	v_add_f32_e32 v3, 1.0, v3
	v_rcp_f32_e32 v8, v3
	v_add_f32_e32 v3, 1.0, v9
	v_rcp_f32_e32 v9, v3
	v_and_b32_e32 v3, 0xffff0000, v14
	v_pk_mul_f32 v[2:3], v[4:5], v[2:3]
	v_pk_mul_f32 v[4:5], v[8:9], v[6:7]
	v_lshlrev_b32_e32 v6, 16, v15
	v_and_b32_e32 v7, 0xffff0000, v15
	v_pk_mul_f32 v[4:5], v[4:5], v[6:7]
	v_cvt_pk_bf16_f32 v2, v2, v3
	v_cvt_pk_bf16_f32 v3, v4, v5
	v_lshlrev_b64 v[4:5], 12, v[56:57]
	v_lshl_add_u64 v[4:5], v[16:17], 0, v[4:5]
	global_store_dwordx4 v[4:5], v[0:3], off
	s_cbranch_scc1 .LBB0_757

; #define LAS __attribute__((address_space(3)))
; __device__ __forceinline__ unsigned cvtpk(float lo, float hi) { f32x2 v = {lo, hi}; bf16x2_t b = __builtin_convertvector(v, bf16x2_t); return __builtin_bit_cast(unsigned, b); }
; __device__ __forceinline__ f32x4 mfma16(bf16x8 a, bf16x8 b, f32x4 c) { return __builtin_amdgcn_mfma_f32_16x16x32_bf16(a, b, c, 0, 0, 0); }
; __device__ __forceinline__ void gla_passC(const Params& p, LAS unsigned char* lds, int item, int wave, int lane) {
;     ...
; #pragma unroll
;                 for (int jj = 0; jj < 4; ++jj) { float v = acc[jj];
;                     if (tj > ti || (tj == ti && fr > 4 * g + jj)) v = 0.f;
;                     *(LAS unsigned short*)(L + G_PL + (16 * ti + 4 * g + jj) * 144 + (16 * tj + fr) * 2) = (unsigned short)(cvtpk(v, 0.f) & 0xffffu); }
;             }
;         }
;         __syncthreads();
;         f32x4 oacc[4][2];
; #pragma unroll
;         for (int ti = 0; ti < 4; ++ti) { oacc[ti][0] = (f32x4){0.f, 0.f, 0.f, 0.f}; oacc[ti][1] = (f32x4){0.f, 0.f, 0.f, 0.f}; }
;         bf16x8 vB[2][2];
; #pragma unroll
;         for (int ks = 0; ks < 2; ++ks)
; #pragma unroll
;             for (int dvi = 0; dvi < 2; ++dvi) { const LAS unsigned char* ap = L + G_VL + (32 * ks + 8 * g + (fr >> 2)) * 528 + (32 * wave + 16 * dvi + 4 * (fr & 3)) * 2;
;                 vB[ks][dvi] = cat8(vtr(ap), vtr(ap + 4 * 528)); }
; #pragma unroll
;         for (int ti = 0; ti < 4; ++ti)
; #pragma unroll
;             for (int ks = 0; ks < 2; ++ks) { if (32 * ks > 16 * ti + 15) continue;
;                 const bf16x8 a = *(const LAS bf16x8*)(L + G_PL + (16 * ti + fr) * 144 + (32 * ks + 8 * g) * 2);
;                 oacc[ti][0] = mfma16(a, vB[ks][0], oacc[ti][0]); oacc[ti][1] = mfma16(a, vB[ks][1], oacc[ti][1]); }
;         __builtin_amdgcn_sched_barrier(0);
; #pragma unroll
;         for (int ks = 0; ks < 4; ++ks) {
; #pragma unroll
;             for (int ti = 0; ti < 4; ++ti) {
;                 const s16x4 qa = *(const LAS s16x4*)(L + G_QL + (16 * ti + fr) * 272 + (32 * ks + 4 * g) * 2);
;                 const s16x4 qb = *(const LAS s16x4*)(L + G_QL + (16 * ti + fr) * 272 + (32 * ks + 16 + 4 * g) * 2);
;                 const bf16x8 a = cat8(qa, qb);
;                 oacc[ti][0] = mfma16(a, sbf[ks][0], oacc[ti][0]); oacc[ti][1] = mfma16(a, sbf[ks][1], oacc[ti][1]); }
;         }
.LBB0_725:
	s_and_b64 s[4:5], s[22:23], s[4:5]
	s_nop 6
	v_cvt_pk_bf16_f32 v44, v44, s0
	s_or_b64 s[4:5], s[18:19], s[4:5]
	v_cndmask_b32_e64 v44, v44, 0, s[4:5]
	v_add3_u32 v82, v83, s34, v84
	s_and_b64 s[4:5], s[22:23], s[6:7]
	ds_write_b16 v82, v44
	v_cvt_pk_bf16_f32 v44, v45, s0
	s_or_b64 s[4:5], s[18:19], s[4:5]
	v_cndmask_b32_e64 v44, v44, 0, s[4:5]
	s_and_b64 s[4:5], s[22:23], s[8:9]
	ds_write_b16 v82, v44 offset:144
	v_cvt_pk_bf16_f32 v44, v46, s0
	s_or_b64 s[4:5], s[18:19], s[4:5]
	v_cndmask_b32_e64 v44, v44, 0, s[4:5]
	s_and_b64 s[4:5], s[22:23], s[10:11]
	ds_write_b16 v82, v44 offset:288
	v_cvt_pk_bf16_f32 v44, v47, s0
	s_or_b64 s[4:5], s[18:19], s[4:5]
	v_cndmask_b32_e64 v44, v44, 0, s[4:5]
	ds_write_b16 v82, v44 offset:432
	v_lshlrev_b32_e32 v126, 3, v79
	v_lshrrev_b32_e32 v44, 2, v80
	v_or_b32_e32 v82, v126, v44
	v_lshlrev_b32_e32 v44, 2, v70
	v_and_or_b32 v44, v44, 12, s28
	v_lshlrev_b32_e32 v83, 1, v44
	v_mul_u32_u24_e32 v44, 0x90, v80
	v_mul_u32_u24_e32 v82, 0x210, v82
	v_add3_u32 v81, s44, v81, v44
	v_add3_u32 v118, 0, v82, v83
	s_waitcnt lgkmcnt(0)
	s_barrier
	ds_read_b128 v[44:47], v81
	ds_read_b64_tr_b16 v[84:85], v118 offset:36928
	ds_read_b64_tr_b16 v[82:83], v118 offset:34816
	ds_read_b64_tr_b16 v[88:89], v118 offset:36960
	ds_read_b64_tr_b16 v[86:87], v118 offset:34848
	ds_read_b128 v[90:93], v81 offset:2304
	ds_read_b128 v[102:105], v81 offset:4608
	ds_read_b128 v[106:109], v81 offset:4672
	ds_read_b64_tr_b16 v[114:115], v118 offset:51712
	ds_read_b64_tr_b16 v[116:117], v118 offset:53824
	ds_read_b64_tr_b16 v[120:121], v118 offset:53856
	ds_read_b64_tr_b16 v[118:119], v118 offset:51744
	s_waitcnt lgkmcnt(5)
	v_mfma_f32_16x16x32_bf16 v[110:113], v[102:105], v[82:85], 0
	v_mfma_f32_16x16x32_bf16 v[102:105], v[102:105], v[86:89], 0
	s_waitcnt lgkmcnt(2)
	v_mfma_f32_16x16x32_bf16 v[110:113], v[106:109], v[114:117], v[110:113]
	s_waitcnt lgkmcnt(0)
	v_mfma_f32_16x16x32_bf16 v[102:105], v[106:109], v[118:121], v[102:105]
	ds_read_b128 v[106:109], v81 offset:6912
	ds_read_b128 v[122:125], v81 offset:6976
	v_mfma_f32_16x16x32_bf16 v[94:97], v[44:47], v[82:85], 0
	v_mfma_f32_16x16x32_bf16 v[98:101], v[90:93], v[82:85], 0
	s_waitcnt lgkmcnt(1)
	v_mfma_f32_16x16x32_bf16 v[82:85], v[106:109], v[82:85], 0
	v_mfma_f32_16x16x32_bf16 v[44:47], v[44:47], v[86:89], 0
	v_mfma_f32_16x16x32_bf16 v[90:93], v[90:93], v[86:89], 0
	v_mfma_f32_16x16x32_bf16 v[86:89], v[106:109], v[86:89], 0
	s_waitcnt lgkmcnt(0)
	v_mfma_f32_16x16x32_bf16 v[82:85], v[122:125], v[114:117], v[82:85]
	v_mfma_f32_16x16x32_bf16 v[86:89], v[122:125], v[118:121], v[86:89]
	v_mul_u32_u24_e32 v81, 0x110, v80
	v_add3_u32 v81, 0, v126, v81
	ds_read2_b64 v[106:109], v81 offset1:4
	v_add_u32_e32 v114, 0x1000, v81
	v_add_u32_e32 v115, 0x2000, v81
	v_add_u32_e32 v116, 0x3000, v81
	s_waitcnt vmcnt(11) lgkmcnt(0)
	v_mfma_f32_16x16x32_bf16 v[94:97], v[106:109], v[36:39], v[94:97]
	s_waitcnt vmcnt(10)
	v_mfma_f32_16x16x32_bf16 v[44:47], v[106:109], v[40:43], v[44:47]
	ds_read2_b64 v[106:109], v114 offset0:32 offset1:36
	s_waitcnt lgkmcnt(0)
	v_mfma_f32_16x16x32_bf16 v[98:101], v[106:109], v[36:39], v[98:101]
	v_mfma_f32_16x16x32_bf16 v[90:93], v[106:109], v[40:43], v[90:93]
	ds_read2_b64 v[106:109], v115 offset0:64 offset1:68
	s_waitcnt lgkmcnt(0)
	v_mfma_f32_16x16x32_bf16 v[110:113], v[106:109], v[36:39], v[110:113]
	v_mfma_f32_16x16x32_bf16 v[102:105], v[106:109], v[40:43], v[102:105]
	ds_read2_b64 v[106:109], v116 offset0:96 offset1:100
	s_waitcnt lgkmcnt(0)
	v_mfma_f32_16x16x32_bf16 v[36:39], v[106:109], v[36:39], v[82:85]
	s_nop 2
	ds_read2_b64 v[82:85], v81 offset0:8 offset1:12
	v_mfma_f32_16x16x32_bf16 v[40:43], v[106:109], v[40:43], v[86:89]
	s_waitcnt vmcnt(9) lgkmcnt(0)
	v_mfma_f32_16x16x32_bf16 v[86:89], v[82:85], v[28:31], v[94:97]
	s_waitcnt vmcnt(8)
	v_mfma_f32_16x16x32_bf16 v[44:47], v[82:85], v[32:35], v[44:47]
	ds_read2_b64 v[82:85], v114 offset0:40 offset1:44
	s_waitcnt lgkmcnt(0)
	v_mfma_f32_16x16x32_bf16 v[94:97], v[82:85], v[28:31], v[98:101]
	v_mfma_f32_16x16x32_bf16 v[82:85], v[82:85], v[32:35], v[90:93]
	s_nop 2
	ds_read2_b64 v[90:93], v115 offset0:72 offset1:76
	s_waitcnt lgkmcnt(0)
	v_mfma_f32_16x16x32_bf16 v[98:101], v[90:93], v[28:31], v[110:113]
	v_mfma_f32_16x16x32_bf16 v[90:93], v[90:93], v[32:35], v[102:105]
	s_nop 2
	ds_read2_b64 v[102:105], v116 offset0:104 offset1:108
	s_waitcnt lgkmcnt(0)
	v_mfma_f32_16x16x32_bf16 v[28:31], v[102:105], v[28:31], v[36:39]
	s_nop 2
	ds_read2_b64 v[36:39], v81 offset0:16 offset1:20
	v_mfma_f32_16x16x32_bf16 v[32:35], v[102:105], v[32:35], v[40:43]
	s_waitcnt vmcnt(7) lgkmcnt(0)
	v_mfma_f32_16x16x32_bf16 v[40:43], v[36:39], v[20:23], v[86:89]
	s_waitcnt vmcnt(6)
	v_mfma_f32_16x16x32_bf16 v[36:39], v[36:39], v[24:27], v[44:47]
	s_nop 2
	ds_read2_b64 v[44:47], v114 offset0:48 offset1:52
	s_waitcnt lgkmcnt(0)
	v_mfma_f32_16x16x32_bf16 v[86:89], v[44:47], v[20:23], v[94:97]
	v_mfma_f32_16x16x32_bf16 v[82:85], v[44:47], v[24:27], v[82:85]
	ds_read2_b64 v[44:47], v115 offset0:80 offset1:84
	s_waitcnt lgkmcnt(0)
	v_mfma_f32_16x16x32_bf16 v[94:97], v[44:47], v[20:23], v[98:101]
	v_mfma_f32_16x16x32_bf16 v[90:93], v[44:47], v[24:27], v[90:93]
	ds_read2_b64 v[44:47], v116 offset0:112 offset1:116
	s_waitcnt lgkmcnt(0)
	v_mfma_f32_16x16x32_bf16 v[98:101], v[44:47], v[24:27], v[32:35]
	ds_read2_b64 v[24:27], v81 offset0:24 offset1:28
	v_mfma_f32_16x16x32_bf16 v[20:23], v[44:47], v[20:23], v[28:31]
	s_waitcnt vmcnt(5) lgkmcnt(0)
	v_mfma_f32_16x16x32_bf16 v[44:47], v[24:27], v[16:19], v[40:43]
	s_waitcnt vmcnt(4)
	v_mfma_f32_16x16x32_bf16 v[40:43], v[24:27], v[48:51], v[36:39]
	ds_read2_b64 v[24:27], v114 offset0:56 offset1:60
	s_waitcnt lgkmcnt(0)
; #define LAS __attribute__((address_space(3)))
; __device__ __forceinline__ f32x4 mfma16(bf16x8 a, bf16x8 b, f32x4 c) { return __builtin_amdgcn_mfma_f32_16x16x32_bf16(a, b, c, 0, 0, 0); }
; __device__ __forceinline__ void gla_passC(const Params& p, LAS unsigned char* lds, int item, int wave, int lane) {
;     ...
;         for (int ks = 0; ks < 4; ++ks) {
; #pragma unroll
;             for (int ti = 0; ti < 4; ++ti) {
;                 const s16x4 qa = *(const LAS s16x4*)(L + G_QL + (16 * ti + fr) * 272 + (32 * ks + 4 * g) * 2);
;                 const s16x4 qb = *(const LAS s16x4*)(L + G_QL + (16 * ti + fr) * 272 + (32 * ks + 16 + 4 * g) * 2);
;                 const bf16x8 a = cat8(qa, qb);
;                 oacc[ti][0] = mfma16(a, sbf[ks][0], oacc[ti][0]); oacc[ti][1] = mfma16(a, sbf[ks][1], oacc[ti][1]); }
;         }
	v_mfma_f32_16x16x32_bf16 v[36:39], v[24:27], v[16:19], v[86:89]
	v_mfma_f32_16x16x32_bf16 v[32:35], v[24:27], v[48:51], v[82:85]
	ds_read2_b64 v[24:27], v115 offset0:88 offset1:92
	s_nop 1
	ds_read2_b64 v[82:85], v116 offset0:120 offset1:124
	s_waitcnt lgkmcnt(1)
	v_mfma_f32_16x16x32_bf16 v[28:31], v[24:27], v[16:19], v[94:97]
	v_mfma_f32_16x16x32_bf16 v[24:27], v[24:27], v[48:51], v[90:93]
	s_waitcnt lgkmcnt(0)
; #define LAS __attribute__((address_space(3)))
; __device__ __forceinline__ void gla_passC(const Params& p, LAS unsigned char* lds, int item, int wave, int lane) {
;     ...
; #pragma unroll
;         for (int ti = 0; ti < 4; ++ti)
; #pragma unroll
;             for (int jj = 0; jj < 4; ++jj) { float s = oacc[ti][0][jj] * oacc[ti][0][jj] + oacc[ti][1][jj] * oacc[ti][1][jj];
;                 s += __shfl_xor(s, 1); s += __shfl_xor(s, 2); s += __shfl_xor(s, 4); s += __shfl_xor(s, 8);
;                 if (fr == 0) *(LAS float*)(L + G_SS + ((16 * ti + 4 * g + jj) * 8 + wave) * 4) = s; }
	v_mfma_f32_16x16x32_bf16 v[20:23], v[82:85], v[16:19], v[20:23]
	v_mfma_f32_16x16x32_bf16 v[16:19], v[82:85], v[48:51], v[98:101]
	v_cmp_eq_u32_e32 vcc, 0, v80
	v_mul_f32_e32 v102, v40, v40
	v_fmac_f32_e32 v102, v44, v44
	v_mul_f32_e32 v103, v41, v41
	v_fmac_f32_e32 v103, v45, v45
	v_mul_f32_e32 v104, v42, v42
	v_fmac_f32_e32 v104, v46, v46
	v_mul_f32_e32 v105, v43, v43
	v_fmac_f32_e32 v105, v47, v47
	v_mul_f32_e32 v106, v32, v32
	v_fmac_f32_e32 v106, v36, v36
	v_mul_f32_e32 v107, v33, v33
	v_fmac_f32_e32 v107, v37, v37
	v_mul_f32_e32 v108, v34, v34
	v_fmac_f32_e32 v108, v38, v38
	v_mul_f32_e32 v109, v35, v35
	v_fmac_f32_e32 v109, v39, v39
	v_mul_f32_e32 v110, v24, v24
	v_fmac_f32_e32 v110, v28, v28
	v_mul_f32_e32 v111, v25, v25
	v_fmac_f32_e32 v111, v29, v29
	v_mul_f32_e32 v112, v26, v26
	v_fmac_f32_e32 v112, v30, v30
	v_mul_f32_e32 v113, v27, v27
	v_fmac_f32_e32 v113, v31, v31
	v_mul_f32_e32 v114, v16, v16
	v_fmac_f32_e32 v114, v20, v20
	v_mul_f32_e32 v115, v17, v17
	v_fmac_f32_e32 v115, v21, v21
	v_mul_f32_e32 v116, v18, v18
	v_fmac_f32_e32 v116, v22, v22
	v_mul_f32_e32 v117, v19, v19
	v_fmac_f32_e32 v117, v23, v23
	s_nop 1
	v_add_f32_dpp v102, v102, v102 quad_perm:[1,0,3,2] row_mask:0xf bank_mask:0xf
	v_add_f32_dpp v103, v103, v103 quad_perm:[1,0,3,2] row_mask:0xf bank_mask:0xf
	v_add_f32_dpp v104, v104, v104 quad_perm:[1,0,3,2] row_mask:0xf bank_mask:0xf
	v_add_f32_dpp v105, v105, v105 quad_perm:[1,0,3,2] row_mask:0xf bank_mask:0xf
	v_add_f32_dpp v106, v106, v106 quad_perm:[1,0,3,2] row_mask:0xf bank_mask:0xf
	v_add_f32_dpp v107, v107, v107 quad_perm:[1,0,3,2] row_mask:0xf bank_mask:0xf
	v_add_f32_dpp v108, v108, v108 quad_perm:[1,0,3,2] row_mask:0xf bank_mask:0xf
	v_add_f32_dpp v109, v109, v109 quad_perm:[1,0,3,2] row_mask:0xf bank_mask:0xf
	v_add_f32_dpp v110, v110, v110 quad_perm:[1,0,3,2] row_mask:0xf bank_mask:0xf
	v_add_f32_dpp v111, v111, v111 quad_perm:[1,0,3,2] row_mask:0xf bank_mask:0xf
	v_add_f32_dpp v112, v112, v112 quad_perm:[1,0,3,2] row_mask:0xf bank_mask:0xf
	v_add_f32_dpp v113, v113, v113 quad_perm:[1,0,3,2] row_mask:0xf bank_mask:0xf
	v_add_f32_dpp v114, v114, v114 quad_perm:[1,0,3,2] row_mask:0xf bank_mask:0xf
	v_add_f32_dpp v115, v115, v115 quad_perm:[1,0,3,2] row_mask:0xf bank_mask:0xf
	v_add_f32_dpp v116, v116, v116 quad_perm:[1,0,3,2] row_mask:0xf bank_mask:0xf
	v_add_f32_dpp v117, v117, v117 quad_perm:[1,0,3,2] row_mask:0xf bank_mask:0xf
	v_add_f32_dpp v102, v102, v102 quad_perm:[2,3,0,1] row_mask:0xf bank_mask:0xf
	v_add_f32_dpp v103, v103, v103 quad_perm:[2,3,0,1] row_mask:0xf bank_mask:0xf
	v_add_f32_dpp v104, v104, v104 quad_perm:[2,3,0,1] row_mask:0xf bank_mask:0xf
	v_add_f32_dpp v105, v105, v105 quad_perm:[2,3,0,1] row_mask:0xf bank_mask:0xf
	v_add_f32_dpp v106, v106, v106 quad_perm:[2,3,0,1] row_mask:0xf bank_mask:0xf
	v_add_f32_dpp v107, v107, v107 quad_perm:[2,3,0,1] row_mask:0xf bank_mask:0xf
	v_add_f32_dpp v108, v108, v108 quad_perm:[2,3,0,1] row_mask:0xf bank_mask:0xf
	v_add_f32_dpp v109, v109, v109 quad_perm:[2,3,0,1] row_mask:0xf bank_mask:0xf
	v_add_f32_dpp v110, v110, v110 quad_perm:[2,3,0,1] row_mask:0xf bank_mask:0xf
	v_add_f32_dpp v111, v111, v111 quad_perm:[2,3,0,1] row_mask:0xf bank_mask:0xf
	v_add_f32_dpp v112, v112, v112 quad_perm:[2,3,0,1] row_mask:0xf bank_mask:0xf
	v_add_f32_dpp v113, v113, v113 quad_perm:[2,3,0,1] row_mask:0xf bank_mask:0xf
	v_add_f32_dpp v114, v114, v114 quad_perm:[2,3,0,1] row_mask:0xf bank_mask:0xf
	v_add_f32_dpp v115, v115, v115 quad_perm:[2,3,0,1] row_mask:0xf bank_mask:0xf
	v_add_f32_dpp v116, v116, v116 quad_perm:[2,3,0,1] row_mask:0xf bank_mask:0xf
	v_add_f32_dpp v117, v117, v117 quad_perm:[2,3,0,1] row_mask:0xf bank_mask:0xf
	v_add_f32_dpp v102, v102, v102 row_half_mirror row_mask:0xf bank_mask:0xf
	v_add_f32_dpp v103, v103, v103 row_half_mirror row_mask:0xf bank_mask:0xf
	v_add_f32_dpp v104, v104, v104 row_half_mirror row_mask:0xf bank_mask:0xf
	v_add_f32_dpp v105, v105, v105 row_half_mirror row_mask:0xf bank_mask:0xf
	v_add_f32_dpp v106, v106, v106 row_half_mirror row_mask:0xf bank_mask:0xf
	v_add_f32_dpp v107, v107, v107 row_half_mirror row_mask:0xf bank_mask:0xf
	v_add_f32_dpp v108, v108, v108 row_half_mirror row_mask:0xf bank_mask:0xf
	v_add_f32_dpp v109, v109, v109 row_half_mirror row_mask:0xf bank_mask:0xf
	v_add_f32_dpp v110, v110, v110 row_half_mirror row_mask:0xf bank_mask:0xf
	v_add_f32_dpp v111, v111, v111 row_half_mirror row_mask:0xf bank_mask:0xf
	v_add_f32_dpp v112, v112, v112 row_half_mirror row_mask:0xf bank_mask:0xf
	v_add_f32_dpp v113, v113, v113 row_half_mirror row_mask:0xf bank_mask:0xf
	v_add_f32_dpp v114, v114, v114 row_half_mirror row_mask:0xf bank_mask:0xf
	v_add_f32_dpp v115, v115, v115 row_half_mirror row_mask:0xf bank_mask:0xf
	v_add_f32_dpp v116, v116, v116 row_half_mirror row_mask:0xf bank_mask:0xf
	v_add_f32_dpp v117, v117, v117 row_half_mirror row_mask:0xf bank_mask:0xf
	v_add_f32_dpp v102, v102, v102 row_ror:8 row_mask:0xf bank_mask:0xf
	v_add_f32_dpp v103, v103, v103 row_ror:8 row_mask:0xf bank_mask:0xf
	v_add_f32_dpp v104, v104, v104 row_ror:8 row_mask:0xf bank_mask:0xf
	v_add_f32_dpp v105, v105, v105 row_ror:8 row_mask:0xf bank_mask:0xf
	v_add_f32_dpp v106, v106, v106 row_ror:8 row_mask:0xf bank_mask:0xf
	v_add_f32_dpp v107, v107, v107 row_ror:8 row_mask:0xf bank_mask:0xf
	v_add_f32_dpp v108, v108, v108 row_ror:8 row_mask:0xf bank_mask:0xf
	v_add_f32_dpp v109, v109, v109 row_ror:8 row_mask:0xf bank_mask:0xf
	v_add_f32_dpp v110, v110, v110 row_ror:8 row_mask:0xf bank_mask:0xf
	v_add_f32_dpp v111, v111, v111 row_ror:8 row_mask:0xf bank_mask:0xf
	v_add_f32_dpp v112, v112, v112 row_ror:8 row_mask:0xf bank_mask:0xf
	v_add_f32_dpp v113, v113, v113 row_ror:8 row_mask:0xf bank_mask:0xf
	v_add_f32_dpp v114, v114, v114 row_ror:8 row_mask:0xf bank_mask:0xf
	v_add_f32_dpp v115, v115, v115 row_ror:8 row_mask:0xf bank_mask:0xf
	v_add_f32_dpp v116, v116, v116 row_ror:8 row_mask:0xf bank_mask:0xf
	v_add_f32_dpp v117, v117, v117 row_ror:8 row_mask:0xf bank_mask:0xf
	v_lshl_add_u32 v83, v79, 7, s35
	v_or_b32_e32 v81, 16, v75
	v_or_b32_e32 v80, 32, v75
	v_or_b32_e32 v51, 48, v75
	v_lshl_or_b32 v49, v75, 5, v67
	s_and_saveexec_b64 s[4:5], vcc
	ds_write_b32 v83, v102
	ds_write_b32 v83, v103 offset:32
	ds_write_b32 v83, v104 offset:64
	ds_write_b32 v83, v105 offset:96
	ds_write_b32 v83, v106 offset:512
	ds_write_b32 v83, v107 offset:544
	ds_write_b32 v83, v108 offset:576
	ds_write_b32 v83, v109 offset:608
	ds_write_b32 v83, v110 offset:1024
	ds_write_b32 v83, v111 offset:1056
	ds_write_b32 v83, v112 offset:1088
	ds_write_b32 v83, v113 offset:1120
	ds_write_b32 v83, v114 offset:1536
	ds_write_b32 v83, v115 offset:1568
	ds_write_b32 v83, v116 offset:1600
	ds_write_b32 v83, v117 offset:1632
	s_or_b64 exec, exec, s[4:5]
	s_branch .LBB0_720

; __device__ __forceinline__ unsigned cvt_pk_bf16(float lo, float hi) { unsigned r; asm volatile("v_cvt_pk_bf16_f32 %0, %1, %2" : "=v"(r) : "v"(lo), "v"(hi)); return r; }
; __device__ __forceinline__ float silu_f(float g) { return g * __builtin_amdgcn_rcpf(1.0f + __builtin_amdgcn_exp2f(-1.44269504089f * g)); }
;     __device__ __forceinline__ void operator()(const f32x4 (&acc)[2][2][4][2], const Unit& u, int wr, int wc, int fr, int fq) const {
;     ...
;             for (int m = 0; m < 4; ++m) { bf16_t* rowp = O + (size_t)(row0 + ai * HALF + m * 16) * ldc + col0;
;                 const float rs = rowss ? 1.0f / sqrtf(rowss[row0 + ai * HALF + m * 16] * (1.0f / 2048.0f) + 1e-6f) : 1.0f;
;                 const f32x4 g0 = acc[ai][0][m][0] * rs, g1 = acc[ai][0][m][1] * rs, u0 = acc[ai][1][m][0] * rs, u1 = acc[ai][1][m][1] * rs;
;                 float h[8];
; #pragma unroll
;                 for (int j = 0; j < 4; ++j) { h[j] = silu_f(g0[j]) * u0[j]; h[4 + j] = silu_f(g1[j]) * u1[j]; }
;                 u32x4 w; w.x = cvt_pk_bf16(h[0], h[1]); w.y = cvt_pk_bf16(h[2], h[3]); w.z = cvt_pk_bf16(h[4], h[5]); w.w = cvt_pk_bf16(h[6], h[7]);
;                 *(u32x4*)rowp = w; }
.LBB0_932:
	v_lshl_add_u32 v144, s4, 8, v150
	v_ashrrev_i32_e32 v145, 31, v144
	v_lshl_add_u64 v[148:149], v[144:145], 2, s[10:11]
	global_load_dword v145, v[148:149], off
	v_mov_b32_e32 v162, v120
	v_mov_b32_e32 v163, v112
	v_mov_b32_e32 v112, v121
	v_lshl_or_b32 v158, s5, 7, v152
	v_ashrrev_i32_e32 v159, 31, v158
	v_mov_b64_e32 v[146:147], s[74:75]
	v_mov_b32_e32 v164, v122
	v_mov_b32_e32 v165, v114
	v_mov_b32_e32 v114, v123
	v_mad_i64_i32 v[122:123], s[4:5], v144, s43, v[146:147]
	v_mov_b32_e32 v160, v124
	v_mov_b32_e32 v124, v126
	v_or_b32_e32 v126, 16, v144
	v_mov_b32_e32 v161, v116
	v_mov_b32_e32 v116, v125
	v_mov_b32_e32 v125, v118
	v_mov_b32_e32 v118, v127
	v_ashrrev_i32_e32 v127, 31, v126
	s_waitcnt vmcnt(0)
	v_fmamk_f32 v120, v145, 0x3a000000, v156
	s_nop 1
	v_rsq_f32_e32 v145, v120
	v_lshlrev_b64 v[120:121], 1, v[158:159]
	v_lshl_add_u64 v[122:123], v[122:123], 0, v[120:121]
	s_nop 1
	s_nop 0
	v_mov_b32_e32 v145, v145
	v_lshl_add_u64 v[158:159], v[126:127], 2, s[10:11]
	s_nop 0
	v_mov_b32_e32 v166, v145
	v_pk_mul_f32 v[116:117], v[116:117], v[166:167] op_sel_hi:[1,0]
	v_pk_mul_f32 v[112:113], v[112:113], v[166:167] op_sel_hi:[1,0]
	v_pk_mul_f32 v[124:125], v[124:125], v[166:167] op_sel_hi:[1,0]
	v_pk_mul_f32 v[114:115], v[114:115], v[166:167] op_sel_hi:[1,0]
	v_pk_mul_f32 v[160:161], v[160:161], v[166:167] op_sel_hi:[1,0]
	v_pk_mul_f32 v[162:163], v[162:163], v[166:167] op_sel_hi:[1,0]
	v_pk_mul_f32 v[164:165], v[164:165], v[166:167] op_sel_hi:[1,0]
	v_pk_mul_f32 v[118:119], v[118:119], v[166:167] op_sel_hi:[1,0]
	v_mul_f32_e32 v166, 0xbfb8aa3b, v117
	v_mul_f32_e32 v167, 0xbfb8aa3b, v113
	v_mul_f32_e32 v168, 0xbfb8aa3b, v125
	v_mul_f32_e32 v171, 0xbfb8aa3b, v115
	v_mul_f32_e32 v127, 0xbfb8aa3b, v161
	v_mul_f32_e32 v145, 0xbfb8aa3b, v163
	v_mul_f32_e32 v169, 0xbfb8aa3b, v165
	v_mul_f32_e32 v170, 0xbfb8aa3b, v119
	v_exp_f32_e32 v166, v166
	v_exp_f32_e32 v167, v167
	v_exp_f32_e32 v168, v168
	v_exp_f32_e32 v171, v171
	v_exp_f32_e32 v127, v127
	v_exp_f32_e32 v145, v145
	v_exp_f32_e32 v169, v169
	v_exp_f32_e32 v170, v170
	v_add_f32_e32 v166, 1.0, v166
	v_add_f32_e32 v167, 1.0, v167
	v_add_f32_e32 v168, 1.0, v168
	v_add_f32_e32 v171, 1.0, v171
	v_add_f32_e32 v127, 1.0, v127
	v_add_f32_e32 v145, 1.0, v145
	v_add_f32_e32 v169, 1.0, v169
	v_add_f32_e32 v170, 1.0, v170
	v_rcp_f32_e32 v166, v166
	v_rcp_f32_e32 v167, v167
	v_rcp_f32_e32 v168, v168
	v_rcp_f32_e32 v171, v171
	v_rcp_f32_e32 v127, v127
	v_rcp_f32_e32 v145, v145
	v_rcp_f32_e32 v169, v169
	v_rcp_f32_e32 v170, v170
	v_mul_f32_e32 v117, v117, v166
	v_mul_f32_e32 v113, v113, v167
	v_mul_f32_e32 v125, v125, v168
	v_mul_f32_e32 v115, v115, v171
	v_mul_f32_e32 v127, v161, v127
	v_mul_f32_e32 v145, v163, v145
	v_mul_f32_e32 v161, v165, v169
	v_mul_f32_e32 v119, v119, v170
	v_mul_f32_e32 v116, v116, v117
	v_mul_f32_e32 v117, v112, v113
	v_mul_f32_e32 v113, v124, v125
	v_mul_f32_e32 v115, v114, v115
	v_mul_f32_e32 v127, v160, v127
	v_mul_f32_e32 v145, v162, v145
	v_mul_f32_e32 v124, v164, v161
	v_mul_f32_e32 v118, v118, v119
	v_cvt_pk_bf16_f32 v112, v127, v116
	v_cvt_pk_bf16_f32 v113, v113, v118
	v_cvt_pk_bf16_f32 v114, v145, v117
	v_cvt_pk_bf16_f32 v115, v124, v115
	global_store_dwordx4 v[122:123], v[112:115], off
	global_load_dword v116, v[158:159], off
	s_nop 0
	v_mov_b32_e32 v113, v100
	v_mov_b32_e32 v100, v109
	v_mov_b32_e32 v109, v98
	v_mov_b32_e32 v98, v107
	v_mov_b32_e32 v114, v104
	v_mov_b32_e32 v104, v110
	v_mov_b32_e32 v115, v96
	v_mov_b32_e32 v96, v105
	v_mov_b32_e32 v105, v102
	v_mov_b32_e32 v102, v111
	v_mov_b32_e32 v112, v108
	v_mov_b32_e32 v108, v106
	v_or_b32_e32 v106, 32, v144
	s_waitcnt vmcnt(0)
	v_fmamk_f32 v107, v116, 0x3a000000, v156
	s_nop 1
	v_rsq_f32_e32 v116, v107
	v_mad_i64_i32 v[110:111], s[4:5], v126, s43, v[146:147]
	v_ashrrev_i32_e32 v107, 31, v106
	v_lshl_add_u64 v[110:111], v[110:111], 0, v[120:121]
	s_nop 0
	s_nop 1
	s_nop 0
	v_mov_b32_e32 v118, v116
	v_lshl_add_u64 v[116:117], v[106:107], 2, s[10:11]
	s_nop 0
	v_mov_b32_e32 v118, v118
	v_pk_mul_f32 v[100:101], v[100:101], v[118:119] op_sel_hi:[1,0]
	v_pk_mul_f32 v[96:97], v[96:97], v[118:119] op_sel_hi:[1,0]
	v_pk_mul_f32 v[104:105], v[104:105], v[118:119] op_sel_hi:[1,0]
	v_pk_mul_f32 v[98:99], v[98:99], v[118:119] op_sel_hi:[1,0]
	v_pk_mul_f32 v[112:113], v[112:113], v[118:119] op_sel_hi:[1,0]
	v_pk_mul_f32 v[114:115], v[114:115], v[118:119] op_sel_hi:[1,0]
	v_pk_mul_f32 v[108:109], v[108:109], v[118:119] op_sel_hi:[1,0]
	v_pk_mul_f32 v[102:103], v[102:103], v[118:119] op_sel_hi:[1,0]
	v_mul_f32_e32 v119, 0xbfb8aa3b, v101
	v_mul_f32_e32 v122, 0xbfb8aa3b, v97
	v_mul_f32_e32 v123, 0xbfb8aa3b, v105
	v_mul_f32_e32 v126, 0xbfb8aa3b, v99
	v_mul_f32_e32 v107, 0xbfb8aa3b, v113
	v_mul_f32_e32 v118, 0xbfb8aa3b, v115
	v_mul_f32_e32 v124, 0xbfb8aa3b, v109
	v_mul_f32_e32 v125, 0xbfb8aa3b, v103
	v_exp_f32_e32 v119, v119
	v_exp_f32_e32 v122, v122
	v_exp_f32_e32 v123, v123
	v_exp_f32_e32 v126, v126
	v_exp_f32_e32 v107, v107
	v_exp_f32_e32 v118, v118
	v_exp_f32_e32 v124, v124
	v_exp_f32_e32 v125, v125
	v_add_f32_e32 v119, 1.0, v119
	v_add_f32_e32 v122, 1.0, v122
	v_add_f32_e32 v123, 1.0, v123
	v_add_f32_e32 v126, 1.0, v126
	v_add_f32_e32 v107, 1.0, v107
	v_add_f32_e32 v118, 1.0, v118
	v_add_f32_e32 v124, 1.0, v124
	v_add_f32_e32 v125, 1.0, v125
	v_rcp_f32_e32 v119, v119
	v_rcp_f32_e32 v122, v122
	v_rcp_f32_e32 v123, v123
	v_rcp_f32_e32 v126, v126
	v_rcp_f32_e32 v107, v107
	v_rcp_f32_e32 v118, v118
	v_rcp_f32_e32 v124, v124
	v_rcp_f32_e32 v125, v125
	v_mul_f32_e32 v101, v101, v119
	v_mul_f32_e32 v97, v97, v122
	v_mul_f32_e32 v105, v105, v123
	v_mul_f32_e32 v99, v99, v126
	v_mul_f32_e32 v107, v113, v107
	v_mul_f32_e32 v113, v115, v118
	v_mul_f32_e32 v109, v109, v124
	v_mul_f32_e32 v103, v103, v125
	v_mul_f32_e32 v100, v100, v101
	v_mul_f32_e32 v101, v96, v97
	v_mul_f32_e32 v97, v104, v105
	v_mul_f32_e32 v99, v98, v99
	v_mul_f32_e32 v107, v112, v107
	v_mul_f32_e32 v112, v114, v113
	v_mul_f32_e32 v104, v108, v109
	v_mul_f32_e32 v102, v102, v103
	v_cvt_pk_bf16_f32 v96, v107, v100
	v_cvt_pk_bf16_f32 v97, v97, v102
	v_cvt_pk_bf16_f32 v98, v112, v101
	v_cvt_pk_bf16_f32 v99, v104, v99
	global_store_dwordx4 v[110:111], v[96:99], off
	global_load_dword v100, v[116:117], off
	s_nop 0
	v_mov_b32_e32 v97, v84
	v_mov_b32_e32 v84, v93
	v_mov_b32_e32 v93, v82
	v_mov_b32_e32 v82, v91
	v_mov_b32_e32 v98, v88
	v_mov_b32_e32 v88, v94
	v_mov_b32_e32 v99, v80
	v_mov_b32_e32 v80, v89
	v_mov_b32_e32 v89, v86
	v_mov_b32_e32 v86, v95
	v_mov_b32_e32 v96, v92
	v_mov_b32_e32 v92, v90
	v_or_b32_e32 v90, 48, v144
	s_waitcnt vmcnt(0)
; __device__ __forceinline__ unsigned cvt_pk_bf16(float lo, float hi) { unsigned r; asm volatile("v_cvt_pk_bf16_f32 %0, %1, %2" : "=v"(r) : "v"(lo), "v"(hi)); return r; }
; __device__ __forceinline__ float silu_f(float g) { return g * __builtin_amdgcn_rcpf(1.0f + __builtin_amdgcn_exp2f(-1.44269504089f * g)); }
;     __device__ __forceinline__ void operator()(const f32x4 (&acc)[2][2][4][2], const Unit& u, int wr, int wc, int fr, int fq) const {
;     ...
;             for (int m = 0; m < 4; ++m) { bf16_t* rowp = O + (size_t)(row0 + ai * HALF + m * 16) * ldc + col0;
;                 const float rs = rowss ? 1.0f / sqrtf(rowss[row0 + ai * HALF + m * 16] * (1.0f / 2048.0f) + 1e-6f) : 1.0f;
;                 const f32x4 g0 = acc[ai][0][m][0] * rs, g1 = acc[ai][0][m][1] * rs, u0 = acc[ai][1][m][0] * rs, u1 = acc[ai][1][m][1] * rs;
;                 float h[8];
; #pragma unroll
;                 for (int j = 0; j < 4; ++j) { h[j] = silu_f(g0[j]) * u0[j]; h[4 + j] = silu_f(g1[j]) * u1[j]; }
;                 u32x4 w; w.x = cvt_pk_bf16(h[0], h[1]); w.y = cvt_pk_bf16(h[2], h[3]); w.z = cvt_pk_bf16(h[4], h[5]); w.w = cvt_pk_bf16(h[6], h[7]);
;                 *(u32x4*)rowp = w; }
	v_fmamk_f32 v91, v100, 0x3a000000, v156
	s_nop 1
	v_rsq_f32_e32 v100, v91
	v_mad_i64_i32 v[94:95], s[4:5], v106, s43, v[146:147]
	v_ashrrev_i32_e32 v91, 31, v90
	v_lshl_add_u64 v[94:95], v[94:95], 0, v[120:121]
	s_nop 0
	s_nop 1
	s_nop 0
	v_mov_b32_e32 v102, v100
	v_lshl_add_u64 v[100:101], v[90:91], 2, s[10:11]
	s_nop 0
	v_mov_b32_e32 v102, v102
	v_pk_mul_f32 v[84:85], v[84:85], v[102:103] op_sel_hi:[1,0]
	v_pk_mul_f32 v[80:81], v[80:81], v[102:103] op_sel_hi:[1,0]
	v_pk_mul_f32 v[88:89], v[88:89], v[102:103] op_sel_hi:[1,0]
	v_pk_mul_f32 v[82:83], v[82:83], v[102:103] op_sel_hi:[1,0]
	v_pk_mul_f32 v[96:97], v[96:97], v[102:103] op_sel_hi:[1,0]
	v_pk_mul_f32 v[98:99], v[98:99], v[102:103] op_sel_hi:[1,0]
	v_pk_mul_f32 v[92:93], v[92:93], v[102:103] op_sel_hi:[1,0]
	v_pk_mul_f32 v[86:87], v[86:87], v[102:103] op_sel_hi:[1,0]
	v_mul_f32_e32 v103, 0xbfb8aa3b, v85
	v_mul_f32_e32 v104, 0xbfb8aa3b, v81
	v_mul_f32_e32 v105, 0xbfb8aa3b, v89
	v_mul_f32_e32 v108, 0xbfb8aa3b, v83
	v_mul_f32_e32 v91, 0xbfb8aa3b, v97
	v_mul_f32_e32 v102, 0xbfb8aa3b, v99
	v_mul_f32_e32 v106, 0xbfb8aa3b, v93
	v_mul_f32_e32 v107, 0xbfb8aa3b, v87
	v_exp_f32_e32 v103, v103
	v_exp_f32_e32 v104, v104
	v_exp_f32_e32 v105, v105
	v_exp_f32_e32 v108, v108
	v_exp_f32_e32 v91, v91
	v_exp_f32_e32 v102, v102
	v_exp_f32_e32 v106, v106
	v_exp_f32_e32 v107, v107
	v_add_f32_e32 v103, 1.0, v103
	v_add_f32_e32 v104, 1.0, v104
	v_add_f32_e32 v105, 1.0, v105
	v_add_f32_e32 v108, 1.0, v108
	v_add_f32_e32 v91, 1.0, v91
	v_add_f32_e32 v102, 1.0, v102
	v_add_f32_e32 v106, 1.0, v106
	v_add_f32_e32 v107, 1.0, v107
	v_rcp_f32_e32 v103, v103
	v_rcp_f32_e32 v104, v104
	v_rcp_f32_e32 v105, v105
	v_rcp_f32_e32 v108, v108
	v_rcp_f32_e32 v91, v91
	v_rcp_f32_e32 v102, v102
	v_rcp_f32_e32 v106, v106
	v_rcp_f32_e32 v107, v107
	v_mul_f32_e32 v85, v85, v103
	v_mul_f32_e32 v81, v81, v104
	v_mul_f32_e32 v89, v89, v105
	v_mul_f32_e32 v83, v83, v108
	v_mul_f32_e32 v91, v97, v91
	v_mul_f32_e32 v97, v99, v102
	v_mul_f32_e32 v93, v93, v106
	v_mul_f32_e32 v87, v87, v107
	v_mul_f32_e32 v84, v84, v85
	v_mul_f32_e32 v85, v80, v81
	v_mul_f32_e32 v81, v88, v89
	v_mul_f32_e32 v83, v82, v83
	v_mul_f32_e32 v91, v96, v91
	v_mul_f32_e32 v96, v98, v97
	v_mul_f32_e32 v88, v92, v93
	v_mul_f32_e32 v86, v86, v87
	v_cvt_pk_bf16_f32 v80, v91, v84
	v_cvt_pk_bf16_f32 v81, v81, v86
	v_cvt_pk_bf16_f32 v82, v96, v85
	v_cvt_pk_bf16_f32 v83, v88, v83
	global_store_dwordx4 v[94:95], v[80:83], off
	global_load_dword v84, v[100:101], off
	s_nop 0
	v_mov_b32_e32 v81, v72
	v_mov_b32_e32 v72, v77
	v_mov_b32_e32 v77, v66
	v_mov_b32_e32 v80, v76
	v_mov_b32_e32 v76, v70
	v_mov_b32_e32 v82, v68
	v_mov_b32_e32 v68, v78
	v_mov_b32_e32 v83, v64
	v_mov_b32_e32 v64, v69
	v_mov_b32_e32 v69, v74
	v_mov_b32_e32 v74, v79
	s_waitcnt vmcnt(0)
	v_fmamk_f32 v66, v84, 0x3a000000, v156
	s_nop 1
	v_rsq_f32_e32 v78, v66
	v_mov_b32_e32 v66, v71
	v_mad_i64_i32 v[70:71], s[4:5], v90, s43, v[146:147]
	v_lshl_add_u64 v[70:71], v[70:71], 0, v[120:121]
	s_nop 0
	s_nop 1
	s_nop 0
	v_mov_b32_e32 v78, v78
	s_nop 0
	v_mov_b32_e32 v78, v78
	v_pk_mul_f32 v[72:73], v[72:73], v[78:79] op_sel_hi:[1,0]
	v_pk_mul_f32 v[64:65], v[64:65], v[78:79] op_sel_hi:[1,0]
	v_pk_mul_f32 v[68:69], v[68:69], v[78:79] op_sel_hi:[1,0]
	v_pk_mul_f32 v[66:67], v[66:67], v[78:79] op_sel_hi:[1,0]
	v_pk_mul_f32 v[80:81], v[80:81], v[78:79] op_sel_hi:[1,0]
	v_pk_mul_f32 v[82:83], v[82:83], v[78:79] op_sel_hi:[1,0]
	v_pk_mul_f32 v[76:77], v[76:77], v[78:79] op_sel_hi:[1,0]
	v_pk_mul_f32 v[74:75], v[74:75], v[78:79] op_sel_hi:[1,0]
	v_mul_f32_e32 v84, 0xbfb8aa3b, v73
	v_mul_f32_e32 v85, 0xbfb8aa3b, v65
	v_mul_f32_e32 v86, 0xbfb8aa3b, v69
	v_mul_f32_e32 v89, 0xbfb8aa3b, v67
	v_mul_f32_e32 v78, 0xbfb8aa3b, v81
	v_mul_f32_e32 v79, 0xbfb8aa3b, v83
	v_mul_f32_e32 v87, 0xbfb8aa3b, v77
	v_mul_f32_e32 v88, 0xbfb8aa3b, v75
	v_exp_f32_e32 v84, v84
	v_exp_f32_e32 v85, v85
	v_exp_f32_e32 v86, v86
	v_exp_f32_e32 v89, v89
	v_exp_f32_e32 v78, v78
	v_exp_f32_e32 v79, v79
	v_exp_f32_e32 v87, v87
	v_exp_f32_e32 v88, v88
	v_add_f32_e32 v84, 1.0, v84
	v_add_f32_e32 v85, 1.0, v85
	v_add_f32_e32 v86, 1.0, v86
	v_add_f32_e32 v89, 1.0, v89
	v_add_f32_e32 v78, 1.0, v78
	v_add_f32_e32 v79, 1.0, v79
	v_add_f32_e32 v87, 1.0, v87
	v_add_f32_e32 v88, 1.0, v88
	v_rcp_f32_e32 v84, v84
	v_rcp_f32_e32 v85, v85
	v_rcp_f32_e32 v86, v86
	v_rcp_f32_e32 v89, v89
	v_rcp_f32_e32 v78, v78
	v_rcp_f32_e32 v79, v79
	v_rcp_f32_e32 v87, v87
	v_rcp_f32_e32 v88, v88
	v_mul_f32_e32 v73, v73, v84
	v_mul_f32_e32 v65, v65, v85
	v_mul_f32_e32 v69, v69, v86
	v_mul_f32_e32 v67, v67, v89
	v_mul_f32_e32 v78, v81, v78
	v_mul_f32_e32 v79, v83, v79
	v_mul_f32_e32 v77, v77, v87
	v_mul_f32_e32 v75, v75, v88
	v_mul_f32_e32 v72, v72, v73
	v_mul_f32_e32 v73, v64, v65
	v_mul_f32_e32 v65, v68, v69
	v_mul_f32_e32 v67, v66, v67
	v_mul_f32_e32 v78, v80, v78
	v_mul_f32_e32 v79, v82, v79
	v_mul_f32_e32 v68, v76, v77
	v_mul_f32_e32 v69, v74, v75
	v_cvt_pk_bf16_f32 v64, v78, v72
	v_cvt_pk_bf16_f32 v65, v65, v69
	v_cvt_pk_bf16_f32 v66, v79, v73
	v_cvt_pk_bf16_f32 v67, v68, v67
	global_store_dwordx4 v[70:71], v[64:67], off
	global_load_dword v68, v[148:149], off offset:512
	s_nop 0
	v_mov_b32_e32 v64, v60
	v_mov_b32_e32 v60, v58
	v_mov_b32_e32 v65, v52
	v_mov_b32_e32 v52, v61
	v_mov_b32_e32 v61, v50
	v_mov_b32_e32 v50, v59
	v_mov_b32_e32 v66, v56
	v_mov_b32_e32 v56, v62
	v_mov_b32_e32 v67, v48
	v_mov_b32_e32 v48, v57
	v_mov_b32_e32 v57, v54
	v_mov_b32_e32 v54, v63
	s_waitcnt vmcnt(0)
; __device__ __forceinline__ unsigned cvt_pk_bf16(float lo, float hi) { unsigned r; asm volatile("v_cvt_pk_bf16_f32 %0, %1, %2" : "=v"(r) : "v"(lo), "v"(hi)); return r; }
; __device__ __forceinline__ float silu_f(float g) { return g * __builtin_amdgcn_rcpf(1.0f + __builtin_amdgcn_exp2f(-1.44269504089f * g)); }
;     __device__ __forceinline__ void operator()(const f32x4 (&acc)[2][2][4][2], const Unit& u, int wr, int wc, int fr, int fq) const {
;     ...
;             for (int m = 0; m < 4; ++m) { bf16_t* rowp = O + (size_t)(row0 + ai * HALF + m * 16) * ldc + col0;
;                 const float rs = rowss ? 1.0f / sqrtf(rowss[row0 + ai * HALF + m * 16] * (1.0f / 2048.0f) + 1e-6f) : 1.0f;
;                 const f32x4 g0 = acc[ai][0][m][0] * rs, g1 = acc[ai][0][m][1] * rs, u0 = acc[ai][1][m][0] * rs, u1 = acc[ai][1][m][1] * rs;
;                 float h[8];
; #pragma unroll
;                 for (int j = 0; j < 4; ++j) { h[j] = silu_f(g0[j]) * u0[j]; h[4 + j] = silu_f(g1[j]) * u1[j]; }
;                 u32x4 w; w.x = cvt_pk_bf16(h[0], h[1]); w.y = cvt_pk_bf16(h[2], h[3]); w.z = cvt_pk_bf16(h[4], h[5]); w.w = cvt_pk_bf16(h[6], h[7]);
;                 *(u32x4*)rowp = w; }
	v_fmamk_f32 v58, v68, 0x3a000000, v156
	s_nop 1
	v_rsq_f32_e32 v62, v58
	v_add_u32_e32 v58, 0x80, v144
	v_mad_i64_i32 v[58:59], s[4:5], v58, s43, v[146:147]
	v_lshl_add_u64 v[58:59], v[58:59], 0, v[120:121]
	s_nop 0
	s_nop 1
	s_nop 0
	v_mov_b32_e32 v62, v62
	s_nop 0
	v_mov_b32_e32 v62, v62
	v_pk_mul_f32 v[52:53], v[52:53], v[62:63] op_sel_hi:[1,0]
	v_pk_mul_f32 v[48:49], v[48:49], v[62:63] op_sel_hi:[1,0]
	v_pk_mul_f32 v[56:57], v[56:57], v[62:63] op_sel_hi:[1,0]
	v_pk_mul_f32 v[50:51], v[50:51], v[62:63] op_sel_hi:[1,0]
	v_pk_mul_f32 v[64:65], v[64:65], v[62:63] op_sel_hi:[1,0]
	v_pk_mul_f32 v[66:67], v[66:67], v[62:63] op_sel_hi:[1,0]
	v_pk_mul_f32 v[60:61], v[60:61], v[62:63] op_sel_hi:[1,0]
	v_pk_mul_f32 v[54:55], v[54:55], v[62:63] op_sel_hi:[1,0]
	v_mul_f32_e32 v68, 0xbfb8aa3b, v53
	v_mul_f32_e32 v69, 0xbfb8aa3b, v49
	v_mul_f32_e32 v70, 0xbfb8aa3b, v57
	v_mul_f32_e32 v73, 0xbfb8aa3b, v51
	v_mul_f32_e32 v62, 0xbfb8aa3b, v65
	v_mul_f32_e32 v63, 0xbfb8aa3b, v67
	v_mul_f32_e32 v71, 0xbfb8aa3b, v61
	v_mul_f32_e32 v72, 0xbfb8aa3b, v55
	v_exp_f32_e32 v68, v68
	v_exp_f32_e32 v69, v69
	v_exp_f32_e32 v70, v70
	v_exp_f32_e32 v73, v73
	v_exp_f32_e32 v62, v62
	v_exp_f32_e32 v63, v63
	v_exp_f32_e32 v71, v71
	v_exp_f32_e32 v72, v72
	v_add_f32_e32 v68, 1.0, v68
	v_add_f32_e32 v69, 1.0, v69
	v_add_f32_e32 v70, 1.0, v70
	v_add_f32_e32 v73, 1.0, v73
	v_add_f32_e32 v62, 1.0, v62
	v_add_f32_e32 v63, 1.0, v63
	v_add_f32_e32 v71, 1.0, v71
	v_add_f32_e32 v72, 1.0, v72
	v_rcp_f32_e32 v68, v68
	v_rcp_f32_e32 v69, v69
	v_rcp_f32_e32 v70, v70
	v_rcp_f32_e32 v73, v73
	v_rcp_f32_e32 v62, v62
	v_rcp_f32_e32 v63, v63
	v_rcp_f32_e32 v71, v71
	v_rcp_f32_e32 v72, v72
	v_mul_f32_e32 v53, v53, v68
	v_mul_f32_e32 v49, v49, v69
	v_mul_f32_e32 v57, v57, v70
	v_mul_f32_e32 v51, v51, v73
	v_mul_f32_e32 v62, v65, v62
	v_mul_f32_e32 v63, v67, v63
	v_mul_f32_e32 v61, v61, v71
	v_mul_f32_e32 v55, v55, v72
	v_mul_f32_e32 v52, v52, v53
	v_mul_f32_e32 v53, v48, v49
	v_mul_f32_e32 v49, v56, v57
	v_mul_f32_e32 v51, v50, v51
	v_mul_f32_e32 v62, v64, v62
	v_mul_f32_e32 v63, v66, v63
	v_mul_f32_e32 v56, v60, v61
	v_mul_f32_e32 v54, v54, v55
	v_cvt_pk_bf16_f32 v48, v62, v52
	v_cvt_pk_bf16_f32 v49, v49, v54
	v_cvt_pk_bf16_f32 v50, v63, v53
	v_cvt_pk_bf16_f32 v51, v56, v51
	global_store_dwordx4 v[58:59], v[48:51], off
	global_load_dword v52, v[148:149], off offset:576
	s_nop 0
	v_mov_b32_e32 v48, v44
	v_mov_b32_e32 v44, v42
	v_mov_b32_e32 v49, v36
	v_mov_b32_e32 v36, v45
	v_mov_b32_e32 v45, v34
	v_mov_b32_e32 v34, v43
	v_mov_b32_e32 v50, v40
	v_mov_b32_e32 v40, v46
	v_mov_b32_e32 v51, v32
	v_mov_b32_e32 v32, v41
	v_mov_b32_e32 v41, v38
	v_mov_b32_e32 v38, v47
	s_waitcnt vmcnt(0)
	v_fmamk_f32 v42, v52, 0x3a000000, v156
	s_nop 1
	v_rsq_f32_e32 v46, v42
	v_add_u32_e32 v42, 0x90, v144
	v_mad_i64_i32 v[42:43], s[4:5], v42, s43, v[146:147]
	v_lshl_add_u64 v[42:43], v[42:43], 0, v[120:121]
	s_nop 0
	s_nop 1
	s_nop 0
	v_mov_b32_e32 v46, v46
	s_nop 0
	v_mov_b32_e32 v46, v46
	v_pk_mul_f32 v[36:37], v[36:37], v[46:47] op_sel_hi:[1,0]
	v_pk_mul_f32 v[32:33], v[32:33], v[46:47] op_sel_hi:[1,0]
	v_pk_mul_f32 v[40:41], v[40:41], v[46:47] op_sel_hi:[1,0]
	v_pk_mul_f32 v[34:35], v[34:35], v[46:47] op_sel_hi:[1,0]
	v_pk_mul_f32 v[48:49], v[48:49], v[46:47] op_sel_hi:[1,0]
	v_pk_mul_f32 v[50:51], v[50:51], v[46:47] op_sel_hi:[1,0]
	v_pk_mul_f32 v[44:45], v[44:45], v[46:47] op_sel_hi:[1,0]
	v_pk_mul_f32 v[38:39], v[38:39], v[46:47] op_sel_hi:[1,0]
	v_mul_f32_e32 v52, 0xbfb8aa3b, v37
	v_mul_f32_e32 v53, 0xbfb8aa3b, v33
	v_mul_f32_e32 v54, 0xbfb8aa3b, v41
	v_mul_f32_e32 v57, 0xbfb8aa3b, v35
	v_mul_f32_e32 v46, 0xbfb8aa3b, v49
	v_mul_f32_e32 v47, 0xbfb8aa3b, v51
	v_mul_f32_e32 v55, 0xbfb8aa3b, v45
	v_mul_f32_e32 v56, 0xbfb8aa3b, v39
	v_exp_f32_e32 v52, v52
	v_exp_f32_e32 v53, v53
	v_exp_f32_e32 v54, v54
	v_exp_f32_e32 v57, v57
	v_exp_f32_e32 v46, v46
	v_exp_f32_e32 v47, v47
	v_exp_f32_e32 v55, v55
	v_exp_f32_e32 v56, v56
	v_add_f32_e32 v52, 1.0, v52
	v_add_f32_e32 v53, 1.0, v53
	v_add_f32_e32 v54, 1.0, v54
	v_add_f32_e32 v57, 1.0, v57
	v_add_f32_e32 v46, 1.0, v46
	v_add_f32_e32 v47, 1.0, v47
	v_add_f32_e32 v55, 1.0, v55
	v_add_f32_e32 v56, 1.0, v56
	v_rcp_f32_e32 v52, v52
	v_rcp_f32_e32 v53, v53
	v_rcp_f32_e32 v54, v54
	v_rcp_f32_e32 v57, v57
	v_rcp_f32_e32 v46, v46
	v_rcp_f32_e32 v47, v47
	v_rcp_f32_e32 v55, v55
	v_rcp_f32_e32 v56, v56
	v_mul_f32_e32 v37, v37, v52
	v_mul_f32_e32 v33, v33, v53
	v_mul_f32_e32 v41, v41, v54
	v_mul_f32_e32 v35, v35, v57
	v_mul_f32_e32 v46, v49, v46
	v_mul_f32_e32 v47, v51, v47
	v_mul_f32_e32 v45, v45, v55
	v_mul_f32_e32 v39, v39, v56
	v_mul_f32_e32 v36, v36, v37
	v_mul_f32_e32 v37, v32, v33
	v_mul_f32_e32 v33, v40, v41
	v_mul_f32_e32 v35, v34, v35
	v_mul_f32_e32 v46, v48, v46
	v_mul_f32_e32 v47, v50, v47
	v_mul_f32_e32 v40, v44, v45
	v_mul_f32_e32 v38, v38, v39
	v_cvt_pk_bf16_f32 v32, v46, v36
	v_cvt_pk_bf16_f32 v33, v33, v38
	v_cvt_pk_bf16_f32 v34, v47, v37
	v_cvt_pk_bf16_f32 v35, v40, v35
	global_store_dwordx4 v[42:43], v[32:35], off
	global_load_dword v36, v[148:149], off offset:640
	s_nop 0
	v_mov_b32_e32 v32, v28
	v_mov_b32_e32 v28, v26
	v_mov_b32_e32 v33, v20
	v_mov_b32_e32 v20, v29
	v_mov_b32_e32 v29, v18
	v_mov_b32_e32 v18, v27
	v_mov_b32_e32 v34, v24
	v_mov_b32_e32 v24, v30
	v_mov_b32_e32 v35, v16
	v_mov_b32_e32 v16, v25
	v_mov_b32_e32 v25, v22
	v_mov_b32_e32 v22, v31
	s_waitcnt vmcnt(0)
; __device__ __forceinline__ unsigned cvt_pk_bf16(float lo, float hi) { unsigned r; asm volatile("v_cvt_pk_bf16_f32 %0, %1, %2" : "=v"(r) : "v"(lo), "v"(hi)); return r; }
; __device__ __forceinline__ float silu_f(float g) { return g * __builtin_amdgcn_rcpf(1.0f + __builtin_amdgcn_exp2f(-1.44269504089f * g)); }
; #define PG8_BAR __builtin_amdgcn_s_barrier()
;     __device__ __forceinline__ void operator()(const f32x4 (&acc)[2][2][4][2], const Unit& u, int wr, int wc, int fr, int fq) const {
;     ...
;             for (int m = 0; m < 4; ++m) { bf16_t* rowp = O + (size_t)(row0 + ai * HALF + m * 16) * ldc + col0;
;                 const float rs = rowss ? 1.0f / sqrtf(rowss[row0 + ai * HALF + m * 16] * (1.0f / 2048.0f) + 1e-6f) : 1.0f;
;                 const f32x4 g0 = acc[ai][0][m][0] * rs, g1 = acc[ai][0][m][1] * rs, u0 = acc[ai][1][m][0] * rs, u1 = acc[ai][1][m][1] * rs;
;                 float h[8];
; #pragma unroll
;                 for (int j = 0; j < 4; ++j) { h[j] = silu_f(g0[j]) * u0[j]; h[4 + j] = silu_f(g1[j]) * u1[j]; }
;                 u32x4 w; w.x = cvt_pk_bf16(h[0], h[1]); w.y = cvt_pk_bf16(h[2], h[3]); w.z = cvt_pk_bf16(h[4], h[5]); w.w = cvt_pk_bf16(h[6], h[7]);
;                 *(u32x4*)rowp = w; }
; template <class Epi, class Sched, bool ALIGN_EPI = false, bool SP2 = false>
; __device__ __forceinline__ void gemm_phase(PG8_LAS unsigned char* lds, const Gemm g, const Sched& S, const Epi& E, int wave_in) {
;     ...
;         if constexpr (ALIGN_EPI) { if (wr == 0) PG8_BAR; }
;         if constexpr (!Epi::AFTER_DRAIN) { E(acc, cur, wr, wc, fr, fq); S.done(cur); }
;         if (!has_next) break;
; #pragma unroll
;         for (int a = 0; a < 2; ++a)
; #pragma unroll
;             for (int b = 0; b < 2; ++b)
; #pragma unroll
;                 for (int m = 0; m < 4; ++m)
; #pragma unroll
;                     for (int n = 0; n < 2; ++n) acc[a][b][m][n] = (f32x4){0.f, 0.f, 0.f, 0.f};
;         cur = nxt; cA = nA; cB = nB; ++ui;
;         if constexpr (ALIGN_EPI) { if (wr == 1) PG8_BAR; }
	v_fmamk_f32 v26, v36, 0x3a000000, v156
	s_nop 1
	v_rsq_f32_e32 v30, v26
	v_add_u32_e32 v26, 0xa0, v144
	v_mad_i64_i32 v[26:27], s[4:5], v26, s43, v[146:147]
	v_lshl_add_u64 v[26:27], v[26:27], 0, v[120:121]
	s_nop 0
	s_nop 1
	s_nop 0
	v_mov_b32_e32 v30, v30
	s_nop 0
	v_mov_b32_e32 v30, v30
	v_pk_mul_f32 v[20:21], v[20:21], v[30:31] op_sel_hi:[1,0]
	v_pk_mul_f32 v[16:17], v[16:17], v[30:31] op_sel_hi:[1,0]
	v_pk_mul_f32 v[24:25], v[24:25], v[30:31] op_sel_hi:[1,0]
	v_pk_mul_f32 v[18:19], v[18:19], v[30:31] op_sel_hi:[1,0]
	v_pk_mul_f32 v[32:33], v[32:33], v[30:31] op_sel_hi:[1,0]
	v_pk_mul_f32 v[34:35], v[34:35], v[30:31] op_sel_hi:[1,0]
	v_pk_mul_f32 v[28:29], v[28:29], v[30:31] op_sel_hi:[1,0]
	v_pk_mul_f32 v[22:23], v[22:23], v[30:31] op_sel_hi:[1,0]
	v_mul_f32_e32 v36, 0xbfb8aa3b, v21
	v_mul_f32_e32 v37, 0xbfb8aa3b, v17
	v_mul_f32_e32 v38, 0xbfb8aa3b, v25
	v_mul_f32_e32 v41, 0xbfb8aa3b, v19
	v_mul_f32_e32 v30, 0xbfb8aa3b, v33
	v_mul_f32_e32 v31, 0xbfb8aa3b, v35
	v_mul_f32_e32 v39, 0xbfb8aa3b, v29
	v_mul_f32_e32 v40, 0xbfb8aa3b, v23
	v_exp_f32_e32 v36, v36
	v_exp_f32_e32 v37, v37
	v_exp_f32_e32 v38, v38
	v_exp_f32_e32 v41, v41
	v_exp_f32_e32 v30, v30
	v_exp_f32_e32 v31, v31
	v_exp_f32_e32 v39, v39
	v_exp_f32_e32 v40, v40
	v_add_f32_e32 v36, 1.0, v36
	v_add_f32_e32 v37, 1.0, v37
	v_add_f32_e32 v38, 1.0, v38
	v_add_f32_e32 v41, 1.0, v41
	v_add_f32_e32 v30, 1.0, v30
	v_add_f32_e32 v31, 1.0, v31
	v_add_f32_e32 v39, 1.0, v39
	v_add_f32_e32 v40, 1.0, v40
	v_rcp_f32_e32 v36, v36
	v_rcp_f32_e32 v37, v37
	v_rcp_f32_e32 v38, v38
	v_rcp_f32_e32 v41, v41
	v_rcp_f32_e32 v30, v30
	v_rcp_f32_e32 v31, v31
	v_rcp_f32_e32 v39, v39
	v_rcp_f32_e32 v40, v40
	v_mul_f32_e32 v21, v21, v36
	v_mul_f32_e32 v17, v17, v37
	v_mul_f32_e32 v25, v25, v38
	v_mul_f32_e32 v19, v19, v41
	v_mul_f32_e32 v30, v33, v30
	v_mul_f32_e32 v31, v35, v31
	v_mul_f32_e32 v29, v29, v39
	v_mul_f32_e32 v23, v23, v40
	v_mul_f32_e32 v20, v20, v21
	v_mul_f32_e32 v21, v16, v17
	v_mul_f32_e32 v17, v24, v25
	v_mul_f32_e32 v19, v18, v19
	v_mul_f32_e32 v30, v32, v30
	v_mul_f32_e32 v31, v34, v31
	v_mul_f32_e32 v24, v28, v29
	v_mul_f32_e32 v22, v22, v23
	v_cvt_pk_bf16_f32 v16, v30, v20
	v_cvt_pk_bf16_f32 v17, v17, v22
	v_cvt_pk_bf16_f32 v18, v31, v21
	v_cvt_pk_bf16_f32 v19, v24, v19
	global_store_dwordx4 v[26:27], v[16:19], off
	global_load_dword v20, v[148:149], off offset:704
	s_nop 0
	v_mov_b32_e32 v17, v4
	v_mov_b32_e32 v4, v13
	v_mov_b32_e32 v13, v2
	v_mov_b32_e32 v2, v11
	v_mov_b32_e32 v18, v8
	v_mov_b32_e32 v8, v14
	v_mov_b32_e32 v19, v0
	v_mov_b32_e32 v0, v9
	v_mov_b32_e32 v9, v6
	v_mov_b32_e32 v6, v15
	v_mov_b32_e32 v16, v12
	v_mov_b32_e32 v12, v10
	v_add_u32_e32 v10, 0xb0, v144
	s_waitcnt vmcnt(0)
	v_fmamk_f32 v11, v20, 0x3a000000, v156
	s_nop 1
	v_rsq_f32_e32 v14, v11
	v_mad_i64_i32 v[10:11], s[4:5], v10, s43, v[146:147]
	v_lshl_add_u64 v[10:11], v[10:11], 0, v[120:121]
	s_nop 1
	s_nop 0
	v_mov_b32_e32 v14, v14
	s_mov_b64 s[4:5], -1
	s_nop 0
	v_mov_b32_e32 v14, v14
	v_pk_mul_f32 v[4:5], v[4:5], v[14:15] op_sel_hi:[1,0]
	v_pk_mul_f32 v[0:1], v[0:1], v[14:15] op_sel_hi:[1,0]
	v_pk_mul_f32 v[8:9], v[8:9], v[14:15] op_sel_hi:[1,0]
	v_pk_mul_f32 v[2:3], v[2:3], v[14:15] op_sel_hi:[1,0]
	v_pk_mul_f32 v[16:17], v[16:17], v[14:15] op_sel_hi:[1,0]
	v_pk_mul_f32 v[18:19], v[18:19], v[14:15] op_sel_hi:[1,0]
	v_pk_mul_f32 v[12:13], v[12:13], v[14:15] op_sel_hi:[1,0]
	v_pk_mul_f32 v[6:7], v[6:7], v[14:15] op_sel_hi:[1,0]
	v_mul_f32_e32 v20, 0xbfb8aa3b, v5
	v_mul_f32_e32 v21, 0xbfb8aa3b, v1
	v_mul_f32_e32 v22, 0xbfb8aa3b, v9
	v_mul_f32_e32 v25, 0xbfb8aa3b, v3
	v_mul_f32_e32 v14, 0xbfb8aa3b, v17
	v_mul_f32_e32 v15, 0xbfb8aa3b, v19
	v_mul_f32_e32 v23, 0xbfb8aa3b, v13
	v_mul_f32_e32 v24, 0xbfb8aa3b, v7
	v_exp_f32_e32 v20, v20
	v_exp_f32_e32 v21, v21
	v_exp_f32_e32 v22, v22
	v_exp_f32_e32 v25, v25
	v_exp_f32_e32 v14, v14
	v_exp_f32_e32 v15, v15
	v_exp_f32_e32 v23, v23
	v_exp_f32_e32 v24, v24
	v_add_f32_e32 v20, 1.0, v20
	v_add_f32_e32 v21, 1.0, v21
	v_add_f32_e32 v22, 1.0, v22
	v_add_f32_e32 v25, 1.0, v25
	v_add_f32_e32 v14, 1.0, v14
	v_add_f32_e32 v15, 1.0, v15
	v_add_f32_e32 v23, 1.0, v23
	v_add_f32_e32 v24, 1.0, v24
	v_rcp_f32_e32 v20, v20
	v_rcp_f32_e32 v21, v21
	v_rcp_f32_e32 v22, v22
	v_rcp_f32_e32 v25, v25
	v_rcp_f32_e32 v14, v14
	v_rcp_f32_e32 v15, v15
	v_rcp_f32_e32 v23, v23
	v_rcp_f32_e32 v24, v24
	v_mul_f32_e32 v5, v5, v20
	v_mul_f32_e32 v1, v1, v21
	v_mul_f32_e32 v9, v9, v22
	v_mul_f32_e32 v3, v3, v25
	s_andn2_b64 vcc, exec, s[6:7]
	v_mul_f32_e32 v14, v17, v14
	v_mul_f32_e32 v15, v19, v15
	v_mul_f32_e32 v13, v13, v23
	v_mul_f32_e32 v7, v7, v24
	v_mul_f32_e32 v4, v4, v5
	v_mul_f32_e32 v5, v0, v1
	v_mul_f32_e32 v1, v8, v9
	v_mul_f32_e32 v3, v2, v3
	v_mul_f32_e32 v14, v16, v14
	v_mul_f32_e32 v15, v18, v15
	v_mul_f32_e32 v8, v12, v13
	v_mul_f32_e32 v6, v6, v7
	v_cvt_pk_bf16_f32 v0, v14, v4
	v_cvt_pk_bf16_f32 v1, v1, v6
	v_cvt_pk_bf16_f32 v2, v15, v5
	v_cvt_pk_bf16_f32 v3, v8, v3
	global_store_dwordx4 v[10:11], v[0:3], off
	s_cbranch_vccnz .LBB0_925
	s_andn2_b64 vcc, exec, s[0:1]
	s_cbranch_vccnz .LBB0_924
	s_barrier
	s_branch .LBB0_924
